# GEMM K loops: all per-phase s_setprio flips deleted, one static s_setprio 1 for waves 4-7 per tile (reset at epilogue), on top of v10
# speedup vs baseline: 1.0118x; 1.0034x over previous
.LBB0_228:
	v_readfirstlane_b32 s100, v216
	s_nop 0
	s_bitcmp1_b32 s100, 8
	s_cbranch_scc0 .Lmy_sp_0
	s_setprio 1

.LBB0_231:
	s_add_u32 s30, s28, 0xfffc0080
	s_addc_u32 s31, s29, -1
	s_add_i32 s64, 0, 0x10000
	s_cmp_eq_u32 s63, 12
	s_cselect_b32 s47, s41, s31
	s_cselect_b32 s46, s59, s30
	v_add_u32_e32 v144, s64, v147
	s_cselect_b32 s31, s39, s62
	s_cselect_b32 s30, s60, s61
	s_add_i32 s66, 0, 0x14000
	ds_read_b128 v[140:143], v144
	ds_read_b128 v[152:155], v144 offset:1024
	ds_read_b128 v[156:159], v144 offset:2048
	ds_read_b128 v[160:163], v144 offset:3072
	v_add_u32_e32 v144, s66, v147
	ds_read_b128 v[164:167], v144
	ds_read_b128 v[168:171], v144 offset:1024
	ds_read_b128 v[172:175], v144 offset:2048
	ds_read_b128 v[176:179], v144 offset:3072
	v_lshl_add_u64 v[144:145], s[28:29], 0, v[136:137]
	s_add_i32 m0, s50, 0xc000
	ds_read_b128 v[180:183], v150
	ds_read_b128 v[198:201], v150 offset:1024
	ds_read_b128 v[202:205], v150 offset:2048
	ds_read_b128 v[206:209], v150 offset:3072
	ds_read_b128 v[210:213], v150 offset:4096
	ds_read_b128 v[220:223], v150 offset:5120
	ds_read_b128 v[224:227], v150 offset:6144
	ds_read_b128 v[228:231], v150 offset:7168
	global_load_lds_dwordx4 v[144:145], off
	v_lshl_add_u64 v[144:145], s[28:29], 0, v[138:139]
	s_add_i32 m0, s50, 0xe000
	s_nop 0
	global_load_lds_dwordx4 v[144:145], off
	s_waitcnt vmcnt(8)
	s_waitcnt lgkmcnt(0)
	s_barrier
	s_waitcnt lgkmcnt(0)
	v_mfma_f32_16x16x32_bf16 v[126:129], v[140:143], v[180:183], v[126:129]
	v_mfma_f32_16x16x32_bf16 v[118:121], v[156:159], v[180:183], v[118:121]
	v_mfma_f32_16x16x32_bf16 v[110:113], v[140:143], v[202:205], v[110:113]
	v_mfma_f32_16x16x32_bf16 v[102:105], v[156:159], v[202:205], v[102:105]
	v_mfma_f32_16x16x32_bf16 v[94:97], v[140:143], v[210:213], v[94:97]
	v_mfma_f32_16x16x32_bf16 v[86:89], v[156:159], v[210:213], v[86:89]
	v_mfma_f32_16x16x32_bf16 v[78:81], v[140:143], v[224:227], v[78:81]
	v_mfma_f32_16x16x32_bf16 v[70:73], v[156:159], v[224:227], v[70:73]
	v_mfma_f32_16x16x32_bf16 v[126:129], v[152:155], v[198:201], v[126:129]
	v_mfma_f32_16x16x32_bf16 v[118:121], v[160:163], v[198:201], v[118:121]
	v_mfma_f32_16x16x32_bf16 v[110:113], v[152:155], v[206:209], v[110:113]
	v_mfma_f32_16x16x32_bf16 v[102:105], v[160:163], v[206:209], v[102:105]
	v_mfma_f32_16x16x32_bf16 v[94:97], v[152:155], v[220:223], v[94:97]
	v_mfma_f32_16x16x32_bf16 v[86:89], v[160:163], v[220:223], v[86:89]
	v_mfma_f32_16x16x32_bf16 v[78:81], v[152:155], v[228:231], v[78:81]
	v_mfma_f32_16x16x32_bf16 v[70:73], v[160:163], v[228:231], v[70:73]
	v_mfma_f32_16x16x32_bf16 v[122:125], v[164:167], v[180:183], v[122:125]
	v_mfma_f32_16x16x32_bf16 v[114:117], v[172:175], v[180:183], v[114:117]
	v_mfma_f32_16x16x32_bf16 v[106:109], v[164:167], v[202:205], v[106:109]
	v_mfma_f32_16x16x32_bf16 v[98:101], v[172:175], v[202:205], v[98:101]
	v_mfma_f32_16x16x32_bf16 v[90:93], v[164:167], v[210:213], v[90:93]
	v_mfma_f32_16x16x32_bf16 v[82:85], v[172:175], v[210:213], v[82:85]
	v_mfma_f32_16x16x32_bf16 v[74:77], v[164:167], v[224:227], v[74:77]
	v_mfma_f32_16x16x32_bf16 v[66:69], v[172:175], v[224:227], v[66:69]
	v_mfma_f32_16x16x32_bf16 v[122:125], v[168:171], v[198:201], v[122:125]
	v_mfma_f32_16x16x32_bf16 v[114:117], v[176:179], v[198:201], v[114:117]
	v_mfma_f32_16x16x32_bf16 v[106:109], v[168:171], v[206:209], v[106:109]
	v_mfma_f32_16x16x32_bf16 v[98:101], v[176:179], v[206:209], v[98:101]
	v_mfma_f32_16x16x32_bf16 v[90:93], v[168:171], v[220:223], v[90:93]
	v_mfma_f32_16x16x32_bf16 v[82:85], v[176:179], v[220:223], v[82:85]
	v_mfma_f32_16x16x32_bf16 v[74:77], v[168:171], v[228:231], v[74:77]
	v_mfma_f32_16x16x32_bf16 v[66:69], v[176:179], v[228:231], v[66:69]
	s_barrier
	s_add_i32 s64, s64, s49
	v_lshl_add_u64 v[144:145], s[30:31], 0, v[0:1]
	s_mov_b32 m0, s64
	ds_read_b128 v[180:183], v150 offset:16384
	ds_read_b128 v[198:201], v150 offset:17408
	ds_read_b128 v[202:205], v150 offset:18432
	ds_read_b128 v[206:209], v150 offset:19456
	ds_read_b128 v[210:213], v150 offset:20480
	ds_read_b128 v[220:223], v150 offset:21504
	ds_read_b128 v[224:227], v150 offset:22528
	ds_read_b128 v[228:231], v150 offset:23552
	global_load_lds_dwordx4 v[144:145], off
	s_add_i32 m0, s64, 0x2000
	s_add_u32 s64, s30, 0x40000
	v_lshl_add_u64 v[214:215], s[30:31], 0, v[130:131]
	s_addc_u32 s65, s31, 0
	s_add_i32 s66, s66, s49
	global_load_lds_dwordx4 v[214:215], off
	v_lshl_add_u64 v[248:249], s[64:65], 0, v[0:1]
	s_mov_b32 m0, s66
	v_lshl_add_u64 v[242:243], s[46:47], 0, v[132:133]
	global_load_lds_dwordx4 v[248:249], off
	v_lshl_add_u64 v[248:249], s[64:65], 0, v[130:131]
	s_add_i32 m0, s66, 0x2000
	s_nop 0
	global_load_lds_dwordx4 v[248:249], off
	v_lshl_add_u64 v[248:249], s[46:47], 0, v[134:135]
	s_mov_b32 m0, s50
	s_nop 0
	global_load_lds_dwordx4 v[248:249], off
	s_mov_b32 m0, s51
	s_nop 0
	global_load_lds_dwordx4 v[242:243], off
	s_waitcnt vmcnt(8)
	s_waitcnt lgkmcnt(0)
	s_barrier
; #define PG8_STAGE(bufoff, gbase, voff) do { _Pragma("unroll") for (int _i = 0; _i < 2; ++_i) \
;         __builtin_amdgcn_global_load_lds((const unsigned*)((const char*)(gbase) + (voff)[_i]), (LAS unsigned*)(lds + (bufoff) + ldsw + _i * 8192), 16, 0, 0); } while (0)
; #define PG8_LDA(dst, b, h) do { _Pragma("unroll") for (int m = 0; m < 4; ++m) _Pragma("unroll") for (int k = 0; k < 2; ++k) dst[m][k] = *(const LAS bf16x8*)(lds + PG8_SA(b, h) + aoff + m * 2048 + k * 1024); } while (0)
; #define PG8_LDB(dst, b, h) do { _Pragma("unroll") for (int n = 0; n < 2; ++n) _Pragma("unroll") for (int k = 0; k < 2; ++k) dst[n][k] = *(const LAS bf16x8*)(lds + PG8_SB(b, h) + boff + n * 2048 + k * 1024); } while (0)
; #define PG8_MMA(ai, bj, At, Bt) do { __builtin_amdgcn_s_setprio(1); _Pragma("unroll") for (int m = 0; m < 4; ++m) _Pragma("unroll") for (int n = 0; n < 2; ++n) _Pragma("unroll") for (int k = 0; k < 2; ++k) \
;         acc[ai][bj][m][n] = __builtin_amdgcn_mfma_f32_16x16x32_bf16(Bt[n][k], At[m][k], acc[ai][bj][m][n], 0, 0, 0); __builtin_amdgcn_s_setprio(0); } while (0)
; #define PG8_WAIT_V(n) asm volatile("s_waitcnt vmcnt(" #n ")" ::: "memory")
; #define PG8_WAIT_L(n) asm volatile("s_waitcnt lgkmcnt(" #n ")" ::: "memory")
; #define PG8_BAR __builtin_amdgcn_s_barrier()
; #define PG8_SCHED __builtin_amdgcn_sched_barrier(0)
; template <class Epi, class Sched, bool ALIGN_EPI = GEMM_ALIGN, bool SP2 = GEMM_SP2>
; __device__ __forceinline__ void gemm_phase(lptr lds, const Gemm g, const Sched& S, const Epi& E) {
;     ...
;             PG8_WAIT_V(8); PG8_WAIT_L(0); PG8_BAR; PG8_MMA(0, 0, At, B0); PG8_MMA(0, 1, At, B1); PG8_BAR; PG8_SCHED;
;             PG8_LDA(At, 0, 1); PG8_STAGE(PG8_SB(0, 0), b2, voffB); PG8_STAGE(PG8_SB(0, 1), b2 + hstepB, voffB); PG8_STAGE(PG8_SA(0, 0), a2, voffA);
;             PG8_WAIT_V(8); PG8_WAIT_L(0); PG8_BAR; PG8_MMA(1, 0, At, B0); PG8_MMA(1, 1, At, B1); PG8_BAR; PG8_SCHED;
;             PG8_LDB(B0, 1, 0); PG8_LDB(B1, 1, 1); PG8_SCHED; PG8_LDA(At, 1, 0); PG8_STAGE(PG8_SA(0, 1), a2 + hstepA, voffA);
;             PG8_WAIT_V(8); PG8_WAIT_L(0); PG8_BAR; PG8_MMA(0, 0, At, B0); PG8_MMA(0, 1, At, B1); PG8_BAR; PG8_SCHED;
	s_waitcnt lgkmcnt(0)
	v_mfma_f32_16x16x32_bf16 v[62:65], v[140:143], v[180:183], v[62:65]
	v_mfma_f32_16x16x32_bf16 v[54:57], v[156:159], v[180:183], v[54:57]
	v_mfma_f32_16x16x32_bf16 v[46:49], v[140:143], v[202:205], v[46:49]
	v_mfma_f32_16x16x32_bf16 v[38:41], v[156:159], v[202:205], v[38:41]
	v_mfma_f32_16x16x32_bf16 v[30:33], v[140:143], v[210:213], v[30:33]
	v_mfma_f32_16x16x32_bf16 v[22:25], v[156:159], v[210:213], v[22:25]
	v_mfma_f32_16x16x32_bf16 v[14:17], v[140:143], v[224:227], v[14:17]
	v_mfma_f32_16x16x32_bf16 v[6:9], v[156:159], v[224:227], v[6:9]
	v_mfma_f32_16x16x32_bf16 v[62:65], v[152:155], v[198:201], v[62:65]
	v_mfma_f32_16x16x32_bf16 v[54:57], v[160:163], v[198:201], v[54:57]
	v_mfma_f32_16x16x32_bf16 v[46:49], v[152:155], v[206:209], v[46:49]
	v_mfma_f32_16x16x32_bf16 v[38:41], v[160:163], v[206:209], v[38:41]
	v_mfma_f32_16x16x32_bf16 v[30:33], v[152:155], v[220:223], v[30:33]
	v_mfma_f32_16x16x32_bf16 v[22:25], v[160:163], v[220:223], v[22:25]
	v_mfma_f32_16x16x32_bf16 v[14:17], v[152:155], v[228:231], v[14:17]
	v_mfma_f32_16x16x32_bf16 v[6:9], v[160:163], v[228:231], v[6:9]
	v_mfma_f32_16x16x32_bf16 v[58:61], v[164:167], v[180:183], v[58:61]
	v_mfma_f32_16x16x32_bf16 v[50:53], v[172:175], v[180:183], v[50:53]
	v_mfma_f32_16x16x32_bf16 v[42:45], v[164:167], v[202:205], v[42:45]
	v_mfma_f32_16x16x32_bf16 v[34:37], v[172:175], v[202:205], v[34:37]
	v_mfma_f32_16x16x32_bf16 v[26:29], v[164:167], v[210:213], v[26:29]
	v_mfma_f32_16x16x32_bf16 v[18:21], v[172:175], v[210:213], v[18:21]
	v_mfma_f32_16x16x32_bf16 v[10:13], v[164:167], v[224:227], v[10:13]
	v_mfma_f32_16x16x32_bf16 v[2:5], v[172:175], v[224:227], v[2:5]
	v_mfma_f32_16x16x32_bf16 v[58:61], v[168:171], v[198:201], v[58:61]
	v_mfma_f32_16x16x32_bf16 v[50:53], v[176:179], v[198:201], v[50:53]
	v_mfma_f32_16x16x32_bf16 v[42:45], v[168:171], v[206:209], v[42:45]
	v_mfma_f32_16x16x32_bf16 v[34:37], v[176:179], v[206:209], v[34:37]
	v_mfma_f32_16x16x32_bf16 v[26:29], v[168:171], v[220:223], v[26:29]
	v_mfma_f32_16x16x32_bf16 v[18:21], v[176:179], v[220:223], v[18:21]
	v_mfma_f32_16x16x32_bf16 v[10:13], v[168:171], v[228:231], v[10:13]
	v_mfma_f32_16x16x32_bf16 v[2:5], v[176:179], v[228:231], v[2:5]
	s_barrier
	s_add_i32 s64, 0, 0x18000
	v_add_u32_e32 v151, s64, v147
	s_add_i32 s65, 0, 0x1c000
	ds_read_b128 v[140:143], v151
	ds_read_b128 v[152:155], v151 offset:1024
	ds_read_b128 v[156:159], v151 offset:2048
	ds_read_b128 v[160:163], v151 offset:3072
	v_add_u32_e32 v151, s65, v147
	ds_read_b128 v[164:167], v151
	ds_read_b128 v[168:171], v151 offset:1024
	ds_read_b128 v[172:175], v151 offset:2048
	ds_read_b128 v[176:179], v151 offset:3072
	s_add_u32 s46, s46, 0x40000
	s_addc_u32 s47, s47, 0
	s_mov_b32 m0, s52
	v_lshl_add_u64 v[232:233], s[46:47], 0, v[134:135]
	ds_read_b128 v[180:183], v150 offset:32768
	ds_read_b128 v[198:201], v150 offset:33792
	ds_read_b128 v[202:205], v150 offset:34816
	ds_read_b128 v[206:209], v150 offset:35840
	ds_read_b128 v[210:213], v150 offset:36864
	ds_read_b128 v[220:223], v150 offset:37888
	ds_read_b128 v[224:227], v150 offset:38912
	ds_read_b128 v[228:231], v150 offset:39936
	global_load_lds_dwordx4 v[232:233], off
	v_lshl_add_u64 v[232:233], s[46:47], 0, v[132:133]
	s_mov_b32 m0, s53
	s_nop 0
	global_load_lds_dwordx4 v[232:233], off
	s_waitcnt vmcnt(8)
	s_waitcnt lgkmcnt(0)
	s_barrier
	s_waitcnt lgkmcnt(0)
	v_mfma_f32_16x16x32_bf16 v[126:129], v[140:143], v[180:183], v[126:129]
	v_mfma_f32_16x16x32_bf16 v[118:121], v[156:159], v[180:183], v[118:121]
	v_mfma_f32_16x16x32_bf16 v[110:113], v[140:143], v[202:205], v[110:113]
	v_mfma_f32_16x16x32_bf16 v[102:105], v[156:159], v[202:205], v[102:105]
	v_mfma_f32_16x16x32_bf16 v[94:97], v[140:143], v[210:213], v[94:97]
	v_mfma_f32_16x16x32_bf16 v[86:89], v[156:159], v[210:213], v[86:89]
	v_mfma_f32_16x16x32_bf16 v[78:81], v[140:143], v[224:227], v[78:81]
	v_mfma_f32_16x16x32_bf16 v[70:73], v[156:159], v[224:227], v[70:73]
	v_mfma_f32_16x16x32_bf16 v[126:129], v[152:155], v[198:201], v[126:129]
	v_mfma_f32_16x16x32_bf16 v[118:121], v[160:163], v[198:201], v[118:121]
	v_mfma_f32_16x16x32_bf16 v[110:113], v[152:155], v[206:209], v[110:113]
	v_mfma_f32_16x16x32_bf16 v[102:105], v[160:163], v[206:209], v[102:105]
	v_mfma_f32_16x16x32_bf16 v[94:97], v[152:155], v[220:223], v[94:97]
	v_mfma_f32_16x16x32_bf16 v[86:89], v[160:163], v[220:223], v[86:89]
	v_mfma_f32_16x16x32_bf16 v[78:81], v[152:155], v[228:231], v[78:81]
	v_mfma_f32_16x16x32_bf16 v[70:73], v[160:163], v[228:231], v[70:73]
	v_mfma_f32_16x16x32_bf16 v[122:125], v[164:167], v[180:183], v[122:125]
	v_mfma_f32_16x16x32_bf16 v[114:117], v[172:175], v[180:183], v[114:117]
	v_mfma_f32_16x16x32_bf16 v[106:109], v[164:167], v[202:205], v[106:109]
	v_mfma_f32_16x16x32_bf16 v[98:101], v[172:175], v[202:205], v[98:101]
	v_mfma_f32_16x16x32_bf16 v[90:93], v[164:167], v[210:213], v[90:93]
	v_mfma_f32_16x16x32_bf16 v[82:85], v[172:175], v[210:213], v[82:85]
	v_mfma_f32_16x16x32_bf16 v[74:77], v[164:167], v[224:227], v[74:77]
	v_mfma_f32_16x16x32_bf16 v[66:69], v[172:175], v[224:227], v[66:69]
	v_mfma_f32_16x16x32_bf16 v[122:125], v[168:171], v[198:201], v[122:125]
	v_mfma_f32_16x16x32_bf16 v[114:117], v[176:179], v[198:201], v[114:117]
	v_mfma_f32_16x16x32_bf16 v[106:109], v[168:171], v[206:209], v[106:109]
	v_mfma_f32_16x16x32_bf16 v[98:101], v[176:179], v[206:209], v[98:101]
	v_mfma_f32_16x16x32_bf16 v[90:93], v[168:171], v[220:223], v[90:93]
	v_mfma_f32_16x16x32_bf16 v[82:85], v[176:179], v[220:223], v[82:85]
	v_mfma_f32_16x16x32_bf16 v[74:77], v[168:171], v[228:231], v[74:77]
	v_mfma_f32_16x16x32_bf16 v[66:69], v[176:179], v[228:231], v[66:69]
	s_barrier
; __device__ __forceinline__ float siluf_(float x) { return x * sigmoidf_(x); }
; #define PG8_STAGE(bufoff, gbase, voff) do { _Pragma("unroll") for (int _i = 0; _i < 2; ++_i) \
;         __builtin_amdgcn_global_load_lds((const unsigned*)((const char*)(gbase) + (voff)[_i]), (LAS unsigned*)(lds + (bufoff) + ldsw + _i * 8192), 16, 0, 0); } while (0)
; #define PG8_LDA(dst, b, h) do { _Pragma("unroll") for (int m = 0; m < 4; ++m) _Pragma("unroll") for (int k = 0; k < 2; ++k) dst[m][k] = *(const LAS bf16x8*)(lds + PG8_SA(b, h) + aoff + m * 2048 + k * 1024); } while (0)
; #define PG8_MMA(ai, bj, At, Bt) do { __builtin_amdgcn_s_setprio(1); _Pragma("unroll") for (int m = 0; m < 4; ++m) _Pragma("unroll") for (int n = 0; n < 2; ++n) _Pragma("unroll") for (int k = 0; k < 2; ++k) \
;         acc[ai][bj][m][n] = __builtin_amdgcn_mfma_f32_16x16x32_bf16(Bt[n][k], At[m][k], acc[ai][bj][m][n], 0, 0, 0); __builtin_amdgcn_s_setprio(0); } while (0)
; #define PG8_WAIT_V(n) asm volatile("s_waitcnt vmcnt(" #n ")" ::: "memory")
; #define PG8_BAR __builtin_amdgcn_s_barrier()
; template <class Epi, class Sched, bool ALIGN_EPI = GEMM_ALIGN, bool SP2 = GEMM_SP2>
; __device__ __forceinline__ void gemm_phase(lptr lds, const Gemm g, const Sched& S, const Epi& E) {
;     ...
;             PG8_LDA(At, 1, 1); PG8_STAGE(PG8_SB(1, 0), b3, voffB); PG8_STAGE(PG8_SB(1, 1), b3 + hstepB, voffB); PG8_STAGE(PG8_SA(1, 0), a3, voffA);
;             PG8_WAIT_V(8); PG8_WAIT_L(0); PG8_BAR; PG8_MMA(1, 0, At, B0); PG8_MMA(1, 1, At, B1); PG8_BAR; PG8_SCHED;
;     ...
;         if constexpr (ALIGN_EPI) { if (wr == 0) PG8_BAR; }
;     __device__ __forceinline__ void operator()(const f32x4 (&acc)[2][2][4][2], const Unit& u, int wr, int wc, int fr, int fq) const {
;         const int row0 = u.pm * BM + wr * 64 + fr, col0 = u.pn * 128 + wc * 32 + 8 * fq;
;         float rsv[2][4];
; #pragma unroll
;         for (int ai = 0; ai < 2; ++ai)
; #pragma unroll
;             for (int m = 0; m < 4; ++m) rsv[ai][m] = rst[u.ord * 256 + wr * 64 + fr + ai * HALF + m * 16];
; #pragma unroll
;         for (int ai = 0; ai < 2; ++ai)
; #pragma unroll
;             for (int m = 0; m < 4; ++m) { float o[8]; const float rs = rsv[ai][m];
; #pragma unroll
;                 for (int n = 0; n < 2; ++n)
; #pragma unroll
;                     for (int j = 0; j < 4; ++j) o[n * 4 + j] = siluf_(acc[ai][0][m][n][j] * rs) * (acc[ai][1][m][n][j] * rs);
	s_add_i32 s46, s64, s49
	v_lshl_add_u64 v[144:145], v[144:145], 0, s[6:7]
	s_mov_b32 m0, s46
	ds_read_b128 v[180:183], v150 offset:49152
	ds_read_b128 v[198:201], v150 offset:50176
	ds_read_b128 v[202:205], v150 offset:51200
	ds_read_b128 v[206:209], v150 offset:52224
	ds_read_b128 v[210:213], v150 offset:53248
	ds_read_b128 v[220:223], v150 offset:54272
	ds_read_b128 v[224:227], v150 offset:55296
	ds_read_b128 v[228:231], v150 offset:56320
	global_load_lds_dwordx4 v[144:145], off
	s_add_i32 m0, s46, 0x2000
	s_add_u32 s30, s30, 0x40080
	v_lshl_add_u64 v[144:145], v[214:215], 0, s[6:7]
	s_addc_u32 s31, s31, 0
	s_add_i32 s46, s65, s49
	global_load_lds_dwordx4 v[144:145], off
	v_lshl_add_u64 v[144:145], s[30:31], 0, v[0:1]
	s_mov_b32 m0, s46
	s_nop 0
	global_load_lds_dwordx4 v[144:145], off
	v_lshl_add_u64 v[144:145], s[30:31], 0, v[130:131]
	s_add_i32 m0, s46, 0x2000
	s_nop 0
	global_load_lds_dwordx4 v[144:145], off
	v_lshl_add_u64 v[144:145], v[248:249], 0, s[6:7]
	s_mov_b32 m0, s54
	s_nop 0
	global_load_lds_dwordx4 v[144:145], off
	v_lshl_add_u64 v[144:145], v[242:243], 0, s[6:7]
	s_mov_b32 m0, s55
	s_nop 0
	global_load_lds_dwordx4 v[144:145], off
	s_waitcnt vmcnt(8)
	s_waitcnt lgkmcnt(0)
	s_barrier
	s_waitcnt lgkmcnt(0)
	v_mfma_f32_16x16x32_bf16 v[62:65], v[140:143], v[180:183], v[62:65]
	v_mfma_f32_16x16x32_bf16 v[54:57], v[156:159], v[180:183], v[54:57]
	v_mfma_f32_16x16x32_bf16 v[46:49], v[140:143], v[202:205], v[46:49]
	v_mfma_f32_16x16x32_bf16 v[38:41], v[156:159], v[202:205], v[38:41]
	v_mfma_f32_16x16x32_bf16 v[30:33], v[140:143], v[210:213], v[30:33]
	v_mfma_f32_16x16x32_bf16 v[22:25], v[156:159], v[210:213], v[22:25]
	v_mfma_f32_16x16x32_bf16 v[14:17], v[140:143], v[224:227], v[14:17]
	v_mfma_f32_16x16x32_bf16 v[6:9], v[156:159], v[224:227], v[6:9]
	v_mfma_f32_16x16x32_bf16 v[62:65], v[152:155], v[198:201], v[62:65]
	v_mfma_f32_16x16x32_bf16 v[54:57], v[160:163], v[198:201], v[54:57]
	v_mfma_f32_16x16x32_bf16 v[46:49], v[152:155], v[206:209], v[46:49]
	v_mfma_f32_16x16x32_bf16 v[38:41], v[160:163], v[206:209], v[38:41]
	v_mfma_f32_16x16x32_bf16 v[30:33], v[152:155], v[220:223], v[30:33]
	v_mfma_f32_16x16x32_bf16 v[22:25], v[160:163], v[220:223], v[22:25]
	v_mfma_f32_16x16x32_bf16 v[14:17], v[152:155], v[228:231], v[14:17]
	v_mfma_f32_16x16x32_bf16 v[6:9], v[160:163], v[228:231], v[6:9]
	v_mfma_f32_16x16x32_bf16 v[58:61], v[164:167], v[180:183], v[58:61]
	v_mfma_f32_16x16x32_bf16 v[50:53], v[172:175], v[180:183], v[50:53]
	v_mfma_f32_16x16x32_bf16 v[42:45], v[164:167], v[202:205], v[42:45]
	v_mfma_f32_16x16x32_bf16 v[34:37], v[172:175], v[202:205], v[34:37]
	v_mfma_f32_16x16x32_bf16 v[26:29], v[164:167], v[210:213], v[26:29]
	v_mfma_f32_16x16x32_bf16 v[18:21], v[172:175], v[210:213], v[18:21]
	v_mfma_f32_16x16x32_bf16 v[10:13], v[164:167], v[224:227], v[10:13]
	v_mfma_f32_16x16x32_bf16 v[2:5], v[172:175], v[224:227], v[2:5]
	v_mfma_f32_16x16x32_bf16 v[58:61], v[168:171], v[198:201], v[58:61]
	v_mfma_f32_16x16x32_bf16 v[50:53], v[176:179], v[198:201], v[50:53]
	v_mfma_f32_16x16x32_bf16 v[42:45], v[168:171], v[206:209], v[42:45]
	v_mfma_f32_16x16x32_bf16 v[34:37], v[176:179], v[206:209], v[34:37]
	v_mfma_f32_16x16x32_bf16 v[26:29], v[168:171], v[220:223], v[26:29]
	v_mfma_f32_16x16x32_bf16 v[18:21], v[176:179], v[220:223], v[18:21]
	v_mfma_f32_16x16x32_bf16 v[10:13], v[168:171], v[228:231], v[10:13]
	v_mfma_f32_16x16x32_bf16 v[2:5], v[176:179], v[228:231], v[2:5]
	s_barrier
	s_add_i32 s63, s63, 2
	s_add_u32 s28, s28, 0x100
	s_addc_u32 s29, s29, 0
	s_add_u32 s61, s61, 0x100
	s_addc_u32 s62, s62, 0
	s_cmp_gt_u32 s63, 13
	s_cbranch_scc0 .LBB0_231
	s_and_b64 vcc, exec, s[26:27]
	s_cbranch_vccz .LBB0_234
	s_barrier
.LBB0_234:
	s_setprio 0
	v_lshl_add_u32 v140, s58, 10, v148
	ds_read2_b32 v[152:153], v140 offset1:16
	ds_read2_b32 v[144:145], v140 offset0:32 offset1:48
	ds_read2_b32 v[142:143], v140 offset0:128 offset1:144
	ds_read2_b32 v[140:141], v140 offset0:160 offset1:176
	v_lshl_or_b32 v154, s25, 7, v149
	s_waitcnt lgkmcnt(0)
	v_pk_mul_f32 v[126:127], v[126:127], v[152:153] op_sel_hi:[1,0]
	v_pk_mul_f32 v[122:123], v[122:123], v[152:153] op_sel_hi:[1,0]
	v_mul_f32_e32 v156, 0xbfb8aa3b, v126
	v_mul_f32_e32 v157, 0xbfb8aa3b, v127
	v_exp_f32_e32 v156, v156
	v_exp_f32_e32 v157, v157
	v_pk_mul_f32 v[124:125], v[124:125], v[152:153] op_sel_hi:[1,0]
	v_pk_mul_f32 v[118:119], v[118:119], v[152:153] op_sel_hi:[1,0]
	v_add_f32_e32 v156, 1.0, v156
	v_add_f32_e32 v157, 1.0, v157
	v_rcp_f32_e32 v156, v156
	v_rcp_f32_e32 v157, v157
	v_pk_mul_f32 v[114:115], v[114:115], v[152:153] op_sel_hi:[1,0]
	v_pk_mul_f32 v[116:117], v[116:117], v[152:153] op_sel_hi:[1,0]
	v_lshl_add_u32 v151, s24, 8, v146
	v_pk_mul_f32 v[126:127], v[126:127], v[156:157]
	v_ashrrev_i32_e32 v155, 31, v154
	v_pk_mul_f32 v[122:123], v[122:123], v[126:127]
	v_pk_mul_f32 v[126:127], v[128:129], v[152:153] op_sel_hi:[1,0]
	s_movk_i32 s28, 0x1600
	v_mul_f32_e32 v128, 0xbfb8aa3b, v126
	v_mul_f32_e32 v129, 0xbfb8aa3b, v127
	v_exp_f32_e32 v128, v128
	v_exp_f32_e32 v129, v129
	v_pk_mul_f32 v[94:95], v[94:95], v[144:145] op_sel_hi:[1,0]
	v_pk_mul_f32 v[90:91], v[90:91], v[144:145] op_sel_hi:[1,0]
	v_add_f32_e32 v128, 1.0, v128
	v_add_f32_e32 v129, 1.0, v129
	v_rcp_f32_e32 v128, v128
	v_rcp_f32_e32 v129, v129
	v_pk_mul_f32 v[92:93], v[92:93], v[144:145] op_sel_hi:[1,0]
	v_pk_mul_f32 v[86:87], v[86:87], v[144:145] op_sel_hi:[1,0]
	v_pk_mul_f32 v[82:83], v[82:83], v[144:145] op_sel_hi:[1,0]
	v_pk_mul_f32 v[126:127], v[126:127], v[128:129]
	v_pk_mul_f32 v[84:85], v[84:85], v[144:145] op_sel_hi:[1,0]
	v_pk_mul_f32 v[124:125], v[124:125], v[126:127]
	v_mul_f32_e32 v126, 0xbfb8aa3b, v118
; __device__ __forceinline__ u32x4 pack8(const float* f) { u32x4 o; o.x = pk2(f[0], f[1]); o.y = pk2(f[2], f[3]); o.z = pk2(f[4], f[5]); o.w = pk2(f[6], f[7]); return o; }
; __device__ __forceinline__ float siluf_(float x) { return x * sigmoidf_(x); }
;     __device__ __forceinline__ void operator()(const f32x4 (&acc)[2][2][4][2], const Unit& u, int wr, int wc, int fr, int fq) const {
;     ...
;             for (int m = 0; m < 4; ++m) { float o[8]; const float rs = rsv[ai][m];
; #pragma unroll
;                 for (int n = 0; n < 2; ++n)
; #pragma unroll
;                     for (int j = 0; j < 4; ++j) o[n * 4 + j] = siluf_(acc[ai][0][m][n][j] * rs) * (acc[ai][1][m][n][j] * rs);
;                 *(u32x4*)(hid + (size_t)(row0 + ai * HALF + m * 16) * FF + col0) = pack8(o); }
	v_mul_f32_e32 v127, 0xbfb8aa3b, v119
	v_exp_f32_e32 v126, v126
	v_exp_f32_e32 v127, v127
	v_pk_mul_f32 v[62:63], v[62:63], v[142:143] op_sel_hi:[1,0]
	v_pk_mul_f32 v[58:59], v[58:59], v[142:143] op_sel_hi:[1,0]
	v_add_f32_e32 v126, 1.0, v126
	v_add_f32_e32 v127, 1.0, v127
	v_rcp_f32_e32 v126, v126
	v_rcp_f32_e32 v127, v127
	v_pk_mul_f32 v[60:61], v[60:61], v[142:143] op_sel_hi:[1,0]
	v_pk_mul_f32 v[54:55], v[54:55], v[142:143] op_sel_hi:[1,0]
	v_pk_mul_f32 v[50:51], v[50:51], v[142:143] op_sel_hi:[1,0]
	v_pk_mul_f32 v[118:119], v[118:119], v[126:127]
	v_pk_mul_f32 v[52:53], v[52:53], v[142:143] op_sel_hi:[1,0]
	v_pk_mul_f32 v[114:115], v[114:115], v[118:119]
	v_pk_mul_f32 v[118:119], v[120:121], v[152:153] op_sel_hi:[1,0]
	v_pk_mul_f32 v[30:31], v[30:31], v[140:141] op_sel_hi:[1,0]
	v_mul_f32_e32 v120, 0xbfb8aa3b, v118
	v_mul_f32_e32 v121, 0xbfb8aa3b, v119
	v_exp_f32_e32 v120, v120
	v_exp_f32_e32 v121, v121
	v_pk_mul_f32 v[26:27], v[26:27], v[140:141] op_sel_hi:[1,0]
	v_pk_mul_f32 v[28:29], v[28:29], v[140:141] op_sel_hi:[1,0]
	v_add_f32_e32 v120, 1.0, v120
	v_add_f32_e32 v121, 1.0, v121
	v_rcp_f32_e32 v120, v120
	v_rcp_f32_e32 v121, v121
	v_pk_mul_f32 v[22:23], v[22:23], v[140:141] op_sel_hi:[1,0]
	v_pk_mul_f32 v[18:19], v[18:19], v[140:141] op_sel_hi:[1,0]
	v_pk_mul_f32 v[20:21], v[20:21], v[140:141] op_sel_hi:[1,0]
	v_pk_mul_f32 v[118:119], v[118:119], v[120:121]
	v_cvt_pk_bf16_f32 v120, v114, v115
	v_pk_mul_f32 v[116:117], v[116:117], v[118:119]
	v_mov_b64_e32 v[114:115], s[68:69]
	v_cvt_pk_bf16_f32 v118, v122, v123
	v_cvt_pk_bf16_f32 v121, v116, v117
	v_mad_i64_i32 v[122:123], s[24:25], v151, s28, v[114:115]
	v_lshlrev_b64 v[116:117], 1, v[154:155]
	v_cvt_pk_bf16_f32 v119, v124, v125
	v_lshl_add_u64 v[122:123], v[122:123], 0, v[116:117]
	global_store_dwordx4 v[122:123], v[118:121], off
	s_andn2_b64 vcc, exec, s[36:37]
	s_nop 0
	v_mov_b32_e32 v118, v153
	v_pk_mul_f32 v[110:111], v[110:111], v[118:119] op_sel_hi:[1,0]
	s_nop 0
	v_mul_f32_e32 v119, 0xbfb8aa3b, v110
	v_exp_f32_e32 v119, v119
	s_nop 0
	v_add_f32_e32 v119, 1.0, v119
	v_rcp_f32_e32 v120, v119
	v_mul_f32_e32 v119, 0xbfb8aa3b, v111
	v_exp_f32_e32 v119, v119
	s_nop 0
	v_add_f32_e32 v119, 1.0, v119
	v_rcp_f32_e32 v121, v119
	v_pk_mul_f32 v[106:107], v[106:107], v[118:119] op_sel_hi:[1,0]
	v_pk_mul_f32 v[108:109], v[108:109], v[118:119] op_sel_hi:[1,0]
	v_pk_mul_f32 v[102:103], v[102:103], v[118:119] op_sel_hi:[1,0]
	v_pk_mul_f32 v[110:111], v[110:111], v[120:121]
	v_pk_mul_f32 v[98:99], v[98:99], v[118:119] op_sel_hi:[1,0]
	v_pk_mul_f32 v[106:107], v[106:107], v[110:111]
	v_pk_mul_f32 v[110:111], v[112:113], v[118:119] op_sel_hi:[1,0]
	v_pk_mul_f32 v[100:101], v[100:101], v[118:119] op_sel_hi:[1,0]
	v_mul_f32_e32 v112, 0xbfb8aa3b, v110
	v_mul_f32_e32 v113, 0xbfb8aa3b, v111
	v_exp_f32_e32 v112, v112
	v_exp_f32_e32 v113, v113
	v_add_f32_e32 v112, 1.0, v112
	v_add_f32_e32 v113, 1.0, v113
	v_rcp_f32_e32 v112, v112
	v_rcp_f32_e32 v113, v113
	s_nop 0
	v_pk_mul_f32 v[110:111], v[110:111], v[112:113]
	s_nop 0
	v_pk_mul_f32 v[108:109], v[108:109], v[110:111]
	v_mul_f32_e32 v110, 0xbfb8aa3b, v102
	v_mul_f32_e32 v111, 0xbfb8aa3b, v103
	v_exp_f32_e32 v110, v110
	v_exp_f32_e32 v111, v111
	v_add_f32_e32 v110, 1.0, v110
	v_add_f32_e32 v111, 1.0, v111
	v_rcp_f32_e32 v110, v110
	v_rcp_f32_e32 v111, v111
	s_nop 0
	v_pk_mul_f32 v[102:103], v[102:103], v[110:111]
	s_nop 0
	v_pk_mul_f32 v[102:103], v[98:99], v[102:103]
	v_pk_mul_f32 v[98:99], v[104:105], v[118:119] op_sel_hi:[1,0]
	s_nop 0
	v_mul_f32_e32 v104, 0xbfb8aa3b, v98
	v_mul_f32_e32 v105, 0xbfb8aa3b, v99
	v_exp_f32_e32 v104, v104
	v_exp_f32_e32 v105, v105
	v_add_f32_e32 v104, 1.0, v104
	v_add_f32_e32 v105, 1.0, v105
	v_rcp_f32_e32 v104, v104
	v_rcp_f32_e32 v105, v105
	s_nop 0
	v_pk_mul_f32 v[98:99], v[98:99], v[104:105]
	s_nop 0
	v_pk_mul_f32 v[104:105], v[100:101], v[98:99]
	v_cvt_pk_bf16_f32 v100, v102, v103
	v_or_b32_e32 v102, 16, v151
	v_mad_i64_i32 v[102:103], s[24:25], v102, s28, v[114:115]
	v_cvt_pk_bf16_f32 v98, v106, v107
	v_cvt_pk_bf16_f32 v99, v108, v109
	v_cvt_pk_bf16_f32 v101, v104, v105
	v_lshl_add_u64 v[102:103], v[102:103], 0, v[116:117]
	global_store_dwordx4 v[102:103], v[98:101], off
	s_nop 1
	v_mul_f32_e32 v98, 0xbfb8aa3b, v94
	v_mul_f32_e32 v99, 0xbfb8aa3b, v95
	v_exp_f32_e32 v98, v98
	v_exp_f32_e32 v99, v99
	v_add_f32_e32 v98, 1.0, v98
	v_add_f32_e32 v99, 1.0, v99
	v_rcp_f32_e32 v98, v98
	v_rcp_f32_e32 v99, v99
	s_nop 0
	v_pk_mul_f32 v[94:95], v[94:95], v[98:99]
	s_nop 0
	v_pk_mul_f32 v[90:91], v[90:91], v[94:95]
	v_pk_mul_f32 v[94:95], v[96:97], v[144:145] op_sel_hi:[1,0]
	s_nop 0
	v_mul_f32_e32 v96, 0xbfb8aa3b, v94
	v_mul_f32_e32 v97, 0xbfb8aa3b, v95
	v_exp_f32_e32 v96, v96
	v_exp_f32_e32 v97, v97
	v_add_f32_e32 v96, 1.0, v96
	v_add_f32_e32 v97, 1.0, v97
	v_rcp_f32_e32 v96, v96
	v_rcp_f32_e32 v97, v97
	s_nop 0
	v_pk_mul_f32 v[94:95], v[94:95], v[96:97]
	s_nop 0
	v_pk_mul_f32 v[92:93], v[92:93], v[94:95]
	v_mul_f32_e32 v94, 0xbfb8aa3b, v86
	v_mul_f32_e32 v95, 0xbfb8aa3b, v87
	v_exp_f32_e32 v94, v94
	v_exp_f32_e32 v95, v95
	v_add_f32_e32 v94, 1.0, v94
	v_add_f32_e32 v95, 1.0, v95
	v_rcp_f32_e32 v94, v94
	v_rcp_f32_e32 v95, v95
	s_nop 0
	v_pk_mul_f32 v[86:87], v[86:87], v[94:95]
	s_nop 0
	v_pk_mul_f32 v[86:87], v[82:83], v[86:87]
	v_pk_mul_f32 v[82:83], v[88:89], v[144:145] op_sel_hi:[1,0]
	s_nop 0
	v_mul_f32_e32 v88, 0xbfb8aa3b, v82
	v_mul_f32_e32 v89, 0xbfb8aa3b, v83
	v_exp_f32_e32 v88, v88
	v_exp_f32_e32 v89, v89
	v_add_f32_e32 v88, 1.0, v88
	v_add_f32_e32 v89, 1.0, v89
	v_rcp_f32_e32 v88, v88
	v_rcp_f32_e32 v89, v89
	s_nop 0
	v_pk_mul_f32 v[82:83], v[82:83], v[88:89]
	s_nop 0
	v_pk_mul_f32 v[88:89], v[84:85], v[82:83]
; __device__ __forceinline__ u32x4 pack8(const float* f) { u32x4 o; o.x = pk2(f[0], f[1]); o.y = pk2(f[2], f[3]); o.z = pk2(f[4], f[5]); o.w = pk2(f[6], f[7]); return o; }
; __device__ __forceinline__ float siluf_(float x) { return x * sigmoidf_(x); }
;     __device__ __forceinline__ void operator()(const f32x4 (&acc)[2][2][4][2], const Unit& u, int wr, int wc, int fr, int fq) const {
;     ...
;             for (int m = 0; m < 4; ++m) { float o[8]; const float rs = rsv[ai][m];
; #pragma unroll
;                 for (int n = 0; n < 2; ++n)
; #pragma unroll
;                     for (int j = 0; j < 4; ++j) o[n * 4 + j] = siluf_(acc[ai][0][m][n][j] * rs) * (acc[ai][1][m][n][j] * rs);
;                 *(u32x4*)(hid + (size_t)(row0 + ai * HALF + m * 16) * FF + col0) = pack8(o); }
	v_cvt_pk_bf16_f32 v84, v86, v87
	v_or_b32_e32 v86, 32, v151
	v_mad_i64_i32 v[86:87], s[24:25], v86, s28, v[114:115]
	v_cvt_pk_bf16_f32 v82, v90, v91
	v_cvt_pk_bf16_f32 v83, v92, v93
	v_cvt_pk_bf16_f32 v85, v88, v89
	v_lshl_add_u64 v[86:87], v[86:87], 0, v[116:117]
	global_store_dwordx4 v[86:87], v[82:85], off
	s_nop 1
	v_mov_b32_e32 v82, v145
	v_pk_mul_f32 v[78:79], v[78:79], v[82:83] op_sel_hi:[1,0]
	s_nop 0
	v_mul_f32_e32 v83, 0xbfb8aa3b, v78
	v_exp_f32_e32 v83, v83
	s_nop 0
	v_add_f32_e32 v83, 1.0, v83
	v_rcp_f32_e32 v84, v83
	v_mul_f32_e32 v83, 0xbfb8aa3b, v79
	v_exp_f32_e32 v83, v83
	s_nop 0
	v_add_f32_e32 v83, 1.0, v83
	v_rcp_f32_e32 v85, v83
	v_pk_mul_f32 v[74:75], v[74:75], v[82:83] op_sel_hi:[1,0]
	v_pk_mul_f32 v[76:77], v[76:77], v[82:83] op_sel_hi:[1,0]
	v_pk_mul_f32 v[70:71], v[70:71], v[82:83] op_sel_hi:[1,0]
	v_pk_mul_f32 v[78:79], v[78:79], v[84:85]
	v_pk_mul_f32 v[66:67], v[66:67], v[82:83] op_sel_hi:[1,0]
	v_pk_mul_f32 v[74:75], v[74:75], v[78:79]
	v_pk_mul_f32 v[78:79], v[80:81], v[82:83] op_sel_hi:[1,0]
	v_pk_mul_f32 v[68:69], v[68:69], v[82:83] op_sel_hi:[1,0]
	v_mul_f32_e32 v80, 0xbfb8aa3b, v78
	v_mul_f32_e32 v81, 0xbfb8aa3b, v79
	v_exp_f32_e32 v80, v80
	v_exp_f32_e32 v81, v81
	v_add_f32_e32 v80, 1.0, v80
	v_add_f32_e32 v81, 1.0, v81
	v_rcp_f32_e32 v80, v80
	v_rcp_f32_e32 v81, v81
	s_nop 0
	v_pk_mul_f32 v[78:79], v[78:79], v[80:81]
	s_nop 0
	v_pk_mul_f32 v[76:77], v[76:77], v[78:79]
	v_mul_f32_e32 v78, 0xbfb8aa3b, v70
	v_mul_f32_e32 v79, 0xbfb8aa3b, v71
	v_exp_f32_e32 v78, v78
	v_exp_f32_e32 v79, v79
	v_add_f32_e32 v78, 1.0, v78
	v_add_f32_e32 v79, 1.0, v79
	v_rcp_f32_e32 v78, v78
	v_rcp_f32_e32 v79, v79
	s_nop 0
	v_pk_mul_f32 v[70:71], v[70:71], v[78:79]
	s_nop 0
	v_pk_mul_f32 v[70:71], v[66:67], v[70:71]
	v_pk_mul_f32 v[66:67], v[72:73], v[82:83] op_sel_hi:[1,0]
	s_nop 0
	v_mul_f32_e32 v72, 0xbfb8aa3b, v66
	v_mul_f32_e32 v73, 0xbfb8aa3b, v67
	v_exp_f32_e32 v72, v72
	v_exp_f32_e32 v73, v73
	v_add_f32_e32 v72, 1.0, v72
	v_add_f32_e32 v73, 1.0, v73
	v_rcp_f32_e32 v72, v72
	v_rcp_f32_e32 v73, v73
	s_nop 0
	v_pk_mul_f32 v[66:67], v[66:67], v[72:73]
	s_nop 0
	v_pk_mul_f32 v[72:73], v[68:69], v[66:67]
	v_cvt_pk_bf16_f32 v68, v70, v71
	v_or_b32_e32 v70, 48, v151
	v_mad_i64_i32 v[70:71], s[24:25], v70, s28, v[114:115]
	v_cvt_pk_bf16_f32 v66, v74, v75
	v_cvt_pk_bf16_f32 v67, v76, v77
	v_cvt_pk_bf16_f32 v69, v72, v73
	v_lshl_add_u64 v[70:71], v[70:71], 0, v[116:117]
	global_store_dwordx4 v[70:71], v[66:69], off
	s_nop 1
	v_mul_f32_e32 v66, 0xbfb8aa3b, v62
	v_mul_f32_e32 v67, 0xbfb8aa3b, v63
	v_exp_f32_e32 v66, v66
	v_exp_f32_e32 v67, v67
	v_add_u32_e32 v68, 0x80, v151
	v_add_f32_e32 v66, 1.0, v66
	v_add_f32_e32 v67, 1.0, v67
	v_rcp_f32_e32 v66, v66
	v_rcp_f32_e32 v67, v67
	s_nop 0
	v_pk_mul_f32 v[62:63], v[62:63], v[66:67]
	s_nop 0
	v_pk_mul_f32 v[58:59], v[58:59], v[62:63]
	v_pk_mul_f32 v[62:63], v[64:65], v[142:143] op_sel_hi:[1,0]
	s_nop 0
	v_mul_f32_e32 v64, 0xbfb8aa3b, v62
	v_mul_f32_e32 v65, 0xbfb8aa3b, v63
	v_exp_f32_e32 v64, v64
	v_exp_f32_e32 v65, v65
	v_add_f32_e32 v64, 1.0, v64
	v_add_f32_e32 v65, 1.0, v65
	v_rcp_f32_e32 v64, v64
	v_rcp_f32_e32 v65, v65
	s_nop 0
	v_pk_mul_f32 v[62:63], v[62:63], v[64:65]
	s_nop 0
	v_pk_mul_f32 v[60:61], v[60:61], v[62:63]
	v_mul_f32_e32 v62, 0xbfb8aa3b, v54
	v_mul_f32_e32 v63, 0xbfb8aa3b, v55
	v_exp_f32_e32 v62, v62
	v_exp_f32_e32 v63, v63
	v_add_f32_e32 v62, 1.0, v62
	v_add_f32_e32 v63, 1.0, v63
	v_rcp_f32_e32 v62, v62
	v_rcp_f32_e32 v63, v63
	s_nop 0
	v_pk_mul_f32 v[54:55], v[54:55], v[62:63]
	s_nop 0
	v_pk_mul_f32 v[54:55], v[50:51], v[54:55]
	v_pk_mul_f32 v[50:51], v[56:57], v[142:143] op_sel_hi:[1,0]
	s_nop 0
	v_mul_f32_e32 v56, 0xbfb8aa3b, v50
	v_mul_f32_e32 v57, 0xbfb8aa3b, v51
	v_exp_f32_e32 v56, v56
	v_exp_f32_e32 v57, v57
	v_add_f32_e32 v56, 1.0, v56
	v_add_f32_e32 v57, 1.0, v57
	v_rcp_f32_e32 v56, v56
	v_rcp_f32_e32 v57, v57
	s_nop 0
	v_pk_mul_f32 v[50:51], v[50:51], v[56:57]
	s_nop 0
	v_pk_mul_f32 v[56:57], v[52:53], v[50:51]
	v_cvt_pk_bf16_f32 v52, v54, v55
	v_mad_i64_i32 v[54:55], s[24:25], v68, s28, v[114:115]
	v_cvt_pk_bf16_f32 v50, v58, v59
	v_cvt_pk_bf16_f32 v51, v60, v61
	v_cvt_pk_bf16_f32 v53, v56, v57
	v_lshl_add_u64 v[54:55], v[54:55], 0, v[116:117]
	global_store_dwordx4 v[54:55], v[50:53], off
	s_nop 1
	v_mov_b32_e32 v50, v143
	v_pk_mul_f32 v[46:47], v[46:47], v[50:51] op_sel_hi:[1,0]
	s_nop 0
	v_mul_f32_e32 v51, 0xbfb8aa3b, v46
	v_exp_f32_e32 v51, v51
	s_nop 0
	v_add_f32_e32 v51, 1.0, v51
	v_rcp_f32_e32 v52, v51
	v_mul_f32_e32 v51, 0xbfb8aa3b, v47
	v_exp_f32_e32 v51, v51
	s_nop 0
	v_add_f32_e32 v51, 1.0, v51
	v_rcp_f32_e32 v53, v51
	v_pk_mul_f32 v[42:43], v[42:43], v[50:51] op_sel_hi:[1,0]
	v_pk_mul_f32 v[44:45], v[44:45], v[50:51] op_sel_hi:[1,0]
	v_pk_mul_f32 v[38:39], v[38:39], v[50:51] op_sel_hi:[1,0]
	v_pk_mul_f32 v[46:47], v[46:47], v[52:53]
	v_pk_mul_f32 v[34:35], v[34:35], v[50:51] op_sel_hi:[1,0]
	v_pk_mul_f32 v[42:43], v[42:43], v[46:47]
	v_pk_mul_f32 v[46:47], v[48:49], v[50:51] op_sel_hi:[1,0]
	v_pk_mul_f32 v[36:37], v[36:37], v[50:51] op_sel_hi:[1,0]
	v_mul_f32_e32 v48, 0xbfb8aa3b, v46
	v_mul_f32_e32 v49, 0xbfb8aa3b, v47
	v_exp_f32_e32 v48, v48
	v_exp_f32_e32 v49, v49
	v_add_f32_e32 v48, 1.0, v48
	v_add_f32_e32 v49, 1.0, v49
; __device__ __forceinline__ u32x4 pack8(const float* f) { u32x4 o; o.x = pk2(f[0], f[1]); o.y = pk2(f[2], f[3]); o.z = pk2(f[4], f[5]); o.w = pk2(f[6], f[7]); return o; }
; __device__ __forceinline__ float siluf_(float x) { return x * sigmoidf_(x); }
; #define PG8_BAR __builtin_amdgcn_s_barrier()
; template <class Epi, class Sched, bool ALIGN_EPI = GEMM_ALIGN, bool SP2 = GEMM_SP2>
; __device__ __forceinline__ void gemm_phase(lptr lds, const Gemm g, const Sched& S, const Epi& E) {
;     ...
;         if (!has_next) break;
;         if (zero_acc)
; #pragma unroll
;         for (int a = 0; a < 2; ++a)
; #pragma unroll
;             for (int b = 0; b < 2; ++b)
; #pragma unroll
;                 for (int m = 0; m < 4; ++m)
; #pragma unroll
;                     for (int n = 0; n < 2; ++n) acc[a][b][m][n] = (f32x4){0.f, 0.f, 0.f, 0.f};
;         cur = nxt; cA = nA; cB = nB; ++ui;
;         if constexpr (ALIGN_EPI) { if (wr == 1) PG8_BAR; }
;     __device__ __forceinline__ void operator()(const f32x4 (&acc)[2][2][4][2], const Unit& u, int wr, int wc, int fr, int fq) const {
;     ...
;             for (int m = 0; m < 4; ++m) { float o[8]; const float rs = rsv[ai][m];
; #pragma unroll
;                 for (int n = 0; n < 2; ++n)
; #pragma unroll
;                     for (int j = 0; j < 4; ++j) o[n * 4 + j] = siluf_(acc[ai][0][m][n][j] * rs) * (acc[ai][1][m][n][j] * rs);
;                 *(u32x4*)(hid + (size_t)(row0 + ai * HALF + m * 16) * FF + col0) = pack8(o); }
;     }
	v_rcp_f32_e32 v48, v48
	v_rcp_f32_e32 v49, v49
	s_nop 0
	v_pk_mul_f32 v[46:47], v[46:47], v[48:49]
	s_nop 0
	v_pk_mul_f32 v[44:45], v[44:45], v[46:47]
	v_mul_f32_e32 v46, 0xbfb8aa3b, v38
	v_mul_f32_e32 v47, 0xbfb8aa3b, v39
	v_exp_f32_e32 v46, v46
	v_exp_f32_e32 v47, v47
	v_add_f32_e32 v46, 1.0, v46
	v_add_f32_e32 v47, 1.0, v47
	v_rcp_f32_e32 v46, v46
	v_rcp_f32_e32 v47, v47
	s_nop 0
	v_pk_mul_f32 v[38:39], v[38:39], v[46:47]
	s_nop 0
	v_pk_mul_f32 v[38:39], v[34:35], v[38:39]
	v_pk_mul_f32 v[34:35], v[40:41], v[50:51] op_sel_hi:[1,0]
	s_nop 0
	v_mul_f32_e32 v40, 0xbfb8aa3b, v34
	v_mul_f32_e32 v41, 0xbfb8aa3b, v35
	v_exp_f32_e32 v40, v40
	v_exp_f32_e32 v41, v41
	v_add_f32_e32 v40, 1.0, v40
	v_add_f32_e32 v41, 1.0, v41
	v_rcp_f32_e32 v40, v40
	v_rcp_f32_e32 v41, v41
	s_nop 0
	v_pk_mul_f32 v[34:35], v[34:35], v[40:41]
	s_nop 0
	v_pk_mul_f32 v[40:41], v[36:37], v[34:35]
	v_cvt_pk_bf16_f32 v36, v38, v39
	v_add_u32_e32 v38, 0x90, v151
	v_mad_i64_i32 v[38:39], s[24:25], v38, s28, v[114:115]
	v_cvt_pk_bf16_f32 v34, v42, v43
	v_cvt_pk_bf16_f32 v35, v44, v45
	v_cvt_pk_bf16_f32 v37, v40, v41
	v_lshl_add_u64 v[38:39], v[38:39], 0, v[116:117]
	global_store_dwordx4 v[38:39], v[34:37], off
	s_nop 1
	v_mul_f32_e32 v34, 0xbfb8aa3b, v30
	v_mul_f32_e32 v35, 0xbfb8aa3b, v31
	v_exp_f32_e32 v34, v34
	v_exp_f32_e32 v35, v35
	v_add_f32_e32 v34, 1.0, v34
	v_add_f32_e32 v35, 1.0, v35
	v_rcp_f32_e32 v34, v34
	v_rcp_f32_e32 v35, v35
	s_nop 0
	v_pk_mul_f32 v[30:31], v[30:31], v[34:35]
	s_nop 0
	v_pk_mul_f32 v[26:27], v[26:27], v[30:31]
	v_pk_mul_f32 v[30:31], v[32:33], v[140:141] op_sel_hi:[1,0]
	s_nop 0
	v_mul_f32_e32 v32, 0xbfb8aa3b, v30
	v_mul_f32_e32 v33, 0xbfb8aa3b, v31
	v_exp_f32_e32 v32, v32
	v_exp_f32_e32 v33, v33
	v_add_f32_e32 v32, 1.0, v32
	v_add_f32_e32 v33, 1.0, v33
	v_rcp_f32_e32 v32, v32
	v_rcp_f32_e32 v33, v33
	s_nop 0
	v_pk_mul_f32 v[30:31], v[30:31], v[32:33]
	s_nop 0
	v_pk_mul_f32 v[28:29], v[28:29], v[30:31]
	v_mul_f32_e32 v30, 0xbfb8aa3b, v22
	v_mul_f32_e32 v31, 0xbfb8aa3b, v23
	v_exp_f32_e32 v30, v30
	v_exp_f32_e32 v31, v31
	v_add_f32_e32 v30, 1.0, v30
	v_add_f32_e32 v31, 1.0, v31
	v_rcp_f32_e32 v30, v30
	v_rcp_f32_e32 v31, v31
	s_nop 0
	v_pk_mul_f32 v[22:23], v[22:23], v[30:31]
	s_nop 0
	v_pk_mul_f32 v[22:23], v[18:19], v[22:23]
	v_pk_mul_f32 v[18:19], v[24:25], v[140:141] op_sel_hi:[1,0]
	s_nop 0
	v_mul_f32_e32 v24, 0xbfb8aa3b, v18
	v_mul_f32_e32 v25, 0xbfb8aa3b, v19
	v_exp_f32_e32 v24, v24
	v_exp_f32_e32 v25, v25
	v_add_f32_e32 v24, 1.0, v24
	v_add_f32_e32 v25, 1.0, v25
	v_rcp_f32_e32 v24, v24
	v_rcp_f32_e32 v25, v25
	s_nop 0
	v_pk_mul_f32 v[18:19], v[18:19], v[24:25]
	s_nop 0
	v_pk_mul_f32 v[24:25], v[20:21], v[18:19]
	v_cvt_pk_bf16_f32 v20, v22, v23
	v_add_u32_e32 v22, 0xa0, v151
	v_mad_i64_i32 v[22:23], s[24:25], v22, s28, v[114:115]
	v_cvt_pk_bf16_f32 v18, v26, v27
	v_cvt_pk_bf16_f32 v19, v28, v29
	v_cvt_pk_bf16_f32 v21, v24, v25
	v_lshl_add_u64 v[22:23], v[22:23], 0, v[116:117]
	global_store_dwordx4 v[22:23], v[18:21], off
	s_nop 1
	v_mov_b32_e32 v18, v141
	v_pk_mul_f32 v[14:15], v[14:15], v[18:19] op_sel_hi:[1,0]
	s_nop 0
	v_mul_f32_e32 v19, 0xbfb8aa3b, v14
	v_exp_f32_e32 v19, v19
	s_nop 0
	v_add_f32_e32 v19, 1.0, v19
	v_rcp_f32_e32 v20, v19
	v_mul_f32_e32 v19, 0xbfb8aa3b, v15
	v_exp_f32_e32 v19, v19
	s_nop 0
	v_add_f32_e32 v19, 1.0, v19
	v_rcp_f32_e32 v21, v19
	v_pk_mul_f32 v[10:11], v[10:11], v[18:19] op_sel_hi:[1,0]
	v_pk_mul_f32 v[12:13], v[12:13], v[18:19] op_sel_hi:[1,0]
	v_pk_mul_f32 v[6:7], v[6:7], v[18:19] op_sel_hi:[1,0]
	v_pk_mul_f32 v[14:15], v[14:15], v[20:21]
	v_pk_mul_f32 v[2:3], v[2:3], v[18:19] op_sel_hi:[1,0]
	v_pk_mul_f32 v[10:11], v[10:11], v[14:15]
	v_pk_mul_f32 v[14:15], v[16:17], v[18:19] op_sel_hi:[1,0]
	v_pk_mul_f32 v[4:5], v[4:5], v[18:19] op_sel_hi:[1,0]
	v_mul_f32_e32 v16, 0xbfb8aa3b, v14
	v_mul_f32_e32 v17, 0xbfb8aa3b, v15
	v_exp_f32_e32 v16, v16
	v_exp_f32_e32 v17, v17
	v_add_f32_e32 v16, 1.0, v16
	v_add_f32_e32 v17, 1.0, v17
	v_rcp_f32_e32 v16, v16
	v_rcp_f32_e32 v17, v17
	s_nop 0
	v_pk_mul_f32 v[14:15], v[14:15], v[16:17]
	s_nop 0
	v_pk_mul_f32 v[12:13], v[12:13], v[14:15]
	v_mul_f32_e32 v14, 0xbfb8aa3b, v6
	v_mul_f32_e32 v15, 0xbfb8aa3b, v7
	v_exp_f32_e32 v14, v14
	v_exp_f32_e32 v15, v15
	v_add_f32_e32 v14, 1.0, v14
	v_add_f32_e32 v15, 1.0, v15
	v_rcp_f32_e32 v14, v14
	v_rcp_f32_e32 v15, v15
	s_nop 0
	v_pk_mul_f32 v[6:7], v[6:7], v[14:15]
	s_nop 0
	v_pk_mul_f32 v[6:7], v[2:3], v[6:7]
	v_pk_mul_f32 v[2:3], v[8:9], v[18:19] op_sel_hi:[1,0]
	s_nop 0
	v_mul_f32_e32 v8, 0xbfb8aa3b, v2
	v_mul_f32_e32 v9, 0xbfb8aa3b, v3
	v_exp_f32_e32 v8, v8
	v_exp_f32_e32 v9, v9
	v_add_f32_e32 v8, 1.0, v8
	v_add_f32_e32 v9, 1.0, v9
	v_rcp_f32_e32 v8, v8
	v_rcp_f32_e32 v9, v9
	s_nop 0
	v_pk_mul_f32 v[2:3], v[2:3], v[8:9]
	s_nop 0
	v_pk_mul_f32 v[8:9], v[4:5], v[2:3]
	v_cvt_pk_bf16_f32 v4, v6, v7
	v_add_u32_e32 v6, 0xb0, v151
	v_mad_i64_i32 v[6:7], s[24:25], v6, s28, v[114:115]
	v_cvt_pk_bf16_f32 v2, v10, v11
	v_cvt_pk_bf16_f32 v3, v12, v13
	v_cvt_pk_bf16_f32 v5, v8, v9
	v_lshl_add_u64 v[6:7], v[6:7], 0, v[116:117]
	s_mov_b64 s[24:25], -1
	global_store_dwordx4 v[6:7], v[2:5], off
	s_cbranch_vccnz .LBB0_227
	s_andn2_b64 vcc, exec, s[2:3]
	s_cbranch_vccnz .LBB0_226
	s_barrier
	s_branch .LBB0_226

; #define PG8_STAGE(bufoff, gbase, voff) do { _Pragma("unroll") for (int _i = 0; _i < 2; ++_i) \
;         __builtin_amdgcn_global_load_lds((const unsigned*)((const char*)(gbase) + (voff)[_i]), (LAS unsigned*)(lds + (bufoff) + ldsw + _i * 8192), 16, 0, 0); } while (0)
; #define PG8_LDA(dst, b, h) do { _Pragma("unroll") for (int m = 0; m < 4; ++m) _Pragma("unroll") for (int k = 0; k < 2; ++k) dst[m][k] = *(const LAS bf16x8*)(lds + PG8_SA(b, h) + aoff + m * 2048 + k * 1024); } while (0)
; #define PG8_LDB(dst, b, h) do { _Pragma("unroll") for (int n = 0; n < 2; ++n) _Pragma("unroll") for (int k = 0; k < 2; ++k) dst[n][k] = *(const LAS bf16x8*)(lds + PG8_SB(b, h) + boff + n * 2048 + k * 1024); } while (0)
; #define PG8_MMA(ai, bj, At, Bt) do { __builtin_amdgcn_s_setprio(1); _Pragma("unroll") for (int m = 0; m < 4; ++m) _Pragma("unroll") for (int n = 0; n < 2; ++n) _Pragma("unroll") for (int k = 0; k < 2; ++k) \
;         acc[ai][bj][m][n] = __builtin_amdgcn_mfma_f32_16x16x32_bf16(Bt[n][k], At[m][k], acc[ai][bj][m][n], 0, 0, 0); __builtin_amdgcn_s_setprio(0); } while (0)
; #define PG8_WAIT_V(n) asm volatile("s_waitcnt vmcnt(" #n ")" ::: "memory")
; #define PG8_WAIT_L(n) asm volatile("s_waitcnt lgkmcnt(" #n ")" ::: "memory")
; #define PG8_BAR __builtin_amdgcn_s_barrier()
; #define PG8_SCHED __builtin_amdgcn_sched_barrier(0)
; template <class Epi, class Sched, bool ALIGN_EPI = GEMM_ALIGN, bool SP2 = GEMM_SP2>
; __device__ __forceinline__ void gemm_phase(lptr lds, const Gemm g, const Sched& S, const Epi& E) {
;     ...
;             PG8_LDB(B0, 0, 0); PG8_LDB(B1, 0, 1); PG8_SCHED; PG8_LDA(At, 0, 0); PG8_STAGE(PG8_SA(1, 1), a1 + hstepA, voffA);
;             PG8_WAIT_V(8); PG8_WAIT_L(0); PG8_BAR; PG8_MMA(0, 0, At, B0); PG8_MMA(0, 1, At, B1); PG8_BAR; PG8_SCHED;
;             PG8_LDA(At, 0, 1); PG8_STAGE(PG8_SB(0, 0), b2, voffB); PG8_STAGE(PG8_SB(0, 1), b2 + hstepB, voffB); PG8_STAGE(PG8_SA(0, 0), a2, voffA);
;             PG8_WAIT_V(8); PG8_WAIT_L(0); PG8_BAR; PG8_MMA(1, 0, At, B0); PG8_MMA(1, 1, At, B1); PG8_BAR; PG8_SCHED;
.LBB0_313:
	s_add_u32 s28, s24, 0x100
	s_addc_u32 s29, s25, 0
	s_add_i32 s67, 0, 0x10000
	s_cmp_eq_u32 s66, 40
	s_cselect_b32 s47, s3, s29
	s_cselect_b32 s46, s2, s28
	s_cselect_b32 s31, s45, s65
	s_cselect_b32 s30, s44, s64
	s_add_i32 s68, 0, 0x14000
	v_add_u32_e32 v62, s67, v177
	v_add_u32_e32 v158, s68, v177
	ds_read_b128 v[50:53], v62
	ds_read_b128 v[54:57], v62 offset:1024
	ds_read_b128 v[58:61], v62 offset:2048
	ds_read_b128 v[62:65], v62 offset:3072
	ds_read_b128 v[146:149], v158
	ds_read_b128 v[150:153], v158 offset:1024
	ds_read_b128 v[154:157], v158 offset:2048
	ds_read_b128 v[158:161], v158 offset:3072
	v_lshl_add_u64 v[214:215], s[24:25], 0, v[164:165]
	s_add_i32 m0, s51, 0xc000
	ds_read_b128 v[168:171], v179
	ds_read_b128 v[172:175], v179 offset:1024
	ds_read_b128 v[180:183], v179 offset:2048
	ds_read_b128 v[198:201], v179 offset:3072
	ds_read_b128 v[202:205], v179 offset:4096
	ds_read_b128 v[206:209], v179 offset:5120
	ds_read_b128 v[210:213], v179 offset:6144
	ds_read_b128 v[220:223], v179 offset:7168
	global_load_lds_dwordx4 v[214:215], off
	v_lshl_add_u64 v[214:215], s[24:25], 0, v[166:167]
	s_add_i32 m0, s51, 0xe000
	s_nop 0
	global_load_lds_dwordx4 v[214:215], off
	s_waitcnt vmcnt(8)
	s_waitcnt lgkmcnt(0)
	s_barrier
	s_waitcnt lgkmcnt(0)
	v_mfma_f32_16x16x32_bf16 v[142:145], v[50:53], v[168:171], v[142:145]
	v_mfma_f32_16x16x32_bf16 v[138:141], v[58:61], v[168:171], v[138:141]
	v_mfma_f32_16x16x32_bf16 v[126:129], v[50:53], v[180:183], v[126:129]
	v_mfma_f32_16x16x32_bf16 v[122:125], v[58:61], v[180:183], v[122:125]
	v_mfma_f32_16x16x32_bf16 v[110:113], v[50:53], v[202:205], v[110:113]
	v_mfma_f32_16x16x32_bf16 v[106:109], v[58:61], v[202:205], v[106:109]
	v_mfma_f32_16x16x32_bf16 v[94:97], v[50:53], v[210:213], v[94:97]
	v_mfma_f32_16x16x32_bf16 v[90:93], v[58:61], v[210:213], v[90:93]
	v_mfma_f32_16x16x32_bf16 v[142:145], v[54:57], v[172:175], v[142:145]
	v_mfma_f32_16x16x32_bf16 v[138:141], v[62:65], v[172:175], v[138:141]
	v_mfma_f32_16x16x32_bf16 v[126:129], v[54:57], v[198:201], v[126:129]
	v_mfma_f32_16x16x32_bf16 v[122:125], v[62:65], v[198:201], v[122:125]
	v_mfma_f32_16x16x32_bf16 v[110:113], v[54:57], v[206:209], v[110:113]
	v_mfma_f32_16x16x32_bf16 v[106:109], v[62:65], v[206:209], v[106:109]
	v_mfma_f32_16x16x32_bf16 v[94:97], v[54:57], v[220:223], v[94:97]
	v_mfma_f32_16x16x32_bf16 v[90:93], v[62:65], v[220:223], v[90:93]
	v_mfma_f32_16x16x32_bf16 v[134:137], v[146:149], v[168:171], v[134:137]
	v_mfma_f32_16x16x32_bf16 v[130:133], v[154:157], v[168:171], v[130:133]
	v_mfma_f32_16x16x32_bf16 v[118:121], v[146:149], v[180:183], v[118:121]
	v_mfma_f32_16x16x32_bf16 v[114:117], v[154:157], v[180:183], v[114:117]
	v_mfma_f32_16x16x32_bf16 v[102:105], v[146:149], v[202:205], v[102:105]
	v_mfma_f32_16x16x32_bf16 v[98:101], v[154:157], v[202:205], v[98:101]
	v_mfma_f32_16x16x32_bf16 v[86:89], v[146:149], v[210:213], v[86:89]
	v_mfma_f32_16x16x32_bf16 v[82:85], v[154:157], v[210:213], v[82:85]
	v_mfma_f32_16x16x32_bf16 v[134:137], v[150:153], v[172:175], v[134:137]
	v_mfma_f32_16x16x32_bf16 v[130:133], v[158:161], v[172:175], v[130:133]
	v_mfma_f32_16x16x32_bf16 v[118:121], v[150:153], v[198:201], v[118:121]
	v_mfma_f32_16x16x32_bf16 v[114:117], v[158:161], v[198:201], v[114:117]
	v_mfma_f32_16x16x32_bf16 v[102:105], v[150:153], v[206:209], v[102:105]
	v_mfma_f32_16x16x32_bf16 v[98:101], v[158:161], v[206:209], v[98:101]
	v_mfma_f32_16x16x32_bf16 v[86:89], v[150:153], v[220:223], v[86:89]
	v_mfma_f32_16x16x32_bf16 v[82:85], v[158:161], v[220:223], v[82:85]
	s_barrier
	s_add_i32 s24, s67, s50
	v_lshl_add_u64 v[214:215], s[30:31], 0, v[0:1]
	s_mov_b32 m0, s24
	ds_read_b128 v[168:171], v179 offset:16384
	ds_read_b128 v[172:175], v179 offset:17408
	ds_read_b128 v[180:183], v179 offset:18432
	ds_read_b128 v[198:201], v179 offset:19456
	ds_read_b128 v[202:205], v179 offset:20480
	ds_read_b128 v[206:209], v179 offset:21504
	ds_read_b128 v[210:213], v179 offset:22528
	ds_read_b128 v[220:223], v179 offset:23552
	global_load_lds_dwordx4 v[214:215], off
	s_add_i32 m0, s24, 0x2000
	s_add_u32 s24, s30, 0xb0000
	v_lshl_add_u64 v[224:225], s[30:31], 0, v[162:163]
	s_addc_u32 s25, s31, 0
	s_add_i32 s67, s68, s50
	global_load_lds_dwordx4 v[224:225], off
	v_lshl_add_u64 v[226:227], s[24:25], 0, v[0:1]
	s_mov_b32 m0, s67
	v_lshl_add_u64 v[228:229], s[46:47], 0, v[162:163]
	global_load_lds_dwordx4 v[226:227], off
	v_lshl_add_u64 v[226:227], s[24:25], 0, v[162:163]
	s_add_i32 m0, s67, 0x2000
	s_nop 0
	global_load_lds_dwordx4 v[226:227], off
	v_lshl_add_u64 v[226:227], s[46:47], 0, v[0:1]
	s_mov_b32 m0, s51
	s_nop 0
	global_load_lds_dwordx4 v[226:227], off
	s_mov_b32 m0, s52
	s_nop 0
	global_load_lds_dwordx4 v[228:229], off
	s_waitcnt vmcnt(8)
	s_waitcnt lgkmcnt(0)
	s_barrier
; #define PG8_STAGE(bufoff, gbase, voff) do { _Pragma("unroll") for (int _i = 0; _i < 2; ++_i) \
;         __builtin_amdgcn_global_load_lds((const unsigned*)((const char*)(gbase) + (voff)[_i]), (LAS unsigned*)(lds + (bufoff) + ldsw + _i * 8192), 16, 0, 0); } while (0)
; #define PG8_LDA(dst, b, h) do { _Pragma("unroll") for (int m = 0; m < 4; ++m) _Pragma("unroll") for (int k = 0; k < 2; ++k) dst[m][k] = *(const LAS bf16x8*)(lds + PG8_SA(b, h) + aoff + m * 2048 + k * 1024); } while (0)
; #define PG8_LDB(dst, b, h) do { _Pragma("unroll") for (int n = 0; n < 2; ++n) _Pragma("unroll") for (int k = 0; k < 2; ++k) dst[n][k] = *(const LAS bf16x8*)(lds + PG8_SB(b, h) + boff + n * 2048 + k * 1024); } while (0)
; #define PG8_MMA(ai, bj, At, Bt) do { __builtin_amdgcn_s_setprio(1); _Pragma("unroll") for (int m = 0; m < 4; ++m) _Pragma("unroll") for (int n = 0; n < 2; ++n) _Pragma("unroll") for (int k = 0; k < 2; ++k) \
;         acc[ai][bj][m][n] = __builtin_amdgcn_mfma_f32_16x16x32_bf16(Bt[n][k], At[m][k], acc[ai][bj][m][n], 0, 0, 0); __builtin_amdgcn_s_setprio(0); } while (0)
; #define PG8_WAIT_V(n) asm volatile("s_waitcnt vmcnt(" #n ")" ::: "memory")
; #define PG8_WAIT_L(n) asm volatile("s_waitcnt lgkmcnt(" #n ")" ::: "memory")
; #define PG8_BAR __builtin_amdgcn_s_barrier()
; #define PG8_SCHED __builtin_amdgcn_sched_barrier(0)
; template <class Epi, class Sched, bool ALIGN_EPI = GEMM_ALIGN, bool SP2 = GEMM_SP2>
; __device__ __forceinline__ void gemm_phase(lptr lds, const Gemm g, const Sched& S, const Epi& E) {
;     ...
;             PG8_WAIT_V(8); PG8_WAIT_L(0); PG8_BAR; PG8_MMA(1, 0, At, B0); PG8_MMA(1, 1, At, B1); PG8_BAR; PG8_SCHED;
;             PG8_LDB(B0, 1, 0); PG8_LDB(B1, 1, 1); PG8_SCHED; PG8_LDA(At, 1, 0); PG8_STAGE(PG8_SA(0, 1), a2 + hstepA, voffA);
;             PG8_WAIT_V(8); PG8_WAIT_L(0); PG8_BAR; PG8_MMA(0, 0, At, B0); PG8_MMA(0, 1, At, B1); PG8_BAR; PG8_SCHED;
	s_waitcnt lgkmcnt(0)
	v_mfma_f32_16x16x32_bf16 v[78:81], v[50:53], v[168:171], v[78:81]
	v_mfma_f32_16x16x32_bf16 v[74:77], v[58:61], v[168:171], v[74:77]
	v_mfma_f32_16x16x32_bf16 v[46:49], v[50:53], v[180:183], v[46:49]
	v_mfma_f32_16x16x32_bf16 v[42:45], v[58:61], v[180:183], v[42:45]
	v_mfma_f32_16x16x32_bf16 v[30:33], v[50:53], v[202:205], v[30:33]
	v_mfma_f32_16x16x32_bf16 v[26:29], v[58:61], v[202:205], v[26:29]
	v_mfma_f32_16x16x32_bf16 v[14:17], v[50:53], v[210:213], v[14:17]
	v_mfma_f32_16x16x32_bf16 v[10:13], v[58:61], v[210:213], v[10:13]
	v_mfma_f32_16x16x32_bf16 v[78:81], v[54:57], v[172:175], v[78:81]
	v_mfma_f32_16x16x32_bf16 v[74:77], v[62:65], v[172:175], v[74:77]
	v_mfma_f32_16x16x32_bf16 v[46:49], v[54:57], v[198:201], v[46:49]
	v_mfma_f32_16x16x32_bf16 v[42:45], v[62:65], v[198:201], v[42:45]
	v_mfma_f32_16x16x32_bf16 v[30:33], v[54:57], v[206:209], v[30:33]
	v_mfma_f32_16x16x32_bf16 v[26:29], v[62:65], v[206:209], v[26:29]
	v_mfma_f32_16x16x32_bf16 v[14:17], v[54:57], v[220:223], v[14:17]
	v_mfma_f32_16x16x32_bf16 v[10:13], v[62:65], v[220:223], v[10:13]
	v_mfma_f32_16x16x32_bf16 v[38:41], v[146:149], v[180:183], v[38:41]
	v_mfma_f32_16x16x32_bf16 v[34:37], v[154:157], v[180:183], v[34:37]
	v_mfma_f32_16x16x32_bf16 v[22:25], v[146:149], v[202:205], v[22:25]
	v_mfma_f32_16x16x32_bf16 v[18:21], v[154:157], v[202:205], v[18:21]
	v_mfma_f32_16x16x32_bf16 v[6:9], v[146:149], v[210:213], v[6:9]
	v_mfma_f32_16x16x32_bf16 v[2:5], v[154:157], v[210:213], v[2:5]
	v_mfma_f32_16x16x32_bf16 v[50:53], v[146:149], v[168:171], v[70:73]
	v_mfma_f32_16x16x32_bf16 v[54:57], v[154:157], v[168:171], v[66:69]
	v_mfma_f32_16x16x32_bf16 v[38:41], v[150:153], v[198:201], v[38:41]
	v_mfma_f32_16x16x32_bf16 v[34:37], v[158:161], v[198:201], v[34:37]
	v_mfma_f32_16x16x32_bf16 v[22:25], v[150:153], v[206:209], v[22:25]
	v_mfma_f32_16x16x32_bf16 v[18:21], v[158:161], v[206:209], v[18:21]
	v_mfma_f32_16x16x32_bf16 v[6:9], v[150:153], v[220:223], v[6:9]
	v_mfma_f32_16x16x32_bf16 v[2:5], v[158:161], v[220:223], v[2:5]
	v_mfma_f32_16x16x32_bf16 v[50:53], v[150:153], v[172:175], v[50:53]
	v_mfma_f32_16x16x32_bf16 v[54:57], v[158:161], v[172:175], v[54:57]
	s_barrier
	s_add_i32 s67, 0, 0x18000
	s_add_i32 s68, 0, 0x1c000
	v_add_u32_e32 v70, s67, v177
	v_add_u32_e32 v158, s68, v177
	ds_read_b128 v[58:61], v70
	ds_read_b128 v[62:65], v70 offset:1024
	ds_read_b128 v[66:69], v70 offset:2048
	ds_read_b128 v[70:73], v70 offset:3072
	ds_read_b128 v[146:149], v158
	ds_read_b128 v[150:153], v158 offset:1024
	ds_read_b128 v[154:157], v158 offset:2048
	ds_read_b128 v[158:161], v158 offset:3072
	s_add_u32 s24, s46, 0xb0000
	s_addc_u32 s25, s47, 0
	s_mov_b32 m0, s53
	v_lshl_add_u64 v[230:231], s[24:25], 0, v[0:1]
	ds_read_b128 v[168:171], v179 offset:32768
	ds_read_b128 v[172:175], v179 offset:33792
	ds_read_b128 v[180:183], v179 offset:34816
	ds_read_b128 v[198:201], v179 offset:35840
	ds_read_b128 v[202:205], v179 offset:36864
	ds_read_b128 v[206:209], v179 offset:37888
	ds_read_b128 v[210:213], v179 offset:38912
	ds_read_b128 v[220:223], v179 offset:39936
	global_load_lds_dwordx4 v[230:231], off
	v_lshl_add_u64 v[230:231], s[24:25], 0, v[162:163]
	s_mov_b32 m0, s54
	s_nop 0
	global_load_lds_dwordx4 v[230:231], off
	s_waitcnt vmcnt(8)
	s_waitcnt lgkmcnt(0)
	s_barrier
	s_waitcnt lgkmcnt(0)
	v_mfma_f32_16x16x32_bf16 v[142:145], v[58:61], v[168:171], v[142:145]
	v_mfma_f32_16x16x32_bf16 v[138:141], v[66:69], v[168:171], v[138:141]
	v_mfma_f32_16x16x32_bf16 v[126:129], v[58:61], v[180:183], v[126:129]
	v_mfma_f32_16x16x32_bf16 v[122:125], v[66:69], v[180:183], v[122:125]
	v_mfma_f32_16x16x32_bf16 v[110:113], v[58:61], v[202:205], v[110:113]
	v_mfma_f32_16x16x32_bf16 v[106:109], v[66:69], v[202:205], v[106:109]
	v_mfma_f32_16x16x32_bf16 v[94:97], v[58:61], v[210:213], v[94:97]
	v_mfma_f32_16x16x32_bf16 v[90:93], v[66:69], v[210:213], v[90:93]
	v_mfma_f32_16x16x32_bf16 v[142:145], v[62:65], v[172:175], v[142:145]
	v_mfma_f32_16x16x32_bf16 v[138:141], v[70:73], v[172:175], v[138:141]
	v_mfma_f32_16x16x32_bf16 v[126:129], v[62:65], v[198:201], v[126:129]
	v_mfma_f32_16x16x32_bf16 v[122:125], v[70:73], v[198:201], v[122:125]
	v_mfma_f32_16x16x32_bf16 v[110:113], v[62:65], v[206:209], v[110:113]
	v_mfma_f32_16x16x32_bf16 v[106:109], v[70:73], v[206:209], v[106:109]
	v_mfma_f32_16x16x32_bf16 v[94:97], v[62:65], v[220:223], v[94:97]
	v_mfma_f32_16x16x32_bf16 v[90:93], v[70:73], v[220:223], v[90:93]
	v_mfma_f32_16x16x32_bf16 v[134:137], v[146:149], v[168:171], v[134:137]
	v_mfma_f32_16x16x32_bf16 v[130:133], v[154:157], v[168:171], v[130:133]
	v_mfma_f32_16x16x32_bf16 v[118:121], v[146:149], v[180:183], v[118:121]
	v_mfma_f32_16x16x32_bf16 v[114:117], v[154:157], v[180:183], v[114:117]
	v_mfma_f32_16x16x32_bf16 v[102:105], v[146:149], v[202:205], v[102:105]
	v_mfma_f32_16x16x32_bf16 v[98:101], v[154:157], v[202:205], v[98:101]
	v_mfma_f32_16x16x32_bf16 v[86:89], v[146:149], v[210:213], v[86:89]
	v_mfma_f32_16x16x32_bf16 v[82:85], v[154:157], v[210:213], v[82:85]
	v_mfma_f32_16x16x32_bf16 v[134:137], v[150:153], v[172:175], v[134:137]
	v_mfma_f32_16x16x32_bf16 v[130:133], v[158:161], v[172:175], v[130:133]
	v_mfma_f32_16x16x32_bf16 v[118:121], v[150:153], v[198:201], v[118:121]
	v_mfma_f32_16x16x32_bf16 v[114:117], v[158:161], v[198:201], v[114:117]
	v_mfma_f32_16x16x32_bf16 v[102:105], v[150:153], v[206:209], v[102:105]
	v_mfma_f32_16x16x32_bf16 v[98:101], v[158:161], v[206:209], v[98:101]
	v_mfma_f32_16x16x32_bf16 v[86:89], v[150:153], v[220:223], v[86:89]
	v_mfma_f32_16x16x32_bf16 v[82:85], v[158:161], v[220:223], v[82:85]
	s_barrier
; #define PG8_STAGE(bufoff, gbase, voff) do { _Pragma("unroll") for (int _i = 0; _i < 2; ++_i) \
;         __builtin_amdgcn_global_load_lds((const unsigned*)((const char*)(gbase) + (voff)[_i]), (LAS unsigned*)(lds + (bufoff) + ldsw + _i * 8192), 16, 0, 0); } while (0)
; #define PG8_LDA(dst, b, h) do { _Pragma("unroll") for (int m = 0; m < 4; ++m) _Pragma("unroll") for (int k = 0; k < 2; ++k) dst[m][k] = *(const LAS bf16x8*)(lds + PG8_SA(b, h) + aoff + m * 2048 + k * 1024); } while (0)
; #define PG8_MMA(ai, bj, At, Bt) do { __builtin_amdgcn_s_setprio(1); _Pragma("unroll") for (int m = 0; m < 4; ++m) _Pragma("unroll") for (int n = 0; n < 2; ++n) _Pragma("unroll") for (int k = 0; k < 2; ++k) \
;         acc[ai][bj][m][n] = __builtin_amdgcn_mfma_f32_16x16x32_bf16(Bt[n][k], At[m][k], acc[ai][bj][m][n], 0, 0, 0); __builtin_amdgcn_s_setprio(0); } while (0)
; #define PG8_WAIT_V(n) asm volatile("s_waitcnt vmcnt(" #n ")" ::: "memory")
; #define PG8_WAIT_L(n) asm volatile("s_waitcnt lgkmcnt(" #n ")" ::: "memory")
; #define PG8_BAR __builtin_amdgcn_s_barrier()
; #define PG8_SCHED __builtin_amdgcn_sched_barrier(0)
; template <class Epi, class Sched, bool ALIGN_EPI = GEMM_ALIGN, bool SP2 = GEMM_SP2>
; __device__ __forceinline__ void gemm_phase(lptr lds, const Gemm g, const Sched& S, const Epi& E) {
;     ...
;             PG8_LDA(At, 1, 1); PG8_STAGE(PG8_SB(1, 0), b3, voffB); PG8_STAGE(PG8_SB(1, 1), b3 + hstepB, voffB); PG8_STAGE(PG8_SA(1, 0), a3, voffA);
;             PG8_WAIT_V(8); PG8_WAIT_L(0); PG8_BAR; PG8_MMA(1, 0, At, B0); PG8_MMA(1, 1, At, B1); PG8_BAR; PG8_SCHED;
;     ...
;         if constexpr (ALIGN_EPI) { if (wr == 0) PG8_BAR; }
	s_add_i32 s24, s67, s50
	v_lshl_add_u64 v[214:215], v[214:215], 0, s[6:7]
	s_mov_b32 m0, s24
	ds_read_b128 v[168:171], v179 offset:49152
	ds_read_b128 v[172:175], v179 offset:50176
	ds_read_b128 v[180:183], v179 offset:51200
	ds_read_b128 v[198:201], v179 offset:52224
	ds_read_b128 v[202:205], v179 offset:53248
	ds_read_b128 v[206:209], v179 offset:54272
	ds_read_b128 v[210:213], v179 offset:55296
	ds_read_b128 v[220:223], v179 offset:56320
	global_load_lds_dwordx4 v[214:215], off
	s_add_i32 m0, s24, 0x2000
	s_add_u32 s24, s30, 0xb0080
	v_lshl_add_u64 v[214:215], v[224:225], 0, s[6:7]
	s_addc_u32 s25, s31, 0
	s_add_i32 s30, s68, s50
	global_load_lds_dwordx4 v[214:215], off
	v_lshl_add_u64 v[214:215], s[24:25], 0, v[0:1]
	s_mov_b32 m0, s30
	s_nop 0
	global_load_lds_dwordx4 v[214:215], off
	v_lshl_add_u64 v[214:215], s[24:25], 0, v[162:163]
	s_add_i32 m0, s30, 0x2000
	s_nop 0
	global_load_lds_dwordx4 v[214:215], off
	v_lshl_add_u64 v[214:215], v[226:227], 0, s[6:7]
	s_mov_b32 m0, s56
	s_nop 0
	global_load_lds_dwordx4 v[214:215], off
	v_lshl_add_u64 v[214:215], v[228:229], 0, s[6:7]
	s_mov_b32 m0, s57
	s_nop 0
	global_load_lds_dwordx4 v[214:215], off
	s_waitcnt vmcnt(8)
	s_waitcnt lgkmcnt(0)
	s_barrier
	s_waitcnt lgkmcnt(0)
	v_mfma_f32_16x16x32_bf16 v[78:81], v[58:61], v[168:171], v[78:81]
	v_mfma_f32_16x16x32_bf16 v[74:77], v[66:69], v[168:171], v[74:77]
	v_mfma_f32_16x16x32_bf16 v[46:49], v[58:61], v[180:183], v[46:49]
	v_mfma_f32_16x16x32_bf16 v[42:45], v[66:69], v[180:183], v[42:45]
	v_mfma_f32_16x16x32_bf16 v[30:33], v[58:61], v[202:205], v[30:33]
	v_mfma_f32_16x16x32_bf16 v[26:29], v[66:69], v[202:205], v[26:29]
	v_mfma_f32_16x16x32_bf16 v[14:17], v[58:61], v[210:213], v[14:17]
	v_mfma_f32_16x16x32_bf16 v[10:13], v[66:69], v[210:213], v[10:13]
	v_mfma_f32_16x16x32_bf16 v[78:81], v[62:65], v[172:175], v[78:81]
	v_mfma_f32_16x16x32_bf16 v[74:77], v[70:73], v[172:175], v[74:77]
	v_mfma_f32_16x16x32_bf16 v[46:49], v[62:65], v[198:201], v[46:49]
	v_mfma_f32_16x16x32_bf16 v[42:45], v[70:73], v[198:201], v[42:45]
	v_mfma_f32_16x16x32_bf16 v[30:33], v[62:65], v[206:209], v[30:33]
	v_mfma_f32_16x16x32_bf16 v[26:29], v[70:73], v[206:209], v[26:29]
	v_mfma_f32_16x16x32_bf16 v[14:17], v[62:65], v[220:223], v[14:17]
	v_mfma_f32_16x16x32_bf16 v[10:13], v[70:73], v[220:223], v[10:13]
	v_mfma_f32_16x16x32_bf16 v[50:53], v[146:149], v[168:171], v[50:53]
	v_mfma_f32_16x16x32_bf16 v[70:73], v[150:153], v[172:175], v[50:53]
	v_mfma_f32_16x16x32_bf16 v[50:53], v[154:157], v[168:171], v[54:57]
	v_mfma_f32_16x16x32_bf16 v[38:41], v[146:149], v[180:183], v[38:41]
	v_mfma_f32_16x16x32_bf16 v[34:37], v[154:157], v[180:183], v[34:37]
	v_mfma_f32_16x16x32_bf16 v[22:25], v[146:149], v[202:205], v[22:25]
	v_mfma_f32_16x16x32_bf16 v[18:21], v[154:157], v[202:205], v[18:21]
	v_mfma_f32_16x16x32_bf16 v[6:9], v[146:149], v[210:213], v[6:9]
	v_mfma_f32_16x16x32_bf16 v[2:5], v[154:157], v[210:213], v[2:5]
	v_mfma_f32_16x16x32_bf16 v[66:69], v[158:161], v[172:175], v[50:53]
	v_mfma_f32_16x16x32_bf16 v[38:41], v[150:153], v[198:201], v[38:41]
	v_mfma_f32_16x16x32_bf16 v[34:37], v[158:161], v[198:201], v[34:37]
	v_mfma_f32_16x16x32_bf16 v[22:25], v[150:153], v[206:209], v[22:25]
	v_mfma_f32_16x16x32_bf16 v[18:21], v[158:161], v[206:209], v[18:21]
	v_mfma_f32_16x16x32_bf16 v[6:9], v[150:153], v[220:223], v[6:9]
	v_mfma_f32_16x16x32_bf16 v[2:5], v[158:161], v[220:223], v[2:5]
	s_barrier
	s_add_i32 s66, s66, 2
	s_add_u32 s64, s64, 0x100
	s_addc_u32 s65, s65, 0
	s_cmp_gt_u32 s66, 41
	s_mov_b64 s[24:25], s[28:29]
	s_cbranch_scc0 .LBB0_313
	s_and_b64 vcc, exec, s[42:43]
	s_cbranch_vccz .LBB0_316
	s_barrier
; __device__ __forceinline__ unsigned pk2(float lo, float hi) { const f32x2 v = {lo, hi}; const bf16x2_t b = __builtin_convertvector(v, bf16x2_t); return __builtin_bit_cast(unsigned, b); }
;     __device__ __forceinline__ void operator()(const f32x4 (&acc)[2][2][4][2], const Unit& u, int wr, int wc, int fr, int fq) const {
;         const int row0 = u.pm * BM + wr * 64 + fr, col0 = u.pn * BM + wc * 32 + 4 * fq;
;         f32x4 gv[2][2];
; #pragma unroll
;         for (int bj = 0; bj < 2; ++bj)
; #pragma unroll
;             for (int n = 0; n < 2; ++n) gv[bj][n] = *(const f32x4*)(gnext + col0 + bj * HALF + n * 16);
; #pragma unroll
;         for (int ai = 0; ai < 2; ++ai)
; #pragma unroll
;             for (int mp = 0; mp < 2; ++mp) { f32x4 xv[2][2][2];
; #pragma unroll
;                 for (int mm = 0; mm < 2; ++mm)
; #pragma unroll
;                     for (int bj = 0; bj < 2; ++bj)
; #pragma unroll
;                         for (int n = 0; n < 2; ++n) xv[mm][bj][n] = *(const f32x4*)(xin + (size_t)(row0 + ai * HALF + (mp * 2 + mm) * 16) * DM + col0 + bj * HALF + n * 16);
; #pragma unroll
;                 for (int mm = 0; mm < 2; ++mm) { const int m = mp * 2 + mm; const int row = row0 + ai * HALF + m * 16; const size_t off = (size_t)row * DM + col0; float ss = 0.f;
; #pragma unroll
;                     for (int bj = 0; bj < 2; ++bj)
; #pragma unroll
;                         for (int n = 0; n < 2; ++n) { const f32x4 v = xv[mm][bj][n] + acc[ai][bj][m][n] * scale; *(f32x4*)(out + off + bj * HALF + n * 16) = v;
;                             if (xq) { ss += (v[0] * v[0] + v[1] * v[1]) + (v[2] * v[2] + v[3] * v[3]); const f32x4 q = v * gv[bj][n]; u32x2 w; w.x = pk2(q[0], q[1]); w.y = pk2(q[2], q[3]); *(u32x2*)(xq + off + bj * HALF + n * 16) = w; } }
;                     if (xq) { ss += __shfl_xor(ss, 16); ss += __shfl_xor(ss, 32); if (fq == 0) rowsq[(size_t)row * 16 + u.pn * 4 + wc] = ss; } } }
.LBB0_316:
	s_setprio 0
	v_lshl_or_b32 v168, s63, 8, v178
	v_ashrrev_i32_e32 v169, 31, v168
	v_lshl_add_u32 v170, s34, 8, v176
	v_lshlrev_b64 v[146:147], 2, v[168:169]
	v_ashrrev_i32_e32 v171, 31, v170
	v_lshl_add_u64 v[50:51], s[40:41], 0, v[146:147]
	v_lshl_add_u64 v[172:173], s[0:1], 0, v[146:147]
	v_lshlrev_b64 v[146:147], 12, v[170:171]
	v_lshl_add_u64 v[146:147], v[172:173], 0, v[146:147]
	global_load_dwordx4 v[62:65], v[50:51], off
	global_load_dwordx4 v[58:61], v[50:51], off offset:64
	global_load_dwordx4 v[54:57], v[50:51], off offset:512
	s_nop 0
	global_load_dwordx4 v[50:53], v[50:51], off offset:576
	s_nop 0
	global_load_dwordx4 v[180:183], v[146:147], off
	global_load_dwordx4 v[198:201], v[146:147], off offset:64
	global_load_dwordx4 v[202:205], v[146:147], off offset:512
	global_load_dwordx4 v[206:209], v[146:147], off offset:576
	v_or_b32_e32 v174, 16, v170
	v_ashrrev_i32_e32 v175, 31, v174
	v_lshlrev_b64 v[146:147], 12, v[174:175]
	v_lshl_add_u64 v[146:147], v[172:173], 0, v[146:147]
	global_load_dwordx4 v[158:161], v[146:147], off
	global_load_dwordx4 v[154:157], v[146:147], off offset:64
	global_load_dwordx4 v[150:153], v[146:147], off offset:512
	s_nop 0
	global_load_dwordx4 v[146:149], v[146:147], off offset:576
	v_lshlrev_b64 v[210:211], 10, v[170:171]
	v_lshl_add_u64 v[210:211], v[210:211], 0, v[168:169]
	v_readlane_b32 s24, v251, 32
	v_readlane_b32 s25, v251, 33
	s_lshl_b32 s46, s63, 2
	s_ashr_i32 s47, s46, 31
	s_waitcnt vmcnt(0)
	v_pk_fma_f32 v[144:145], v[144:145], 0.5, v[182:183] op_sel_hi:[1,0,1]
	v_pk_fma_f32 v[142:143], v[142:143], 0.5, v[180:181] op_sel_hi:[1,0,1]
	v_lshl_add_u64 v[180:181], v[210:211], 2, s[86:87]
	v_mul_f32_e32 v182, v143, v143
	v_mul_f32_e32 v183, v145, v145
	global_store_dwordx4 v[180:181], v[142:145], off
	v_fmac_f32_e32 v182, v142, v142
	v_fmac_f32_e32 v183, v144, v144
	v_pk_mul_f32 v[144:145], v[64:65], v[144:145]
	v_pk_mul_f32 v[142:143], v[62:63], v[142:143]
	v_pk_fma_f32 v[140:141], v[140:141], 0.5, v[200:201] op_sel_hi:[1,0,1]
	v_cvt_pk_bf16_f32 v142, v142, v143
	v_cvt_pk_bf16_f32 v143, v144, v145
	v_lshl_add_u64 v[144:145], v[210:211], 1, s[24:25]
	v_pk_fma_f32 v[138:139], v[138:139], 0.5, v[198:199] op_sel_hi:[1,0,1]
	global_store_dwordx2 v[144:145], v[142:143], off
	v_mul_f32_e32 v142, v139, v139
	v_mul_f32_e32 v143, v141, v141
	global_store_dwordx4 v[180:181], v[138:141], off offset:64
	v_fmac_f32_e32 v142, v138, v138
	v_fmac_f32_e32 v143, v140, v140
	v_pk_mul_f32 v[140:141], v[60:61], v[140:141]
	v_pk_mul_f32 v[138:139], v[58:59], v[138:139]
	v_pk_fma_f32 v[136:137], v[136:137], 0.5, v[204:205] op_sel_hi:[1,0,1]
	v_cvt_pk_bf16_f32 v138, v138, v139
	v_cvt_pk_bf16_f32 v139, v140, v141
	v_pk_fma_f32 v[134:135], v[134:135], 0.5, v[202:203] op_sel_hi:[1,0,1]
	global_store_dwordx2 v[144:145], v[138:139], off offset:32
	v_mul_f32_e32 v138, v135, v135
	v_mul_f32_e32 v139, v137, v137
	global_store_dwordx4 v[180:181], v[134:137], off offset:512
	v_fmac_f32_e32 v138, v134, v134
	v_fmac_f32_e32 v139, v136, v136
	v_pk_mul_f32 v[136:137], v[56:57], v[136:137]
	v_pk_mul_f32 v[134:135], v[54:55], v[134:135]
	v_pk_fma_f32 v[132:133], v[132:133], 0.5, v[208:209] op_sel_hi:[1,0,1]
	v_cvt_pk_bf16_f32 v134, v134, v135
	v_cvt_pk_bf16_f32 v135, v136, v137
	v_pk_fma_f32 v[130:131], v[130:131], 0.5, v[206:207] op_sel_hi:[1,0,1]
	global_store_dwordx2 v[144:145], v[134:135], off offset:256
	global_store_dwordx4 v[180:181], v[130:133], off offset:576
	v_pk_mul_f32 v[136:137], v[50:51], v[130:131]
	v_pk_mul_f32 v[134:135], v[52:53], v[132:133]
	v_mul_f32_e32 v131, v131, v131
	v_fmac_f32_e32 v131, v130, v130
	v_mul_f32_e32 v130, v133, v133
	v_fmac_f32_e32 v130, v132, v132
	v_and_b32_e32 v132, 64, v234
	v_add_f32_e32 v182, v182, v183
	v_add_f32_e32 v142, v142, v143
	v_add_f32_e32 v130, v131, v130
	v_xor_b32_e32 v131, 16, v234
	v_add_u32_e32 v132, 64, v132
	v_add_f32_e32 v142, v182, v142
	v_add_f32_e32 v138, v138, v139
	v_cmp_lt_i32_e32 vcc, v131, v132
	v_add_f32_e32 v138, v142, v138
	v_add_f32_e32 v130, v138, v130
	v_cndmask_b32_e32 v131, v234, v131, vcc
	v_lshlrev_b32_e32 v138, 2, v131
	ds_bpermute_b32 v131, v138, v130
	v_cvt_pk_bf16_f32 v136, v136, v137
	v_cvt_pk_bf16_f32 v137, v134, v135
	global_store_dwordx2 v[144:145], v[136:137], off offset:288
	s_waitcnt lgkmcnt(0)
	v_add_f32_e32 v130, v130, v131
	v_xor_b32_e32 v131, 32, v234
	v_cmp_lt_i32_e32 vcc, v131, v132
	s_nop 1
	v_cndmask_b32_e32 v131, v234, v131, vcc
	v_lshlrev_b32_e32 v139, 2, v131
	ds_bpermute_b32 v131, v139, v130
	s_and_saveexec_b64 s[24:25], s[36:37]
	s_mov_b64 s[64:65], s[88:89]
	s_cbranch_execz .LBB0_318
	v_readlane_b32 s28, v251, 42
	v_lshlrev_b64 v[132:133], 6, v[170:171]
	v_readlane_b32 s29, v251, 43
	s_lshl_b32 s34, s55, 2
	s_waitcnt lgkmcnt(0)
	v_add_f32_e32 v130, v130, v131
	v_lshl_add_u64 v[132:133], s[28:29], 0, v[132:133]
	v_lshl_add_u64 v[132:133], s[46:47], 2, v[132:133]
	v_lshl_add_u64 v[132:133], v[132:133], 0, s[34:35]
	global_store_dword v[132:133], v130, off

; #define PG8_STAGE(bufoff, gbase, voff) do { _Pragma("unroll") for (int _i = 0; _i < 2; ++_i) \
;         __builtin_amdgcn_global_load_lds((const unsigned*)((const char*)(gbase) + (voff)[_i]), (LAS unsigned*)(lds + (bufoff) + ldsw + _i * 8192), 16, 0, 0); } while (0)
; #define PG8_LDA(dst, b, h) do { _Pragma("unroll") for (int m = 0; m < 4; ++m) _Pragma("unroll") for (int k = 0; k < 2; ++k) dst[m][k] = *(const LAS bf16x8*)(lds + PG8_SA(b, h) + aoff + m * 2048 + k * 1024); } while (0)
; #define PG8_LDB(dst, b, h) do { _Pragma("unroll") for (int n = 0; n < 2; ++n) _Pragma("unroll") for (int k = 0; k < 2; ++k) dst[n][k] = *(const LAS bf16x8*)(lds + PG8_SB(b, h) + boff + n * 2048 + k * 1024); } while (0)
; #define PG8_MMA(ai, bj, At, Bt) do { __builtin_amdgcn_s_setprio(1); _Pragma("unroll") for (int m = 0; m < 4; ++m) _Pragma("unroll") for (int n = 0; n < 2; ++n) _Pragma("unroll") for (int k = 0; k < 2; ++k) \
;         acc[ai][bj][m][n] = __builtin_amdgcn_mfma_f32_16x16x32_bf16(Bt[n][k], At[m][k], acc[ai][bj][m][n], 0, 0, 0); __builtin_amdgcn_s_setprio(0); } while (0)
; #define PG8_WAIT_V(n) asm volatile("s_waitcnt vmcnt(" #n ")" ::: "memory")
; #define PG8_WAIT_L(n) asm volatile("s_waitcnt lgkmcnt(" #n ")" ::: "memory")
; #define PG8_BAR __builtin_amdgcn_s_barrier()
; #define PG8_SCHED __builtin_amdgcn_sched_barrier(0)
; template <class Epi, class Sched, bool ALIGN_EPI = GEMM_ALIGN, bool SP2 = GEMM_SP2>
; __device__ __forceinline__ void gemm_phase(lptr lds, const Gemm g, const Sched& S, const Epi& E) {
;     ...
;             PG8_LDB(B0, 0, 0); PG8_LDB(B1, 0, 1); PG8_SCHED; PG8_LDA(At, 0, 0); PG8_STAGE(PG8_SA(1, 1), a1 + hstepA, voffA);
;             PG8_WAIT_V(8); PG8_WAIT_L(0); PG8_BAR; PG8_MMA(0, 0, At, B0); PG8_MMA(0, 1, At, B1); PG8_BAR; PG8_SCHED;
;             PG8_LDA(At, 0, 1); PG8_STAGE(PG8_SB(0, 0), b2, voffB); PG8_STAGE(PG8_SB(0, 1), b2 + hstepB, voffB); PG8_STAGE(PG8_SA(0, 0), a2, voffA);
;             PG8_WAIT_V(8); PG8_WAIT_L(0); PG8_BAR; PG8_MMA(1, 0, At, B0); PG8_MMA(1, 1, At, B1); PG8_BAR; PG8_SCHED;
.LBB0_435:
	s_add_u32 s24, s2, 0xfffc0080
	s_addc_u32 s25, s3, -1
	s_add_i32 s64, 0, 0x10000
	s_cmp_eq_u32 s63, 12
	s_cselect_b32 s29, s43, s25
	s_cselect_b32 s28, s59, s24
	v_add_u32_e32 v153, s64, v149
	s_cselect_b32 s25, s41, s62
	s_cselect_b32 s24, s60, s61
	s_add_i32 s66, 0, 0x14000
	ds_read_b128 v[140:143], v153
	ds_read_b128 v[144:147], v153 offset:1024
	ds_read_b128 v[154:157], v153 offset:2048
	ds_read_b128 v[158:161], v153 offset:3072
	v_add_u32_e32 v153, s66, v149
	ds_read_b128 v[162:165], v153
	ds_read_b128 v[166:169], v153 offset:1024
	ds_read_b128 v[170:173], v153 offset:2048
	ds_read_b128 v[174:177], v153 offset:3072
	v_lshl_add_u64 v[182:183], s[2:3], 0, v[136:137]
	s_add_i32 m0, s31, 0xc000
	ds_read_b128 v[178:181], v152
	ds_read_b128 v[198:201], v152 offset:1024
	ds_read_b128 v[202:205], v152 offset:2048
	ds_read_b128 v[206:209], v152 offset:3072
	ds_read_b128 v[210:213], v152 offset:4096
	ds_read_b128 v[220:223], v152 offset:5120
	ds_read_b128 v[224:227], v152 offset:6144
	ds_read_b128 v[228:231], v152 offset:7168
	global_load_lds_dwordx4 v[182:183], off
	v_lshl_add_u64 v[182:183], s[2:3], 0, v[138:139]
	s_add_i32 m0, s31, 0xe000
	s_nop 0
	global_load_lds_dwordx4 v[182:183], off
	s_waitcnt vmcnt(8)
	s_waitcnt lgkmcnt(0)
	s_barrier
	s_waitcnt lgkmcnt(0)
	v_mfma_f32_16x16x32_bf16 v[126:129], v[140:143], v[178:181], v[126:129]
	v_mfma_f32_16x16x32_bf16 v[122:125], v[154:157], v[178:181], v[122:125]
	v_mfma_f32_16x16x32_bf16 v[110:113], v[140:143], v[202:205], v[110:113]
	v_mfma_f32_16x16x32_bf16 v[106:109], v[154:157], v[202:205], v[106:109]
	v_mfma_f32_16x16x32_bf16 v[94:97], v[140:143], v[210:213], v[94:97]
	v_mfma_f32_16x16x32_bf16 v[90:93], v[154:157], v[210:213], v[90:93]
	v_mfma_f32_16x16x32_bf16 v[78:81], v[140:143], v[224:227], v[78:81]
	v_mfma_f32_16x16x32_bf16 v[74:77], v[154:157], v[224:227], v[74:77]
	v_mfma_f32_16x16x32_bf16 v[126:129], v[144:147], v[198:201], v[126:129]
	v_mfma_f32_16x16x32_bf16 v[122:125], v[158:161], v[198:201], v[122:125]
	v_mfma_f32_16x16x32_bf16 v[110:113], v[144:147], v[206:209], v[110:113]
	v_mfma_f32_16x16x32_bf16 v[106:109], v[158:161], v[206:209], v[106:109]
	v_mfma_f32_16x16x32_bf16 v[94:97], v[144:147], v[220:223], v[94:97]
	v_mfma_f32_16x16x32_bf16 v[90:93], v[158:161], v[220:223], v[90:93]
	v_mfma_f32_16x16x32_bf16 v[78:81], v[144:147], v[228:231], v[78:81]
	v_mfma_f32_16x16x32_bf16 v[74:77], v[158:161], v[228:231], v[74:77]
	v_mfma_f32_16x16x32_bf16 v[118:121], v[162:165], v[178:181], v[118:121]
	v_mfma_f32_16x16x32_bf16 v[114:117], v[170:173], v[178:181], v[114:117]
	v_mfma_f32_16x16x32_bf16 v[102:105], v[162:165], v[202:205], v[102:105]
	v_mfma_f32_16x16x32_bf16 v[98:101], v[170:173], v[202:205], v[98:101]
	v_mfma_f32_16x16x32_bf16 v[86:89], v[162:165], v[210:213], v[86:89]
	v_mfma_f32_16x16x32_bf16 v[82:85], v[170:173], v[210:213], v[82:85]
	v_mfma_f32_16x16x32_bf16 v[70:73], v[162:165], v[224:227], v[70:73]
	v_mfma_f32_16x16x32_bf16 v[66:69], v[170:173], v[224:227], v[66:69]
	v_mfma_f32_16x16x32_bf16 v[118:121], v[166:169], v[198:201], v[118:121]
	v_mfma_f32_16x16x32_bf16 v[114:117], v[174:177], v[198:201], v[114:117]
	v_mfma_f32_16x16x32_bf16 v[102:105], v[166:169], v[206:209], v[102:105]
	v_mfma_f32_16x16x32_bf16 v[98:101], v[174:177], v[206:209], v[98:101]
	v_mfma_f32_16x16x32_bf16 v[86:89], v[166:169], v[220:223], v[86:89]
	v_mfma_f32_16x16x32_bf16 v[82:85], v[174:177], v[220:223], v[82:85]
	v_mfma_f32_16x16x32_bf16 v[70:73], v[166:169], v[228:231], v[70:73]
	v_mfma_f32_16x16x32_bf16 v[66:69], v[174:177], v[228:231], v[66:69]
	s_barrier
	s_add_i32 s64, s64, s49
	v_lshl_add_u64 v[182:183], s[24:25], 0, v[0:1]
	s_mov_b32 m0, s64
	ds_read_b128 v[178:181], v152 offset:16384
	ds_read_b128 v[198:201], v152 offset:17408
	ds_read_b128 v[202:205], v152 offset:18432
	ds_read_b128 v[206:209], v152 offset:19456
	ds_read_b128 v[210:213], v152 offset:20480
	ds_read_b128 v[220:223], v152 offset:21504
	ds_read_b128 v[224:227], v152 offset:22528
	ds_read_b128 v[228:231], v152 offset:23552
	global_load_lds_dwordx4 v[182:183], off
	s_add_i32 m0, s64, 0x2000
	s_add_u32 s64, s24, 0x40000
	v_lshl_add_u64 v[214:215], s[24:25], 0, v[134:135]
	s_addc_u32 s65, s25, 0
	s_add_i32 s66, s66, s49
	global_load_lds_dwordx4 v[214:215], off
	v_lshl_add_u64 v[232:233], s[64:65], 0, v[0:1]
	s_mov_b32 m0, s66
	v_lshl_add_u64 v[242:243], s[28:29], 0, v[132:133]
	global_load_lds_dwordx4 v[232:233], off
	v_lshl_add_u64 v[232:233], s[64:65], 0, v[134:135]
	s_add_i32 m0, s66, 0x2000
	s_nop 0
	global_load_lds_dwordx4 v[232:233], off
	v_lshl_add_u64 v[232:233], s[28:29], 0, v[130:131]
	s_mov_b32 m0, s31
	s_nop 0
	global_load_lds_dwordx4 v[232:233], off
	s_mov_b32 m0, s52
	s_nop 0
	global_load_lds_dwordx4 v[242:243], off
	s_waitcnt vmcnt(8)
	s_waitcnt lgkmcnt(0)
	s_barrier
; #define PG8_STAGE(bufoff, gbase, voff) do { _Pragma("unroll") for (int _i = 0; _i < 2; ++_i) \
;         __builtin_amdgcn_global_load_lds((const unsigned*)((const char*)(gbase) + (voff)[_i]), (LAS unsigned*)(lds + (bufoff) + ldsw + _i * 8192), 16, 0, 0); } while (0)
; #define PG8_LDA(dst, b, h) do { _Pragma("unroll") for (int m = 0; m < 4; ++m) _Pragma("unroll") for (int k = 0; k < 2; ++k) dst[m][k] = *(const LAS bf16x8*)(lds + PG8_SA(b, h) + aoff + m * 2048 + k * 1024); } while (0)
; #define PG8_LDB(dst, b, h) do { _Pragma("unroll") for (int n = 0; n < 2; ++n) _Pragma("unroll") for (int k = 0; k < 2; ++k) dst[n][k] = *(const LAS bf16x8*)(lds + PG8_SB(b, h) + boff + n * 2048 + k * 1024); } while (0)
; #define PG8_MMA(ai, bj, At, Bt) do { __builtin_amdgcn_s_setprio(1); _Pragma("unroll") for (int m = 0; m < 4; ++m) _Pragma("unroll") for (int n = 0; n < 2; ++n) _Pragma("unroll") for (int k = 0; k < 2; ++k) \
;         acc[ai][bj][m][n] = __builtin_amdgcn_mfma_f32_16x16x32_bf16(Bt[n][k], At[m][k], acc[ai][bj][m][n], 0, 0, 0); __builtin_amdgcn_s_setprio(0); } while (0)
; #define PG8_WAIT_V(n) asm volatile("s_waitcnt vmcnt(" #n ")" ::: "memory")
; #define PG8_WAIT_L(n) asm volatile("s_waitcnt lgkmcnt(" #n ")" ::: "memory")
; #define PG8_BAR __builtin_amdgcn_s_barrier()
; #define PG8_SCHED __builtin_amdgcn_sched_barrier(0)
; template <class Epi, class Sched, bool ALIGN_EPI = GEMM_ALIGN, bool SP2 = GEMM_SP2>
; __device__ __forceinline__ void gemm_phase(lptr lds, const Gemm g, const Sched& S, const Epi& E) {
;     ...
;             PG8_WAIT_V(8); PG8_WAIT_L(0); PG8_BAR; PG8_MMA(1, 0, At, B0); PG8_MMA(1, 1, At, B1); PG8_BAR; PG8_SCHED;
;             PG8_LDB(B0, 1, 0); PG8_LDB(B1, 1, 1); PG8_SCHED; PG8_LDA(At, 1, 0); PG8_STAGE(PG8_SA(0, 1), a2 + hstepA, voffA);
;             PG8_WAIT_V(8); PG8_WAIT_L(0); PG8_BAR; PG8_MMA(0, 0, At, B0); PG8_MMA(0, 1, At, B1); PG8_BAR; PG8_SCHED;
	s_waitcnt lgkmcnt(0)
	v_mfma_f32_16x16x32_bf16 v[62:65], v[140:143], v[178:181], v[62:65]
	v_mfma_f32_16x16x32_bf16 v[58:61], v[154:157], v[178:181], v[58:61]
	v_mfma_f32_16x16x32_bf16 v[46:49], v[140:143], v[202:205], v[46:49]
	v_mfma_f32_16x16x32_bf16 v[42:45], v[154:157], v[202:205], v[42:45]
	v_mfma_f32_16x16x32_bf16 v[30:33], v[140:143], v[210:213], v[30:33]
	v_mfma_f32_16x16x32_bf16 v[26:29], v[154:157], v[210:213], v[26:29]
	v_mfma_f32_16x16x32_bf16 v[14:17], v[140:143], v[224:227], v[14:17]
	v_mfma_f32_16x16x32_bf16 v[10:13], v[154:157], v[224:227], v[10:13]
	v_mfma_f32_16x16x32_bf16 v[62:65], v[144:147], v[198:201], v[62:65]
	v_mfma_f32_16x16x32_bf16 v[58:61], v[158:161], v[198:201], v[58:61]
	v_mfma_f32_16x16x32_bf16 v[46:49], v[144:147], v[206:209], v[46:49]
	v_mfma_f32_16x16x32_bf16 v[42:45], v[158:161], v[206:209], v[42:45]
	v_mfma_f32_16x16x32_bf16 v[30:33], v[144:147], v[220:223], v[30:33]
	v_mfma_f32_16x16x32_bf16 v[26:29], v[158:161], v[220:223], v[26:29]
	v_mfma_f32_16x16x32_bf16 v[14:17], v[144:147], v[228:231], v[14:17]
	v_mfma_f32_16x16x32_bf16 v[10:13], v[158:161], v[228:231], v[10:13]
	v_mfma_f32_16x16x32_bf16 v[54:57], v[162:165], v[178:181], v[54:57]
	v_mfma_f32_16x16x32_bf16 v[50:53], v[170:173], v[178:181], v[50:53]
	v_mfma_f32_16x16x32_bf16 v[38:41], v[162:165], v[202:205], v[38:41]
	v_mfma_f32_16x16x32_bf16 v[34:37], v[170:173], v[202:205], v[34:37]
	v_mfma_f32_16x16x32_bf16 v[22:25], v[162:165], v[210:213], v[22:25]
	v_mfma_f32_16x16x32_bf16 v[18:21], v[170:173], v[210:213], v[18:21]
	v_mfma_f32_16x16x32_bf16 v[6:9], v[162:165], v[224:227], v[6:9]
	v_mfma_f32_16x16x32_bf16 v[2:5], v[170:173], v[224:227], v[2:5]
	v_mfma_f32_16x16x32_bf16 v[54:57], v[166:169], v[198:201], v[54:57]
	v_mfma_f32_16x16x32_bf16 v[50:53], v[174:177], v[198:201], v[50:53]
	v_mfma_f32_16x16x32_bf16 v[38:41], v[166:169], v[206:209], v[38:41]
	v_mfma_f32_16x16x32_bf16 v[34:37], v[174:177], v[206:209], v[34:37]
	v_mfma_f32_16x16x32_bf16 v[22:25], v[166:169], v[220:223], v[22:25]
	v_mfma_f32_16x16x32_bf16 v[18:21], v[174:177], v[220:223], v[18:21]
	v_mfma_f32_16x16x32_bf16 v[6:9], v[166:169], v[228:231], v[6:9]
	v_mfma_f32_16x16x32_bf16 v[2:5], v[174:177], v[228:231], v[2:5]
	s_barrier
	s_add_i32 s64, 0, 0x18000
	v_add_u32_e32 v153, s64, v149
	s_add_i32 s65, 0, 0x1c000
	ds_read_b128 v[140:143], v153
	ds_read_b128 v[144:147], v153 offset:1024
	ds_read_b128 v[154:157], v153 offset:2048
	ds_read_b128 v[158:161], v153 offset:3072
	v_add_u32_e32 v153, s65, v149
	ds_read_b128 v[162:165], v153
	ds_read_b128 v[166:169], v153 offset:1024
	ds_read_b128 v[170:173], v153 offset:2048
	ds_read_b128 v[174:177], v153 offset:3072
	s_add_u32 s28, s28, 0x40000
	s_addc_u32 s29, s29, 0
	s_mov_b32 m0, s53
	v_lshl_add_u64 v[248:249], s[28:29], 0, v[130:131]
	ds_read_b128 v[178:181], v152 offset:32768
	ds_read_b128 v[198:201], v152 offset:33792
	ds_read_b128 v[202:205], v152 offset:34816
	ds_read_b128 v[206:209], v152 offset:35840
	ds_read_b128 v[210:213], v152 offset:36864
	ds_read_b128 v[220:223], v152 offset:37888
	ds_read_b128 v[224:227], v152 offset:38912
	ds_read_b128 v[228:231], v152 offset:39936
	global_load_lds_dwordx4 v[248:249], off
	v_lshl_add_u64 v[248:249], s[28:29], 0, v[132:133]
	s_mov_b32 m0, s54
	s_nop 0
	global_load_lds_dwordx4 v[248:249], off
	s_waitcnt vmcnt(8)
	s_waitcnt lgkmcnt(0)
	s_barrier
	s_waitcnt lgkmcnt(0)
	v_mfma_f32_16x16x32_bf16 v[126:129], v[140:143], v[178:181], v[126:129]
	v_mfma_f32_16x16x32_bf16 v[122:125], v[154:157], v[178:181], v[122:125]
	v_mfma_f32_16x16x32_bf16 v[110:113], v[140:143], v[202:205], v[110:113]
	v_mfma_f32_16x16x32_bf16 v[106:109], v[154:157], v[202:205], v[106:109]
	v_mfma_f32_16x16x32_bf16 v[94:97], v[140:143], v[210:213], v[94:97]
	v_mfma_f32_16x16x32_bf16 v[90:93], v[154:157], v[210:213], v[90:93]
	v_mfma_f32_16x16x32_bf16 v[78:81], v[140:143], v[224:227], v[78:81]
	v_mfma_f32_16x16x32_bf16 v[74:77], v[154:157], v[224:227], v[74:77]
	v_mfma_f32_16x16x32_bf16 v[126:129], v[144:147], v[198:201], v[126:129]
	v_mfma_f32_16x16x32_bf16 v[122:125], v[158:161], v[198:201], v[122:125]
	v_mfma_f32_16x16x32_bf16 v[110:113], v[144:147], v[206:209], v[110:113]
	v_mfma_f32_16x16x32_bf16 v[106:109], v[158:161], v[206:209], v[106:109]
	v_mfma_f32_16x16x32_bf16 v[94:97], v[144:147], v[220:223], v[94:97]
	v_mfma_f32_16x16x32_bf16 v[90:93], v[158:161], v[220:223], v[90:93]
	v_mfma_f32_16x16x32_bf16 v[78:81], v[144:147], v[228:231], v[78:81]
	v_mfma_f32_16x16x32_bf16 v[74:77], v[158:161], v[228:231], v[74:77]
	v_mfma_f32_16x16x32_bf16 v[118:121], v[162:165], v[178:181], v[118:121]
	v_mfma_f32_16x16x32_bf16 v[114:117], v[170:173], v[178:181], v[114:117]
	v_mfma_f32_16x16x32_bf16 v[102:105], v[162:165], v[202:205], v[102:105]
	v_mfma_f32_16x16x32_bf16 v[98:101], v[170:173], v[202:205], v[98:101]
	v_mfma_f32_16x16x32_bf16 v[86:89], v[162:165], v[210:213], v[86:89]
	v_mfma_f32_16x16x32_bf16 v[82:85], v[170:173], v[210:213], v[82:85]
	v_mfma_f32_16x16x32_bf16 v[70:73], v[162:165], v[224:227], v[70:73]
	v_mfma_f32_16x16x32_bf16 v[66:69], v[170:173], v[224:227], v[66:69]
	v_mfma_f32_16x16x32_bf16 v[118:121], v[166:169], v[198:201], v[118:121]
	v_mfma_f32_16x16x32_bf16 v[114:117], v[174:177], v[198:201], v[114:117]
	v_mfma_f32_16x16x32_bf16 v[102:105], v[166:169], v[206:209], v[102:105]
	v_mfma_f32_16x16x32_bf16 v[98:101], v[174:177], v[206:209], v[98:101]
	v_mfma_f32_16x16x32_bf16 v[86:89], v[166:169], v[220:223], v[86:89]
	v_mfma_f32_16x16x32_bf16 v[82:85], v[174:177], v[220:223], v[82:85]
	v_mfma_f32_16x16x32_bf16 v[70:73], v[166:169], v[228:231], v[70:73]
	v_mfma_f32_16x16x32_bf16 v[66:69], v[174:177], v[228:231], v[66:69]
	s_barrier
; #define PG8_STAGE(bufoff, gbase, voff) do { _Pragma("unroll") for (int _i = 0; _i < 2; ++_i) \
;         __builtin_amdgcn_global_load_lds((const unsigned*)((const char*)(gbase) + (voff)[_i]), (LAS unsigned*)(lds + (bufoff) + ldsw + _i * 8192), 16, 0, 0); } while (0)
; #define PG8_LDA(dst, b, h) do { _Pragma("unroll") for (int m = 0; m < 4; ++m) _Pragma("unroll") for (int k = 0; k < 2; ++k) dst[m][k] = *(const LAS bf16x8*)(lds + PG8_SA(b, h) + aoff + m * 2048 + k * 1024); } while (0)
; #define PG8_MMA(ai, bj, At, Bt) do { __builtin_amdgcn_s_setprio(1); _Pragma("unroll") for (int m = 0; m < 4; ++m) _Pragma("unroll") for (int n = 0; n < 2; ++n) _Pragma("unroll") for (int k = 0; k < 2; ++k) \
;         acc[ai][bj][m][n] = __builtin_amdgcn_mfma_f32_16x16x32_bf16(Bt[n][k], At[m][k], acc[ai][bj][m][n], 0, 0, 0); __builtin_amdgcn_s_setprio(0); } while (0)
; #define PG8_WAIT_V(n) asm volatile("s_waitcnt vmcnt(" #n ")" ::: "memory")
; #define PG8_WAIT_L(n) asm volatile("s_waitcnt lgkmcnt(" #n ")" ::: "memory")
; #define PG8_BAR __builtin_amdgcn_s_barrier()
; #define PG8_SCHED __builtin_amdgcn_sched_barrier(0)
; template <class Epi, class Sched, bool ALIGN_EPI = GEMM_ALIGN, bool SP2 = GEMM_SP2>
; __device__ __forceinline__ void gemm_phase(lptr lds, const Gemm g, const Sched& S, const Epi& E) {
;     ...
;             PG8_LDA(At, 1, 1); PG8_STAGE(PG8_SB(1, 0), b3, voffB); PG8_STAGE(PG8_SB(1, 1), b3 + hstepB, voffB); PG8_STAGE(PG8_SA(1, 0), a3, voffA);
;             PG8_WAIT_V(8); PG8_WAIT_L(0); PG8_BAR; PG8_MMA(1, 0, At, B0); PG8_MMA(1, 1, At, B1); PG8_BAR; PG8_SCHED;
;     ...
;         if constexpr (ALIGN_EPI) { if (wr == 0) PG8_BAR; }
;     __device__ __forceinline__ void operator()(const f32x4 (&acc)[2][2][4][2], const Unit& u, int wr, int wc, int fr, int fq) const {
;         const int row0 = u.pm * BM + wr * 64 + fr;
;         const int mode = u.pn < 4 ? 0 : (u.pn < 20 ? 1 : 2);
;         float rsv[2][4];
; #pragma unroll
;         for (int ai = 0; ai < 2; ++ai)
; #pragma unroll
;             for (int m = 0; m < 4; ++m) rsv[ai][m] = rst[u.ord * 256 + wr * 64 + fr + ai * HALF + m * 16];
	s_add_i32 s28, s64, s49
	v_lshl_add_u64 v[182:183], v[182:183], 0, s[6:7]
	s_mov_b32 m0, s28
	ds_read_b128 v[178:181], v152 offset:49152
	ds_read_b128 v[198:201], v152 offset:50176
	ds_read_b128 v[202:205], v152 offset:51200
	ds_read_b128 v[206:209], v152 offset:52224
	ds_read_b128 v[210:213], v152 offset:53248
	ds_read_b128 v[220:223], v152 offset:54272
	ds_read_b128 v[224:227], v152 offset:55296
	ds_read_b128 v[228:231], v152 offset:56320
	global_load_lds_dwordx4 v[182:183], off
	s_add_i32 m0, s28, 0x2000
	s_add_u32 s24, s24, 0x40080
	v_lshl_add_u64 v[182:183], v[214:215], 0, s[6:7]
	s_addc_u32 s25, s25, 0
	s_add_i32 s28, s65, s49
	global_load_lds_dwordx4 v[182:183], off
	v_lshl_add_u64 v[182:183], s[24:25], 0, v[0:1]
	s_mov_b32 m0, s28
	s_nop 0
	global_load_lds_dwordx4 v[182:183], off
	v_lshl_add_u64 v[182:183], s[24:25], 0, v[134:135]
	s_add_i32 m0, s28, 0x2000
	s_nop 0
	global_load_lds_dwordx4 v[182:183], off
	v_lshl_add_u64 v[182:183], v[232:233], 0, s[6:7]
	s_mov_b32 m0, s55
	s_nop 0
	global_load_lds_dwordx4 v[182:183], off
	v_lshl_add_u64 v[182:183], v[242:243], 0, s[6:7]
	s_mov_b32 m0, s56
	s_nop 0
	global_load_lds_dwordx4 v[182:183], off
	s_waitcnt vmcnt(8)
	s_waitcnt lgkmcnt(0)
	s_barrier
	s_waitcnt lgkmcnt(0)
	v_mfma_f32_16x16x32_bf16 v[62:65], v[140:143], v[178:181], v[62:65]
	v_mfma_f32_16x16x32_bf16 v[58:61], v[154:157], v[178:181], v[58:61]
	v_mfma_f32_16x16x32_bf16 v[46:49], v[140:143], v[202:205], v[46:49]
	v_mfma_f32_16x16x32_bf16 v[42:45], v[154:157], v[202:205], v[42:45]
	v_mfma_f32_16x16x32_bf16 v[30:33], v[140:143], v[210:213], v[30:33]
	v_mfma_f32_16x16x32_bf16 v[26:29], v[154:157], v[210:213], v[26:29]
	v_mfma_f32_16x16x32_bf16 v[14:17], v[140:143], v[224:227], v[14:17]
	v_mfma_f32_16x16x32_bf16 v[10:13], v[154:157], v[224:227], v[10:13]
	v_mfma_f32_16x16x32_bf16 v[62:65], v[144:147], v[198:201], v[62:65]
	v_mfma_f32_16x16x32_bf16 v[58:61], v[158:161], v[198:201], v[58:61]
	v_mfma_f32_16x16x32_bf16 v[46:49], v[144:147], v[206:209], v[46:49]
	v_mfma_f32_16x16x32_bf16 v[42:45], v[158:161], v[206:209], v[42:45]
	v_mfma_f32_16x16x32_bf16 v[30:33], v[144:147], v[220:223], v[30:33]
	v_mfma_f32_16x16x32_bf16 v[26:29], v[158:161], v[220:223], v[26:29]
	v_mfma_f32_16x16x32_bf16 v[14:17], v[144:147], v[228:231], v[14:17]
	v_mfma_f32_16x16x32_bf16 v[10:13], v[158:161], v[228:231], v[10:13]
	v_mfma_f32_16x16x32_bf16 v[54:57], v[162:165], v[178:181], v[54:57]
	v_mfma_f32_16x16x32_bf16 v[50:53], v[170:173], v[178:181], v[50:53]
	v_mfma_f32_16x16x32_bf16 v[38:41], v[162:165], v[202:205], v[38:41]
	v_mfma_f32_16x16x32_bf16 v[34:37], v[170:173], v[202:205], v[34:37]
	v_mfma_f32_16x16x32_bf16 v[22:25], v[162:165], v[210:213], v[22:25]
	v_mfma_f32_16x16x32_bf16 v[18:21], v[170:173], v[210:213], v[18:21]
	v_mfma_f32_16x16x32_bf16 v[6:9], v[162:165], v[224:227], v[6:9]
	v_mfma_f32_16x16x32_bf16 v[2:5], v[170:173], v[224:227], v[2:5]
	v_mfma_f32_16x16x32_bf16 v[54:57], v[166:169], v[198:201], v[54:57]
	v_mfma_f32_16x16x32_bf16 v[50:53], v[174:177], v[198:201], v[50:53]
	v_mfma_f32_16x16x32_bf16 v[38:41], v[166:169], v[206:209], v[38:41]
	v_mfma_f32_16x16x32_bf16 v[34:37], v[174:177], v[206:209], v[34:37]
	v_mfma_f32_16x16x32_bf16 v[22:25], v[166:169], v[220:223], v[22:25]
	v_mfma_f32_16x16x32_bf16 v[18:21], v[174:177], v[220:223], v[18:21]
	v_mfma_f32_16x16x32_bf16 v[6:9], v[166:169], v[228:231], v[6:9]
	v_mfma_f32_16x16x32_bf16 v[2:5], v[174:177], v[228:231], v[2:5]
	s_barrier
	s_add_i32 s63, s63, 2
	s_add_u32 s2, s2, 0x100
	s_addc_u32 s3, s3, 0
	s_add_u32 s61, s61, 0x100
	s_addc_u32 s62, s62, 0
	s_cmp_gt_u32 s63, 13
	s_cbranch_scc0 .LBB0_435
	s_and_b64 vcc, exec, s[26:27]
	s_cbranch_vccz .LBB0_438
	s_barrier
.LBB0_438:
	s_setprio 0
	s_cmp_lt_i32 s30, 20
	v_lshl_add_u32 v140, s39, 10, v150
	s_cselect_b32 s2, 1, 2
	ds_read2_b32 v[146:147], v140 offset1:16
	ds_read2_b32 v[144:145], v140 offset0:32 offset1:48
	ds_read2_b32 v[142:143], v140 offset0:128 offset1:144
	ds_read2_b32 v[140:141], v140 offset0:160 offset1:176
	s_cmp_gt_i32 s30, 3
	s_cselect_b32 s28, s2, 0
	s_mov_b64 s[64:65], s[88:89]
	v_lshl_add_u32 v153, s38, 8, v148
	s_cmp_eq_u32 s28, 2
	s_cbranch_scc1 .Lmy_ip_m2
	s_movk_i32 s2, 0x1320
	v_lshl_or_b32 v154, s30, 8, v151
	v_or_b32_e32 v155, 0x80, v154
	v_cmp_gt_i32_e64 s[24:25], s2, v154
	v_mul_lo_u32 v153, v153, s70
	v_cmp_gt_i32_e64 s[38:39], s2, v155
	v_lshl_add_u32 v153, v154, 1, v153
	s_cmp_eq_u32 s28, 1
	s_waitcnt lgkmcnt(0)
	s_cbranch_scc1 .Lmy_ip_m1
; __device__ __forceinline__ u32x4 pack8(const float* f) { u32x4 o; o.x = pk2(f[0], f[1]); o.y = pk2(f[2], f[3]); o.z = pk2(f[4], f[5]); o.w = pk2(f[6], f[7]); return o; }
; __device__ __forceinline__ float sigmoidf_(float x) { return rcpf(1.0f + __expf(-x)); }
; __device__ __forceinline__ float gelu_tanh(float v) { const float u = 0.7978845608f * (v + 0.044715f * v * v * v); return v * rcpf(1.0f + __expf(-2.0f * u)); }
;     __device__ __forceinline__ void operator()(const f32x4 (&acc)[2][2][4][2], const Unit& u, int wr, int wc, int fr, int fq) const {
;     ...
;                         for (int j = 0; j < 4; ++j) { const float v = acc[ai][bj][m][n][j] * rs; o[n * 4 + j] = mode == 0 ? gelu_tanh(v) : (mode == 1 ? v : sigmoidf_(v)); }
;     ...
;                     else if (c0 < PLD) *(u32x4*)(proj + row * PLD + c0) = pack8(o); } }
	s_mov_b32 s2, 0x3d372713
	s_mov_b32 s3, 0x3f4c422a
	s_mov_b32 s28, 0x3fb8aa3b
	v_mul_f32_e32 v126, v126, v146
	v_mul_f32_e32 v127, v127, v146
	v_mul_f32_e32 v128, v128, v146
	v_mul_f32_e32 v129, v129, v146
	v_mul_f32_e32 v122, v122, v146
	v_mul_f32_e32 v123, v123, v146
	v_mul_f32_e32 v124, v124, v146
	v_mul_f32_e32 v125, v125, v146
	v_mul_f32_e32 v156, s2, v126
	v_mul_f32_e32 v157, s2, v127
	v_mul_f32_e32 v158, s2, v128
	v_mul_f32_e32 v159, s2, v129
	v_mul_f32_e32 v160, s2, v122
	v_mul_f32_e32 v161, s2, v123
	v_mul_f32_e32 v162, s2, v124
	v_mul_f32_e32 v163, s2, v125
	v_mul_f32_e32 v156, v126, v156
	v_mul_f32_e32 v157, v127, v157
	v_mul_f32_e32 v158, v128, v158
	v_mul_f32_e32 v159, v129, v159
	v_mul_f32_e32 v160, v122, v160
	v_mul_f32_e32 v161, v123, v161
	v_mul_f32_e32 v162, v124, v162
	v_mul_f32_e32 v163, v125, v163
	v_fma_f32 v156, v126, v156, v126
	v_fma_f32 v157, v127, v157, v127
	v_fma_f32 v158, v128, v158, v128
	v_fma_f32 v159, v129, v159, v129
	v_fma_f32 v160, v122, v160, v122
	v_fma_f32 v161, v123, v161, v123
	v_fma_f32 v162, v124, v162, v124
	v_fma_f32 v163, v125, v163, v125
	v_mul_f32_e32 v156, s3, v156
	v_mul_f32_e32 v157, s3, v157
	v_mul_f32_e32 v158, s3, v158
	v_mul_f32_e32 v159, s3, v159
	v_mul_f32_e32 v160, s3, v160
	v_mul_f32_e32 v161, s3, v161
	v_mul_f32_e32 v162, s3, v162
	v_mul_f32_e32 v163, s3, v163
	v_mul_f32_e32 v156, -2.0, v156
	v_mul_f32_e32 v157, -2.0, v157
	v_mul_f32_e32 v158, -2.0, v158
	v_mul_f32_e32 v159, -2.0, v159
	v_mul_f32_e32 v160, -2.0, v160
	v_mul_f32_e32 v161, -2.0, v161
	v_mul_f32_e32 v162, -2.0, v162
	v_mul_f32_e32 v163, -2.0, v163
	v_mul_f32_e32 v156, s28, v156
	v_mul_f32_e32 v157, s28, v157
	v_mul_f32_e32 v158, s28, v158
	v_mul_f32_e32 v159, s28, v159
	v_mul_f32_e32 v160, s28, v160
	v_mul_f32_e32 v161, s28, v161
	v_mul_f32_e32 v162, s28, v162
	v_mul_f32_e32 v163, s28, v163
	v_exp_f32_e32 v156, v156
	v_exp_f32_e32 v157, v157
	v_exp_f32_e32 v158, v158
	v_exp_f32_e32 v159, v159
	v_exp_f32_e32 v160, v160
	v_exp_f32_e32 v161, v161
	v_exp_f32_e32 v162, v162
	v_exp_f32_e32 v163, v163
	v_add_f32_e32 v156, 1.0, v156
	v_add_f32_e32 v157, 1.0, v157
	v_add_f32_e32 v158, 1.0, v158
	v_add_f32_e32 v159, 1.0, v159
	v_add_f32_e32 v160, 1.0, v160
	v_add_f32_e32 v161, 1.0, v161
	v_add_f32_e32 v162, 1.0, v162
	v_add_f32_e32 v163, 1.0, v163
	v_rcp_f32_e32 v156, v156
	v_rcp_f32_e32 v157, v157
	v_rcp_f32_e32 v158, v158
	v_rcp_f32_e32 v159, v159
	v_rcp_f32_e32 v160, v160
	v_rcp_f32_e32 v161, v161
	v_rcp_f32_e32 v162, v162
	v_rcp_f32_e32 v163, v163
	v_mul_f32_e32 v126, v126, v156
	v_mul_f32_e32 v127, v127, v157
	v_mul_f32_e32 v128, v128, v158
	v_mul_f32_e32 v129, v129, v159
	v_mul_f32_e32 v122, v122, v160
	v_mul_f32_e32 v123, v123, v161
	v_mul_f32_e32 v124, v124, v162
	v_mul_f32_e32 v125, v125, v163
	v_cvt_pk_bf16_f32 v164, v126, v127
	v_cvt_pk_bf16_f32 v165, v128, v129
	v_cvt_pk_bf16_f32 v166, v122, v123
	v_cvt_pk_bf16_f32 v167, v124, v125
	s_mov_b64 exec, s[24:25]
	global_store_dwordx4 v153, v[164:167], s[68:69]
	s_mov_b64 exec, -1
	v_mul_f32_e32 v118, v118, v146
	v_mul_f32_e32 v119, v119, v146
	v_mul_f32_e32 v120, v120, v146
	v_mul_f32_e32 v121, v121, v146
	v_mul_f32_e32 v114, v114, v146
	v_mul_f32_e32 v115, v115, v146
	v_mul_f32_e32 v116, v116, v146
	v_mul_f32_e32 v117, v117, v146
	v_mul_f32_e32 v156, s2, v118
	v_mul_f32_e32 v157, s2, v119
	v_mul_f32_e32 v158, s2, v120
	v_mul_f32_e32 v159, s2, v121
	v_mul_f32_e32 v160, s2, v114
	v_mul_f32_e32 v161, s2, v115
	v_mul_f32_e32 v162, s2, v116
	v_mul_f32_e32 v163, s2, v117
	v_mul_f32_e32 v156, v118, v156
	v_mul_f32_e32 v157, v119, v157
	v_mul_f32_e32 v158, v120, v158
	v_mul_f32_e32 v159, v121, v159
	v_mul_f32_e32 v160, v114, v160
	v_mul_f32_e32 v161, v115, v161
	v_mul_f32_e32 v162, v116, v162
	v_mul_f32_e32 v163, v117, v163
	v_fma_f32 v156, v118, v156, v118
	v_fma_f32 v157, v119, v157, v119
	v_fma_f32 v158, v120, v158, v120
	v_fma_f32 v159, v121, v159, v121
	v_fma_f32 v160, v114, v160, v114
	v_fma_f32 v161, v115, v161, v115
	v_fma_f32 v162, v116, v162, v116
	v_fma_f32 v163, v117, v163, v117
	v_mul_f32_e32 v156, s3, v156
	v_mul_f32_e32 v157, s3, v157
	v_mul_f32_e32 v158, s3, v158
	v_mul_f32_e32 v159, s3, v159
	v_mul_f32_e32 v160, s3, v160
	v_mul_f32_e32 v161, s3, v161
	v_mul_f32_e32 v162, s3, v162
	v_mul_f32_e32 v163, s3, v163
	v_mul_f32_e32 v156, -2.0, v156
	v_mul_f32_e32 v157, -2.0, v157
	v_mul_f32_e32 v158, -2.0, v158
	v_mul_f32_e32 v159, -2.0, v159
	v_mul_f32_e32 v160, -2.0, v160
	v_mul_f32_e32 v161, -2.0, v161
	v_mul_f32_e32 v162, -2.0, v162
	v_mul_f32_e32 v163, -2.0, v163
	v_mul_f32_e32 v156, s28, v156
	v_mul_f32_e32 v157, s28, v157
	v_mul_f32_e32 v158, s28, v158
	v_mul_f32_e32 v159, s28, v159
	v_mul_f32_e32 v160, s28, v160
	v_mul_f32_e32 v161, s28, v161
	v_mul_f32_e32 v162, s28, v162
	v_mul_f32_e32 v163, s28, v163
	v_exp_f32_e32 v156, v156
	v_exp_f32_e32 v157, v157
	v_exp_f32_e32 v158, v158
	v_exp_f32_e32 v159, v159
	v_exp_f32_e32 v160, v160
	v_exp_f32_e32 v161, v161
	v_exp_f32_e32 v162, v162
	v_exp_f32_e32 v163, v163
	v_add_f32_e32 v156, 1.0, v156
	v_add_f32_e32 v157, 1.0, v157
	v_add_f32_e32 v158, 1.0, v158
	v_add_f32_e32 v159, 1.0, v159
	v_add_f32_e32 v160, 1.0, v160
	v_add_f32_e32 v161, 1.0, v161
	v_add_f32_e32 v162, 1.0, v162
	v_add_f32_e32 v163, 1.0, v163
	v_rcp_f32_e32 v156, v156
	v_rcp_f32_e32 v157, v157
	v_rcp_f32_e32 v158, v158
	v_rcp_f32_e32 v159, v159
	v_rcp_f32_e32 v160, v160
	v_rcp_f32_e32 v161, v161
	v_rcp_f32_e32 v162, v162
	v_rcp_f32_e32 v163, v163
	v_mul_f32_e32 v118, v118, v156
	v_mul_f32_e32 v119, v119, v157
	v_mul_f32_e32 v120, v120, v158
	v_mul_f32_e32 v121, v121, v159
	v_mul_f32_e32 v114, v114, v160
	v_mul_f32_e32 v115, v115, v161
; __device__ __forceinline__ u32x4 pack8(const float* f) { u32x4 o; o.x = pk2(f[0], f[1]); o.y = pk2(f[2], f[3]); o.z = pk2(f[4], f[5]); o.w = pk2(f[6], f[7]); return o; }
; __device__ __forceinline__ float sigmoidf_(float x) { return rcpf(1.0f + __expf(-x)); }
; __device__ __forceinline__ float gelu_tanh(float v) { const float u = 0.7978845608f * (v + 0.044715f * v * v * v); return v * rcpf(1.0f + __expf(-2.0f * u)); }
;     __device__ __forceinline__ void operator()(const f32x4 (&acc)[2][2][4][2], const Unit& u, int wr, int wc, int fr, int fq) const {
;     ...
;                         for (int j = 0; j < 4; ++j) { const float v = acc[ai][bj][m][n][j] * rs; o[n * 4 + j] = mode == 0 ? gelu_tanh(v) : (mode == 1 ? v : sigmoidf_(v)); }
;     ...
;                     else if (c0 < PLD) *(u32x4*)(proj + row * PLD + c0) = pack8(o); } }
	v_mul_f32_e32 v116, v116, v162
	v_mul_f32_e32 v117, v117, v163
	v_cvt_pk_bf16_f32 v168, v118, v119
	v_cvt_pk_bf16_f32 v169, v120, v121
	v_cvt_pk_bf16_f32 v170, v114, v115
	v_cvt_pk_bf16_f32 v171, v116, v117
	s_mov_b64 exec, s[38:39]
	global_store_dwordx4 v153, v[168:171], s[68:69] offset:256
	s_mov_b64 exec, -1
	v_mul_f32_e32 v110, v110, v147
	v_mul_f32_e32 v111, v111, v147
	v_mul_f32_e32 v112, v112, v147
	v_mul_f32_e32 v113, v113, v147
	v_mul_f32_e32 v106, v106, v147
	v_mul_f32_e32 v107, v107, v147
	v_mul_f32_e32 v108, v108, v147
	v_mul_f32_e32 v109, v109, v147
	v_mul_f32_e32 v156, s2, v110
	v_mul_f32_e32 v157, s2, v111
	v_mul_f32_e32 v158, s2, v112
	v_mul_f32_e32 v159, s2, v113
	v_mul_f32_e32 v160, s2, v106
	v_mul_f32_e32 v161, s2, v107
	v_mul_f32_e32 v162, s2, v108
	v_mul_f32_e32 v163, s2, v109
	v_mul_f32_e32 v156, v110, v156
	v_mul_f32_e32 v157, v111, v157
	v_mul_f32_e32 v158, v112, v158
	v_mul_f32_e32 v159, v113, v159
	v_mul_f32_e32 v160, v106, v160
	v_mul_f32_e32 v161, v107, v161
	v_mul_f32_e32 v162, v108, v162
	v_mul_f32_e32 v163, v109, v163
	v_fma_f32 v156, v110, v156, v110
	v_fma_f32 v157, v111, v157, v111
	v_fma_f32 v158, v112, v158, v112
	v_fma_f32 v159, v113, v159, v113
	v_fma_f32 v160, v106, v160, v106
	v_fma_f32 v161, v107, v161, v107
	v_fma_f32 v162, v108, v162, v108
	v_fma_f32 v163, v109, v163, v109
	v_mul_f32_e32 v156, s3, v156
	v_mul_f32_e32 v157, s3, v157
	v_mul_f32_e32 v158, s3, v158
	v_mul_f32_e32 v159, s3, v159
	v_mul_f32_e32 v160, s3, v160
	v_mul_f32_e32 v161, s3, v161
	v_mul_f32_e32 v162, s3, v162
	v_mul_f32_e32 v163, s3, v163
	v_mul_f32_e32 v156, -2.0, v156
	v_mul_f32_e32 v157, -2.0, v157
	v_mul_f32_e32 v158, -2.0, v158
	v_mul_f32_e32 v159, -2.0, v159
	v_mul_f32_e32 v160, -2.0, v160
	v_mul_f32_e32 v161, -2.0, v161
	v_mul_f32_e32 v162, -2.0, v162
	v_mul_f32_e32 v163, -2.0, v163
	v_mul_f32_e32 v156, s28, v156
	v_mul_f32_e32 v157, s28, v157
	v_mul_f32_e32 v158, s28, v158
	v_mul_f32_e32 v159, s28, v159
	v_mul_f32_e32 v160, s28, v160
	v_mul_f32_e32 v161, s28, v161
	v_mul_f32_e32 v162, s28, v162
	v_mul_f32_e32 v163, s28, v163
	v_exp_f32_e32 v156, v156
	v_exp_f32_e32 v157, v157
	v_exp_f32_e32 v158, v158
	v_exp_f32_e32 v159, v159
	v_exp_f32_e32 v160, v160
	v_exp_f32_e32 v161, v161
	v_exp_f32_e32 v162, v162
	v_exp_f32_e32 v163, v163
	v_add_f32_e32 v156, 1.0, v156
	v_add_f32_e32 v157, 1.0, v157
	v_add_f32_e32 v158, 1.0, v158
	v_add_f32_e32 v159, 1.0, v159
	v_add_f32_e32 v160, 1.0, v160
	v_add_f32_e32 v161, 1.0, v161
	v_add_f32_e32 v162, 1.0, v162
	v_add_f32_e32 v163, 1.0, v163
	v_rcp_f32_e32 v156, v156
	v_rcp_f32_e32 v157, v157
	v_rcp_f32_e32 v158, v158
	v_rcp_f32_e32 v159, v159
	v_rcp_f32_e32 v160, v160
	v_rcp_f32_e32 v161, v161
	v_rcp_f32_e32 v162, v162
	v_rcp_f32_e32 v163, v163
	v_mul_f32_e32 v110, v110, v156
	v_mul_f32_e32 v111, v111, v157
	v_mul_f32_e32 v112, v112, v158
	v_mul_f32_e32 v113, v113, v159
	v_mul_f32_e32 v106, v106, v160
	v_mul_f32_e32 v107, v107, v161
	v_mul_f32_e32 v108, v108, v162
	v_mul_f32_e32 v109, v109, v163
	v_add_u32_e32 v153, 0x26400, v153
	v_cvt_pk_bf16_f32 v164, v110, v111
	v_cvt_pk_bf16_f32 v165, v112, v113
	v_cvt_pk_bf16_f32 v166, v106, v107
	v_cvt_pk_bf16_f32 v167, v108, v109
	s_mov_b64 exec, s[24:25]
	global_store_dwordx4 v153, v[164:167], s[68:69]
	s_mov_b64 exec, -1
	v_mul_f32_e32 v102, v102, v147
	v_mul_f32_e32 v103, v103, v147
	v_mul_f32_e32 v104, v104, v147
	v_mul_f32_e32 v105, v105, v147
	v_mul_f32_e32 v98, v98, v147
	v_mul_f32_e32 v99, v99, v147
	v_mul_f32_e32 v100, v100, v147
	v_mul_f32_e32 v101, v101, v147
	v_mul_f32_e32 v156, s2, v102
	v_mul_f32_e32 v157, s2, v103
	v_mul_f32_e32 v158, s2, v104
	v_mul_f32_e32 v159, s2, v105
	v_mul_f32_e32 v160, s2, v98
	v_mul_f32_e32 v161, s2, v99
	v_mul_f32_e32 v162, s2, v100
	v_mul_f32_e32 v163, s2, v101
	v_mul_f32_e32 v156, v102, v156
	v_mul_f32_e32 v157, v103, v157
	v_mul_f32_e32 v158, v104, v158
	v_mul_f32_e32 v159, v105, v159
	v_mul_f32_e32 v160, v98, v160
	v_mul_f32_e32 v161, v99, v161
	v_mul_f32_e32 v162, v100, v162
	v_mul_f32_e32 v163, v101, v163
	v_fma_f32 v156, v102, v156, v102
	v_fma_f32 v157, v103, v157, v103
	v_fma_f32 v158, v104, v158, v104
	v_fma_f32 v159, v105, v159, v105
	v_fma_f32 v160, v98, v160, v98
	v_fma_f32 v161, v99, v161, v99
	v_fma_f32 v162, v100, v162, v100
	v_fma_f32 v163, v101, v163, v101
	v_mul_f32_e32 v156, s3, v156
	v_mul_f32_e32 v157, s3, v157
	v_mul_f32_e32 v158, s3, v158
	v_mul_f32_e32 v159, s3, v159
	v_mul_f32_e32 v160, s3, v160
	v_mul_f32_e32 v161, s3, v161
	v_mul_f32_e32 v162, s3, v162
	v_mul_f32_e32 v163, s3, v163
	v_mul_f32_e32 v156, -2.0, v156
	v_mul_f32_e32 v157, -2.0, v157
	v_mul_f32_e32 v158, -2.0, v158
	v_mul_f32_e32 v159, -2.0, v159
	v_mul_f32_e32 v160, -2.0, v160
	v_mul_f32_e32 v161, -2.0, v161
	v_mul_f32_e32 v162, -2.0, v162
	v_mul_f32_e32 v163, -2.0, v163
	v_mul_f32_e32 v156, s28, v156
	v_mul_f32_e32 v157, s28, v157
	v_mul_f32_e32 v158, s28, v158
	v_mul_f32_e32 v159, s28, v159
	v_mul_f32_e32 v160, s28, v160
	v_mul_f32_e32 v161, s28, v161
	v_mul_f32_e32 v162, s28, v162
	v_mul_f32_e32 v163, s28, v163
	v_exp_f32_e32 v156, v156
	v_exp_f32_e32 v157, v157
	v_exp_f32_e32 v158, v158
	v_exp_f32_e32 v159, v159
	v_exp_f32_e32 v160, v160
	v_exp_f32_e32 v161, v161
	v_exp_f32_e32 v162, v162
	v_exp_f32_e32 v163, v163
	v_add_f32_e32 v156, 1.0, v156
	v_add_f32_e32 v157, 1.0, v157
	v_add_f32_e32 v158, 1.0, v158
	v_add_f32_e32 v159, 1.0, v159
	v_add_f32_e32 v160, 1.0, v160
	v_add_f32_e32 v161, 1.0, v161
	v_add_f32_e32 v162, 1.0, v162
	v_add_f32_e32 v163, 1.0, v163
	v_rcp_f32_e32 v156, v156
	v_rcp_f32_e32 v157, v157
	v_rcp_f32_e32 v158, v158
	v_rcp_f32_e32 v159, v159
	v_rcp_f32_e32 v160, v160
	v_rcp_f32_e32 v161, v161
; __device__ __forceinline__ u32x4 pack8(const float* f) { u32x4 o; o.x = pk2(f[0], f[1]); o.y = pk2(f[2], f[3]); o.z = pk2(f[4], f[5]); o.w = pk2(f[6], f[7]); return o; }
; __device__ __forceinline__ float sigmoidf_(float x) { return rcpf(1.0f + __expf(-x)); }
; __device__ __forceinline__ float gelu_tanh(float v) { const float u = 0.7978845608f * (v + 0.044715f * v * v * v); return v * rcpf(1.0f + __expf(-2.0f * u)); }
;     __device__ __forceinline__ void operator()(const f32x4 (&acc)[2][2][4][2], const Unit& u, int wr, int wc, int fr, int fq) const {
;     ...
;                         for (int j = 0; j < 4; ++j) { const float v = acc[ai][bj][m][n][j] * rs; o[n * 4 + j] = mode == 0 ? gelu_tanh(v) : (mode == 1 ? v : sigmoidf_(v)); }
;     ...
;                     else if (c0 < PLD) *(u32x4*)(proj + row * PLD + c0) = pack8(o); } }
	v_rcp_f32_e32 v162, v162
	v_rcp_f32_e32 v163, v163
	v_mul_f32_e32 v102, v102, v156
	v_mul_f32_e32 v103, v103, v157
	v_mul_f32_e32 v104, v104, v158
	v_mul_f32_e32 v105, v105, v159
	v_mul_f32_e32 v98, v98, v160
	v_mul_f32_e32 v99, v99, v161
	v_mul_f32_e32 v100, v100, v162
	v_mul_f32_e32 v101, v101, v163
	v_cvt_pk_bf16_f32 v168, v102, v103
	v_cvt_pk_bf16_f32 v169, v104, v105
	v_cvt_pk_bf16_f32 v170, v98, v99
	v_cvt_pk_bf16_f32 v171, v100, v101
	s_mov_b64 exec, s[38:39]
	global_store_dwordx4 v153, v[168:171], s[68:69] offset:256
	s_mov_b64 exec, -1
	v_mul_f32_e32 v94, v94, v144
	v_mul_f32_e32 v95, v95, v144
	v_mul_f32_e32 v96, v96, v144
	v_mul_f32_e32 v97, v97, v144
	v_mul_f32_e32 v90, v90, v144
	v_mul_f32_e32 v91, v91, v144
	v_mul_f32_e32 v92, v92, v144
	v_mul_f32_e32 v93, v93, v144
	v_mul_f32_e32 v156, s2, v94
	v_mul_f32_e32 v157, s2, v95
	v_mul_f32_e32 v158, s2, v96
	v_mul_f32_e32 v159, s2, v97
	v_mul_f32_e32 v160, s2, v90
	v_mul_f32_e32 v161, s2, v91
	v_mul_f32_e32 v162, s2, v92
	v_mul_f32_e32 v163, s2, v93
	v_mul_f32_e32 v156, v94, v156
	v_mul_f32_e32 v157, v95, v157
	v_mul_f32_e32 v158, v96, v158
	v_mul_f32_e32 v159, v97, v159
	v_mul_f32_e32 v160, v90, v160
	v_mul_f32_e32 v161, v91, v161
	v_mul_f32_e32 v162, v92, v162
	v_mul_f32_e32 v163, v93, v163
	v_fma_f32 v156, v94, v156, v94
	v_fma_f32 v157, v95, v157, v95
	v_fma_f32 v158, v96, v158, v96
	v_fma_f32 v159, v97, v159, v97
	v_fma_f32 v160, v90, v160, v90
	v_fma_f32 v161, v91, v161, v91
	v_fma_f32 v162, v92, v162, v92
	v_fma_f32 v163, v93, v163, v93
	v_mul_f32_e32 v156, s3, v156
	v_mul_f32_e32 v157, s3, v157
	v_mul_f32_e32 v158, s3, v158
	v_mul_f32_e32 v159, s3, v159
	v_mul_f32_e32 v160, s3, v160
	v_mul_f32_e32 v161, s3, v161
	v_mul_f32_e32 v162, s3, v162
	v_mul_f32_e32 v163, s3, v163
	v_mul_f32_e32 v156, -2.0, v156
	v_mul_f32_e32 v157, -2.0, v157
	v_mul_f32_e32 v158, -2.0, v158
	v_mul_f32_e32 v159, -2.0, v159
	v_mul_f32_e32 v160, -2.0, v160
	v_mul_f32_e32 v161, -2.0, v161
	v_mul_f32_e32 v162, -2.0, v162
	v_mul_f32_e32 v163, -2.0, v163
	v_mul_f32_e32 v156, s28, v156
	v_mul_f32_e32 v157, s28, v157
	v_mul_f32_e32 v158, s28, v158
	v_mul_f32_e32 v159, s28, v159
	v_mul_f32_e32 v160, s28, v160
	v_mul_f32_e32 v161, s28, v161
	v_mul_f32_e32 v162, s28, v162
	v_mul_f32_e32 v163, s28, v163
	v_exp_f32_e32 v156, v156
	v_exp_f32_e32 v157, v157
	v_exp_f32_e32 v158, v158
	v_exp_f32_e32 v159, v159
	v_exp_f32_e32 v160, v160
	v_exp_f32_e32 v161, v161
	v_exp_f32_e32 v162, v162
	v_exp_f32_e32 v163, v163
	v_add_f32_e32 v156, 1.0, v156
	v_add_f32_e32 v157, 1.0, v157
	v_add_f32_e32 v158, 1.0, v158
	v_add_f32_e32 v159, 1.0, v159
	v_add_f32_e32 v160, 1.0, v160
	v_add_f32_e32 v161, 1.0, v161
	v_add_f32_e32 v162, 1.0, v162
	v_add_f32_e32 v163, 1.0, v163
	v_rcp_f32_e32 v156, v156
	v_rcp_f32_e32 v157, v157
	v_rcp_f32_e32 v158, v158
	v_rcp_f32_e32 v159, v159
	v_rcp_f32_e32 v160, v160
	v_rcp_f32_e32 v161, v161
	v_rcp_f32_e32 v162, v162
	v_rcp_f32_e32 v163, v163
	v_mul_f32_e32 v94, v94, v156
	v_mul_f32_e32 v95, v95, v157
	v_mul_f32_e32 v96, v96, v158
	v_mul_f32_e32 v97, v97, v159
	v_mul_f32_e32 v90, v90, v160
	v_mul_f32_e32 v91, v91, v161
	v_mul_f32_e32 v92, v92, v162
	v_mul_f32_e32 v93, v93, v163
	v_add_u32_e32 v153, 0x26400, v153
	v_cvt_pk_bf16_f32 v164, v94, v95
	v_cvt_pk_bf16_f32 v165, v96, v97
	v_cvt_pk_bf16_f32 v166, v90, v91
	v_cvt_pk_bf16_f32 v167, v92, v93
	s_mov_b64 exec, s[24:25]
	global_store_dwordx4 v153, v[164:167], s[68:69]
	s_mov_b64 exec, -1
	v_mul_f32_e32 v86, v86, v144
	v_mul_f32_e32 v87, v87, v144
	v_mul_f32_e32 v88, v88, v144
	v_mul_f32_e32 v89, v89, v144
	v_mul_f32_e32 v82, v82, v144
	v_mul_f32_e32 v83, v83, v144
	v_mul_f32_e32 v84, v84, v144
	v_mul_f32_e32 v85, v85, v144
	v_mul_f32_e32 v156, s2, v86
	v_mul_f32_e32 v157, s2, v87
	v_mul_f32_e32 v158, s2, v88
	v_mul_f32_e32 v159, s2, v89
	v_mul_f32_e32 v160, s2, v82
	v_mul_f32_e32 v161, s2, v83
	v_mul_f32_e32 v162, s2, v84
	v_mul_f32_e32 v163, s2, v85
	v_mul_f32_e32 v156, v86, v156
	v_mul_f32_e32 v157, v87, v157
	v_mul_f32_e32 v158, v88, v158
	v_mul_f32_e32 v159, v89, v159
	v_mul_f32_e32 v160, v82, v160
	v_mul_f32_e32 v161, v83, v161
	v_mul_f32_e32 v162, v84, v162
	v_mul_f32_e32 v163, v85, v163
	v_fma_f32 v156, v86, v156, v86
	v_fma_f32 v157, v87, v157, v87
	v_fma_f32 v158, v88, v158, v88
	v_fma_f32 v159, v89, v159, v89
	v_fma_f32 v160, v82, v160, v82
	v_fma_f32 v161, v83, v161, v83
	v_fma_f32 v162, v84, v162, v84
	v_fma_f32 v163, v85, v163, v85
	v_mul_f32_e32 v156, s3, v156
	v_mul_f32_e32 v157, s3, v157
	v_mul_f32_e32 v158, s3, v158
	v_mul_f32_e32 v159, s3, v159
	v_mul_f32_e32 v160, s3, v160
	v_mul_f32_e32 v161, s3, v161
	v_mul_f32_e32 v162, s3, v162
	v_mul_f32_e32 v163, s3, v163
	v_mul_f32_e32 v156, -2.0, v156
	v_mul_f32_e32 v157, -2.0, v157
	v_mul_f32_e32 v158, -2.0, v158
	v_mul_f32_e32 v159, -2.0, v159
	v_mul_f32_e32 v160, -2.0, v160
	v_mul_f32_e32 v161, -2.0, v161
	v_mul_f32_e32 v162, -2.0, v162
	v_mul_f32_e32 v163, -2.0, v163
	v_mul_f32_e32 v156, s28, v156
	v_mul_f32_e32 v157, s28, v157
	v_mul_f32_e32 v158, s28, v158
	v_mul_f32_e32 v159, s28, v159
	v_mul_f32_e32 v160, s28, v160
	v_mul_f32_e32 v161, s28, v161
	v_mul_f32_e32 v162, s28, v162
	v_mul_f32_e32 v163, s28, v163
	v_exp_f32_e32 v156, v156
	v_exp_f32_e32 v157, v157
	v_exp_f32_e32 v158, v158
	v_exp_f32_e32 v159, v159
	v_exp_f32_e32 v160, v160
	v_exp_f32_e32 v161, v161
	v_exp_f32_e32 v162, v162
	v_exp_f32_e32 v163, v163
	v_add_f32_e32 v156, 1.0, v156
	v_add_f32_e32 v157, 1.0, v157
	v_add_f32_e32 v158, 1.0, v158
	v_add_f32_e32 v159, 1.0, v159
	v_add_f32_e32 v160, 1.0, v160
	v_add_f32_e32 v161, 1.0, v161
	v_add_f32_e32 v162, 1.0, v162
	v_add_f32_e32 v163, 1.0, v163
	v_rcp_f32_e32 v156, v156
; __device__ __forceinline__ u32x4 pack8(const float* f) { u32x4 o; o.x = pk2(f[0], f[1]); o.y = pk2(f[2], f[3]); o.z = pk2(f[4], f[5]); o.w = pk2(f[6], f[7]); return o; }
; __device__ __forceinline__ float sigmoidf_(float x) { return rcpf(1.0f + __expf(-x)); }
; __device__ __forceinline__ float gelu_tanh(float v) { const float u = 0.7978845608f * (v + 0.044715f * v * v * v); return v * rcpf(1.0f + __expf(-2.0f * u)); }
;     __device__ __forceinline__ void operator()(const f32x4 (&acc)[2][2][4][2], const Unit& u, int wr, int wc, int fr, int fq) const {
;     ...
;                         for (int j = 0; j < 4; ++j) { const float v = acc[ai][bj][m][n][j] * rs; o[n * 4 + j] = mode == 0 ? gelu_tanh(v) : (mode == 1 ? v : sigmoidf_(v)); }
;     ...
;                     else if (c0 < PLD) *(u32x4*)(proj + row * PLD + c0) = pack8(o); } }
	v_rcp_f32_e32 v157, v157
	v_rcp_f32_e32 v158, v158
	v_rcp_f32_e32 v159, v159
	v_rcp_f32_e32 v160, v160
	v_rcp_f32_e32 v161, v161
	v_rcp_f32_e32 v162, v162
	v_rcp_f32_e32 v163, v163
	v_mul_f32_e32 v86, v86, v156
	v_mul_f32_e32 v87, v87, v157
	v_mul_f32_e32 v88, v88, v158
	v_mul_f32_e32 v89, v89, v159
	v_mul_f32_e32 v82, v82, v160
	v_mul_f32_e32 v83, v83, v161
	v_mul_f32_e32 v84, v84, v162
	v_mul_f32_e32 v85, v85, v163
	v_cvt_pk_bf16_f32 v168, v86, v87
	v_cvt_pk_bf16_f32 v169, v88, v89
	v_cvt_pk_bf16_f32 v170, v82, v83
	v_cvt_pk_bf16_f32 v171, v84, v85
	s_mov_b64 exec, s[38:39]
	global_store_dwordx4 v153, v[168:171], s[68:69] offset:256
	s_mov_b64 exec, -1
	v_mul_f32_e32 v78, v78, v145
	v_mul_f32_e32 v79, v79, v145
	v_mul_f32_e32 v80, v80, v145
	v_mul_f32_e32 v81, v81, v145
	v_mul_f32_e32 v74, v74, v145
	v_mul_f32_e32 v75, v75, v145
	v_mul_f32_e32 v76, v76, v145
	v_mul_f32_e32 v77, v77, v145
	v_mul_f32_e32 v156, s2, v78
	v_mul_f32_e32 v157, s2, v79
	v_mul_f32_e32 v158, s2, v80
	v_mul_f32_e32 v159, s2, v81
	v_mul_f32_e32 v160, s2, v74
	v_mul_f32_e32 v161, s2, v75
	v_mul_f32_e32 v162, s2, v76
	v_mul_f32_e32 v163, s2, v77
	v_mul_f32_e32 v156, v78, v156
	v_mul_f32_e32 v157, v79, v157
	v_mul_f32_e32 v158, v80, v158
	v_mul_f32_e32 v159, v81, v159
	v_mul_f32_e32 v160, v74, v160
	v_mul_f32_e32 v161, v75, v161
	v_mul_f32_e32 v162, v76, v162
	v_mul_f32_e32 v163, v77, v163
	v_fma_f32 v156, v78, v156, v78
	v_fma_f32 v157, v79, v157, v79
	v_fma_f32 v158, v80, v158, v80
	v_fma_f32 v159, v81, v159, v81
	v_fma_f32 v160, v74, v160, v74
	v_fma_f32 v161, v75, v161, v75
	v_fma_f32 v162, v76, v162, v76
	v_fma_f32 v163, v77, v163, v77
	v_mul_f32_e32 v156, s3, v156
	v_mul_f32_e32 v157, s3, v157
	v_mul_f32_e32 v158, s3, v158
	v_mul_f32_e32 v159, s3, v159
	v_mul_f32_e32 v160, s3, v160
	v_mul_f32_e32 v161, s3, v161
	v_mul_f32_e32 v162, s3, v162
	v_mul_f32_e32 v163, s3, v163
	v_mul_f32_e32 v156, -2.0, v156
	v_mul_f32_e32 v157, -2.0, v157
	v_mul_f32_e32 v158, -2.0, v158
	v_mul_f32_e32 v159, -2.0, v159
	v_mul_f32_e32 v160, -2.0, v160
	v_mul_f32_e32 v161, -2.0, v161
	v_mul_f32_e32 v162, -2.0, v162
	v_mul_f32_e32 v163, -2.0, v163
	v_mul_f32_e32 v156, s28, v156
	v_mul_f32_e32 v157, s28, v157
	v_mul_f32_e32 v158, s28, v158
	v_mul_f32_e32 v159, s28, v159
	v_mul_f32_e32 v160, s28, v160
	v_mul_f32_e32 v161, s28, v161
	v_mul_f32_e32 v162, s28, v162
	v_mul_f32_e32 v163, s28, v163
	v_exp_f32_e32 v156, v156
	v_exp_f32_e32 v157, v157
	v_exp_f32_e32 v158, v158
	v_exp_f32_e32 v159, v159
	v_exp_f32_e32 v160, v160
	v_exp_f32_e32 v161, v161
	v_exp_f32_e32 v162, v162
	v_exp_f32_e32 v163, v163
	v_add_f32_e32 v156, 1.0, v156
	v_add_f32_e32 v157, 1.0, v157
	v_add_f32_e32 v158, 1.0, v158
	v_add_f32_e32 v159, 1.0, v159
	v_add_f32_e32 v160, 1.0, v160
	v_add_f32_e32 v161, 1.0, v161
	v_add_f32_e32 v162, 1.0, v162
	v_add_f32_e32 v163, 1.0, v163
	v_rcp_f32_e32 v156, v156
	v_rcp_f32_e32 v157, v157
	v_rcp_f32_e32 v158, v158
	v_rcp_f32_e32 v159, v159
	v_rcp_f32_e32 v160, v160
	v_rcp_f32_e32 v161, v161
	v_rcp_f32_e32 v162, v162
	v_rcp_f32_e32 v163, v163
	v_mul_f32_e32 v78, v78, v156
	v_mul_f32_e32 v79, v79, v157
	v_mul_f32_e32 v80, v80, v158
	v_mul_f32_e32 v81, v81, v159
	v_mul_f32_e32 v74, v74, v160
	v_mul_f32_e32 v75, v75, v161
	v_mul_f32_e32 v76, v76, v162
	v_mul_f32_e32 v77, v77, v163
	v_add_u32_e32 v153, 0x26400, v153
	v_cvt_pk_bf16_f32 v164, v78, v79
	v_cvt_pk_bf16_f32 v165, v80, v81
	v_cvt_pk_bf16_f32 v166, v74, v75
	v_cvt_pk_bf16_f32 v167, v76, v77
	s_mov_b64 exec, s[24:25]
	global_store_dwordx4 v153, v[164:167], s[68:69]
	s_mov_b64 exec, -1
	v_mul_f32_e32 v70, v70, v145
	v_mul_f32_e32 v71, v71, v145
	v_mul_f32_e32 v72, v72, v145
	v_mul_f32_e32 v73, v73, v145
	v_mul_f32_e32 v66, v66, v145
	v_mul_f32_e32 v67, v67, v145
	v_mul_f32_e32 v68, v68, v145
	v_mul_f32_e32 v69, v69, v145
	v_mul_f32_e32 v156, s2, v70
	v_mul_f32_e32 v157, s2, v71
	v_mul_f32_e32 v158, s2, v72
	v_mul_f32_e32 v159, s2, v73
	v_mul_f32_e32 v160, s2, v66
	v_mul_f32_e32 v161, s2, v67
	v_mul_f32_e32 v162, s2, v68
	v_mul_f32_e32 v163, s2, v69
	v_mul_f32_e32 v156, v70, v156
	v_mul_f32_e32 v157, v71, v157
	v_mul_f32_e32 v158, v72, v158
	v_mul_f32_e32 v159, v73, v159
	v_mul_f32_e32 v160, v66, v160
	v_mul_f32_e32 v161, v67, v161
	v_mul_f32_e32 v162, v68, v162
	v_mul_f32_e32 v163, v69, v163
	v_fma_f32 v156, v70, v156, v70
	v_fma_f32 v157, v71, v157, v71
	v_fma_f32 v158, v72, v158, v72
	v_fma_f32 v159, v73, v159, v73
	v_fma_f32 v160, v66, v160, v66
	v_fma_f32 v161, v67, v161, v67
	v_fma_f32 v162, v68, v162, v68
	v_fma_f32 v163, v69, v163, v69
	v_mul_f32_e32 v156, s3, v156
	v_mul_f32_e32 v157, s3, v157
	v_mul_f32_e32 v158, s3, v158
	v_mul_f32_e32 v159, s3, v159
	v_mul_f32_e32 v160, s3, v160
	v_mul_f32_e32 v161, s3, v161
	v_mul_f32_e32 v162, s3, v162
	v_mul_f32_e32 v163, s3, v163
	v_mul_f32_e32 v156, -2.0, v156
	v_mul_f32_e32 v157, -2.0, v157
	v_mul_f32_e32 v158, -2.0, v158
	v_mul_f32_e32 v159, -2.0, v159
	v_mul_f32_e32 v160, -2.0, v160
	v_mul_f32_e32 v161, -2.0, v161
	v_mul_f32_e32 v162, -2.0, v162
	v_mul_f32_e32 v163, -2.0, v163
	v_mul_f32_e32 v156, s28, v156
	v_mul_f32_e32 v157, s28, v157
	v_mul_f32_e32 v158, s28, v158
	v_mul_f32_e32 v159, s28, v159
	v_mul_f32_e32 v160, s28, v160
	v_mul_f32_e32 v161, s28, v161
	v_mul_f32_e32 v162, s28, v162
	v_mul_f32_e32 v163, s28, v163
	v_exp_f32_e32 v156, v156
	v_exp_f32_e32 v157, v157
	v_exp_f32_e32 v158, v158
	v_exp_f32_e32 v159, v159
	v_exp_f32_e32 v160, v160
	v_exp_f32_e32 v161, v161
	v_exp_f32_e32 v162, v162
	v_exp_f32_e32 v163, v163
	v_add_f32_e32 v156, 1.0, v156
	v_add_f32_e32 v157, 1.0, v157
	v_add_f32_e32 v158, 1.0, v158
	v_add_f32_e32 v159, 1.0, v159
	v_add_f32_e32 v160, 1.0, v160
; __device__ __forceinline__ u32x4 pack8(const float* f) { u32x4 o; o.x = pk2(f[0], f[1]); o.y = pk2(f[2], f[3]); o.z = pk2(f[4], f[5]); o.w = pk2(f[6], f[7]); return o; }
; __device__ __forceinline__ float sigmoidf_(float x) { return rcpf(1.0f + __expf(-x)); }
; __device__ __forceinline__ float gelu_tanh(float v) { const float u = 0.7978845608f * (v + 0.044715f * v * v * v); return v * rcpf(1.0f + __expf(-2.0f * u)); }
;     __device__ __forceinline__ void operator()(const f32x4 (&acc)[2][2][4][2], const Unit& u, int wr, int wc, int fr, int fq) const {
;     ...
;                         for (int j = 0; j < 4; ++j) { const float v = acc[ai][bj][m][n][j] * rs; o[n * 4 + j] = mode == 0 ? gelu_tanh(v) : (mode == 1 ? v : sigmoidf_(v)); }
;     ...
;                     else if (c0 < PLD) *(u32x4*)(proj + row * PLD + c0) = pack8(o); } }
	v_add_f32_e32 v161, 1.0, v161
	v_add_f32_e32 v162, 1.0, v162
	v_add_f32_e32 v163, 1.0, v163
	v_rcp_f32_e32 v156, v156
	v_rcp_f32_e32 v157, v157
	v_rcp_f32_e32 v158, v158
	v_rcp_f32_e32 v159, v159
	v_rcp_f32_e32 v160, v160
	v_rcp_f32_e32 v161, v161
	v_rcp_f32_e32 v162, v162
	v_rcp_f32_e32 v163, v163
	v_mul_f32_e32 v70, v70, v156
	v_mul_f32_e32 v71, v71, v157
	v_mul_f32_e32 v72, v72, v158
	v_mul_f32_e32 v73, v73, v159
	v_mul_f32_e32 v66, v66, v160
	v_mul_f32_e32 v67, v67, v161
	v_mul_f32_e32 v68, v68, v162
	v_mul_f32_e32 v69, v69, v163
	v_cvt_pk_bf16_f32 v168, v70, v71
	v_cvt_pk_bf16_f32 v169, v72, v73
	v_cvt_pk_bf16_f32 v170, v66, v67
	v_cvt_pk_bf16_f32 v171, v68, v69
	s_mov_b64 exec, s[38:39]
	global_store_dwordx4 v153, v[168:171], s[68:69] offset:256
	s_mov_b64 exec, -1
	v_mul_f32_e32 v62, v62, v142
	v_mul_f32_e32 v63, v63, v142
	v_mul_f32_e32 v64, v64, v142
	v_mul_f32_e32 v65, v65, v142
	v_mul_f32_e32 v58, v58, v142
	v_mul_f32_e32 v59, v59, v142
	v_mul_f32_e32 v60, v60, v142
	v_mul_f32_e32 v61, v61, v142
	v_mul_f32_e32 v156, s2, v62
	v_mul_f32_e32 v157, s2, v63
	v_mul_f32_e32 v158, s2, v64
	v_mul_f32_e32 v159, s2, v65
	v_mul_f32_e32 v160, s2, v58
	v_mul_f32_e32 v161, s2, v59
	v_mul_f32_e32 v162, s2, v60
	v_mul_f32_e32 v163, s2, v61
	v_mul_f32_e32 v156, v62, v156
	v_mul_f32_e32 v157, v63, v157
	v_mul_f32_e32 v158, v64, v158
	v_mul_f32_e32 v159, v65, v159
	v_mul_f32_e32 v160, v58, v160
	v_mul_f32_e32 v161, v59, v161
	v_mul_f32_e32 v162, v60, v162
	v_mul_f32_e32 v163, v61, v163
	v_fma_f32 v156, v62, v156, v62
	v_fma_f32 v157, v63, v157, v63
	v_fma_f32 v158, v64, v158, v64
	v_fma_f32 v159, v65, v159, v65
	v_fma_f32 v160, v58, v160, v58
	v_fma_f32 v161, v59, v161, v59
	v_fma_f32 v162, v60, v162, v60
	v_fma_f32 v163, v61, v163, v61
	v_mul_f32_e32 v156, s3, v156
	v_mul_f32_e32 v157, s3, v157
	v_mul_f32_e32 v158, s3, v158
	v_mul_f32_e32 v159, s3, v159
	v_mul_f32_e32 v160, s3, v160
	v_mul_f32_e32 v161, s3, v161
	v_mul_f32_e32 v162, s3, v162
	v_mul_f32_e32 v163, s3, v163
	v_mul_f32_e32 v156, -2.0, v156
	v_mul_f32_e32 v157, -2.0, v157
	v_mul_f32_e32 v158, -2.0, v158
	v_mul_f32_e32 v159, -2.0, v159
	v_mul_f32_e32 v160, -2.0, v160
	v_mul_f32_e32 v161, -2.0, v161
	v_mul_f32_e32 v162, -2.0, v162
	v_mul_f32_e32 v163, -2.0, v163
	v_mul_f32_e32 v156, s28, v156
	v_mul_f32_e32 v157, s28, v157
	v_mul_f32_e32 v158, s28, v158
	v_mul_f32_e32 v159, s28, v159
	v_mul_f32_e32 v160, s28, v160
	v_mul_f32_e32 v161, s28, v161
	v_mul_f32_e32 v162, s28, v162
	v_mul_f32_e32 v163, s28, v163
	v_exp_f32_e32 v156, v156
	v_exp_f32_e32 v157, v157
	v_exp_f32_e32 v158, v158
	v_exp_f32_e32 v159, v159
	v_exp_f32_e32 v160, v160
	v_exp_f32_e32 v161, v161
	v_exp_f32_e32 v162, v162
	v_exp_f32_e32 v163, v163
	v_add_f32_e32 v156, 1.0, v156
	v_add_f32_e32 v157, 1.0, v157
	v_add_f32_e32 v158, 1.0, v158
	v_add_f32_e32 v159, 1.0, v159
	v_add_f32_e32 v160, 1.0, v160
	v_add_f32_e32 v161, 1.0, v161
	v_add_f32_e32 v162, 1.0, v162
	v_add_f32_e32 v163, 1.0, v163
	v_rcp_f32_e32 v156, v156
	v_rcp_f32_e32 v157, v157
	v_rcp_f32_e32 v158, v158
	v_rcp_f32_e32 v159, v159
	v_rcp_f32_e32 v160, v160
	v_rcp_f32_e32 v161, v161
	v_rcp_f32_e32 v162, v162
	v_rcp_f32_e32 v163, v163
	v_mul_f32_e32 v62, v62, v156
	v_mul_f32_e32 v63, v63, v157
	v_mul_f32_e32 v64, v64, v158
	v_mul_f32_e32 v65, v65, v159
	v_mul_f32_e32 v58, v58, v160
	v_mul_f32_e32 v59, v59, v161
	v_mul_f32_e32 v60, v60, v162
	v_mul_f32_e32 v61, v61, v163
	v_add_u32_e32 v153, 0xbf400, v153
	v_cvt_pk_bf16_f32 v164, v62, v63
	v_cvt_pk_bf16_f32 v165, v64, v65
	v_cvt_pk_bf16_f32 v166, v58, v59
	v_cvt_pk_bf16_f32 v167, v60, v61
	s_mov_b64 exec, s[24:25]
	global_store_dwordx4 v153, v[164:167], s[68:69]
	s_mov_b64 exec, -1
	v_mul_f32_e32 v54, v54, v142
	v_mul_f32_e32 v55, v55, v142
	v_mul_f32_e32 v56, v56, v142
	v_mul_f32_e32 v57, v57, v142
	v_mul_f32_e32 v50, v50, v142
	v_mul_f32_e32 v51, v51, v142
	v_mul_f32_e32 v52, v52, v142
	v_mul_f32_e32 v53, v53, v142
	v_mul_f32_e32 v156, s2, v54
	v_mul_f32_e32 v157, s2, v55
	v_mul_f32_e32 v158, s2, v56
	v_mul_f32_e32 v159, s2, v57
	v_mul_f32_e32 v160, s2, v50
	v_mul_f32_e32 v161, s2, v51
	v_mul_f32_e32 v162, s2, v52
	v_mul_f32_e32 v163, s2, v53
	v_mul_f32_e32 v156, v54, v156
	v_mul_f32_e32 v157, v55, v157
	v_mul_f32_e32 v158, v56, v158
	v_mul_f32_e32 v159, v57, v159
	v_mul_f32_e32 v160, v50, v160
	v_mul_f32_e32 v161, v51, v161
	v_mul_f32_e32 v162, v52, v162
	v_mul_f32_e32 v163, v53, v163
	v_fma_f32 v156, v54, v156, v54
	v_fma_f32 v157, v55, v157, v55
	v_fma_f32 v158, v56, v158, v56
	v_fma_f32 v159, v57, v159, v57
	v_fma_f32 v160, v50, v160, v50
	v_fma_f32 v161, v51, v161, v51
	v_fma_f32 v162, v52, v162, v52
	v_fma_f32 v163, v53, v163, v53
	v_mul_f32_e32 v156, s3, v156
	v_mul_f32_e32 v157, s3, v157
	v_mul_f32_e32 v158, s3, v158
	v_mul_f32_e32 v159, s3, v159
	v_mul_f32_e32 v160, s3, v160
	v_mul_f32_e32 v161, s3, v161
	v_mul_f32_e32 v162, s3, v162
	v_mul_f32_e32 v163, s3, v163
	v_mul_f32_e32 v156, -2.0, v156
	v_mul_f32_e32 v157, -2.0, v157
	v_mul_f32_e32 v158, -2.0, v158
	v_mul_f32_e32 v159, -2.0, v159
	v_mul_f32_e32 v160, -2.0, v160
	v_mul_f32_e32 v161, -2.0, v161
	v_mul_f32_e32 v162, -2.0, v162
	v_mul_f32_e32 v163, -2.0, v163
	v_mul_f32_e32 v156, s28, v156
	v_mul_f32_e32 v157, s28, v157
	v_mul_f32_e32 v158, s28, v158
	v_mul_f32_e32 v159, s28, v159
	v_mul_f32_e32 v160, s28, v160
	v_mul_f32_e32 v161, s28, v161
	v_mul_f32_e32 v162, s28, v162
	v_mul_f32_e32 v163, s28, v163
	v_exp_f32_e32 v156, v156
	v_exp_f32_e32 v157, v157
	v_exp_f32_e32 v158, v158
	v_exp_f32_e32 v159, v159
	v_exp_f32_e32 v160, v160
	v_exp_f32_e32 v161, v161
	v_exp_f32_e32 v162, v162
	v_exp_f32_e32 v163, v163
	v_add_f32_e32 v156, 1.0, v156
; __device__ __forceinline__ u32x4 pack8(const float* f) { u32x4 o; o.x = pk2(f[0], f[1]); o.y = pk2(f[2], f[3]); o.z = pk2(f[4], f[5]); o.w = pk2(f[6], f[7]); return o; }
; __device__ __forceinline__ float sigmoidf_(float x) { return rcpf(1.0f + __expf(-x)); }
; __device__ __forceinline__ float gelu_tanh(float v) { const float u = 0.7978845608f * (v + 0.044715f * v * v * v); return v * rcpf(1.0f + __expf(-2.0f * u)); }
;     __device__ __forceinline__ void operator()(const f32x4 (&acc)[2][2][4][2], const Unit& u, int wr, int wc, int fr, int fq) const {
;     ...
;                         for (int j = 0; j < 4; ++j) { const float v = acc[ai][bj][m][n][j] * rs; o[n * 4 + j] = mode == 0 ? gelu_tanh(v) : (mode == 1 ? v : sigmoidf_(v)); }
;     ...
;                     else if (c0 < PLD) *(u32x4*)(proj + row * PLD + c0) = pack8(o); } }
	v_add_f32_e32 v157, 1.0, v157
	v_add_f32_e32 v158, 1.0, v158
	v_add_f32_e32 v159, 1.0, v159
	v_add_f32_e32 v160, 1.0, v160
	v_add_f32_e32 v161, 1.0, v161
	v_add_f32_e32 v162, 1.0, v162
	v_add_f32_e32 v163, 1.0, v163
	v_rcp_f32_e32 v156, v156
	v_rcp_f32_e32 v157, v157
	v_rcp_f32_e32 v158, v158
	v_rcp_f32_e32 v159, v159
	v_rcp_f32_e32 v160, v160
	v_rcp_f32_e32 v161, v161
	v_rcp_f32_e32 v162, v162
	v_rcp_f32_e32 v163, v163
	v_mul_f32_e32 v54, v54, v156
	v_mul_f32_e32 v55, v55, v157
	v_mul_f32_e32 v56, v56, v158
	v_mul_f32_e32 v57, v57, v159
	v_mul_f32_e32 v50, v50, v160
	v_mul_f32_e32 v51, v51, v161
	v_mul_f32_e32 v52, v52, v162
	v_mul_f32_e32 v53, v53, v163
	v_cvt_pk_bf16_f32 v168, v54, v55
	v_cvt_pk_bf16_f32 v169, v56, v57
	v_cvt_pk_bf16_f32 v170, v50, v51
	v_cvt_pk_bf16_f32 v171, v52, v53
	s_mov_b64 exec, s[38:39]
	global_store_dwordx4 v153, v[168:171], s[68:69] offset:256
	s_mov_b64 exec, -1
	v_mul_f32_e32 v46, v46, v143
	v_mul_f32_e32 v47, v47, v143
	v_mul_f32_e32 v48, v48, v143
	v_mul_f32_e32 v49, v49, v143
	v_mul_f32_e32 v42, v42, v143
	v_mul_f32_e32 v43, v43, v143
	v_mul_f32_e32 v44, v44, v143
	v_mul_f32_e32 v45, v45, v143
	v_mul_f32_e32 v156, s2, v46
	v_mul_f32_e32 v157, s2, v47
	v_mul_f32_e32 v158, s2, v48
	v_mul_f32_e32 v159, s2, v49
	v_mul_f32_e32 v160, s2, v42
	v_mul_f32_e32 v161, s2, v43
	v_mul_f32_e32 v162, s2, v44
	v_mul_f32_e32 v163, s2, v45
	v_mul_f32_e32 v156, v46, v156
	v_mul_f32_e32 v157, v47, v157
	v_mul_f32_e32 v158, v48, v158
	v_mul_f32_e32 v159, v49, v159
	v_mul_f32_e32 v160, v42, v160
	v_mul_f32_e32 v161, v43, v161
	v_mul_f32_e32 v162, v44, v162
	v_mul_f32_e32 v163, v45, v163
	v_fma_f32 v156, v46, v156, v46
	v_fma_f32 v157, v47, v157, v47
	v_fma_f32 v158, v48, v158, v48
	v_fma_f32 v159, v49, v159, v49
	v_fma_f32 v160, v42, v160, v42
	v_fma_f32 v161, v43, v161, v43
	v_fma_f32 v162, v44, v162, v44
	v_fma_f32 v163, v45, v163, v45
	v_mul_f32_e32 v156, s3, v156
	v_mul_f32_e32 v157, s3, v157
	v_mul_f32_e32 v158, s3, v158
	v_mul_f32_e32 v159, s3, v159
	v_mul_f32_e32 v160, s3, v160
	v_mul_f32_e32 v161, s3, v161
	v_mul_f32_e32 v162, s3, v162
	v_mul_f32_e32 v163, s3, v163
	v_mul_f32_e32 v156, -2.0, v156
	v_mul_f32_e32 v157, -2.0, v157
	v_mul_f32_e32 v158, -2.0, v158
	v_mul_f32_e32 v159, -2.0, v159
	v_mul_f32_e32 v160, -2.0, v160
	v_mul_f32_e32 v161, -2.0, v161
	v_mul_f32_e32 v162, -2.0, v162
	v_mul_f32_e32 v163, -2.0, v163
	v_mul_f32_e32 v156, s28, v156
	v_mul_f32_e32 v157, s28, v157
	v_mul_f32_e32 v158, s28, v158
	v_mul_f32_e32 v159, s28, v159
	v_mul_f32_e32 v160, s28, v160
	v_mul_f32_e32 v161, s28, v161
	v_mul_f32_e32 v162, s28, v162
	v_mul_f32_e32 v163, s28, v163
	v_exp_f32_e32 v156, v156
	v_exp_f32_e32 v157, v157
	v_exp_f32_e32 v158, v158
	v_exp_f32_e32 v159, v159
	v_exp_f32_e32 v160, v160
	v_exp_f32_e32 v161, v161
	v_exp_f32_e32 v162, v162
	v_exp_f32_e32 v163, v163
	v_add_f32_e32 v156, 1.0, v156
	v_add_f32_e32 v157, 1.0, v157
	v_add_f32_e32 v158, 1.0, v158
	v_add_f32_e32 v159, 1.0, v159
	v_add_f32_e32 v160, 1.0, v160
	v_add_f32_e32 v161, 1.0, v161
	v_add_f32_e32 v162, 1.0, v162
	v_add_f32_e32 v163, 1.0, v163
	v_rcp_f32_e32 v156, v156
	v_rcp_f32_e32 v157, v157
	v_rcp_f32_e32 v158, v158
	v_rcp_f32_e32 v159, v159
	v_rcp_f32_e32 v160, v160
	v_rcp_f32_e32 v161, v161
	v_rcp_f32_e32 v162, v162
	v_rcp_f32_e32 v163, v163
	v_mul_f32_e32 v46, v46, v156
	v_mul_f32_e32 v47, v47, v157
	v_mul_f32_e32 v48, v48, v158
	v_mul_f32_e32 v49, v49, v159
	v_mul_f32_e32 v42, v42, v160
	v_mul_f32_e32 v43, v43, v161
	v_mul_f32_e32 v44, v44, v162
	v_mul_f32_e32 v45, v45, v163
	v_add_u32_e32 v153, 0x26400, v153
	v_cvt_pk_bf16_f32 v164, v46, v47
	v_cvt_pk_bf16_f32 v165, v48, v49
	v_cvt_pk_bf16_f32 v166, v42, v43
	v_cvt_pk_bf16_f32 v167, v44, v45
	s_mov_b64 exec, s[24:25]
	global_store_dwordx4 v153, v[164:167], s[68:69]
	s_mov_b64 exec, -1
	v_mul_f32_e32 v38, v38, v143
	v_mul_f32_e32 v39, v39, v143
	v_mul_f32_e32 v40, v40, v143
	v_mul_f32_e32 v41, v41, v143
	v_mul_f32_e32 v34, v34, v143
	v_mul_f32_e32 v35, v35, v143
	v_mul_f32_e32 v36, v36, v143
	v_mul_f32_e32 v37, v37, v143
	v_mul_f32_e32 v156, s2, v38
	v_mul_f32_e32 v157, s2, v39
	v_mul_f32_e32 v158, s2, v40
	v_mul_f32_e32 v159, s2, v41
	v_mul_f32_e32 v160, s2, v34
	v_mul_f32_e32 v161, s2, v35
	v_mul_f32_e32 v162, s2, v36
	v_mul_f32_e32 v163, s2, v37
	v_mul_f32_e32 v156, v38, v156
	v_mul_f32_e32 v157, v39, v157
	v_mul_f32_e32 v158, v40, v158
	v_mul_f32_e32 v159, v41, v159
	v_mul_f32_e32 v160, v34, v160
	v_mul_f32_e32 v161, v35, v161
	v_mul_f32_e32 v162, v36, v162
	v_mul_f32_e32 v163, v37, v163
	v_fma_f32 v156, v38, v156, v38
	v_fma_f32 v157, v39, v157, v39
	v_fma_f32 v158, v40, v158, v40
	v_fma_f32 v159, v41, v159, v41
	v_fma_f32 v160, v34, v160, v34
	v_fma_f32 v161, v35, v161, v35
	v_fma_f32 v162, v36, v162, v36
	v_fma_f32 v163, v37, v163, v37
	v_mul_f32_e32 v156, s3, v156
	v_mul_f32_e32 v157, s3, v157
	v_mul_f32_e32 v158, s3, v158
	v_mul_f32_e32 v159, s3, v159
	v_mul_f32_e32 v160, s3, v160
	v_mul_f32_e32 v161, s3, v161
	v_mul_f32_e32 v162, s3, v162
	v_mul_f32_e32 v163, s3, v163
	v_mul_f32_e32 v156, -2.0, v156
	v_mul_f32_e32 v157, -2.0, v157
	v_mul_f32_e32 v158, -2.0, v158
	v_mul_f32_e32 v159, -2.0, v159
	v_mul_f32_e32 v160, -2.0, v160
	v_mul_f32_e32 v161, -2.0, v161
	v_mul_f32_e32 v162, -2.0, v162
	v_mul_f32_e32 v163, -2.0, v163
	v_mul_f32_e32 v156, s28, v156
	v_mul_f32_e32 v157, s28, v157
	v_mul_f32_e32 v158, s28, v158
	v_mul_f32_e32 v159, s28, v159
	v_mul_f32_e32 v160, s28, v160
	v_mul_f32_e32 v161, s28, v161
	v_mul_f32_e32 v162, s28, v162
	v_mul_f32_e32 v163, s28, v163
	v_exp_f32_e32 v156, v156
	v_exp_f32_e32 v157, v157
	v_exp_f32_e32 v158, v158
	v_exp_f32_e32 v159, v159
	v_exp_f32_e32 v160, v160
; __device__ __forceinline__ u32x4 pack8(const float* f) { u32x4 o; o.x = pk2(f[0], f[1]); o.y = pk2(f[2], f[3]); o.z = pk2(f[4], f[5]); o.w = pk2(f[6], f[7]); return o; }
; __device__ __forceinline__ float sigmoidf_(float x) { return rcpf(1.0f + __expf(-x)); }
; __device__ __forceinline__ float gelu_tanh(float v) { const float u = 0.7978845608f * (v + 0.044715f * v * v * v); return v * rcpf(1.0f + __expf(-2.0f * u)); }
;     __device__ __forceinline__ void operator()(const f32x4 (&acc)[2][2][4][2], const Unit& u, int wr, int wc, int fr, int fq) const {
;     ...
;                         for (int j = 0; j < 4; ++j) { const float v = acc[ai][bj][m][n][j] * rs; o[n * 4 + j] = mode == 0 ? gelu_tanh(v) : (mode == 1 ? v : sigmoidf_(v)); }
;     ...
;                     else if (c0 < PLD) *(u32x4*)(proj + row * PLD + c0) = pack8(o); } }
	v_exp_f32_e32 v161, v161
	v_exp_f32_e32 v162, v162
	v_exp_f32_e32 v163, v163
	v_add_f32_e32 v156, 1.0, v156
	v_add_f32_e32 v157, 1.0, v157
	v_add_f32_e32 v158, 1.0, v158
	v_add_f32_e32 v159, 1.0, v159
	v_add_f32_e32 v160, 1.0, v160
	v_add_f32_e32 v161, 1.0, v161
	v_add_f32_e32 v162, 1.0, v162
	v_add_f32_e32 v163, 1.0, v163
	v_rcp_f32_e32 v156, v156
	v_rcp_f32_e32 v157, v157
	v_rcp_f32_e32 v158, v158
	v_rcp_f32_e32 v159, v159
	v_rcp_f32_e32 v160, v160
	v_rcp_f32_e32 v161, v161
	v_rcp_f32_e32 v162, v162
	v_rcp_f32_e32 v163, v163
	v_mul_f32_e32 v38, v38, v156
	v_mul_f32_e32 v39, v39, v157
	v_mul_f32_e32 v40, v40, v158
	v_mul_f32_e32 v41, v41, v159
	v_mul_f32_e32 v34, v34, v160
	v_mul_f32_e32 v35, v35, v161
	v_mul_f32_e32 v36, v36, v162
	v_mul_f32_e32 v37, v37, v163
	v_cvt_pk_bf16_f32 v168, v38, v39
	v_cvt_pk_bf16_f32 v169, v40, v41
	v_cvt_pk_bf16_f32 v170, v34, v35
	v_cvt_pk_bf16_f32 v171, v36, v37
	s_mov_b64 exec, s[38:39]
	global_store_dwordx4 v153, v[168:171], s[68:69] offset:256
	s_mov_b64 exec, -1
	v_mul_f32_e32 v30, v30, v140
	v_mul_f32_e32 v31, v31, v140
	v_mul_f32_e32 v32, v32, v140
	v_mul_f32_e32 v33, v33, v140
	v_mul_f32_e32 v26, v26, v140
	v_mul_f32_e32 v27, v27, v140
	v_mul_f32_e32 v28, v28, v140
	v_mul_f32_e32 v29, v29, v140
	v_mul_f32_e32 v156, s2, v30
	v_mul_f32_e32 v157, s2, v31
	v_mul_f32_e32 v158, s2, v32
	v_mul_f32_e32 v159, s2, v33
	v_mul_f32_e32 v160, s2, v26
	v_mul_f32_e32 v161, s2, v27
	v_mul_f32_e32 v162, s2, v28
	v_mul_f32_e32 v163, s2, v29
	v_mul_f32_e32 v156, v30, v156
	v_mul_f32_e32 v157, v31, v157
	v_mul_f32_e32 v158, v32, v158
	v_mul_f32_e32 v159, v33, v159
	v_mul_f32_e32 v160, v26, v160
	v_mul_f32_e32 v161, v27, v161
	v_mul_f32_e32 v162, v28, v162
	v_mul_f32_e32 v163, v29, v163
	v_fma_f32 v156, v30, v156, v30
	v_fma_f32 v157, v31, v157, v31
	v_fma_f32 v158, v32, v158, v32
	v_fma_f32 v159, v33, v159, v33
	v_fma_f32 v160, v26, v160, v26
	v_fma_f32 v161, v27, v161, v27
	v_fma_f32 v162, v28, v162, v28
	v_fma_f32 v163, v29, v163, v29
	v_mul_f32_e32 v156, s3, v156
	v_mul_f32_e32 v157, s3, v157
	v_mul_f32_e32 v158, s3, v158
	v_mul_f32_e32 v159, s3, v159
	v_mul_f32_e32 v160, s3, v160
	v_mul_f32_e32 v161, s3, v161
	v_mul_f32_e32 v162, s3, v162
	v_mul_f32_e32 v163, s3, v163
	v_mul_f32_e32 v156, -2.0, v156
	v_mul_f32_e32 v157, -2.0, v157
	v_mul_f32_e32 v158, -2.0, v158
	v_mul_f32_e32 v159, -2.0, v159
	v_mul_f32_e32 v160, -2.0, v160
	v_mul_f32_e32 v161, -2.0, v161
	v_mul_f32_e32 v162, -2.0, v162
	v_mul_f32_e32 v163, -2.0, v163
	v_mul_f32_e32 v156, s28, v156
	v_mul_f32_e32 v157, s28, v157
	v_mul_f32_e32 v158, s28, v158
	v_mul_f32_e32 v159, s28, v159
	v_mul_f32_e32 v160, s28, v160
	v_mul_f32_e32 v161, s28, v161
	v_mul_f32_e32 v162, s28, v162
	v_mul_f32_e32 v163, s28, v163
	v_exp_f32_e32 v156, v156
	v_exp_f32_e32 v157, v157
	v_exp_f32_e32 v158, v158
	v_exp_f32_e32 v159, v159
	v_exp_f32_e32 v160, v160
	v_exp_f32_e32 v161, v161
	v_exp_f32_e32 v162, v162
	v_exp_f32_e32 v163, v163
	v_add_f32_e32 v156, 1.0, v156
	v_add_f32_e32 v157, 1.0, v157
	v_add_f32_e32 v158, 1.0, v158
	v_add_f32_e32 v159, 1.0, v159
	v_add_f32_e32 v160, 1.0, v160
	v_add_f32_e32 v161, 1.0, v161
	v_add_f32_e32 v162, 1.0, v162
	v_add_f32_e32 v163, 1.0, v163
	v_rcp_f32_e32 v156, v156
	v_rcp_f32_e32 v157, v157
	v_rcp_f32_e32 v158, v158
	v_rcp_f32_e32 v159, v159
	v_rcp_f32_e32 v160, v160
	v_rcp_f32_e32 v161, v161
	v_rcp_f32_e32 v162, v162
	v_rcp_f32_e32 v163, v163
	v_mul_f32_e32 v30, v30, v156
	v_mul_f32_e32 v31, v31, v157
	v_mul_f32_e32 v32, v32, v158
	v_mul_f32_e32 v33, v33, v159
	v_mul_f32_e32 v26, v26, v160
	v_mul_f32_e32 v27, v27, v161
	v_mul_f32_e32 v28, v28, v162
	v_mul_f32_e32 v29, v29, v163
	v_add_u32_e32 v153, 0x26400, v153
	v_cvt_pk_bf16_f32 v164, v30, v31
	v_cvt_pk_bf16_f32 v165, v32, v33
	v_cvt_pk_bf16_f32 v166, v26, v27
	v_cvt_pk_bf16_f32 v167, v28, v29
	s_mov_b64 exec, s[24:25]
	global_store_dwordx4 v153, v[164:167], s[68:69]
	s_mov_b64 exec, -1
	v_mul_f32_e32 v22, v22, v140
	v_mul_f32_e32 v23, v23, v140
	v_mul_f32_e32 v24, v24, v140
	v_mul_f32_e32 v25, v25, v140
	v_mul_f32_e32 v18, v18, v140
	v_mul_f32_e32 v19, v19, v140
	v_mul_f32_e32 v20, v20, v140
	v_mul_f32_e32 v21, v21, v140
	v_mul_f32_e32 v156, s2, v22
	v_mul_f32_e32 v157, s2, v23
	v_mul_f32_e32 v158, s2, v24
	v_mul_f32_e32 v159, s2, v25
	v_mul_f32_e32 v160, s2, v18
	v_mul_f32_e32 v161, s2, v19
	v_mul_f32_e32 v162, s2, v20
	v_mul_f32_e32 v163, s2, v21
	v_mul_f32_e32 v156, v22, v156
	v_mul_f32_e32 v157, v23, v157
	v_mul_f32_e32 v158, v24, v158
	v_mul_f32_e32 v159, v25, v159
	v_mul_f32_e32 v160, v18, v160
	v_mul_f32_e32 v161, v19, v161
	v_mul_f32_e32 v162, v20, v162
	v_mul_f32_e32 v163, v21, v163
	v_fma_f32 v156, v22, v156, v22
	v_fma_f32 v157, v23, v157, v23
	v_fma_f32 v158, v24, v158, v24
	v_fma_f32 v159, v25, v159, v25
	v_fma_f32 v160, v18, v160, v18
	v_fma_f32 v161, v19, v161, v19
	v_fma_f32 v162, v20, v162, v20
	v_fma_f32 v163, v21, v163, v21
	v_mul_f32_e32 v156, s3, v156
	v_mul_f32_e32 v157, s3, v157
	v_mul_f32_e32 v158, s3, v158
	v_mul_f32_e32 v159, s3, v159
	v_mul_f32_e32 v160, s3, v160
	v_mul_f32_e32 v161, s3, v161
	v_mul_f32_e32 v162, s3, v162
	v_mul_f32_e32 v163, s3, v163
	v_mul_f32_e32 v156, -2.0, v156
	v_mul_f32_e32 v157, -2.0, v157
	v_mul_f32_e32 v158, -2.0, v158
	v_mul_f32_e32 v159, -2.0, v159
	v_mul_f32_e32 v160, -2.0, v160
	v_mul_f32_e32 v161, -2.0, v161
	v_mul_f32_e32 v162, -2.0, v162
	v_mul_f32_e32 v163, -2.0, v163
	v_mul_f32_e32 v156, s28, v156
	v_mul_f32_e32 v157, s28, v157
	v_mul_f32_e32 v158, s28, v158
	v_mul_f32_e32 v159, s28, v159
	v_mul_f32_e32 v160, s28, v160
	v_mul_f32_e32 v161, s28, v161
	v_mul_f32_e32 v162, s28, v162
	v_mul_f32_e32 v163, s28, v163
	v_exp_f32_e32 v156, v156
; __device__ __forceinline__ u32x4 pack8(const float* f) { u32x4 o; o.x = pk2(f[0], f[1]); o.y = pk2(f[2], f[3]); o.z = pk2(f[4], f[5]); o.w = pk2(f[6], f[7]); return o; }
; __device__ __forceinline__ float sigmoidf_(float x) { return rcpf(1.0f + __expf(-x)); }
; __device__ __forceinline__ float gelu_tanh(float v) { const float u = 0.7978845608f * (v + 0.044715f * v * v * v); return v * rcpf(1.0f + __expf(-2.0f * u)); }
;     __device__ __forceinline__ void operator()(const f32x4 (&acc)[2][2][4][2], const Unit& u, int wr, int wc, int fr, int fq) const {
;     ...
;                         for (int j = 0; j < 4; ++j) { const float v = acc[ai][bj][m][n][j] * rs; o[n * 4 + j] = mode == 0 ? gelu_tanh(v) : (mode == 1 ? v : sigmoidf_(v)); }
;     ...
;                     else if (c0 < PLD) *(u32x4*)(proj + row * PLD + c0) = pack8(o); } }
	v_exp_f32_e32 v157, v157
	v_exp_f32_e32 v158, v158
	v_exp_f32_e32 v159, v159
	v_exp_f32_e32 v160, v160
	v_exp_f32_e32 v161, v161
	v_exp_f32_e32 v162, v162
	v_exp_f32_e32 v163, v163
	v_add_f32_e32 v156, 1.0, v156
	v_add_f32_e32 v157, 1.0, v157
	v_add_f32_e32 v158, 1.0, v158
	v_add_f32_e32 v159, 1.0, v159
	v_add_f32_e32 v160, 1.0, v160
	v_add_f32_e32 v161, 1.0, v161
	v_add_f32_e32 v162, 1.0, v162
	v_add_f32_e32 v163, 1.0, v163
	v_rcp_f32_e32 v156, v156
	v_rcp_f32_e32 v157, v157
	v_rcp_f32_e32 v158, v158
	v_rcp_f32_e32 v159, v159
	v_rcp_f32_e32 v160, v160
	v_rcp_f32_e32 v161, v161
	v_rcp_f32_e32 v162, v162
	v_rcp_f32_e32 v163, v163
	v_mul_f32_e32 v22, v22, v156
	v_mul_f32_e32 v23, v23, v157
	v_mul_f32_e32 v24, v24, v158
	v_mul_f32_e32 v25, v25, v159
	v_mul_f32_e32 v18, v18, v160
	v_mul_f32_e32 v19, v19, v161
	v_mul_f32_e32 v20, v20, v162
	v_mul_f32_e32 v21, v21, v163
	v_cvt_pk_bf16_f32 v168, v22, v23
	v_cvt_pk_bf16_f32 v169, v24, v25
	v_cvt_pk_bf16_f32 v170, v18, v19
	v_cvt_pk_bf16_f32 v171, v20, v21
	s_mov_b64 exec, s[38:39]
	global_store_dwordx4 v153, v[168:171], s[68:69] offset:256
	s_mov_b64 exec, -1
	v_mul_f32_e32 v14, v14, v141
	v_mul_f32_e32 v15, v15, v141
	v_mul_f32_e32 v16, v16, v141
	v_mul_f32_e32 v17, v17, v141
	v_mul_f32_e32 v10, v10, v141
	v_mul_f32_e32 v11, v11, v141
	v_mul_f32_e32 v12, v12, v141
	v_mul_f32_e32 v13, v13, v141
	v_mul_f32_e32 v156, s2, v14
	v_mul_f32_e32 v157, s2, v15
	v_mul_f32_e32 v158, s2, v16
	v_mul_f32_e32 v159, s2, v17
	v_mul_f32_e32 v160, s2, v10
	v_mul_f32_e32 v161, s2, v11
	v_mul_f32_e32 v162, s2, v12
	v_mul_f32_e32 v163, s2, v13
	v_mul_f32_e32 v156, v14, v156
	v_mul_f32_e32 v157, v15, v157
	v_mul_f32_e32 v158, v16, v158
	v_mul_f32_e32 v159, v17, v159
	v_mul_f32_e32 v160, v10, v160
	v_mul_f32_e32 v161, v11, v161
	v_mul_f32_e32 v162, v12, v162
	v_mul_f32_e32 v163, v13, v163
	v_fma_f32 v156, v14, v156, v14
	v_fma_f32 v157, v15, v157, v15
	v_fma_f32 v158, v16, v158, v16
	v_fma_f32 v159, v17, v159, v17
	v_fma_f32 v160, v10, v160, v10
	v_fma_f32 v161, v11, v161, v11
	v_fma_f32 v162, v12, v162, v12
	v_fma_f32 v163, v13, v163, v13
	v_mul_f32_e32 v156, s3, v156
	v_mul_f32_e32 v157, s3, v157
	v_mul_f32_e32 v158, s3, v158
	v_mul_f32_e32 v159, s3, v159
	v_mul_f32_e32 v160, s3, v160
	v_mul_f32_e32 v161, s3, v161
	v_mul_f32_e32 v162, s3, v162
	v_mul_f32_e32 v163, s3, v163
	v_mul_f32_e32 v156, -2.0, v156
	v_mul_f32_e32 v157, -2.0, v157
	v_mul_f32_e32 v158, -2.0, v158
	v_mul_f32_e32 v159, -2.0, v159
	v_mul_f32_e32 v160, -2.0, v160
	v_mul_f32_e32 v161, -2.0, v161
	v_mul_f32_e32 v162, -2.0, v162
	v_mul_f32_e32 v163, -2.0, v163
	v_mul_f32_e32 v156, s28, v156
	v_mul_f32_e32 v157, s28, v157
	v_mul_f32_e32 v158, s28, v158
	v_mul_f32_e32 v159, s28, v159
	v_mul_f32_e32 v160, s28, v160
	v_mul_f32_e32 v161, s28, v161
	v_mul_f32_e32 v162, s28, v162
	v_mul_f32_e32 v163, s28, v163
	v_exp_f32_e32 v156, v156
	v_exp_f32_e32 v157, v157
	v_exp_f32_e32 v158, v158
	v_exp_f32_e32 v159, v159
	v_exp_f32_e32 v160, v160
	v_exp_f32_e32 v161, v161
	v_exp_f32_e32 v162, v162
	v_exp_f32_e32 v163, v163
	v_add_f32_e32 v156, 1.0, v156
	v_add_f32_e32 v157, 1.0, v157
	v_add_f32_e32 v158, 1.0, v158
	v_add_f32_e32 v159, 1.0, v159
	v_add_f32_e32 v160, 1.0, v160
	v_add_f32_e32 v161, 1.0, v161
	v_add_f32_e32 v162, 1.0, v162
	v_add_f32_e32 v163, 1.0, v163
	v_rcp_f32_e32 v156, v156
	v_rcp_f32_e32 v157, v157
	v_rcp_f32_e32 v158, v158
	v_rcp_f32_e32 v159, v159
	v_rcp_f32_e32 v160, v160
	v_rcp_f32_e32 v161, v161
	v_rcp_f32_e32 v162, v162
	v_rcp_f32_e32 v163, v163
	v_mul_f32_e32 v14, v14, v156
	v_mul_f32_e32 v15, v15, v157
	v_mul_f32_e32 v16, v16, v158
	v_mul_f32_e32 v17, v17, v159
	v_mul_f32_e32 v10, v10, v160
	v_mul_f32_e32 v11, v11, v161
	v_mul_f32_e32 v12, v12, v162
	v_mul_f32_e32 v13, v13, v163
	v_add_u32_e32 v153, 0x26400, v153
	v_cvt_pk_bf16_f32 v164, v14, v15
	v_cvt_pk_bf16_f32 v165, v16, v17
	v_cvt_pk_bf16_f32 v166, v10, v11
	v_cvt_pk_bf16_f32 v167, v12, v13
	s_mov_b64 exec, s[24:25]
	global_store_dwordx4 v153, v[164:167], s[68:69]
	s_mov_b64 exec, -1
	v_mul_f32_e32 v6, v6, v141
	v_mul_f32_e32 v7, v7, v141
	v_mul_f32_e32 v8, v8, v141
	v_mul_f32_e32 v9, v9, v141
	v_mul_f32_e32 v2, v2, v141
	v_mul_f32_e32 v3, v3, v141
	v_mul_f32_e32 v4, v4, v141
	v_mul_f32_e32 v5, v5, v141
	v_mul_f32_e32 v156, s2, v6
	v_mul_f32_e32 v157, s2, v7
	v_mul_f32_e32 v158, s2, v8
	v_mul_f32_e32 v159, s2, v9
	v_mul_f32_e32 v160, s2, v2
	v_mul_f32_e32 v161, s2, v3
	v_mul_f32_e32 v162, s2, v4
	v_mul_f32_e32 v163, s2, v5
	v_mul_f32_e32 v156, v6, v156
	v_mul_f32_e32 v157, v7, v157
	v_mul_f32_e32 v158, v8, v158
	v_mul_f32_e32 v159, v9, v159
	v_mul_f32_e32 v160, v2, v160
	v_mul_f32_e32 v161, v3, v161
	v_mul_f32_e32 v162, v4, v162
	v_mul_f32_e32 v163, v5, v163
	v_fma_f32 v156, v6, v156, v6
	v_fma_f32 v157, v7, v157, v7
	v_fma_f32 v158, v8, v158, v8
	v_fma_f32 v159, v9, v159, v9
	v_fma_f32 v160, v2, v160, v2
	v_fma_f32 v161, v3, v161, v3
	v_fma_f32 v162, v4, v162, v4
	v_fma_f32 v163, v5, v163, v5
	v_mul_f32_e32 v156, s3, v156
	v_mul_f32_e32 v157, s3, v157
	v_mul_f32_e32 v158, s3, v158
	v_mul_f32_e32 v159, s3, v159
	v_mul_f32_e32 v160, s3, v160
	v_mul_f32_e32 v161, s3, v161
	v_mul_f32_e32 v162, s3, v162
	v_mul_f32_e32 v163, s3, v163
	v_mul_f32_e32 v156, -2.0, v156
	v_mul_f32_e32 v157, -2.0, v157
	v_mul_f32_e32 v158, -2.0, v158
	v_mul_f32_e32 v159, -2.0, v159
	v_mul_f32_e32 v160, -2.0, v160
	v_mul_f32_e32 v161, -2.0, v161
	v_mul_f32_e32 v162, -2.0, v162
	v_mul_f32_e32 v163, -2.0, v163
	v_mul_f32_e32 v156, s28, v156
	v_mul_f32_e32 v157, s28, v157
	v_mul_f32_e32 v158, s28, v158
	v_mul_f32_e32 v159, s28, v159
	v_mul_f32_e32 v160, s28, v160
	v_mul_f32_e32 v161, s28, v161
	v_mul_f32_e32 v162, s28, v162
	v_mul_f32_e32 v163, s28, v163
	v_exp_f32_e32 v156, v156
	v_exp_f32_e32 v157, v157
	v_exp_f32_e32 v158, v158
	v_exp_f32_e32 v159, v159
	v_exp_f32_e32 v160, v160
	v_exp_f32_e32 v161, v161
	v_exp_f32_e32 v162, v162
	v_exp_f32_e32 v163, v163
	v_add_f32_e32 v156, 1.0, v156
	v_add_f32_e32 v157, 1.0, v157
	v_add_f32_e32 v158, 1.0, v158
	v_add_f32_e32 v159, 1.0, v159
	v_add_f32_e32 v160, 1.0, v160
	v_add_f32_e32 v161, 1.0, v161
	v_add_f32_e32 v162, 1.0, v162
	v_add_f32_e32 v163, 1.0, v163
	v_rcp_f32_e32 v156, v156
	v_rcp_f32_e32 v157, v157
	v_rcp_f32_e32 v158, v158
	v_rcp_f32_e32 v159, v159
	v_rcp_f32_e32 v160, v160
	v_rcp_f32_e32 v161, v161
	v_rcp_f32_e32 v162, v162
	v_rcp_f32_e32 v163, v163
	v_mul_f32_e32 v6, v6, v156
	v_mul_f32_e32 v7, v7, v157
	v_mul_f32_e32 v8, v8, v158
	v_mul_f32_e32 v9, v9, v159
	v_mul_f32_e32 v2, v2, v160
	v_mul_f32_e32 v3, v3, v161
	v_mul_f32_e32 v4, v4, v162
	v_mul_f32_e32 v5, v5, v163
	v_cvt_pk_bf16_f32 v168, v6, v7
	v_cvt_pk_bf16_f32 v169, v8, v9
	v_cvt_pk_bf16_f32 v170, v2, v3
	v_cvt_pk_bf16_f32 v171, v4, v5
	s_mov_b64 exec, s[38:39]
	global_store_dwordx4 v153, v[168:171], s[68:69] offset:256
	s_mov_b64 exec, -1
	s_branch .Lmy_ip_done

; #define PG8_STAGE(bufoff, gbase, voff) do { _Pragma("unroll") for (int _i = 0; _i < 2; ++_i) \
;         __builtin_amdgcn_global_load_lds((const unsigned*)((const char*)(gbase) + (voff)[_i]), (LAS unsigned*)(lds + (bufoff) + ldsw + _i * 8192), 16, 0, 0); } while (0)
; #define PG8_LDA(dst, b, h) do { _Pragma("unroll") for (int m = 0; m < 4; ++m) _Pragma("unroll") for (int k = 0; k < 2; ++k) dst[m][k] = *(const LAS bf16x8*)(lds + PG8_SA(b, h) + aoff + m * 2048 + k * 1024); } while (0)
; #define PG8_LDB(dst, b, h) do { _Pragma("unroll") for (int n = 0; n < 2; ++n) _Pragma("unroll") for (int k = 0; k < 2; ++k) dst[n][k] = *(const LAS bf16x8*)(lds + PG8_SB(b, h) + boff + n * 2048 + k * 1024); } while (0)
; #define PG8_MMA(ai, bj, At, Bt) do { __builtin_amdgcn_s_setprio(1); _Pragma("unroll") for (int m = 0; m < 4; ++m) _Pragma("unroll") for (int n = 0; n < 2; ++n) _Pragma("unroll") for (int k = 0; k < 2; ++k) \
;         acc[ai][bj][m][n] = __builtin_amdgcn_mfma_f32_16x16x32_bf16(Bt[n][k], At[m][k], acc[ai][bj][m][n], 0, 0, 0); __builtin_amdgcn_s_setprio(0); } while (0)
; #define PG8_WAIT_V(n) asm volatile("s_waitcnt vmcnt(" #n ")" ::: "memory")
; #define PG8_WAIT_L(n) asm volatile("s_waitcnt lgkmcnt(" #n ")" ::: "memory")
; #define PG8_BAR __builtin_amdgcn_s_barrier()
; #define PG8_SCHED __builtin_amdgcn_sched_barrier(0)
; template <class Epi, class Sched, bool ALIGN_EPI = GEMM_ALIGN, bool SP2 = GEMM_SP2>
; __device__ __forceinline__ void gemm_phase(lptr lds, const Gemm g, const Sched& S, const Epi& E) {
;     ...
;             PG8_LDB(B0, 0, 0); PG8_LDB(B1, 0, 1); PG8_SCHED; PG8_LDA(At, 0, 0); PG8_STAGE(PG8_SA(1, 1), a1 + hstepA, voffA);
;             PG8_WAIT_V(8); PG8_WAIT_L(0); PG8_BAR; PG8_MMA(0, 0, At, B0); PG8_MMA(0, 1, At, B1); PG8_BAR; PG8_SCHED;
;             PG8_LDA(At, 0, 1); PG8_STAGE(PG8_SB(0, 0), b2, voffB); PG8_STAGE(PG8_SB(0, 1), b2 + hstepB, voffB); PG8_STAGE(PG8_SA(0, 0), a2, voffA);
;             PG8_WAIT_V(8); PG8_WAIT_L(0); PG8_BAR; PG8_MMA(1, 0, At, B0); PG8_MMA(1, 1, At, B1); PG8_BAR; PG8_SCHED;
.LBB0_2008:
	s_add_u32 s28, s24, 0xfff80080
	s_addc_u32 s29, s25, -1
	s_add_i32 s62, 0, 0x10000
	s_cmp_eq_u32 s47, 4
	s_cselect_b32 s39, s3, s29
	s_cselect_b32 s38, s31, s28
	v_add_u32_e32 v0, s62, v169
	s_cselect_b32 s29, s40, s45
	s_cselect_b32 s28, s41, s43
	s_add_i32 s64, 0, 0x14000
	ds_read_b128 v[142:145], v0
	ds_read_b128 v[146:149], v0 offset:1024
	ds_read_b128 v[150:153], v0 offset:2048
	ds_read_b128 v[154:157], v0 offset:3072
	v_add_u32_e32 v0, s64, v169
	ds_read_b128 v[158:161], v0
	ds_read_b128 v[162:165], v0 offset:1024
	ds_read_b128 v[172:175], v0 offset:2048
	ds_read_b128 v[176:179], v0 offset:3072
	v_lshl_add_u64 v[166:167], s[24:25], 0, v[138:139]
	s_add_i32 m0, s54, 0xc000
	ds_read_b128 v[180:183], v171
	ds_read_b128 v[198:201], v171 offset:1024
	ds_read_b128 v[202:205], v171 offset:2048
	ds_read_b128 v[206:209], v171 offset:3072
	ds_read_b128 v[210:213], v171 offset:4096
	ds_read_b128 v[220:223], v171 offset:5120
	ds_read_b128 v[224:227], v171 offset:6144
	ds_read_b128 v[228:231], v171 offset:7168
	global_load_lds_dwordx4 v[166:167], off
	v_lshl_add_u64 v[166:167], s[24:25], 0, v[140:141]
	s_add_i32 m0, s54, 0xe000
	s_nop 0
	global_load_lds_dwordx4 v[166:167], off
	s_waitcnt vmcnt(8)
	s_waitcnt lgkmcnt(0)
	s_barrier
	s_waitcnt lgkmcnt(0)
	v_mfma_f32_16x16x32_bf16 v[126:129], v[142:145], v[180:183], v[126:129]
	v_mfma_f32_16x16x32_bf16 v[122:125], v[150:153], v[180:183], v[122:125]
	v_mfma_f32_16x16x32_bf16 v[118:121], v[142:145], v[202:205], v[118:121]
	v_mfma_f32_16x16x32_bf16 v[114:117], v[150:153], v[202:205], v[114:117]
	v_mfma_f32_16x16x32_bf16 v[110:113], v[142:145], v[210:213], v[110:113]
	v_mfma_f32_16x16x32_bf16 v[106:109], v[150:153], v[210:213], v[106:109]
	v_mfma_f32_16x16x32_bf16 v[102:105], v[142:145], v[224:227], v[102:105]
	v_mfma_f32_16x16x32_bf16 v[98:101], v[150:153], v[224:227], v[98:101]
	v_mfma_f32_16x16x32_bf16 v[126:129], v[146:149], v[198:201], v[126:129]
	v_mfma_f32_16x16x32_bf16 v[122:125], v[154:157], v[198:201], v[122:125]
	v_mfma_f32_16x16x32_bf16 v[118:121], v[146:149], v[206:209], v[118:121]
	v_mfma_f32_16x16x32_bf16 v[114:117], v[154:157], v[206:209], v[114:117]
	v_mfma_f32_16x16x32_bf16 v[110:113], v[146:149], v[220:223], v[110:113]
	v_mfma_f32_16x16x32_bf16 v[106:109], v[154:157], v[220:223], v[106:109]
	v_mfma_f32_16x16x32_bf16 v[102:105], v[146:149], v[228:231], v[102:105]
	v_mfma_f32_16x16x32_bf16 v[98:101], v[154:157], v[228:231], v[98:101]
	v_mfma_f32_16x16x32_bf16 v[94:97], v[158:161], v[180:183], v[94:97]
	v_mfma_f32_16x16x32_bf16 v[90:93], v[172:175], v[180:183], v[90:93]
	v_mfma_f32_16x16x32_bf16 v[86:89], v[158:161], v[202:205], v[86:89]
	v_mfma_f32_16x16x32_bf16 v[82:85], v[172:175], v[202:205], v[82:85]
	v_mfma_f32_16x16x32_bf16 v[78:81], v[158:161], v[210:213], v[78:81]
	v_mfma_f32_16x16x32_bf16 v[74:77], v[172:175], v[210:213], v[74:77]
	v_mfma_f32_16x16x32_bf16 v[70:73], v[158:161], v[224:227], v[70:73]
	v_mfma_f32_16x16x32_bf16 v[66:69], v[172:175], v[224:227], v[66:69]
	v_mfma_f32_16x16x32_bf16 v[94:97], v[162:165], v[198:201], v[94:97]
	v_mfma_f32_16x16x32_bf16 v[90:93], v[176:179], v[198:201], v[90:93]
	v_mfma_f32_16x16x32_bf16 v[86:89], v[162:165], v[206:209], v[86:89]
	v_mfma_f32_16x16x32_bf16 v[82:85], v[176:179], v[206:209], v[82:85]
	v_mfma_f32_16x16x32_bf16 v[78:81], v[162:165], v[220:223], v[78:81]
	v_mfma_f32_16x16x32_bf16 v[74:77], v[176:179], v[220:223], v[74:77]
	v_mfma_f32_16x16x32_bf16 v[70:73], v[162:165], v[228:231], v[70:73]
	v_mfma_f32_16x16x32_bf16 v[66:69], v[176:179], v[228:231], v[66:69]
	s_barrier
	s_add_i32 s62, s62, s53
	v_lshl_add_u64 v[166:167], s[28:29], 0, v[132:133]
	s_mov_b32 m0, s62
	ds_read_b128 v[180:183], v171 offset:16384
	ds_read_b128 v[198:201], v171 offset:17408
	ds_read_b128 v[202:205], v171 offset:18432
	ds_read_b128 v[206:209], v171 offset:19456
	ds_read_b128 v[210:213], v171 offset:20480
	ds_read_b128 v[220:223], v171 offset:21504
	ds_read_b128 v[224:227], v171 offset:22528
	ds_read_b128 v[228:231], v171 offset:23552
	global_load_lds_dwordx4 v[166:167], off
	s_add_i32 m0, s62, 0x2000
	s_add_u32 s62, s28, 0x20000
	v_lshl_add_u64 v[214:215], s[28:29], 0, v[136:137]
	s_addc_u32 s63, s29, 0
	s_add_i32 s64, s64, s53
	global_load_lds_dwordx4 v[214:215], off
	v_lshl_add_u64 v[232:233], s[62:63], 0, v[132:133]
	s_mov_b32 m0, s64
	v_lshl_add_u64 v[242:243], s[38:39], 0, v[134:135]
	global_load_lds_dwordx4 v[232:233], off
	v_lshl_add_u64 v[232:233], s[62:63], 0, v[136:137]
	s_add_i32 m0, s64, 0x2000
	s_nop 0
	global_load_lds_dwordx4 v[232:233], off
	v_lshl_add_u64 v[232:233], s[38:39], 0, v[130:131]
	s_mov_b32 m0, s54
	s_nop 0
	global_load_lds_dwordx4 v[232:233], off
	s_mov_b32 m0, s55
	s_nop 0
	global_load_lds_dwordx4 v[242:243], off
	s_waitcnt vmcnt(8)
	s_waitcnt lgkmcnt(0)
	s_barrier
; #define PG8_STAGE(bufoff, gbase, voff) do { _Pragma("unroll") for (int _i = 0; _i < 2; ++_i) \
;         __builtin_amdgcn_global_load_lds((const unsigned*)((const char*)(gbase) + (voff)[_i]), (LAS unsigned*)(lds + (bufoff) + ldsw + _i * 8192), 16, 0, 0); } while (0)
; #define PG8_LDA(dst, b, h) do { _Pragma("unroll") for (int m = 0; m < 4; ++m) _Pragma("unroll") for (int k = 0; k < 2; ++k) dst[m][k] = *(const LAS bf16x8*)(lds + PG8_SA(b, h) + aoff + m * 2048 + k * 1024); } while (0)
; #define PG8_LDB(dst, b, h) do { _Pragma("unroll") for (int n = 0; n < 2; ++n) _Pragma("unroll") for (int k = 0; k < 2; ++k) dst[n][k] = *(const LAS bf16x8*)(lds + PG8_SB(b, h) + boff + n * 2048 + k * 1024); } while (0)
; #define PG8_MMA(ai, bj, At, Bt) do { __builtin_amdgcn_s_setprio(1); _Pragma("unroll") for (int m = 0; m < 4; ++m) _Pragma("unroll") for (int n = 0; n < 2; ++n) _Pragma("unroll") for (int k = 0; k < 2; ++k) \
;         acc[ai][bj][m][n] = __builtin_amdgcn_mfma_f32_16x16x32_bf16(Bt[n][k], At[m][k], acc[ai][bj][m][n], 0, 0, 0); __builtin_amdgcn_s_setprio(0); } while (0)
; #define PG8_WAIT_V(n) asm volatile("s_waitcnt vmcnt(" #n ")" ::: "memory")
; #define PG8_WAIT_L(n) asm volatile("s_waitcnt lgkmcnt(" #n ")" ::: "memory")
; #define PG8_BAR __builtin_amdgcn_s_barrier()
; #define PG8_SCHED __builtin_amdgcn_sched_barrier(0)
; template <class Epi, class Sched, bool ALIGN_EPI = GEMM_ALIGN, bool SP2 = GEMM_SP2>
; __device__ __forceinline__ void gemm_phase(lptr lds, const Gemm g, const Sched& S, const Epi& E) {
;     ...
;             PG8_WAIT_V(8); PG8_WAIT_L(0); PG8_BAR; PG8_MMA(1, 0, At, B0); PG8_MMA(1, 1, At, B1); PG8_BAR; PG8_SCHED;
;             PG8_LDB(B0, 1, 0); PG8_LDB(B1, 1, 1); PG8_SCHED; PG8_LDA(At, 1, 0); PG8_STAGE(PG8_SA(0, 1), a2 + hstepA, voffA);
;             PG8_WAIT_V(8); PG8_WAIT_L(0); PG8_BAR; PG8_MMA(0, 0, At, B0); PG8_MMA(0, 1, At, B1); PG8_BAR; PG8_SCHED;
	s_waitcnt lgkmcnt(0)
	v_mfma_f32_16x16x32_bf16 v[62:65], v[142:145], v[180:183], v[62:65]
	v_mfma_f32_16x16x32_bf16 v[58:61], v[150:153], v[180:183], v[58:61]
	v_mfma_f32_16x16x32_bf16 v[54:57], v[142:145], v[202:205], v[54:57]
	v_mfma_f32_16x16x32_bf16 v[50:53], v[150:153], v[202:205], v[50:53]
	v_mfma_f32_16x16x32_bf16 v[46:49], v[142:145], v[210:213], v[46:49]
	v_mfma_f32_16x16x32_bf16 v[42:45], v[150:153], v[210:213], v[42:45]
	v_mfma_f32_16x16x32_bf16 v[38:41], v[142:145], v[224:227], v[38:41]
	v_mfma_f32_16x16x32_bf16 v[34:37], v[150:153], v[224:227], v[34:37]
	v_mfma_f32_16x16x32_bf16 v[62:65], v[146:149], v[198:201], v[62:65]
	v_mfma_f32_16x16x32_bf16 v[58:61], v[154:157], v[198:201], v[58:61]
	v_mfma_f32_16x16x32_bf16 v[54:57], v[146:149], v[206:209], v[54:57]
	v_mfma_f32_16x16x32_bf16 v[50:53], v[154:157], v[206:209], v[50:53]
	v_mfma_f32_16x16x32_bf16 v[46:49], v[146:149], v[220:223], v[46:49]
	v_mfma_f32_16x16x32_bf16 v[42:45], v[154:157], v[220:223], v[42:45]
	v_mfma_f32_16x16x32_bf16 v[38:41], v[146:149], v[228:231], v[38:41]
	v_mfma_f32_16x16x32_bf16 v[34:37], v[154:157], v[228:231], v[34:37]
	v_mfma_f32_16x16x32_bf16 v[30:33], v[158:161], v[180:183], v[30:33]
	v_mfma_f32_16x16x32_bf16 v[26:29], v[172:175], v[180:183], v[26:29]
	v_mfma_f32_16x16x32_bf16 v[22:25], v[158:161], v[202:205], v[22:25]
	v_mfma_f32_16x16x32_bf16 v[18:21], v[172:175], v[202:205], v[18:21]
	v_mfma_f32_16x16x32_bf16 v[14:17], v[158:161], v[210:213], v[14:17]
	v_mfma_f32_16x16x32_bf16 v[10:13], v[172:175], v[210:213], v[10:13]
	v_mfma_f32_16x16x32_bf16 v[6:9], v[158:161], v[224:227], v[6:9]
	v_mfma_f32_16x16x32_bf16 v[2:5], v[172:175], v[224:227], v[2:5]
	v_mfma_f32_16x16x32_bf16 v[30:33], v[162:165], v[198:201], v[30:33]
	v_mfma_f32_16x16x32_bf16 v[26:29], v[176:179], v[198:201], v[26:29]
	v_mfma_f32_16x16x32_bf16 v[22:25], v[162:165], v[206:209], v[22:25]
	v_mfma_f32_16x16x32_bf16 v[18:21], v[176:179], v[206:209], v[18:21]
	v_mfma_f32_16x16x32_bf16 v[14:17], v[162:165], v[220:223], v[14:17]
	v_mfma_f32_16x16x32_bf16 v[10:13], v[176:179], v[220:223], v[10:13]
	v_mfma_f32_16x16x32_bf16 v[6:9], v[162:165], v[228:231], v[6:9]
	v_mfma_f32_16x16x32_bf16 v[2:5], v[176:179], v[228:231], v[2:5]
	s_barrier
	s_add_i32 s62, 0, 0x18000
	v_add_u32_e32 v0, s62, v169
	s_add_i32 s63, 0, 0x1c000
	ds_read_b128 v[142:145], v0
	ds_read_b128 v[146:149], v0 offset:1024
	ds_read_b128 v[150:153], v0 offset:2048
	ds_read_b128 v[154:157], v0 offset:3072
	v_add_u32_e32 v0, s63, v169
	ds_read_b128 v[158:161], v0
	ds_read_b128 v[162:165], v0 offset:1024
	ds_read_b128 v[172:175], v0 offset:2048
	ds_read_b128 v[176:179], v0 offset:3072
	s_add_u32 s38, s38, 0x80000
	s_addc_u32 s39, s39, 0
	s_mov_b32 m0, s56
	v_lshl_add_u64 v[248:249], s[38:39], 0, v[130:131]
	ds_read_b128 v[180:183], v171 offset:32768
	ds_read_b128 v[198:201], v171 offset:33792
	ds_read_b128 v[202:205], v171 offset:34816
	ds_read_b128 v[206:209], v171 offset:35840
	ds_read_b128 v[210:213], v171 offset:36864
	ds_read_b128 v[220:223], v171 offset:37888
	ds_read_b128 v[224:227], v171 offset:38912
	ds_read_b128 v[228:231], v171 offset:39936
	global_load_lds_dwordx4 v[248:249], off
	v_lshl_add_u64 v[248:249], s[38:39], 0, v[134:135]
	s_mov_b32 m0, s57
	s_nop 0
	global_load_lds_dwordx4 v[248:249], off
	s_waitcnt vmcnt(8)
	s_waitcnt lgkmcnt(0)
	s_barrier
	s_waitcnt lgkmcnt(0)
	v_mfma_f32_16x16x32_bf16 v[126:129], v[142:145], v[180:183], v[126:129]
	v_mfma_f32_16x16x32_bf16 v[122:125], v[150:153], v[180:183], v[122:125]
	v_mfma_f32_16x16x32_bf16 v[118:121], v[142:145], v[202:205], v[118:121]
	v_mfma_f32_16x16x32_bf16 v[114:117], v[150:153], v[202:205], v[114:117]
	v_mfma_f32_16x16x32_bf16 v[110:113], v[142:145], v[210:213], v[110:113]
	v_mfma_f32_16x16x32_bf16 v[106:109], v[150:153], v[210:213], v[106:109]
	v_mfma_f32_16x16x32_bf16 v[102:105], v[142:145], v[224:227], v[102:105]
	v_mfma_f32_16x16x32_bf16 v[98:101], v[150:153], v[224:227], v[98:101]
	v_mfma_f32_16x16x32_bf16 v[126:129], v[146:149], v[198:201], v[126:129]
	v_mfma_f32_16x16x32_bf16 v[122:125], v[154:157], v[198:201], v[122:125]
	v_mfma_f32_16x16x32_bf16 v[118:121], v[146:149], v[206:209], v[118:121]
	v_mfma_f32_16x16x32_bf16 v[114:117], v[154:157], v[206:209], v[114:117]
	v_mfma_f32_16x16x32_bf16 v[110:113], v[146:149], v[220:223], v[110:113]
	v_mfma_f32_16x16x32_bf16 v[106:109], v[154:157], v[220:223], v[106:109]
	v_mfma_f32_16x16x32_bf16 v[102:105], v[146:149], v[228:231], v[102:105]
	v_mfma_f32_16x16x32_bf16 v[98:101], v[154:157], v[228:231], v[98:101]
	v_mfma_f32_16x16x32_bf16 v[94:97], v[158:161], v[180:183], v[94:97]
	v_mfma_f32_16x16x32_bf16 v[90:93], v[172:175], v[180:183], v[90:93]
	v_mfma_f32_16x16x32_bf16 v[86:89], v[158:161], v[202:205], v[86:89]
	v_mfma_f32_16x16x32_bf16 v[82:85], v[172:175], v[202:205], v[82:85]
	v_mfma_f32_16x16x32_bf16 v[78:81], v[158:161], v[210:213], v[78:81]
	v_mfma_f32_16x16x32_bf16 v[74:77], v[172:175], v[210:213], v[74:77]
	v_mfma_f32_16x16x32_bf16 v[70:73], v[158:161], v[224:227], v[70:73]
	v_mfma_f32_16x16x32_bf16 v[66:69], v[172:175], v[224:227], v[66:69]
	v_mfma_f32_16x16x32_bf16 v[94:97], v[162:165], v[198:201], v[94:97]
	v_mfma_f32_16x16x32_bf16 v[90:93], v[176:179], v[198:201], v[90:93]
	v_mfma_f32_16x16x32_bf16 v[86:89], v[162:165], v[206:209], v[86:89]
	v_mfma_f32_16x16x32_bf16 v[82:85], v[176:179], v[206:209], v[82:85]
	v_mfma_f32_16x16x32_bf16 v[78:81], v[162:165], v[220:223], v[78:81]
	v_mfma_f32_16x16x32_bf16 v[74:77], v[176:179], v[220:223], v[74:77]
	v_mfma_f32_16x16x32_bf16 v[70:73], v[162:165], v[228:231], v[70:73]
	v_mfma_f32_16x16x32_bf16 v[66:69], v[176:179], v[228:231], v[66:69]
	s_barrier
; template <class Epi, class Sched, bool ALIGN_EPI = GEMM_ALIGN, bool SP2 = GEMM_SP2>
; __device__ __forceinline__ void gemm_phase(lptr lds, const Gemm g, const Sched& S, const Epi& E) {
;     ...
;             PG8_LDB(B0, 1, 0); PG8_LDB(B1, 1, 1); PG8_SCHED; PG8_LDA(At, 1, 0); PG8_STAGE(PG8_SA(0, 1), a2 + hstepA, voffA);
;             PG8_WAIT_V(8); PG8_WAIT_L(0); PG8_BAR; PG8_MMA(0, 0, At, B0); PG8_MMA(0, 1, At, B1); PG8_BAR; PG8_SCHED;
;             PG8_LDA(At, 1, 1); PG8_STAGE(PG8_SB(1, 0), b3, voffB); PG8_STAGE(PG8_SB(1, 1), b3 + hstepB, voffB); PG8_STAGE(PG8_SA(1, 0), a3, voffA);
;             PG8_WAIT_V(8); PG8_WAIT_L(0); PG8_BAR; PG8_MMA(1, 0, At, B0); PG8_MMA(1, 1, At, B1); PG8_BAR; PG8_SCHED;
;             } else {
;             PG8_LDB(B0, 0, 0); PG8_SCHED; PG8_LDA(At, 0, 0); PG8_STAGE(PG8_SA(1, 1), a1 + hstepA, voffA);
;             PG8_WAIT_L(8); PG8_BAR; PG8_WAIT_L(0); PG8_MMA(0, 0, At, B0); PG8_BAR; PG8_SCHED;
;             PG8_LDB(B1, 0, 1); PG8_STAGE(PG8_SB(0, 0), b2, voffB);
;             PG8_BAR; PG8_WAIT_L(0); PG8_MMA(0, 1, At, B1); PG8_BAR;
;             PG8_LDA(At, 0, 1); PG8_STAGE(PG8_SA(0, 0), a2, voffA);
;             PG8_BAR; PG8_WAIT_L(0); PG8_MMA(1, 0, At, B0); PG8_BAR; PG8_SCHED;
;             PG8_STAGE(PG8_SB(0, 1), b2 + hstepB, voffB);
;             PG8_WAIT_V(6); PG8_BAR; PG8_MMA(1, 1, At, B1); PG8_BAR;
;             PG8_LDB(B0, 1, 0); PG8_SCHED; PG8_LDA(At, 1, 0); PG8_STAGE(PG8_SA(0, 1), a2 + hstepA, voffA);
;             PG8_WAIT_L(8); PG8_BAR; PG8_WAIT_L(0); PG8_MMA(0, 0, At, B0); PG8_BAR; PG8_SCHED;
;             PG8_LDB(B1, 1, 1); PG8_STAGE(PG8_SB(1, 0), b3, voffB);
;             PG8_BAR; PG8_WAIT_L(0); PG8_MMA(0, 1, At, B1); PG8_BAR;
;             PG8_LDA(At, 1, 1); PG8_STAGE(PG8_SA(1, 0), a3, voffA);
;             PG8_BAR; PG8_WAIT_L(0); PG8_MMA(1, 0, At, B0); PG8_BAR; PG8_SCHED;
;             PG8_STAGE(PG8_SB(1, 1), b3 + hstepB, voffB);
;             PG8_WAIT_V(6); PG8_BAR; PG8_MMA(1, 1, At, B1); PG8_BAR;
;             }
;         }
;         if constexpr (ALIGN_EPI) { if (wr == 0) PG8_BAR; }
;     __device__ __forceinline__ bool chain(f32x4 (&acc)[2][2][4][2], const Unit& u, int wr, int wc, int fr, int fq) const {
;         const int row0 = u.pm * BM + wr * 64 + fr; const int bi = u.pn >> 2, nn = u.pn & 3; const bool lastb = bi == 3;
; #pragma unroll
;         for (int ai = 0; ai < 2; ++ai)
; #pragma unroll
	s_add_i32 s38, s62, s53
	v_lshl_add_u64 v[166:167], v[166:167], 0, s[6:7]
	s_mov_b32 m0, s38
	ds_read_b128 v[180:183], v171 offset:49152
	ds_read_b128 v[198:201], v171 offset:50176
	ds_read_b128 v[202:205], v171 offset:51200
	ds_read_b128 v[206:209], v171 offset:52224
	ds_read_b128 v[210:213], v171 offset:53248
	ds_read_b128 v[220:223], v171 offset:54272
	ds_read_b128 v[224:227], v171 offset:55296
	ds_read_b128 v[228:231], v171 offset:56320
	global_load_lds_dwordx4 v[166:167], off
	s_add_i32 m0, s38, 0x2000
	s_add_u32 s28, s28, 0x20080
	v_lshl_add_u64 v[166:167], v[214:215], 0, s[6:7]
	s_addc_u32 s29, s29, 0
	s_add_i32 s38, s63, s53
	global_load_lds_dwordx4 v[166:167], off
	v_lshl_add_u64 v[166:167], s[28:29], 0, v[132:133]
	s_mov_b32 m0, s38
	s_nop 0
	global_load_lds_dwordx4 v[166:167], off
	v_lshl_add_u64 v[166:167], s[28:29], 0, v[136:137]
	s_add_i32 m0, s38, 0x2000
	s_nop 0
	global_load_lds_dwordx4 v[166:167], off
	v_lshl_add_u64 v[166:167], v[232:233], 0, s[6:7]
	s_mov_b32 m0, s58
	s_nop 0
	global_load_lds_dwordx4 v[166:167], off
	v_lshl_add_u64 v[166:167], v[242:243], 0, s[6:7]
	s_mov_b32 m0, s59
	s_nop 0
	global_load_lds_dwordx4 v[166:167], off
	s_waitcnt vmcnt(8)
	s_waitcnt lgkmcnt(0)
	s_barrier
	s_waitcnt lgkmcnt(0)
	v_mfma_f32_16x16x32_bf16 v[62:65], v[142:145], v[180:183], v[62:65]
	v_mfma_f32_16x16x32_bf16 v[58:61], v[150:153], v[180:183], v[58:61]
	v_mfma_f32_16x16x32_bf16 v[54:57], v[142:145], v[202:205], v[54:57]
	v_mfma_f32_16x16x32_bf16 v[50:53], v[150:153], v[202:205], v[50:53]
	v_mfma_f32_16x16x32_bf16 v[46:49], v[142:145], v[210:213], v[46:49]
	v_mfma_f32_16x16x32_bf16 v[42:45], v[150:153], v[210:213], v[42:45]
	v_mfma_f32_16x16x32_bf16 v[38:41], v[142:145], v[224:227], v[38:41]
	v_mfma_f32_16x16x32_bf16 v[34:37], v[150:153], v[224:227], v[34:37]
	v_mfma_f32_16x16x32_bf16 v[62:65], v[146:149], v[198:201], v[62:65]
	v_mfma_f32_16x16x32_bf16 v[58:61], v[154:157], v[198:201], v[58:61]
	v_mfma_f32_16x16x32_bf16 v[54:57], v[146:149], v[206:209], v[54:57]
	v_mfma_f32_16x16x32_bf16 v[50:53], v[154:157], v[206:209], v[50:53]
	v_mfma_f32_16x16x32_bf16 v[46:49], v[146:149], v[220:223], v[46:49]
	v_mfma_f32_16x16x32_bf16 v[42:45], v[154:157], v[220:223], v[42:45]
	v_mfma_f32_16x16x32_bf16 v[38:41], v[146:149], v[228:231], v[38:41]
	v_mfma_f32_16x16x32_bf16 v[34:37], v[154:157], v[228:231], v[34:37]
	v_mfma_f32_16x16x32_bf16 v[30:33], v[158:161], v[180:183], v[30:33]
	v_mfma_f32_16x16x32_bf16 v[26:29], v[172:175], v[180:183], v[26:29]
	v_mfma_f32_16x16x32_bf16 v[22:25], v[158:161], v[202:205], v[22:25]
	v_mfma_f32_16x16x32_bf16 v[18:21], v[172:175], v[202:205], v[18:21]
	v_mfma_f32_16x16x32_bf16 v[14:17], v[158:161], v[210:213], v[14:17]
	v_mfma_f32_16x16x32_bf16 v[10:13], v[172:175], v[210:213], v[10:13]
	v_mfma_f32_16x16x32_bf16 v[6:9], v[158:161], v[224:227], v[6:9]
	v_mfma_f32_16x16x32_bf16 v[2:5], v[172:175], v[224:227], v[2:5]
	v_mfma_f32_16x16x32_bf16 v[30:33], v[162:165], v[198:201], v[30:33]
	v_mfma_f32_16x16x32_bf16 v[26:29], v[176:179], v[198:201], v[26:29]
	v_mfma_f32_16x16x32_bf16 v[22:25], v[162:165], v[206:209], v[22:25]
	v_mfma_f32_16x16x32_bf16 v[18:21], v[176:179], v[206:209], v[18:21]
	v_mfma_f32_16x16x32_bf16 v[14:17], v[162:165], v[220:223], v[14:17]
	v_mfma_f32_16x16x32_bf16 v[10:13], v[176:179], v[220:223], v[10:13]
	v_mfma_f32_16x16x32_bf16 v[6:9], v[162:165], v[228:231], v[6:9]
	v_mfma_f32_16x16x32_bf16 v[2:5], v[176:179], v[228:231], v[2:5]
	s_barrier
	s_add_i32 s47, s47, 2
	s_add_u32 s24, s24, 0x100
	s_addc_u32 s25, s25, 0
	s_add_u32 s43, s43, 0x100
	s_addc_u32 s45, s45, 0
	s_cmp_gt_u32 s47, 5
	s_cbranch_scc0 .LBB0_2008
	s_and_b64 vcc, exec, s[26:27]
	s_cbranch_vccz .LBB0_2011
	s_barrier
.LBB0_2011:
	s_setprio 0
	s_ashr_i32 s24, s30, 2
	s_lshl_b32 s25, s30, 8
	s_and_b32 s25, s25, 0x300
	s_mov_b64 s[64:65], s[66:67]
	v_readlane_b32 s28, v251, 34
	v_readlane_b32 s29, v251, 35
	v_lshl_add_u32 v142, s2, 8, v168
	s_lshl_b32 s31, s24, 10
	s_add_i32 s31, s31, s25
	v_lshlrev_b32_e32 v143, 11, v142
	v_lshlrev_b32_e32 v142, 12, v142
	v_add_u32_e32 v142, v142, v170
	s_add_u32 s28, s28, s31
	s_addc_u32 s29, s29, 0
	s_cmp_eq_u32 s24, 3
	s_cselect_b64 s[38:39], 0, -1
	s_cbranch_scc1 .Lmy_mg_last
	global_load_dwordx2 v[144:145], v142, s[28:29]
	global_load_dwordx2 v[146:147], v142, s[28:29] offset:128
	global_load_dwordx2 v[148:149], v142, s[28:29] offset:1024
	global_load_dwordx2 v[150:151], v142, s[28:29] offset:1152
	v_add_u32_e32 v142, 0x10000, v142
	global_load_dwordx2 v[152:153], v142, s[28:29]
	global_load_dwordx2 v[154:155], v142, s[28:29] offset:128
	global_load_dwordx2 v[156:157], v142, s[28:29] offset:1024
	global_load_dwordx2 v[158:159], v142, s[28:29] offset:1152
	v_add_u32_e32 v142, 0x10000, v142
	global_load_dwordx2 v[160:161], v142, s[28:29]
	global_load_dwordx2 v[162:163], v142, s[28:29] offset:128
	global_load_dwordx2 v[164:165], v142, s[28:29] offset:1024
	global_load_dwordx2 v[166:167], v142, s[28:29] offset:1152
	v_add_u32_e32 v142, 0x10000, v142
	global_load_dwordx2 v[172:173], v142, s[28:29]
	global_load_dwordx2 v[174:175], v142, s[28:29] offset:128
	global_load_dwordx2 v[176:177], v142, s[28:29] offset:1024
	global_load_dwordx2 v[178:179], v142, s[28:29] offset:1152
	v_add_u32_e32 v142, 0x50000, v142
	global_load_dwordx2 v[180:181], v142, s[28:29]
	global_load_dwordx2 v[182:183], v142, s[28:29] offset:128
	global_load_dwordx2 v[198:199], v142, s[28:29] offset:1024
	global_load_dwordx2 v[200:201], v142, s[28:29] offset:1152
	v_add_u32_e32 v142, 0x10000, v142
	global_load_dwordx2 v[202:203], v142, s[28:29]
	global_load_dwordx2 v[204:205], v142, s[28:29] offset:128
	global_load_dwordx2 v[206:207], v142, s[28:29] offset:1024
	global_load_dwordx2 v[208:209], v142, s[28:29] offset:1152
	v_add_u32_e32 v142, 0x10000, v142
	global_load_dwordx2 v[210:211], v142, s[28:29]
	global_load_dwordx2 v[212:213], v142, s[28:29] offset:128
	global_load_dwordx2 v[214:215], v142, s[28:29] offset:1024
	global_load_dwordx2 v[220:221], v142, s[28:29] offset:1152
	v_add_u32_e32 v142, 0x10000, v142
	global_load_dwordx2 v[222:223], v142, s[28:29]
	global_load_dwordx2 v[224:225], v142, s[28:29] offset:128
	global_load_dwordx2 v[226:227], v142, s[28:29] offset:1024
	global_load_dwordx2 v[228:229], v142, s[28:29] offset:1152
	s_waitcnt vmcnt(28)
; __device__ __forceinline__ float rcpf(float x) { return __builtin_amdgcn_rcpf(x); }
; __device__ __forceinline__ void unpack_u8x8(u32x2 w, float* f) {
; #pragma unroll
;     for (int j = 0; j < 4; ++j) { f[j] = (float)((w.x >> (8 * j)) & 0xffu); f[4 + j] = (float)((w.y >> (8 * j)) & 0xffu); }
; }
;     __device__ __forceinline__ bool chain(f32x4 (&acc)[2][2][4][2], const Unit& u, int wr, int wc, int fr, int fq) const {
;     ...
;                     for (int bj = 0; bj < 2; ++bj) { const int m = mp * 2 + mm; const size_t row = (size_t)(row0 + ai * HALF + m * 16); const int c0 = nn * BM + bj * HALF + wc * 32 + 8 * fq; float ga[8], gb[8], o[8];
;                         unpack_u8x8(g0[mm][bj], ga); unpack_u8x8(g1[mm][bj], gb);
; #pragma unroll
;                         for (int n = 0; n < 2; ++n)
; #pragma unroll
;                             for (int j = 0; j < 4; ++j) { const float f = lastb ? ga[n * 4 + j] * (1.f / 255.f) : ga[n * 4 + j] * rcpf(gb[n * 4 + j]); const float v = acc[ai][bj][m][n][j] * f; acc[ai][bj][m][n][j] = v; o[n * 4 + j] = v; }
	v_cvt_f32_ubyte0_e32 v230, v144
	v_cvt_f32_ubyte1_e32 v231, v144
	v_cvt_f32_ubyte2_e32 v232, v144
	v_cvt_f32_ubyte3_e32 v233, v144
	v_cvt_f32_ubyte0_e32 v242, v148
	v_cvt_f32_ubyte1_e32 v243, v148
	v_cvt_f32_ubyte2_e32 v248, v148
	v_cvt_f32_ubyte3_e32 v249, v148
	v_rcp_iflag_f32_e32 v242, v242
	v_rcp_iflag_f32_e32 v243, v243
	v_rcp_iflag_f32_e32 v248, v248
	v_rcp_iflag_f32_e32 v249, v249
	v_mul_f32_e32 v230, v242, v230
	v_mul_f32_e32 v231, v243, v231
	v_mul_f32_e32 v232, v248, v232
	v_mul_f32_e32 v233, v249, v233
	v_mul_f32_e32 v126, v126, v230
	v_mul_f32_e32 v127, v127, v231
	v_mul_f32_e32 v128, v128, v232
	v_mul_f32_e32 v129, v129, v233
	v_cvt_f32_ubyte0_e32 v230, v145
	v_cvt_f32_ubyte1_e32 v231, v145
	v_cvt_f32_ubyte2_e32 v232, v145
	v_cvt_f32_ubyte3_e32 v233, v145
	v_cvt_f32_ubyte0_e32 v242, v149
	v_cvt_f32_ubyte1_e32 v243, v149
	v_cvt_f32_ubyte2_e32 v248, v149
	v_cvt_f32_ubyte3_e32 v249, v149
	v_rcp_iflag_f32_e32 v242, v242
	v_rcp_iflag_f32_e32 v243, v243
	v_rcp_iflag_f32_e32 v248, v248
	v_rcp_iflag_f32_e32 v249, v249
	v_mul_f32_e32 v230, v242, v230
	v_mul_f32_e32 v231, v243, v231
	v_mul_f32_e32 v232, v248, v232
	v_mul_f32_e32 v233, v249, v233
	v_mul_f32_e32 v122, v122, v230
	v_mul_f32_e32 v123, v123, v231
	v_mul_f32_e32 v124, v124, v232
	v_mul_f32_e32 v125, v125, v233
	v_cvt_f32_ubyte0_e32 v230, v146
	v_cvt_f32_ubyte1_e32 v231, v146
	v_cvt_f32_ubyte2_e32 v232, v146
	v_cvt_f32_ubyte3_e32 v233, v146
	v_cvt_f32_ubyte0_e32 v242, v150
	v_cvt_f32_ubyte1_e32 v243, v150
	v_cvt_f32_ubyte2_e32 v248, v150
	v_cvt_f32_ubyte3_e32 v249, v150
	v_rcp_iflag_f32_e32 v242, v242
	v_rcp_iflag_f32_e32 v243, v243
	v_rcp_iflag_f32_e32 v248, v248
	v_rcp_iflag_f32_e32 v249, v249
	v_mul_f32_e32 v230, v242, v230
	v_mul_f32_e32 v231, v243, v231
	v_mul_f32_e32 v232, v248, v232
	v_mul_f32_e32 v233, v249, v233
	v_mul_f32_e32 v94, v94, v230
	v_mul_f32_e32 v95, v95, v231
	v_mul_f32_e32 v96, v96, v232
	v_mul_f32_e32 v97, v97, v233
	v_cvt_f32_ubyte0_e32 v230, v147
	v_cvt_f32_ubyte1_e32 v231, v147
	v_cvt_f32_ubyte2_e32 v232, v147
	v_cvt_f32_ubyte3_e32 v233, v147
	v_cvt_f32_ubyte0_e32 v242, v151
	v_cvt_f32_ubyte1_e32 v243, v151
	v_cvt_f32_ubyte2_e32 v248, v151
	v_cvt_f32_ubyte3_e32 v249, v151
	v_rcp_iflag_f32_e32 v242, v242
	v_rcp_iflag_f32_e32 v243, v243
	v_rcp_iflag_f32_e32 v248, v248
	v_rcp_iflag_f32_e32 v249, v249
	v_mul_f32_e32 v230, v242, v230
	v_mul_f32_e32 v231, v243, v231
	v_mul_f32_e32 v232, v248, v232
	v_mul_f32_e32 v233, v249, v233
	v_mul_f32_e32 v90, v90, v230
	v_mul_f32_e32 v91, v91, v231
	v_mul_f32_e32 v92, v92, v232
	v_mul_f32_e32 v93, v93, v233
	s_waitcnt vmcnt(24)
	v_cvt_f32_ubyte0_e32 v230, v152
	v_cvt_f32_ubyte1_e32 v231, v152
	v_cvt_f32_ubyte2_e32 v232, v152
	v_cvt_f32_ubyte3_e32 v233, v152
	v_cvt_f32_ubyte0_e32 v242, v156
	v_cvt_f32_ubyte1_e32 v243, v156
	v_cvt_f32_ubyte2_e32 v248, v156
	v_cvt_f32_ubyte3_e32 v249, v156
	v_rcp_iflag_f32_e32 v242, v242
	v_rcp_iflag_f32_e32 v243, v243
	v_rcp_iflag_f32_e32 v248, v248
	v_rcp_iflag_f32_e32 v249, v249
	v_mul_f32_e32 v230, v242, v230
	v_mul_f32_e32 v231, v243, v231
	v_mul_f32_e32 v232, v248, v232
	v_mul_f32_e32 v233, v249, v233
	v_mul_f32_e32 v118, v118, v230
	v_mul_f32_e32 v119, v119, v231
	v_mul_f32_e32 v120, v120, v232
	v_mul_f32_e32 v121, v121, v233
	v_cvt_f32_ubyte0_e32 v230, v153
	v_cvt_f32_ubyte1_e32 v231, v153
	v_cvt_f32_ubyte2_e32 v232, v153
	v_cvt_f32_ubyte3_e32 v233, v153
	v_cvt_f32_ubyte0_e32 v242, v157
	v_cvt_f32_ubyte1_e32 v243, v157
	v_cvt_f32_ubyte2_e32 v248, v157
	v_cvt_f32_ubyte3_e32 v249, v157
	v_rcp_iflag_f32_e32 v242, v242
	v_rcp_iflag_f32_e32 v243, v243
	v_rcp_iflag_f32_e32 v248, v248
	v_rcp_iflag_f32_e32 v249, v249
	v_mul_f32_e32 v230, v242, v230
	v_mul_f32_e32 v231, v243, v231
	v_mul_f32_e32 v232, v248, v232
	v_mul_f32_e32 v233, v249, v233
	v_mul_f32_e32 v114, v114, v230
	v_mul_f32_e32 v115, v115, v231
	v_mul_f32_e32 v116, v116, v232
	v_mul_f32_e32 v117, v117, v233
	v_cvt_f32_ubyte0_e32 v230, v154
	v_cvt_f32_ubyte1_e32 v231, v154
	v_cvt_f32_ubyte2_e32 v232, v154
	v_cvt_f32_ubyte3_e32 v233, v154
	v_cvt_f32_ubyte0_e32 v242, v158
	v_cvt_f32_ubyte1_e32 v243, v158
	v_cvt_f32_ubyte2_e32 v248, v158
	v_cvt_f32_ubyte3_e32 v249, v158
	v_rcp_iflag_f32_e32 v242, v242
	v_rcp_iflag_f32_e32 v243, v243
	v_rcp_iflag_f32_e32 v248, v248
	v_rcp_iflag_f32_e32 v249, v249
	v_mul_f32_e32 v230, v242, v230
	v_mul_f32_e32 v231, v243, v231
	v_mul_f32_e32 v232, v248, v232
	v_mul_f32_e32 v233, v249, v233
	v_mul_f32_e32 v86, v86, v230
	v_mul_f32_e32 v87, v87, v231
	v_mul_f32_e32 v88, v88, v232
	v_mul_f32_e32 v89, v89, v233
	v_cvt_f32_ubyte0_e32 v230, v155
	v_cvt_f32_ubyte1_e32 v231, v155
	v_cvt_f32_ubyte2_e32 v232, v155
	v_cvt_f32_ubyte3_e32 v233, v155
	v_cvt_f32_ubyte0_e32 v242, v159
	v_cvt_f32_ubyte1_e32 v243, v159
	v_cvt_f32_ubyte2_e32 v248, v159
	v_cvt_f32_ubyte3_e32 v249, v159
	v_rcp_iflag_f32_e32 v242, v242
	v_rcp_iflag_f32_e32 v243, v243
	v_rcp_iflag_f32_e32 v248, v248
	v_rcp_iflag_f32_e32 v249, v249
	v_mul_f32_e32 v230, v242, v230
	v_mul_f32_e32 v231, v243, v231
	v_mul_f32_e32 v232, v248, v232
	v_mul_f32_e32 v233, v249, v233
	v_mul_f32_e32 v82, v82, v230
	v_mul_f32_e32 v83, v83, v231
	v_mul_f32_e32 v84, v84, v232
	v_mul_f32_e32 v85, v85, v233
	s_waitcnt vmcnt(20)
; __device__ __forceinline__ float rcpf(float x) { return __builtin_amdgcn_rcpf(x); }
; __device__ __forceinline__ void unpack_u8x8(u32x2 w, float* f) {
; #pragma unroll
;     for (int j = 0; j < 4; ++j) { f[j] = (float)((w.x >> (8 * j)) & 0xffu); f[4 + j] = (float)((w.y >> (8 * j)) & 0xffu); }
; }
;     __device__ __forceinline__ bool chain(f32x4 (&acc)[2][2][4][2], const Unit& u, int wr, int wc, int fr, int fq) const {
;     ...
;                     for (int bj = 0; bj < 2; ++bj) { const int m = mp * 2 + mm; const size_t row = (size_t)(row0 + ai * HALF + m * 16); const int c0 = nn * BM + bj * HALF + wc * 32 + 8 * fq; float ga[8], gb[8], o[8];
;                         unpack_u8x8(g0[mm][bj], ga); unpack_u8x8(g1[mm][bj], gb);
; #pragma unroll
;                         for (int n = 0; n < 2; ++n)
; #pragma unroll
;                             for (int j = 0; j < 4; ++j) { const float f = lastb ? ga[n * 4 + j] * (1.f / 255.f) : ga[n * 4 + j] * rcpf(gb[n * 4 + j]); const float v = acc[ai][bj][m][n][j] * f; acc[ai][bj][m][n][j] = v; o[n * 4 + j] = v; }
	v_cvt_f32_ubyte0_e32 v230, v160
	v_cvt_f32_ubyte1_e32 v231, v160
	v_cvt_f32_ubyte2_e32 v232, v160
	v_cvt_f32_ubyte3_e32 v233, v160
	v_cvt_f32_ubyte0_e32 v242, v164
	v_cvt_f32_ubyte1_e32 v243, v164
	v_cvt_f32_ubyte2_e32 v248, v164
	v_cvt_f32_ubyte3_e32 v249, v164
	v_rcp_iflag_f32_e32 v242, v242
	v_rcp_iflag_f32_e32 v243, v243
	v_rcp_iflag_f32_e32 v248, v248
	v_rcp_iflag_f32_e32 v249, v249
	v_mul_f32_e32 v230, v242, v230
	v_mul_f32_e32 v231, v243, v231
	v_mul_f32_e32 v232, v248, v232
	v_mul_f32_e32 v233, v249, v233
	v_mul_f32_e32 v110, v110, v230
	v_mul_f32_e32 v111, v111, v231
	v_mul_f32_e32 v112, v112, v232
	v_mul_f32_e32 v113, v113, v233
	v_cvt_f32_ubyte0_e32 v230, v161
	v_cvt_f32_ubyte1_e32 v231, v161
	v_cvt_f32_ubyte2_e32 v232, v161
	v_cvt_f32_ubyte3_e32 v233, v161
	v_cvt_f32_ubyte0_e32 v242, v165
	v_cvt_f32_ubyte1_e32 v243, v165
	v_cvt_f32_ubyte2_e32 v248, v165
	v_cvt_f32_ubyte3_e32 v249, v165
	v_rcp_iflag_f32_e32 v242, v242
	v_rcp_iflag_f32_e32 v243, v243
	v_rcp_iflag_f32_e32 v248, v248
	v_rcp_iflag_f32_e32 v249, v249
	v_mul_f32_e32 v230, v242, v230
	v_mul_f32_e32 v231, v243, v231
	v_mul_f32_e32 v232, v248, v232
	v_mul_f32_e32 v233, v249, v233
	v_mul_f32_e32 v106, v106, v230
	v_mul_f32_e32 v107, v107, v231
	v_mul_f32_e32 v108, v108, v232
	v_mul_f32_e32 v109, v109, v233
	v_cvt_f32_ubyte0_e32 v230, v162
	v_cvt_f32_ubyte1_e32 v231, v162
	v_cvt_f32_ubyte2_e32 v232, v162
	v_cvt_f32_ubyte3_e32 v233, v162
	v_cvt_f32_ubyte0_e32 v242, v166
	v_cvt_f32_ubyte1_e32 v243, v166
	v_cvt_f32_ubyte2_e32 v248, v166
	v_cvt_f32_ubyte3_e32 v249, v166
	v_rcp_iflag_f32_e32 v242, v242
	v_rcp_iflag_f32_e32 v243, v243
	v_rcp_iflag_f32_e32 v248, v248
	v_rcp_iflag_f32_e32 v249, v249
	v_mul_f32_e32 v230, v242, v230
	v_mul_f32_e32 v231, v243, v231
	v_mul_f32_e32 v232, v248, v232
	v_mul_f32_e32 v233, v249, v233
	v_mul_f32_e32 v78, v78, v230
	v_mul_f32_e32 v79, v79, v231
	v_mul_f32_e32 v80, v80, v232
	v_mul_f32_e32 v81, v81, v233
	v_cvt_f32_ubyte0_e32 v230, v163
	v_cvt_f32_ubyte1_e32 v231, v163
	v_cvt_f32_ubyte2_e32 v232, v163
	v_cvt_f32_ubyte3_e32 v233, v163
	v_cvt_f32_ubyte0_e32 v242, v167
	v_cvt_f32_ubyte1_e32 v243, v167
	v_cvt_f32_ubyte2_e32 v248, v167
	v_cvt_f32_ubyte3_e32 v249, v167
	v_rcp_iflag_f32_e32 v242, v242
	v_rcp_iflag_f32_e32 v243, v243
	v_rcp_iflag_f32_e32 v248, v248
	v_rcp_iflag_f32_e32 v249, v249
	v_mul_f32_e32 v230, v242, v230
	v_mul_f32_e32 v231, v243, v231
	v_mul_f32_e32 v232, v248, v232
	v_mul_f32_e32 v233, v249, v233
	v_mul_f32_e32 v74, v74, v230
	v_mul_f32_e32 v75, v75, v231
	v_mul_f32_e32 v76, v76, v232
	v_mul_f32_e32 v77, v77, v233
	s_waitcnt vmcnt(16)
	v_cvt_f32_ubyte0_e32 v230, v172
	v_cvt_f32_ubyte1_e32 v231, v172
	v_cvt_f32_ubyte2_e32 v232, v172
	v_cvt_f32_ubyte3_e32 v233, v172
	v_cvt_f32_ubyte0_e32 v242, v176
	v_cvt_f32_ubyte1_e32 v243, v176
	v_cvt_f32_ubyte2_e32 v248, v176
	v_cvt_f32_ubyte3_e32 v249, v176
	v_rcp_iflag_f32_e32 v242, v242
	v_rcp_iflag_f32_e32 v243, v243
	v_rcp_iflag_f32_e32 v248, v248
	v_rcp_iflag_f32_e32 v249, v249
	v_mul_f32_e32 v230, v242, v230
	v_mul_f32_e32 v231, v243, v231
	v_mul_f32_e32 v232, v248, v232
	v_mul_f32_e32 v233, v249, v233
	v_mul_f32_e32 v102, v102, v230
	v_mul_f32_e32 v103, v103, v231
	v_mul_f32_e32 v104, v104, v232
	v_mul_f32_e32 v105, v105, v233
	v_cvt_f32_ubyte0_e32 v230, v173
	v_cvt_f32_ubyte1_e32 v231, v173
	v_cvt_f32_ubyte2_e32 v232, v173
	v_cvt_f32_ubyte3_e32 v233, v173
	v_cvt_f32_ubyte0_e32 v242, v177
	v_cvt_f32_ubyte1_e32 v243, v177
	v_cvt_f32_ubyte2_e32 v248, v177
	v_cvt_f32_ubyte3_e32 v249, v177
	v_rcp_iflag_f32_e32 v242, v242
	v_rcp_iflag_f32_e32 v243, v243
	v_rcp_iflag_f32_e32 v248, v248
	v_rcp_iflag_f32_e32 v249, v249
	v_mul_f32_e32 v230, v242, v230
	v_mul_f32_e32 v231, v243, v231
	v_mul_f32_e32 v232, v248, v232
	v_mul_f32_e32 v233, v249, v233
	v_mul_f32_e32 v98, v98, v230
	v_mul_f32_e32 v99, v99, v231
	v_mul_f32_e32 v100, v100, v232
	v_mul_f32_e32 v101, v101, v233
	v_cvt_f32_ubyte0_e32 v230, v174
	v_cvt_f32_ubyte1_e32 v231, v174
	v_cvt_f32_ubyte2_e32 v232, v174
	v_cvt_f32_ubyte3_e32 v233, v174
	v_cvt_f32_ubyte0_e32 v242, v178
	v_cvt_f32_ubyte1_e32 v243, v178
	v_cvt_f32_ubyte2_e32 v248, v178
	v_cvt_f32_ubyte3_e32 v249, v178
	v_rcp_iflag_f32_e32 v242, v242
	v_rcp_iflag_f32_e32 v243, v243
	v_rcp_iflag_f32_e32 v248, v248
	v_rcp_iflag_f32_e32 v249, v249
	v_mul_f32_e32 v230, v242, v230
	v_mul_f32_e32 v231, v243, v231
	v_mul_f32_e32 v232, v248, v232
	v_mul_f32_e32 v233, v249, v233
	v_mul_f32_e32 v70, v70, v230
	v_mul_f32_e32 v71, v71, v231
	v_mul_f32_e32 v72, v72, v232
	v_mul_f32_e32 v73, v73, v233
	v_cvt_f32_ubyte0_e32 v230, v175
	v_cvt_f32_ubyte1_e32 v231, v175
	v_cvt_f32_ubyte2_e32 v232, v175
	v_cvt_f32_ubyte3_e32 v233, v175
	v_cvt_f32_ubyte0_e32 v242, v179
	v_cvt_f32_ubyte1_e32 v243, v179
	v_cvt_f32_ubyte2_e32 v248, v179
	v_cvt_f32_ubyte3_e32 v249, v179
	v_rcp_iflag_f32_e32 v242, v242
	v_rcp_iflag_f32_e32 v243, v243
	v_rcp_iflag_f32_e32 v248, v248
	v_rcp_iflag_f32_e32 v249, v249
	v_mul_f32_e32 v230, v242, v230
	v_mul_f32_e32 v231, v243, v231
	v_mul_f32_e32 v232, v248, v232
	v_mul_f32_e32 v233, v249, v233
	v_mul_f32_e32 v66, v66, v230
	v_mul_f32_e32 v67, v67, v231
	v_mul_f32_e32 v68, v68, v232
	v_mul_f32_e32 v69, v69, v233
	s_waitcnt vmcnt(12)
; __device__ __forceinline__ float rcpf(float x) { return __builtin_amdgcn_rcpf(x); }
; __device__ __forceinline__ void unpack_u8x8(u32x2 w, float* f) {
; #pragma unroll
;     for (int j = 0; j < 4; ++j) { f[j] = (float)((w.x >> (8 * j)) & 0xffu); f[4 + j] = (float)((w.y >> (8 * j)) & 0xffu); }
; }
;     __device__ __forceinline__ bool chain(f32x4 (&acc)[2][2][4][2], const Unit& u, int wr, int wc, int fr, int fq) const {
;     ...
;                     for (int bj = 0; bj < 2; ++bj) { const int m = mp * 2 + mm; const size_t row = (size_t)(row0 + ai * HALF + m * 16); const int c0 = nn * BM + bj * HALF + wc * 32 + 8 * fq; float ga[8], gb[8], o[8];
;                         unpack_u8x8(g0[mm][bj], ga); unpack_u8x8(g1[mm][bj], gb);
; #pragma unroll
;                         for (int n = 0; n < 2; ++n)
; #pragma unroll
;                             for (int j = 0; j < 4; ++j) { const float f = lastb ? ga[n * 4 + j] * (1.f / 255.f) : ga[n * 4 + j] * rcpf(gb[n * 4 + j]); const float v = acc[ai][bj][m][n][j] * f; acc[ai][bj][m][n][j] = v; o[n * 4 + j] = v; }
	v_cvt_f32_ubyte0_e32 v230, v180
	v_cvt_f32_ubyte1_e32 v231, v180
	v_cvt_f32_ubyte2_e32 v232, v180
	v_cvt_f32_ubyte3_e32 v233, v180
	v_cvt_f32_ubyte0_e32 v242, v198
	v_cvt_f32_ubyte1_e32 v243, v198
	v_cvt_f32_ubyte2_e32 v248, v198
	v_cvt_f32_ubyte3_e32 v249, v198
	v_rcp_iflag_f32_e32 v242, v242
	v_rcp_iflag_f32_e32 v243, v243
	v_rcp_iflag_f32_e32 v248, v248
	v_rcp_iflag_f32_e32 v249, v249
	v_mul_f32_e32 v230, v242, v230
	v_mul_f32_e32 v231, v243, v231
	v_mul_f32_e32 v232, v248, v232
	v_mul_f32_e32 v233, v249, v233
	v_mul_f32_e32 v62, v62, v230
	v_mul_f32_e32 v63, v63, v231
	v_mul_f32_e32 v64, v64, v232
	v_mul_f32_e32 v65, v65, v233
	v_cvt_f32_ubyte0_e32 v230, v181
	v_cvt_f32_ubyte1_e32 v231, v181
	v_cvt_f32_ubyte2_e32 v232, v181
	v_cvt_f32_ubyte3_e32 v233, v181
	v_cvt_f32_ubyte0_e32 v242, v199
	v_cvt_f32_ubyte1_e32 v243, v199
	v_cvt_f32_ubyte2_e32 v248, v199
	v_cvt_f32_ubyte3_e32 v249, v199
	v_rcp_iflag_f32_e32 v242, v242
	v_rcp_iflag_f32_e32 v243, v243
	v_rcp_iflag_f32_e32 v248, v248
	v_rcp_iflag_f32_e32 v249, v249
	v_mul_f32_e32 v230, v242, v230
	v_mul_f32_e32 v231, v243, v231
	v_mul_f32_e32 v232, v248, v232
	v_mul_f32_e32 v233, v249, v233
	v_mul_f32_e32 v58, v58, v230
	v_mul_f32_e32 v59, v59, v231
	v_mul_f32_e32 v60, v60, v232
	v_mul_f32_e32 v61, v61, v233
	v_cvt_f32_ubyte0_e32 v230, v182
	v_cvt_f32_ubyte1_e32 v231, v182
	v_cvt_f32_ubyte2_e32 v232, v182
	v_cvt_f32_ubyte3_e32 v233, v182
	v_cvt_f32_ubyte0_e32 v242, v200
	v_cvt_f32_ubyte1_e32 v243, v200
	v_cvt_f32_ubyte2_e32 v248, v200
	v_cvt_f32_ubyte3_e32 v249, v200
	v_rcp_iflag_f32_e32 v242, v242
	v_rcp_iflag_f32_e32 v243, v243
	v_rcp_iflag_f32_e32 v248, v248
	v_rcp_iflag_f32_e32 v249, v249
	v_mul_f32_e32 v230, v242, v230
	v_mul_f32_e32 v231, v243, v231
	v_mul_f32_e32 v232, v248, v232
	v_mul_f32_e32 v233, v249, v233
	v_mul_f32_e32 v30, v30, v230
	v_mul_f32_e32 v31, v31, v231
	v_mul_f32_e32 v32, v32, v232
	v_mul_f32_e32 v33, v33, v233
	v_cvt_f32_ubyte0_e32 v230, v183
	v_cvt_f32_ubyte1_e32 v231, v183
	v_cvt_f32_ubyte2_e32 v232, v183
	v_cvt_f32_ubyte3_e32 v233, v183
	v_cvt_f32_ubyte0_e32 v242, v201
	v_cvt_f32_ubyte1_e32 v243, v201
	v_cvt_f32_ubyte2_e32 v248, v201
	v_cvt_f32_ubyte3_e32 v249, v201
	v_rcp_iflag_f32_e32 v242, v242
	v_rcp_iflag_f32_e32 v243, v243
	v_rcp_iflag_f32_e32 v248, v248
	v_rcp_iflag_f32_e32 v249, v249
	v_mul_f32_e32 v230, v242, v230
	v_mul_f32_e32 v231, v243, v231
	v_mul_f32_e32 v232, v248, v232
	v_mul_f32_e32 v233, v249, v233
	v_mul_f32_e32 v26, v26, v230
	v_mul_f32_e32 v27, v27, v231
	v_mul_f32_e32 v28, v28, v232
	v_mul_f32_e32 v29, v29, v233
	s_waitcnt vmcnt(8)
	v_cvt_f32_ubyte0_e32 v230, v202
	v_cvt_f32_ubyte1_e32 v231, v202
	v_cvt_f32_ubyte2_e32 v232, v202
	v_cvt_f32_ubyte3_e32 v233, v202
	v_cvt_f32_ubyte0_e32 v242, v206
	v_cvt_f32_ubyte1_e32 v243, v206
	v_cvt_f32_ubyte2_e32 v248, v206
	v_cvt_f32_ubyte3_e32 v249, v206
	v_rcp_iflag_f32_e32 v242, v242
	v_rcp_iflag_f32_e32 v243, v243
	v_rcp_iflag_f32_e32 v248, v248
	v_rcp_iflag_f32_e32 v249, v249
	v_mul_f32_e32 v230, v242, v230
	v_mul_f32_e32 v231, v243, v231
	v_mul_f32_e32 v232, v248, v232
	v_mul_f32_e32 v233, v249, v233
	v_mul_f32_e32 v54, v54, v230
	v_mul_f32_e32 v55, v55, v231
	v_mul_f32_e32 v56, v56, v232
	v_mul_f32_e32 v57, v57, v233
	v_cvt_f32_ubyte0_e32 v230, v203
	v_cvt_f32_ubyte1_e32 v231, v203
	v_cvt_f32_ubyte2_e32 v232, v203
	v_cvt_f32_ubyte3_e32 v233, v203
	v_cvt_f32_ubyte0_e32 v242, v207
	v_cvt_f32_ubyte1_e32 v243, v207
	v_cvt_f32_ubyte2_e32 v248, v207
	v_cvt_f32_ubyte3_e32 v249, v207
	v_rcp_iflag_f32_e32 v242, v242
	v_rcp_iflag_f32_e32 v243, v243
	v_rcp_iflag_f32_e32 v248, v248
	v_rcp_iflag_f32_e32 v249, v249
	v_mul_f32_e32 v230, v242, v230
	v_mul_f32_e32 v231, v243, v231
	v_mul_f32_e32 v232, v248, v232
	v_mul_f32_e32 v233, v249, v233
	v_mul_f32_e32 v50, v50, v230
	v_mul_f32_e32 v51, v51, v231
	v_mul_f32_e32 v52, v52, v232
	v_mul_f32_e32 v53, v53, v233
	v_cvt_f32_ubyte0_e32 v230, v204
	v_cvt_f32_ubyte1_e32 v231, v204
	v_cvt_f32_ubyte2_e32 v232, v204
	v_cvt_f32_ubyte3_e32 v233, v204
	v_cvt_f32_ubyte0_e32 v242, v208
	v_cvt_f32_ubyte1_e32 v243, v208
	v_cvt_f32_ubyte2_e32 v248, v208
	v_cvt_f32_ubyte3_e32 v249, v208
	v_rcp_iflag_f32_e32 v242, v242
	v_rcp_iflag_f32_e32 v243, v243
	v_rcp_iflag_f32_e32 v248, v248
	v_rcp_iflag_f32_e32 v249, v249
	v_mul_f32_e32 v230, v242, v230
	v_mul_f32_e32 v231, v243, v231
	v_mul_f32_e32 v232, v248, v232
	v_mul_f32_e32 v233, v249, v233
	v_mul_f32_e32 v22, v22, v230
	v_mul_f32_e32 v23, v23, v231
	v_mul_f32_e32 v24, v24, v232
	v_mul_f32_e32 v25, v25, v233
	v_cvt_f32_ubyte0_e32 v230, v205
	v_cvt_f32_ubyte1_e32 v231, v205
	v_cvt_f32_ubyte2_e32 v232, v205
	v_cvt_f32_ubyte3_e32 v233, v205
	v_cvt_f32_ubyte0_e32 v242, v209
	v_cvt_f32_ubyte1_e32 v243, v209
	v_cvt_f32_ubyte2_e32 v248, v209
	v_cvt_f32_ubyte3_e32 v249, v209
	v_rcp_iflag_f32_e32 v242, v242
	v_rcp_iflag_f32_e32 v243, v243
	v_rcp_iflag_f32_e32 v248, v248
	v_rcp_iflag_f32_e32 v249, v249
	v_mul_f32_e32 v230, v242, v230
	v_mul_f32_e32 v231, v243, v231
	v_mul_f32_e32 v232, v248, v232
	v_mul_f32_e32 v233, v249, v233
	v_mul_f32_e32 v18, v18, v230
	v_mul_f32_e32 v19, v19, v231
	v_mul_f32_e32 v20, v20, v232
	v_mul_f32_e32 v21, v21, v233
	s_waitcnt vmcnt(4)
; __device__ __forceinline__ float rcpf(float x) { return __builtin_amdgcn_rcpf(x); }
; __device__ __forceinline__ void unpack_u8x8(u32x2 w, float* f) {
; #pragma unroll
;     for (int j = 0; j < 4; ++j) { f[j] = (float)((w.x >> (8 * j)) & 0xffu); f[4 + j] = (float)((w.y >> (8 * j)) & 0xffu); }
; }
;     __device__ __forceinline__ bool chain(f32x4 (&acc)[2][2][4][2], const Unit& u, int wr, int wc, int fr, int fq) const {
;     ...
;                     for (int bj = 0; bj < 2; ++bj) { const int m = mp * 2 + mm; const size_t row = (size_t)(row0 + ai * HALF + m * 16); const int c0 = nn * BM + bj * HALF + wc * 32 + 8 * fq; float ga[8], gb[8], o[8];
;                         unpack_u8x8(g0[mm][bj], ga); unpack_u8x8(g1[mm][bj], gb);
; #pragma unroll
;                         for (int n = 0; n < 2; ++n)
; #pragma unroll
;                             for (int j = 0; j < 4; ++j) { const float f = lastb ? ga[n * 4 + j] * (1.f / 255.f) : ga[n * 4 + j] * rcpf(gb[n * 4 + j]); const float v = acc[ai][bj][m][n][j] * f; acc[ai][bj][m][n][j] = v; o[n * 4 + j] = v; }
	v_cvt_f32_ubyte0_e32 v230, v210
	v_cvt_f32_ubyte1_e32 v231, v210
	v_cvt_f32_ubyte2_e32 v232, v210
	v_cvt_f32_ubyte3_e32 v233, v210
	v_cvt_f32_ubyte0_e32 v242, v214
	v_cvt_f32_ubyte1_e32 v243, v214
	v_cvt_f32_ubyte2_e32 v248, v214
	v_cvt_f32_ubyte3_e32 v249, v214
	v_rcp_iflag_f32_e32 v242, v242
	v_rcp_iflag_f32_e32 v243, v243
	v_rcp_iflag_f32_e32 v248, v248
	v_rcp_iflag_f32_e32 v249, v249
	v_mul_f32_e32 v230, v242, v230
	v_mul_f32_e32 v231, v243, v231
	v_mul_f32_e32 v232, v248, v232
	v_mul_f32_e32 v233, v249, v233
	v_mul_f32_e32 v46, v46, v230
	v_mul_f32_e32 v47, v47, v231
	v_mul_f32_e32 v48, v48, v232
	v_mul_f32_e32 v49, v49, v233
	v_cvt_f32_ubyte0_e32 v230, v211
	v_cvt_f32_ubyte1_e32 v231, v211
	v_cvt_f32_ubyte2_e32 v232, v211
	v_cvt_f32_ubyte3_e32 v233, v211
	v_cvt_f32_ubyte0_e32 v242, v215
	v_cvt_f32_ubyte1_e32 v243, v215
	v_cvt_f32_ubyte2_e32 v248, v215
	v_cvt_f32_ubyte3_e32 v249, v215
	v_rcp_iflag_f32_e32 v242, v242
	v_rcp_iflag_f32_e32 v243, v243
	v_rcp_iflag_f32_e32 v248, v248
	v_rcp_iflag_f32_e32 v249, v249
	v_mul_f32_e32 v230, v242, v230
	v_mul_f32_e32 v231, v243, v231
	v_mul_f32_e32 v232, v248, v232
	v_mul_f32_e32 v233, v249, v233
	v_mul_f32_e32 v42, v42, v230
	v_mul_f32_e32 v43, v43, v231
	v_mul_f32_e32 v44, v44, v232
	v_mul_f32_e32 v45, v45, v233
	v_cvt_f32_ubyte0_e32 v230, v212
	v_cvt_f32_ubyte1_e32 v231, v212
	v_cvt_f32_ubyte2_e32 v232, v212
	v_cvt_f32_ubyte3_e32 v233, v212
	v_cvt_f32_ubyte0_e32 v242, v220
	v_cvt_f32_ubyte1_e32 v243, v220
	v_cvt_f32_ubyte2_e32 v248, v220
	v_cvt_f32_ubyte3_e32 v249, v220
	v_rcp_iflag_f32_e32 v242, v242
	v_rcp_iflag_f32_e32 v243, v243
	v_rcp_iflag_f32_e32 v248, v248
	v_rcp_iflag_f32_e32 v249, v249
	v_mul_f32_e32 v230, v242, v230
	v_mul_f32_e32 v231, v243, v231
	v_mul_f32_e32 v232, v248, v232
	v_mul_f32_e32 v233, v249, v233
	v_mul_f32_e32 v14, v14, v230
	v_mul_f32_e32 v15, v15, v231
	v_mul_f32_e32 v16, v16, v232
	v_mul_f32_e32 v17, v17, v233
	v_cvt_f32_ubyte0_e32 v230, v213
	v_cvt_f32_ubyte1_e32 v231, v213
	v_cvt_f32_ubyte2_e32 v232, v213
	v_cvt_f32_ubyte3_e32 v233, v213
	v_cvt_f32_ubyte0_e32 v242, v221
	v_cvt_f32_ubyte1_e32 v243, v221
	v_cvt_f32_ubyte2_e32 v248, v221
	v_cvt_f32_ubyte3_e32 v249, v221
	v_rcp_iflag_f32_e32 v242, v242
	v_rcp_iflag_f32_e32 v243, v243
	v_rcp_iflag_f32_e32 v248, v248
	v_rcp_iflag_f32_e32 v249, v249
	v_mul_f32_e32 v230, v242, v230
	v_mul_f32_e32 v231, v243, v231
	v_mul_f32_e32 v232, v248, v232
	v_mul_f32_e32 v233, v249, v233
	v_mul_f32_e32 v10, v10, v230
	v_mul_f32_e32 v11, v11, v231
	v_mul_f32_e32 v12, v12, v232
	v_mul_f32_e32 v13, v13, v233
	s_waitcnt vmcnt(0)
	v_cvt_f32_ubyte0_e32 v230, v222
	v_cvt_f32_ubyte1_e32 v231, v222
	v_cvt_f32_ubyte2_e32 v232, v222
	v_cvt_f32_ubyte3_e32 v233, v222
	v_cvt_f32_ubyte0_e32 v242, v226
	v_cvt_f32_ubyte1_e32 v243, v226
	v_cvt_f32_ubyte2_e32 v248, v226
	v_cvt_f32_ubyte3_e32 v249, v226
	v_rcp_iflag_f32_e32 v242, v242
	v_rcp_iflag_f32_e32 v243, v243
	v_rcp_iflag_f32_e32 v248, v248
	v_rcp_iflag_f32_e32 v249, v249
	v_mul_f32_e32 v230, v242, v230
	v_mul_f32_e32 v231, v243, v231
	v_mul_f32_e32 v232, v248, v232
	v_mul_f32_e32 v233, v249, v233
	v_mul_f32_e32 v38, v38, v230
	v_mul_f32_e32 v39, v39, v231
	v_mul_f32_e32 v40, v40, v232
	v_mul_f32_e32 v41, v41, v233
	v_cvt_f32_ubyte0_e32 v230, v223
	v_cvt_f32_ubyte1_e32 v231, v223
	v_cvt_f32_ubyte2_e32 v232, v223
	v_cvt_f32_ubyte3_e32 v233, v223
	v_cvt_f32_ubyte0_e32 v242, v227
	v_cvt_f32_ubyte1_e32 v243, v227
	v_cvt_f32_ubyte2_e32 v248, v227
	v_cvt_f32_ubyte3_e32 v249, v227
	v_rcp_iflag_f32_e32 v242, v242
	v_rcp_iflag_f32_e32 v243, v243
	v_rcp_iflag_f32_e32 v248, v248
	v_rcp_iflag_f32_e32 v249, v249
	v_mul_f32_e32 v230, v242, v230
	v_mul_f32_e32 v231, v243, v231
	v_mul_f32_e32 v232, v248, v232
	v_mul_f32_e32 v233, v249, v233
	v_mul_f32_e32 v34, v34, v230
	v_mul_f32_e32 v35, v35, v231
	v_mul_f32_e32 v36, v36, v232
	v_mul_f32_e32 v37, v37, v233
	v_cvt_f32_ubyte0_e32 v230, v224
	v_cvt_f32_ubyte1_e32 v231, v224
	v_cvt_f32_ubyte2_e32 v232, v224
	v_cvt_f32_ubyte3_e32 v233, v224
	v_cvt_f32_ubyte0_e32 v242, v228
	v_cvt_f32_ubyte1_e32 v243, v228
	v_cvt_f32_ubyte2_e32 v248, v228
	v_cvt_f32_ubyte3_e32 v249, v228
	v_rcp_iflag_f32_e32 v242, v242
	v_rcp_iflag_f32_e32 v243, v243
	v_rcp_iflag_f32_e32 v248, v248
	v_rcp_iflag_f32_e32 v249, v249
	v_mul_f32_e32 v230, v242, v230
	v_mul_f32_e32 v231, v243, v231
	v_mul_f32_e32 v232, v248, v232
	v_mul_f32_e32 v233, v249, v233
	v_mul_f32_e32 v6, v6, v230
	v_mul_f32_e32 v7, v7, v231
	v_mul_f32_e32 v8, v8, v232
	v_mul_f32_e32 v9, v9, v233
	v_cvt_f32_ubyte0_e32 v230, v225
	v_cvt_f32_ubyte1_e32 v231, v225
	v_cvt_f32_ubyte2_e32 v232, v225
	v_cvt_f32_ubyte3_e32 v233, v225
	v_cvt_f32_ubyte0_e32 v242, v229
	v_cvt_f32_ubyte1_e32 v243, v229
	v_cvt_f32_ubyte2_e32 v248, v229
	v_cvt_f32_ubyte3_e32 v249, v229
	v_rcp_iflag_f32_e32 v242, v242
	v_rcp_iflag_f32_e32 v243, v243
	v_rcp_iflag_f32_e32 v248, v248
	v_rcp_iflag_f32_e32 v249, v249
	v_mul_f32_e32 v230, v242, v230
	v_mul_f32_e32 v231, v243, v231
	v_mul_f32_e32 v232, v248, v232
	v_mul_f32_e32 v233, v249, v233
	v_mul_f32_e32 v2, v2, v230
	v_mul_f32_e32 v3, v3, v231
	v_mul_f32_e32 v4, v4, v232
	v_mul_f32_e32 v5, v5, v233
	s_branch .LBB0_2139

; #define PG8_STAGE(bufoff, gbase, voff) do { _Pragma("unroll") for (int _i = 0; _i < 2; ++_i) \
;         __builtin_amdgcn_global_load_lds((const unsigned*)((const char*)(gbase) + (voff)[_i]), (LAS unsigned*)(lds + (bufoff) + ldsw + _i * 8192), 16, 0, 0); } while (0)
; #define PG8_LDA(dst, b, h) do { _Pragma("unroll") for (int m = 0; m < 4; ++m) _Pragma("unroll") for (int k = 0; k < 2; ++k) dst[m][k] = *(const LAS bf16x8*)(lds + PG8_SA(b, h) + aoff + m * 2048 + k * 1024); } while (0)
; #define PG8_LDB(dst, b, h) do { _Pragma("unroll") for (int n = 0; n < 2; ++n) _Pragma("unroll") for (int k = 0; k < 2; ++k) dst[n][k] = *(const LAS bf16x8*)(lds + PG8_SB(b, h) + boff + n * 2048 + k * 1024); } while (0)
; #define PG8_MMA(ai, bj, At, Bt) do { __builtin_amdgcn_s_setprio(1); _Pragma("unroll") for (int m = 0; m < 4; ++m) _Pragma("unroll") for (int n = 0; n < 2; ++n) _Pragma("unroll") for (int k = 0; k < 2; ++k) \
;         acc[ai][bj][m][n] = __builtin_amdgcn_mfma_f32_16x16x32_bf16(Bt[n][k], At[m][k], acc[ai][bj][m][n], 0, 0, 0); __builtin_amdgcn_s_setprio(0); } while (0)
; template <class Epi, class Sched, bool ALIGN_EPI = GEMM_ALIGN, bool SP2 = GEMM_SP2>
; __device__ __forceinline__ void gemm_phase(lptr lds, const Gemm g, const Sched& S, const Epi& E) {
;     ...
;         const char* nA = has_next ? (const char*)g.A + (size_t)nxt.pm * tstepA + (size_t)nxt.acol * 2 : cA; const char* nB = has_next ? (const char*)g.Bt + (size_t)nxt.pn * tstepB : cB;
;         for (int t = 0; t < nt; t += 2) {
;             const bool last = (t == nt - 2);
;             const char* a1 = cA + (size_t)(t + 1) * kstep;
;             const char* a2 = last ? nA : cA + (size_t)(t + 2) * kstep; const char* b2 = last ? nB : cB + (size_t)(t + 2) * kstep;
;             const char* a3 = a2 + kstep; const char* b3 = b2 + kstep;
;             if constexpr (SP2) {
;             PG8_LDB(B0, 0, 0); PG8_LDB(B1, 0, 1); PG8_SCHED; PG8_LDA(At, 0, 0); PG8_STAGE(PG8_SA(1, 1), a1 + hstepA, voffA);
;             PG8_WAIT_V(8); PG8_WAIT_L(0); PG8_BAR; PG8_MMA(0, 0, At, B0); PG8_MMA(0, 1, At, B1); PG8_BAR; PG8_SCHED;
;             PG8_LDA(At, 0, 1); PG8_STAGE(PG8_SB(0, 0), b2, voffB); PG8_STAGE(PG8_SB(0, 1), b2 + hstepB, voffB); PG8_STAGE(PG8_SA(0, 0), a2, voffA);
;             PG8_WAIT_V(8); PG8_WAIT_L(0); PG8_BAR; PG8_MMA(1, 0, At, B0); PG8_MMA(1, 1, At, B1); PG8_BAR; PG8_SCHED;
.LBB0_2216:
	s_add_u32 s48, s30, 0xfffc0080
	s_addc_u32 s49, s31, -1
	s_add_i32 s67, 0, 0x10000
	s_cmp_eq_u32 s66, 12
	s_cselect_b32 s51, s25, s49
	s_cselect_b32 s50, s34, s48
	s_cselect_b32 s49, s41, s65
	s_cselect_b32 s48, s43, s64
	s_add_i32 s70, 0, 0x14000
	v_add_u32_e32 v94, s67, v179
	v_add_u32_e32 v158, s70, v179
	ds_read_b128 v[74:77], v94
	ds_read_b128 v[82:85], v94 offset:1024
	ds_read_b128 v[90:93], v94 offset:2048
	ds_read_b128 v[94:97], v94 offset:3072
	ds_read_b128 v[146:149], v158
	ds_read_b128 v[150:153], v158 offset:1024
	ds_read_b128 v[154:157], v158 offset:2048
	ds_read_b128 v[158:161], v158 offset:3072
	v_lshl_add_u64 v[176:177], s[30:31], 0, v[164:165]
	s_add_i32 m0, s29, 0xc000
	ds_read_b128 v[168:171], v181
	ds_read_b128 v[172:175], v181 offset:1024
	ds_read_b128 v[198:201], v181 offset:2048
	ds_read_b128 v[202:205], v181 offset:3072
	ds_read_b128 v[206:209], v181 offset:4096
	ds_read_b128 v[210:213], v181 offset:5120
	ds_read_b128 v[220:223], v181 offset:6144
	ds_read_b128 v[224:227], v181 offset:7168
	global_load_lds_dwordx4 v[176:177], off
	v_lshl_add_u64 v[176:177], s[30:31], 0, v[166:167]
	s_add_i32 m0, s29, 0xe000
	s_nop 0
	global_load_lds_dwordx4 v[176:177], off
	s_waitcnt vmcnt(8)
	s_waitcnt lgkmcnt(0)
	s_barrier
	s_waitcnt lgkmcnt(0)
	v_mfma_f32_16x16x32_bf16 v[142:145], v[74:77], v[168:171], v[142:145]
	v_mfma_f32_16x16x32_bf16 v[138:141], v[90:93], v[168:171], v[138:141]
	v_mfma_f32_16x16x32_bf16 v[126:129], v[74:77], v[198:201], v[126:129]
	v_mfma_f32_16x16x32_bf16 v[122:125], v[90:93], v[198:201], v[122:125]
	v_mfma_f32_16x16x32_bf16 v[110:113], v[74:77], v[206:209], v[110:113]
	v_mfma_f32_16x16x32_bf16 v[106:109], v[90:93], v[206:209], v[106:109]
	v_mfma_f32_16x16x32_bf16 v[86:89], v[74:77], v[220:223], v[86:89]
	v_mfma_f32_16x16x32_bf16 v[78:81], v[90:93], v[220:223], v[78:81]
	v_mfma_f32_16x16x32_bf16 v[142:145], v[82:85], v[172:175], v[142:145]
	v_mfma_f32_16x16x32_bf16 v[138:141], v[94:97], v[172:175], v[138:141]
	v_mfma_f32_16x16x32_bf16 v[126:129], v[82:85], v[202:205], v[126:129]
	v_mfma_f32_16x16x32_bf16 v[122:125], v[94:97], v[202:205], v[122:125]
	v_mfma_f32_16x16x32_bf16 v[110:113], v[82:85], v[210:213], v[110:113]
	v_mfma_f32_16x16x32_bf16 v[106:109], v[94:97], v[210:213], v[106:109]
	v_mfma_f32_16x16x32_bf16 v[86:89], v[82:85], v[224:227], v[86:89]
	v_mfma_f32_16x16x32_bf16 v[78:81], v[94:97], v[224:227], v[78:81]
	v_mfma_f32_16x16x32_bf16 v[134:137], v[146:149], v[168:171], v[134:137]
	v_mfma_f32_16x16x32_bf16 v[130:133], v[154:157], v[168:171], v[130:133]
	v_mfma_f32_16x16x32_bf16 v[118:121], v[146:149], v[198:201], v[118:121]
	v_mfma_f32_16x16x32_bf16 v[114:117], v[154:157], v[198:201], v[114:117]
	v_mfma_f32_16x16x32_bf16 v[102:105], v[146:149], v[206:209], v[102:105]
	v_mfma_f32_16x16x32_bf16 v[98:101], v[154:157], v[206:209], v[98:101]
	v_mfma_f32_16x16x32_bf16 v[70:73], v[146:149], v[220:223], v[70:73]
	v_mfma_f32_16x16x32_bf16 v[66:69], v[154:157], v[220:223], v[66:69]
	v_mfma_f32_16x16x32_bf16 v[134:137], v[150:153], v[172:175], v[134:137]
	v_mfma_f32_16x16x32_bf16 v[130:133], v[158:161], v[172:175], v[130:133]
	v_mfma_f32_16x16x32_bf16 v[118:121], v[150:153], v[202:205], v[118:121]
	v_mfma_f32_16x16x32_bf16 v[114:117], v[158:161], v[202:205], v[114:117]
	v_mfma_f32_16x16x32_bf16 v[102:105], v[150:153], v[210:213], v[102:105]
	v_mfma_f32_16x16x32_bf16 v[98:101], v[158:161], v[210:213], v[98:101]
	v_mfma_f32_16x16x32_bf16 v[70:73], v[150:153], v[224:227], v[70:73]
	v_mfma_f32_16x16x32_bf16 v[66:69], v[158:161], v[224:227], v[66:69]
	s_barrier
	s_add_i32 s67, s67, s54
	v_lshl_add_u64 v[176:177], s[48:49], 0, v[0:1]
	s_mov_b32 m0, s67
	ds_read_b128 v[168:171], v181 offset:16384
	ds_read_b128 v[172:175], v181 offset:17408
	ds_read_b128 v[198:201], v181 offset:18432
	ds_read_b128 v[202:205], v181 offset:19456
	ds_read_b128 v[206:209], v181 offset:20480
	ds_read_b128 v[210:213], v181 offset:21504
	ds_read_b128 v[220:223], v181 offset:22528
	ds_read_b128 v[224:227], v181 offset:23552
	global_load_lds_dwordx4 v[176:177], off
	s_add_i32 m0, s67, 0x2000
	s_add_u32 s68, s48, 0x40000
	v_lshl_add_u64 v[182:183], s[48:49], 0, v[162:163]
	s_addc_u32 s69, s49, 0
	s_add_i32 s67, s70, s54
	global_load_lds_dwordx4 v[182:183], off
	v_lshl_add_u64 v[214:215], s[68:69], 0, v[0:1]
	s_mov_b32 m0, s67
	v_lshl_add_u64 v[228:229], s[50:51], 0, v[162:163]
	global_load_lds_dwordx4 v[214:215], off
	v_lshl_add_u64 v[214:215], s[68:69], 0, v[162:163]
	s_add_i32 m0, s67, 0x2000
	s_nop 0
	global_load_lds_dwordx4 v[214:215], off
	v_lshl_add_u64 v[214:215], s[50:51], 0, v[0:1]
	s_mov_b32 m0, s29
	s_nop 0
	global_load_lds_dwordx4 v[214:215], off
	s_mov_b32 m0, s55
	s_nop 0
	global_load_lds_dwordx4 v[228:229], off
	s_waitcnt vmcnt(8)
	s_waitcnt lgkmcnt(0)
	s_barrier
; #define PG8_STAGE(bufoff, gbase, voff) do { _Pragma("unroll") for (int _i = 0; _i < 2; ++_i) \
;         __builtin_amdgcn_global_load_lds((const unsigned*)((const char*)(gbase) + (voff)[_i]), (LAS unsigned*)(lds + (bufoff) + ldsw + _i * 8192), 16, 0, 0); } while (0)
; #define PG8_LDA(dst, b, h) do { _Pragma("unroll") for (int m = 0; m < 4; ++m) _Pragma("unroll") for (int k = 0; k < 2; ++k) dst[m][k] = *(const LAS bf16x8*)(lds + PG8_SA(b, h) + aoff + m * 2048 + k * 1024); } while (0)
; #define PG8_LDB(dst, b, h) do { _Pragma("unroll") for (int n = 0; n < 2; ++n) _Pragma("unroll") for (int k = 0; k < 2; ++k) dst[n][k] = *(const LAS bf16x8*)(lds + PG8_SB(b, h) + boff + n * 2048 + k * 1024); } while (0)
; #define PG8_MMA(ai, bj, At, Bt) do { __builtin_amdgcn_s_setprio(1); _Pragma("unroll") for (int m = 0; m < 4; ++m) _Pragma("unroll") for (int n = 0; n < 2; ++n) _Pragma("unroll") for (int k = 0; k < 2; ++k) \
;         acc[ai][bj][m][n] = __builtin_amdgcn_mfma_f32_16x16x32_bf16(Bt[n][k], At[m][k], acc[ai][bj][m][n], 0, 0, 0); __builtin_amdgcn_s_setprio(0); } while (0)
; #define PG8_WAIT_V(n) asm volatile("s_waitcnt vmcnt(" #n ")" ::: "memory")
; #define PG8_WAIT_L(n) asm volatile("s_waitcnt lgkmcnt(" #n ")" ::: "memory")
; #define PG8_BAR __builtin_amdgcn_s_barrier()
; #define PG8_SCHED __builtin_amdgcn_sched_barrier(0)
; template <class Epi, class Sched, bool ALIGN_EPI = GEMM_ALIGN, bool SP2 = GEMM_SP2>
; __device__ __forceinline__ void gemm_phase(lptr lds, const Gemm g, const Sched& S, const Epi& E) {
;     ...
;             PG8_WAIT_V(8); PG8_WAIT_L(0); PG8_BAR; PG8_MMA(1, 0, At, B0); PG8_MMA(1, 1, At, B1); PG8_BAR; PG8_SCHED;
;             PG8_LDB(B0, 1, 0); PG8_LDB(B1, 1, 1); PG8_SCHED; PG8_LDA(At, 1, 0); PG8_STAGE(PG8_SA(0, 1), a2 + hstepA, voffA);
;             PG8_WAIT_V(8); PG8_WAIT_L(0); PG8_BAR; PG8_MMA(0, 0, At, B0); PG8_MMA(0, 1, At, B1); PG8_BAR; PG8_SCHED;
;             PG8_LDA(At, 1, 1); PG8_STAGE(PG8_SB(1, 0), b3, voffB); PG8_STAGE(PG8_SB(1, 1), b3 + hstepB, voffB); PG8_STAGE(PG8_SA(1, 0), a3, voffA);
	s_waitcnt lgkmcnt(0)
	v_mfma_f32_16x16x32_bf16 v[62:65], v[74:77], v[168:171], v[62:65]
	v_mfma_f32_16x16x32_bf16 v[58:61], v[90:93], v[168:171], v[58:61]
	v_mfma_f32_16x16x32_bf16 v[46:49], v[74:77], v[198:201], v[46:49]
	v_mfma_f32_16x16x32_bf16 v[42:45], v[90:93], v[198:201], v[42:45]
	v_mfma_f32_16x16x32_bf16 v[30:33], v[74:77], v[206:209], v[30:33]
	v_mfma_f32_16x16x32_bf16 v[26:29], v[90:93], v[206:209], v[26:29]
	v_mfma_f32_16x16x32_bf16 v[14:17], v[74:77], v[220:223], v[14:17]
	v_mfma_f32_16x16x32_bf16 v[10:13], v[90:93], v[220:223], v[10:13]
	v_mfma_f32_16x16x32_bf16 v[62:65], v[82:85], v[172:175], v[62:65]
	v_mfma_f32_16x16x32_bf16 v[58:61], v[94:97], v[172:175], v[58:61]
	v_mfma_f32_16x16x32_bf16 v[46:49], v[82:85], v[202:205], v[46:49]
	v_mfma_f32_16x16x32_bf16 v[42:45], v[94:97], v[202:205], v[42:45]
	v_mfma_f32_16x16x32_bf16 v[30:33], v[82:85], v[210:213], v[30:33]
	v_mfma_f32_16x16x32_bf16 v[26:29], v[94:97], v[210:213], v[26:29]
	v_mfma_f32_16x16x32_bf16 v[14:17], v[82:85], v[224:227], v[14:17]
	v_mfma_f32_16x16x32_bf16 v[10:13], v[94:97], v[224:227], v[10:13]
	v_mfma_f32_16x16x32_bf16 v[54:57], v[146:149], v[168:171], v[54:57]
	v_mfma_f32_16x16x32_bf16 v[50:53], v[154:157], v[168:171], v[50:53]
	v_mfma_f32_16x16x32_bf16 v[38:41], v[146:149], v[198:201], v[38:41]
	v_mfma_f32_16x16x32_bf16 v[34:37], v[154:157], v[198:201], v[34:37]
	v_mfma_f32_16x16x32_bf16 v[22:25], v[146:149], v[206:209], v[22:25]
	v_mfma_f32_16x16x32_bf16 v[18:21], v[154:157], v[206:209], v[18:21]
	v_mfma_f32_16x16x32_bf16 v[6:9], v[146:149], v[220:223], v[6:9]
	v_mfma_f32_16x16x32_bf16 v[2:5], v[154:157], v[220:223], v[2:5]
	v_mfma_f32_16x16x32_bf16 v[54:57], v[150:153], v[172:175], v[54:57]
	v_mfma_f32_16x16x32_bf16 v[50:53], v[158:161], v[172:175], v[50:53]
	v_mfma_f32_16x16x32_bf16 v[38:41], v[150:153], v[202:205], v[38:41]
	v_mfma_f32_16x16x32_bf16 v[34:37], v[158:161], v[202:205], v[34:37]
	v_mfma_f32_16x16x32_bf16 v[22:25], v[150:153], v[210:213], v[22:25]
	v_mfma_f32_16x16x32_bf16 v[18:21], v[158:161], v[210:213], v[18:21]
	v_mfma_f32_16x16x32_bf16 v[6:9], v[150:153], v[224:227], v[6:9]
	v_mfma_f32_16x16x32_bf16 v[2:5], v[158:161], v[224:227], v[2:5]
	s_barrier
	s_add_i32 s67, 0, 0x18000
	s_add_i32 s68, 0, 0x1c000
	v_add_u32_e32 v94, s67, v179
	v_add_u32_e32 v158, s68, v179
	ds_read_b128 v[74:77], v94
	ds_read_b128 v[82:85], v94 offset:1024
	ds_read_b128 v[90:93], v94 offset:2048
	ds_read_b128 v[94:97], v94 offset:3072
	ds_read_b128 v[146:149], v158
	ds_read_b128 v[150:153], v158 offset:1024
	ds_read_b128 v[154:157], v158 offset:2048
	ds_read_b128 v[158:161], v158 offset:3072
	s_add_u32 s50, s50, 0x40000
	s_addc_u32 s51, s51, 0
	s_mov_b32 m0, s56
	v_lshl_add_u64 v[230:231], s[50:51], 0, v[0:1]
	ds_read_b128 v[168:171], v181 offset:32768
	ds_read_b128 v[172:175], v181 offset:33792
	ds_read_b128 v[198:201], v181 offset:34816
	ds_read_b128 v[202:205], v181 offset:35840
	ds_read_b128 v[206:209], v181 offset:36864
	ds_read_b128 v[210:213], v181 offset:37888
	ds_read_b128 v[220:223], v181 offset:38912
	ds_read_b128 v[224:227], v181 offset:39936
	global_load_lds_dwordx4 v[230:231], off
	v_lshl_add_u64 v[230:231], s[50:51], 0, v[162:163]
	s_mov_b32 m0, s57
	s_nop 0
	global_load_lds_dwordx4 v[230:231], off
	s_waitcnt vmcnt(8)
	s_waitcnt lgkmcnt(0)
	s_barrier
	s_waitcnt lgkmcnt(0)
	v_mfma_f32_16x16x32_bf16 v[142:145], v[74:77], v[168:171], v[142:145]
	v_mfma_f32_16x16x32_bf16 v[138:141], v[90:93], v[168:171], v[138:141]
	v_mfma_f32_16x16x32_bf16 v[126:129], v[74:77], v[198:201], v[126:129]
	v_mfma_f32_16x16x32_bf16 v[122:125], v[90:93], v[198:201], v[122:125]
	v_mfma_f32_16x16x32_bf16 v[110:113], v[74:77], v[206:209], v[110:113]
	v_mfma_f32_16x16x32_bf16 v[106:109], v[90:93], v[206:209], v[106:109]
	v_mfma_f32_16x16x32_bf16 v[86:89], v[74:77], v[220:223], v[86:89]
	v_mfma_f32_16x16x32_bf16 v[78:81], v[90:93], v[220:223], v[78:81]
	v_mfma_f32_16x16x32_bf16 v[142:145], v[82:85], v[172:175], v[142:145]
	v_mfma_f32_16x16x32_bf16 v[138:141], v[94:97], v[172:175], v[138:141]
	v_mfma_f32_16x16x32_bf16 v[126:129], v[82:85], v[202:205], v[126:129]
	v_mfma_f32_16x16x32_bf16 v[122:125], v[94:97], v[202:205], v[122:125]
	v_mfma_f32_16x16x32_bf16 v[110:113], v[82:85], v[210:213], v[110:113]
	v_mfma_f32_16x16x32_bf16 v[106:109], v[94:97], v[210:213], v[106:109]
	v_mfma_f32_16x16x32_bf16 v[86:89], v[82:85], v[224:227], v[86:89]
	v_mfma_f32_16x16x32_bf16 v[78:81], v[94:97], v[224:227], v[78:81]
	v_mfma_f32_16x16x32_bf16 v[134:137], v[146:149], v[168:171], v[134:137]
	v_mfma_f32_16x16x32_bf16 v[130:133], v[154:157], v[168:171], v[130:133]
	v_mfma_f32_16x16x32_bf16 v[118:121], v[146:149], v[198:201], v[118:121]
	v_mfma_f32_16x16x32_bf16 v[114:117], v[154:157], v[198:201], v[114:117]
	v_mfma_f32_16x16x32_bf16 v[102:105], v[146:149], v[206:209], v[102:105]
	v_mfma_f32_16x16x32_bf16 v[98:101], v[154:157], v[206:209], v[98:101]
	v_mfma_f32_16x16x32_bf16 v[70:73], v[146:149], v[220:223], v[70:73]
	v_mfma_f32_16x16x32_bf16 v[66:69], v[154:157], v[220:223], v[66:69]
	v_mfma_f32_16x16x32_bf16 v[134:137], v[150:153], v[172:175], v[134:137]
	v_mfma_f32_16x16x32_bf16 v[130:133], v[158:161], v[172:175], v[130:133]
	v_mfma_f32_16x16x32_bf16 v[118:121], v[150:153], v[202:205], v[118:121]
	v_mfma_f32_16x16x32_bf16 v[114:117], v[158:161], v[202:205], v[114:117]
	v_mfma_f32_16x16x32_bf16 v[102:105], v[150:153], v[210:213], v[102:105]
	v_mfma_f32_16x16x32_bf16 v[98:101], v[158:161], v[210:213], v[98:101]
	v_mfma_f32_16x16x32_bf16 v[70:73], v[150:153], v[224:227], v[70:73]
	v_mfma_f32_16x16x32_bf16 v[66:69], v[158:161], v[224:227], v[66:69]
	s_barrier
; #define PG8_STAGE(bufoff, gbase, voff) do { _Pragma("unroll") for (int _i = 0; _i < 2; ++_i) \
;         __builtin_amdgcn_global_load_lds((const unsigned*)((const char*)(gbase) + (voff)[_i]), (LAS unsigned*)(lds + (bufoff) + ldsw + _i * 8192), 16, 0, 0); } while (0)
; #define PG8_LDA(dst, b, h) do { _Pragma("unroll") for (int m = 0; m < 4; ++m) _Pragma("unroll") for (int k = 0; k < 2; ++k) dst[m][k] = *(const LAS bf16x8*)(lds + PG8_SA(b, h) + aoff + m * 2048 + k * 1024); } while (0)
; #define PG8_MMA(ai, bj, At, Bt) do { __builtin_amdgcn_s_setprio(1); _Pragma("unroll") for (int m = 0; m < 4; ++m) _Pragma("unroll") for (int n = 0; n < 2; ++n) _Pragma("unroll") for (int k = 0; k < 2; ++k) \
;         acc[ai][bj][m][n] = __builtin_amdgcn_mfma_f32_16x16x32_bf16(Bt[n][k], At[m][k], acc[ai][bj][m][n], 0, 0, 0); __builtin_amdgcn_s_setprio(0); } while (0)
; #define PG8_WAIT_V(n) asm volatile("s_waitcnt vmcnt(" #n ")" ::: "memory")
; #define PG8_WAIT_L(n) asm volatile("s_waitcnt lgkmcnt(" #n ")" ::: "memory")
; #define PG8_BAR __builtin_amdgcn_s_barrier()
; #define PG8_SCHED __builtin_amdgcn_sched_barrier(0)
; template <class Epi, class Sched, bool ALIGN_EPI = GEMM_ALIGN, bool SP2 = GEMM_SP2>
; __device__ __forceinline__ void gemm_phase(lptr lds, const Gemm g, const Sched& S, const Epi& E) {
;     ...
;             PG8_LDA(At, 1, 1); PG8_STAGE(PG8_SB(1, 0), b3, voffB); PG8_STAGE(PG8_SB(1, 1), b3 + hstepB, voffB); PG8_STAGE(PG8_SA(1, 0), a3, voffA);
;             PG8_WAIT_V(8); PG8_WAIT_L(0); PG8_BAR; PG8_MMA(1, 0, At, B0); PG8_MMA(1, 1, At, B1); PG8_BAR; PG8_SCHED;
;     ...
;         if constexpr (ALIGN_EPI) { if (wr == 0) PG8_BAR; }
	s_add_i32 s50, s67, s54
	v_lshl_add_u64 v[176:177], v[176:177], 0, s[6:7]
	s_mov_b32 m0, s50
	ds_read_b128 v[168:171], v181 offset:49152
	ds_read_b128 v[172:175], v181 offset:50176
	ds_read_b128 v[198:201], v181 offset:51200
	ds_read_b128 v[202:205], v181 offset:52224
	ds_read_b128 v[206:209], v181 offset:53248
	ds_read_b128 v[210:213], v181 offset:54272
	ds_read_b128 v[220:223], v181 offset:55296
	ds_read_b128 v[224:227], v181 offset:56320
	global_load_lds_dwordx4 v[176:177], off
	s_add_i32 m0, s50, 0x2000
	s_add_u32 s48, s48, 0x40080
	v_lshl_add_u64 v[176:177], v[182:183], 0, s[6:7]
	s_addc_u32 s49, s49, 0
	s_add_i32 s50, s68, s54
	global_load_lds_dwordx4 v[176:177], off
	v_lshl_add_u64 v[176:177], s[48:49], 0, v[0:1]
	s_mov_b32 m0, s50
	s_nop 0
	global_load_lds_dwordx4 v[176:177], off
	v_lshl_add_u64 v[176:177], s[48:49], 0, v[162:163]
	s_add_i32 m0, s50, 0x2000
	s_nop 0
	global_load_lds_dwordx4 v[176:177], off
	v_lshl_add_u64 v[176:177], v[214:215], 0, s[6:7]
	s_mov_b32 m0, s59
	s_nop 0
	global_load_lds_dwordx4 v[176:177], off
	v_lshl_add_u64 v[176:177], v[228:229], 0, s[6:7]
	s_mov_b32 m0, s60
	s_nop 0
	global_load_lds_dwordx4 v[176:177], off
	s_waitcnt vmcnt(8)
	s_waitcnt lgkmcnt(0)
	s_barrier
	s_waitcnt lgkmcnt(0)
	v_mfma_f32_16x16x32_bf16 v[62:65], v[74:77], v[168:171], v[62:65]
	v_mfma_f32_16x16x32_bf16 v[58:61], v[90:93], v[168:171], v[58:61]
	v_mfma_f32_16x16x32_bf16 v[46:49], v[74:77], v[198:201], v[46:49]
	v_mfma_f32_16x16x32_bf16 v[42:45], v[90:93], v[198:201], v[42:45]
	v_mfma_f32_16x16x32_bf16 v[30:33], v[74:77], v[206:209], v[30:33]
	v_mfma_f32_16x16x32_bf16 v[26:29], v[90:93], v[206:209], v[26:29]
	v_mfma_f32_16x16x32_bf16 v[14:17], v[74:77], v[220:223], v[14:17]
	v_mfma_f32_16x16x32_bf16 v[10:13], v[90:93], v[220:223], v[10:13]
	v_mfma_f32_16x16x32_bf16 v[62:65], v[82:85], v[172:175], v[62:65]
	v_mfma_f32_16x16x32_bf16 v[58:61], v[94:97], v[172:175], v[58:61]
	v_mfma_f32_16x16x32_bf16 v[46:49], v[82:85], v[202:205], v[46:49]
	v_mfma_f32_16x16x32_bf16 v[42:45], v[94:97], v[202:205], v[42:45]
	v_mfma_f32_16x16x32_bf16 v[30:33], v[82:85], v[210:213], v[30:33]
	v_mfma_f32_16x16x32_bf16 v[26:29], v[94:97], v[210:213], v[26:29]
	v_mfma_f32_16x16x32_bf16 v[14:17], v[82:85], v[224:227], v[14:17]
	v_mfma_f32_16x16x32_bf16 v[10:13], v[94:97], v[224:227], v[10:13]
	v_mfma_f32_16x16x32_bf16 v[54:57], v[146:149], v[168:171], v[54:57]
	v_mfma_f32_16x16x32_bf16 v[50:53], v[154:157], v[168:171], v[50:53]
	v_mfma_f32_16x16x32_bf16 v[38:41], v[146:149], v[198:201], v[38:41]
	v_mfma_f32_16x16x32_bf16 v[34:37], v[154:157], v[198:201], v[34:37]
	v_mfma_f32_16x16x32_bf16 v[22:25], v[146:149], v[206:209], v[22:25]
	v_mfma_f32_16x16x32_bf16 v[18:21], v[154:157], v[206:209], v[18:21]
	v_mfma_f32_16x16x32_bf16 v[6:9], v[146:149], v[220:223], v[6:9]
	v_mfma_f32_16x16x32_bf16 v[2:5], v[154:157], v[220:223], v[2:5]
	v_mfma_f32_16x16x32_bf16 v[54:57], v[150:153], v[172:175], v[54:57]
	v_mfma_f32_16x16x32_bf16 v[50:53], v[158:161], v[172:175], v[50:53]
	v_mfma_f32_16x16x32_bf16 v[38:41], v[150:153], v[202:205], v[38:41]
	v_mfma_f32_16x16x32_bf16 v[34:37], v[158:161], v[202:205], v[34:37]
	v_mfma_f32_16x16x32_bf16 v[22:25], v[150:153], v[210:213], v[22:25]
	v_mfma_f32_16x16x32_bf16 v[18:21], v[158:161], v[210:213], v[18:21]
	v_mfma_f32_16x16x32_bf16 v[6:9], v[150:153], v[224:227], v[6:9]
	v_mfma_f32_16x16x32_bf16 v[2:5], v[158:161], v[224:227], v[2:5]
	s_barrier
	s_add_i32 s66, s66, 2
	s_add_u32 s30, s30, 0x100
	s_addc_u32 s31, s31, 0
	s_add_u32 s64, s64, 0x100
	s_addc_u32 s65, s65, 0
	s_cmp_gt_u32 s66, 13
	s_cbranch_scc0 .LBB0_2216
	s_and_b64 vcc, exec, s[26:27]
	s_cbranch_vccz .LBB0_2219
	s_barrier
; __device__ __forceinline__ unsigned pk2(float lo, float hi) { const f32x2 v = {lo, hi}; const bf16x2_t b = __builtin_convertvector(v, bf16x2_t); return __builtin_bit_cast(unsigned, b); }
;     __device__ __forceinline__ void operator()(const f32x4 (&acc)[2][2][4][2], const Unit& u, int wr, int wc, int fr, int fq) const {
;         const int row0 = u.pm * BM + wr * 64 + fr, col0 = u.pn * BM + wc * 32 + 4 * fq;
;         f32x4 gv[2][2];
; #pragma unroll
;         for (int bj = 0; bj < 2; ++bj)
; #pragma unroll
;             for (int n = 0; n < 2; ++n) gv[bj][n] = *(const f32x4*)(gnext + col0 + bj * HALF + n * 16);
; #pragma unroll
;         for (int ai = 0; ai < 2; ++ai)
; #pragma unroll
;             for (int mp = 0; mp < 2; ++mp) { f32x4 xv[2][2][2];
; #pragma unroll
;                 for (int mm = 0; mm < 2; ++mm)
; #pragma unroll
;                     for (int bj = 0; bj < 2; ++bj)
; #pragma unroll
;                         for (int n = 0; n < 2; ++n) xv[mm][bj][n] = *(const f32x4*)(xin + (size_t)(row0 + ai * HALF + (mp * 2 + mm) * 16) * DM + col0 + bj * HALF + n * 16);
; #pragma unroll
;                 for (int mm = 0; mm < 2; ++mm) { const int m = mp * 2 + mm; const int row = row0 + ai * HALF + m * 16; const size_t off = (size_t)row * DM + col0; float ss = 0.f;
; #pragma unroll
;                     for (int bj = 0; bj < 2; ++bj)
; #pragma unroll
;                         for (int n = 0; n < 2; ++n) { const f32x4 v = xv[mm][bj][n] + acc[ai][bj][m][n] * scale; *(f32x4*)(out + off + bj * HALF + n * 16) = v;
;                             if (xq) { ss += (v[0] * v[0] + v[1] * v[1]) + (v[2] * v[2] + v[3] * v[3]); const f32x4 q = v * gv[bj][n]; u32x2 w; w.x = pk2(q[0], q[1]); w.y = pk2(q[2], q[3]); *(u32x2*)(xq + off + bj * HALF + n * 16) = w; } }
;                     if (xq) { ss += __shfl_xor(ss, 16); ss += __shfl_xor(ss, 32); if (fq == 0) rowsq[(size_t)row * 16 + u.pn * 4 + wc] = ss; } } }
.LBB0_2219:
	s_setprio 0
	v_lshl_or_b32 v168, s28, 8, v180
	v_ashrrev_i32_e32 v169, 31, v168
	v_lshl_add_u32 v170, s24, 8, v178
	v_lshlrev_b64 v[146:147], 2, v[168:169]
	v_ashrrev_i32_e32 v171, 31, v170
	v_lshl_add_u64 v[74:75], s[2:3], 0, v[146:147]
	v_lshl_add_u64 v[172:173], s[86:87], 0, v[146:147]
	v_lshlrev_b64 v[146:147], 12, v[170:171]
	v_lshl_add_u64 v[182:183], v[172:173], 0, v[146:147]
	global_load_dwordx4 v[94:97], v[74:75], off
	global_load_dwordx4 v[90:93], v[74:75], off offset:64
	global_load_dwordx4 v[82:85], v[74:75], off offset:512
	s_nop 0
	global_load_dwordx4 v[74:77], v[74:75], off offset:576
	s_nop 0
	global_load_dwordx4 v[198:201], v[182:183], off
	global_load_dwordx4 v[202:205], v[182:183], off offset:64
	global_load_dwordx4 v[206:209], v[182:183], off offset:512
	global_load_dwordx4 v[210:213], v[182:183], off offset:576
	v_or_b32_e32 v174, 16, v170
	v_ashrrev_i32_e32 v175, 31, v174
	v_lshlrev_b64 v[146:147], 12, v[174:175]
	v_lshl_add_u64 v[176:177], v[172:173], 0, v[146:147]
	global_load_dwordx4 v[158:161], v[176:177], off
	global_load_dwordx4 v[154:157], v[176:177], off offset:64
	global_load_dwordx4 v[150:153], v[176:177], off offset:512
	global_load_dwordx4 v[146:149], v[176:177], off offset:576
	v_lshlrev_b64 v[214:215], 10, v[170:171]
	v_readlane_b32 s24, v251, 32
	v_lshl_add_u64 v[214:215], v[214:215], 0, v[168:169]
	v_readlane_b32 s25, v251, 33
	s_lshl_b32 s30, s28, 2
	s_ashr_i32 s31, s30, 31
	s_waitcnt vmcnt(0)
	v_pk_add_f32 v[144:145], v[144:145], v[200:201]
	v_pk_add_f32 v[142:143], v[142:143], v[198:199]
	v_mul_f32_e32 v198, v145, v145
	v_mul_f32_e32 v197, v143, v143
	global_store_dwordx4 v[182:183], v[142:145], off
	v_fmac_f32_e32 v197, v142, v142
	v_fmac_f32_e32 v198, v144, v144
	v_pk_mul_f32 v[144:145], v[96:97], v[144:145]
	v_pk_mul_f32 v[142:143], v[94:95], v[142:143]
	v_pk_add_f32 v[140:141], v[140:141], v[204:205]
	v_cvt_pk_bf16_f32 v142, v142, v143
	v_cvt_pk_bf16_f32 v143, v144, v145
	v_lshl_add_u64 v[144:145], v[214:215], 1, s[24:25]
	v_pk_add_f32 v[138:139], v[138:139], v[202:203]
	global_store_dwordx2 v[144:145], v[142:143], off
	v_mul_f32_e32 v142, v139, v139
	v_mul_f32_e32 v143, v141, v141
	global_store_dwordx4 v[182:183], v[138:141], off offset:64
	v_fmac_f32_e32 v142, v138, v138
	v_fmac_f32_e32 v143, v140, v140
	v_pk_mul_f32 v[140:141], v[92:93], v[140:141]
	v_pk_mul_f32 v[138:139], v[90:91], v[138:139]
	v_pk_add_f32 v[136:137], v[136:137], v[208:209]
	v_cvt_pk_bf16_f32 v138, v138, v139
	v_cvt_pk_bf16_f32 v139, v140, v141
	v_pk_add_f32 v[134:135], v[134:135], v[206:207]
	global_store_dwordx2 v[144:145], v[138:139], off offset:32
	v_mul_f32_e32 v138, v135, v135
	v_mul_f32_e32 v139, v137, v137
	global_store_dwordx4 v[182:183], v[134:137], off offset:512
	v_fmac_f32_e32 v138, v134, v134
	v_fmac_f32_e32 v139, v136, v136
	v_pk_mul_f32 v[136:137], v[84:85], v[136:137]
	v_pk_mul_f32 v[134:135], v[82:83], v[134:135]
	v_pk_add_f32 v[132:133], v[132:133], v[212:213]
	v_cvt_pk_bf16_f32 v134, v134, v135
	v_cvt_pk_bf16_f32 v135, v136, v137
	v_pk_add_f32 v[130:131], v[130:131], v[210:211]
	global_store_dwordx2 v[144:145], v[134:135], off offset:256
	global_store_dwordx4 v[182:183], v[130:133], off offset:576
	v_pk_mul_f32 v[136:137], v[74:75], v[130:131]
	v_pk_mul_f32 v[134:135], v[76:77], v[132:133]
	v_mul_f32_e32 v131, v131, v131
	v_fmac_f32_e32 v131, v130, v130
	v_mul_f32_e32 v130, v133, v133
	v_fmac_f32_e32 v130, v132, v132
	v_and_b32_e32 v132, 64, v234
	v_add_f32_e32 v197, v197, v198
	v_add_f32_e32 v142, v142, v143
	v_add_f32_e32 v130, v131, v130
	v_xor_b32_e32 v131, 16, v234
	v_add_u32_e32 v132, 64, v132
	v_add_f32_e32 v142, v197, v142
	v_add_f32_e32 v138, v138, v139
	v_cmp_lt_i32_e32 vcc, v131, v132
	v_add_f32_e32 v138, v142, v138
	v_cvt_pk_bf16_f32 v136, v136, v137
	v_cvt_pk_bf16_f32 v137, v134, v135
	v_cndmask_b32_e32 v131, v234, v131, vcc
	global_store_dwordx2 v[144:145], v[136:137], off offset:288
	v_add_f32_e32 v130, v138, v130
	v_lshlrev_b32_e32 v136, 2, v131
	ds_bpermute_b32 v131, v136, v130
	s_waitcnt lgkmcnt(0)
	v_add_f32_e32 v130, v130, v131
	v_xor_b32_e32 v131, 32, v234
	v_cmp_lt_i32_e32 vcc, v131, v132
	s_nop 1
	v_cndmask_b32_e32 v131, v234, v131, vcc
	v_lshlrev_b32_e32 v137, 2, v131
	ds_bpermute_b32 v131, v137, v130
	s_and_saveexec_b64 s[24:25], s[36:37]
	s_mov_b64 s[64:65], s[88:89]
	s_cbranch_execz .LBB0_2221
	v_readlane_b32 s48, v251, 44
	v_lshlrev_b64 v[132:133], 6, v[170:171]
	v_readlane_b32 s49, v251, 45
	s_lshl_b32 s34, s58, 2
	s_waitcnt lgkmcnt(0)
	v_add_f32_e32 v130, v130, v131
	v_lshl_add_u64 v[132:133], s[48:49], 0, v[132:133]
	v_lshl_add_u64 v[132:133], s[30:31], 2, v[132:133]
	v_lshl_add_u64 v[132:133], v[132:133], 0, s[34:35]
	global_store_dword v[132:133], v130, off

; #define PG8_STAGE(bufoff, gbase, voff) do { _Pragma("unroll") for (int _i = 0; _i < 2; ++_i) \
;         __builtin_amdgcn_global_load_lds((const unsigned*)((const char*)(gbase) + (voff)[_i]), (LAS unsigned*)(lds + (bufoff) + ldsw + _i * 8192), 16, 0, 0); } while (0)
; #define PG8_LDA(dst, b, h) do { _Pragma("unroll") for (int m = 0; m < 4; ++m) _Pragma("unroll") for (int k = 0; k < 2; ++k) dst[m][k] = *(const LAS bf16x8*)(lds + PG8_SA(b, h) + aoff + m * 2048 + k * 1024); } while (0)
; #define PG8_LDB(dst, b, h) do { _Pragma("unroll") for (int n = 0; n < 2; ++n) _Pragma("unroll") for (int k = 0; k < 2; ++k) dst[n][k] = *(const LAS bf16x8*)(lds + PG8_SB(b, h) + boff + n * 2048 + k * 1024); } while (0)
; #define PG8_MMA(ai, bj, At, Bt) do { __builtin_amdgcn_s_setprio(1); _Pragma("unroll") for (int m = 0; m < 4; ++m) _Pragma("unroll") for (int n = 0; n < 2; ++n) _Pragma("unroll") for (int k = 0; k < 2; ++k) \
;         acc[ai][bj][m][n] = __builtin_amdgcn_mfma_f32_16x16x32_bf16(Bt[n][k], At[m][k], acc[ai][bj][m][n], 0, 0, 0); __builtin_amdgcn_s_setprio(0); } while (0)
; template <class Epi, class Sched, bool ALIGN_EPI = GEMM_ALIGN, bool SP2 = GEMM_SP2>
; __device__ __forceinline__ void gemm_phase(lptr lds, const Gemm g, const Sched& S, const Epi& E) {
;     ...
;         const char* nA = has_next ? (const char*)g.A + (size_t)nxt.pm * tstepA + (size_t)nxt.acol * 2 : cA; const char* nB = has_next ? (const char*)g.Bt + (size_t)nxt.pn * tstepB : cB;
;         for (int t = 0; t < nt; t += 2) {
;             const bool last = (t == nt - 2);
;             const char* a1 = cA + (size_t)(t + 1) * kstep;
;             const char* a2 = last ? nA : cA + (size_t)(t + 2) * kstep; const char* b2 = last ? nB : cB + (size_t)(t + 2) * kstep;
;             const char* a3 = a2 + kstep; const char* b3 = b2 + kstep;
;             if constexpr (SP2) {
;             PG8_LDB(B0, 0, 0); PG8_LDB(B1, 0, 1); PG8_SCHED; PG8_LDA(At, 0, 0); PG8_STAGE(PG8_SA(1, 1), a1 + hstepA, voffA);
;             PG8_WAIT_V(8); PG8_WAIT_L(0); PG8_BAR; PG8_MMA(0, 0, At, B0); PG8_MMA(0, 1, At, B1); PG8_BAR; PG8_SCHED;
;             PG8_LDA(At, 0, 1); PG8_STAGE(PG8_SB(0, 0), b2, voffB); PG8_STAGE(PG8_SB(0, 1), b2 + hstepB, voffB); PG8_STAGE(PG8_SA(0, 0), a2, voffA);
;             PG8_WAIT_V(8); PG8_WAIT_L(0); PG8_BAR; PG8_MMA(1, 0, At, B0); PG8_MMA(1, 1, At, B1); PG8_BAR; PG8_SCHED;
.LBB0_2336:
	s_add_u32 s30, s28, 0xfffc0080
	s_addc_u32 s31, s29, -1
	s_add_i32 s64, 0, 0x10000
	s_cmp_eq_u32 s63, 12
	s_cselect_b32 s45, s39, s31
	s_cselect_b32 s44, s59, s30
	v_add_u32_e32 v144, s64, v147
	s_cselect_b32 s31, s27, s62
	s_cselect_b32 s30, s60, s61
	s_add_i32 s66, 0, 0x14000
	ds_read_b128 v[140:143], v144
	ds_read_b128 v[152:155], v144 offset:1024
	ds_read_b128 v[156:159], v144 offset:2048
	ds_read_b128 v[160:163], v144 offset:3072
	v_add_u32_e32 v144, s66, v147
	ds_read_b128 v[164:167], v144
	ds_read_b128 v[168:171], v144 offset:1024
	ds_read_b128 v[172:175], v144 offset:2048
	ds_read_b128 v[176:179], v144 offset:3072
	v_lshl_add_u64 v[144:145], s[28:29], 0, v[136:137]
	s_add_i32 m0, s50, 0xc000
	ds_read_b128 v[180:183], v150
	ds_read_b128 v[198:201], v150 offset:1024
	ds_read_b128 v[202:205], v150 offset:2048
	ds_read_b128 v[206:209], v150 offset:3072
	ds_read_b128 v[210:213], v150 offset:4096
	ds_read_b128 v[220:223], v150 offset:5120
	ds_read_b128 v[224:227], v150 offset:6144
	ds_read_b128 v[228:231], v150 offset:7168
	global_load_lds_dwordx4 v[144:145], off
	v_lshl_add_u64 v[144:145], s[28:29], 0, v[138:139]
	s_add_i32 m0, s50, 0xe000
	s_nop 0
	global_load_lds_dwordx4 v[144:145], off
	s_waitcnt vmcnt(8)
	s_waitcnt lgkmcnt(0)
	s_barrier
	s_waitcnt lgkmcnt(0)
	v_mfma_f32_16x16x32_bf16 v[126:129], v[140:143], v[180:183], v[126:129]
	v_mfma_f32_16x16x32_bf16 v[118:121], v[156:159], v[180:183], v[118:121]
	v_mfma_f32_16x16x32_bf16 v[110:113], v[140:143], v[202:205], v[110:113]
	v_mfma_f32_16x16x32_bf16 v[102:105], v[156:159], v[202:205], v[102:105]
	v_mfma_f32_16x16x32_bf16 v[94:97], v[140:143], v[210:213], v[94:97]
	v_mfma_f32_16x16x32_bf16 v[86:89], v[156:159], v[210:213], v[86:89]
	v_mfma_f32_16x16x32_bf16 v[78:81], v[140:143], v[224:227], v[78:81]
	v_mfma_f32_16x16x32_bf16 v[70:73], v[156:159], v[224:227], v[70:73]
	v_mfma_f32_16x16x32_bf16 v[126:129], v[152:155], v[198:201], v[126:129]
	v_mfma_f32_16x16x32_bf16 v[118:121], v[160:163], v[198:201], v[118:121]
	v_mfma_f32_16x16x32_bf16 v[110:113], v[152:155], v[206:209], v[110:113]
	v_mfma_f32_16x16x32_bf16 v[102:105], v[160:163], v[206:209], v[102:105]
	v_mfma_f32_16x16x32_bf16 v[94:97], v[152:155], v[220:223], v[94:97]
	v_mfma_f32_16x16x32_bf16 v[86:89], v[160:163], v[220:223], v[86:89]
	v_mfma_f32_16x16x32_bf16 v[78:81], v[152:155], v[228:231], v[78:81]
	v_mfma_f32_16x16x32_bf16 v[70:73], v[160:163], v[228:231], v[70:73]
	v_mfma_f32_16x16x32_bf16 v[122:125], v[164:167], v[180:183], v[122:125]
	v_mfma_f32_16x16x32_bf16 v[114:117], v[172:175], v[180:183], v[114:117]
	v_mfma_f32_16x16x32_bf16 v[106:109], v[164:167], v[202:205], v[106:109]
	v_mfma_f32_16x16x32_bf16 v[98:101], v[172:175], v[202:205], v[98:101]
	v_mfma_f32_16x16x32_bf16 v[90:93], v[164:167], v[210:213], v[90:93]
	v_mfma_f32_16x16x32_bf16 v[82:85], v[172:175], v[210:213], v[82:85]
	v_mfma_f32_16x16x32_bf16 v[74:77], v[164:167], v[224:227], v[74:77]
	v_mfma_f32_16x16x32_bf16 v[66:69], v[172:175], v[224:227], v[66:69]
	v_mfma_f32_16x16x32_bf16 v[122:125], v[168:171], v[198:201], v[122:125]
	v_mfma_f32_16x16x32_bf16 v[114:117], v[176:179], v[198:201], v[114:117]
	v_mfma_f32_16x16x32_bf16 v[106:109], v[168:171], v[206:209], v[106:109]
	v_mfma_f32_16x16x32_bf16 v[98:101], v[176:179], v[206:209], v[98:101]
	v_mfma_f32_16x16x32_bf16 v[90:93], v[168:171], v[220:223], v[90:93]
	v_mfma_f32_16x16x32_bf16 v[82:85], v[176:179], v[220:223], v[82:85]
	v_mfma_f32_16x16x32_bf16 v[74:77], v[168:171], v[228:231], v[74:77]
	v_mfma_f32_16x16x32_bf16 v[66:69], v[176:179], v[228:231], v[66:69]
	s_barrier
	s_add_i32 s64, s64, s47
	v_lshl_add_u64 v[144:145], s[30:31], 0, v[0:1]
	s_mov_b32 m0, s64
	ds_read_b128 v[180:183], v150 offset:16384
	ds_read_b128 v[198:201], v150 offset:17408
	ds_read_b128 v[202:205], v150 offset:18432
	ds_read_b128 v[206:209], v150 offset:19456
	ds_read_b128 v[210:213], v150 offset:20480
	ds_read_b128 v[220:223], v150 offset:21504
	ds_read_b128 v[224:227], v150 offset:22528
	ds_read_b128 v[228:231], v150 offset:23552
	global_load_lds_dwordx4 v[144:145], off
	s_add_i32 m0, s64, 0x2000
	s_add_u32 s64, s30, 0x40000
	v_lshl_add_u64 v[214:215], s[30:31], 0, v[130:131]
	s_addc_u32 s65, s31, 0
	s_add_i32 s66, s66, s47
	global_load_lds_dwordx4 v[214:215], off
	v_lshl_add_u64 v[232:233], s[64:65], 0, v[0:1]
	s_mov_b32 m0, s66
	v_lshl_add_u64 v[242:243], s[44:45], 0, v[132:133]
	global_load_lds_dwordx4 v[232:233], off
	v_lshl_add_u64 v[232:233], s[64:65], 0, v[130:131]
	s_add_i32 m0, s66, 0x2000
	s_nop 0
	global_load_lds_dwordx4 v[232:233], off
	v_lshl_add_u64 v[232:233], s[44:45], 0, v[134:135]
	s_mov_b32 m0, s50
	s_nop 0
	global_load_lds_dwordx4 v[232:233], off
	s_mov_b32 m0, s51
	s_nop 0
	global_load_lds_dwordx4 v[242:243], off
	s_waitcnt vmcnt(8)
	s_waitcnt lgkmcnt(0)
	s_barrier
; #define PG8_STAGE(bufoff, gbase, voff) do { _Pragma("unroll") for (int _i = 0; _i < 2; ++_i) \
;         __builtin_amdgcn_global_load_lds((const unsigned*)((const char*)(gbase) + (voff)[_i]), (LAS unsigned*)(lds + (bufoff) + ldsw + _i * 8192), 16, 0, 0); } while (0)
; #define PG8_LDA(dst, b, h) do { _Pragma("unroll") for (int m = 0; m < 4; ++m) _Pragma("unroll") for (int k = 0; k < 2; ++k) dst[m][k] = *(const LAS bf16x8*)(lds + PG8_SA(b, h) + aoff + m * 2048 + k * 1024); } while (0)
; #define PG8_LDB(dst, b, h) do { _Pragma("unroll") for (int n = 0; n < 2; ++n) _Pragma("unroll") for (int k = 0; k < 2; ++k) dst[n][k] = *(const LAS bf16x8*)(lds + PG8_SB(b, h) + boff + n * 2048 + k * 1024); } while (0)
; #define PG8_MMA(ai, bj, At, Bt) do { __builtin_amdgcn_s_setprio(1); _Pragma("unroll") for (int m = 0; m < 4; ++m) _Pragma("unroll") for (int n = 0; n < 2; ++n) _Pragma("unroll") for (int k = 0; k < 2; ++k) \
;         acc[ai][bj][m][n] = __builtin_amdgcn_mfma_f32_16x16x32_bf16(Bt[n][k], At[m][k], acc[ai][bj][m][n], 0, 0, 0); __builtin_amdgcn_s_setprio(0); } while (0)
; #define PG8_WAIT_V(n) asm volatile("s_waitcnt vmcnt(" #n ")" ::: "memory")
; #define PG8_WAIT_L(n) asm volatile("s_waitcnt lgkmcnt(" #n ")" ::: "memory")
; #define PG8_BAR __builtin_amdgcn_s_barrier()
; #define PG8_SCHED __builtin_amdgcn_sched_barrier(0)
; template <class Epi, class Sched, bool ALIGN_EPI = GEMM_ALIGN, bool SP2 = GEMM_SP2>
; __device__ __forceinline__ void gemm_phase(lptr lds, const Gemm g, const Sched& S, const Epi& E) {
;     ...
;             PG8_WAIT_V(8); PG8_WAIT_L(0); PG8_BAR; PG8_MMA(1, 0, At, B0); PG8_MMA(1, 1, At, B1); PG8_BAR; PG8_SCHED;
;             PG8_LDB(B0, 1, 0); PG8_LDB(B1, 1, 1); PG8_SCHED; PG8_LDA(At, 1, 0); PG8_STAGE(PG8_SA(0, 1), a2 + hstepA, voffA);
;             PG8_WAIT_V(8); PG8_WAIT_L(0); PG8_BAR; PG8_MMA(0, 0, At, B0); PG8_MMA(0, 1, At, B1); PG8_BAR; PG8_SCHED;
;             PG8_LDA(At, 1, 1); PG8_STAGE(PG8_SB(1, 0), b3, voffB); PG8_STAGE(PG8_SB(1, 1), b3 + hstepB, voffB); PG8_STAGE(PG8_SA(1, 0), a3, voffA);
	s_waitcnt lgkmcnt(0)
	v_mfma_f32_16x16x32_bf16 v[62:65], v[140:143], v[180:183], v[62:65]
	v_mfma_f32_16x16x32_bf16 v[54:57], v[156:159], v[180:183], v[54:57]
	v_mfma_f32_16x16x32_bf16 v[46:49], v[140:143], v[202:205], v[46:49]
	v_mfma_f32_16x16x32_bf16 v[38:41], v[156:159], v[202:205], v[38:41]
	v_mfma_f32_16x16x32_bf16 v[30:33], v[140:143], v[210:213], v[30:33]
	v_mfma_f32_16x16x32_bf16 v[22:25], v[156:159], v[210:213], v[22:25]
	v_mfma_f32_16x16x32_bf16 v[14:17], v[140:143], v[224:227], v[14:17]
	v_mfma_f32_16x16x32_bf16 v[6:9], v[156:159], v[224:227], v[6:9]
	v_mfma_f32_16x16x32_bf16 v[62:65], v[152:155], v[198:201], v[62:65]
	v_mfma_f32_16x16x32_bf16 v[54:57], v[160:163], v[198:201], v[54:57]
	v_mfma_f32_16x16x32_bf16 v[46:49], v[152:155], v[206:209], v[46:49]
	v_mfma_f32_16x16x32_bf16 v[38:41], v[160:163], v[206:209], v[38:41]
	v_mfma_f32_16x16x32_bf16 v[30:33], v[152:155], v[220:223], v[30:33]
	v_mfma_f32_16x16x32_bf16 v[22:25], v[160:163], v[220:223], v[22:25]
	v_mfma_f32_16x16x32_bf16 v[14:17], v[152:155], v[228:231], v[14:17]
	v_mfma_f32_16x16x32_bf16 v[6:9], v[160:163], v[228:231], v[6:9]
	v_mfma_f32_16x16x32_bf16 v[58:61], v[164:167], v[180:183], v[58:61]
	v_mfma_f32_16x16x32_bf16 v[50:53], v[172:175], v[180:183], v[50:53]
	v_mfma_f32_16x16x32_bf16 v[42:45], v[164:167], v[202:205], v[42:45]
	v_mfma_f32_16x16x32_bf16 v[34:37], v[172:175], v[202:205], v[34:37]
	v_mfma_f32_16x16x32_bf16 v[26:29], v[164:167], v[210:213], v[26:29]
	v_mfma_f32_16x16x32_bf16 v[18:21], v[172:175], v[210:213], v[18:21]
	v_mfma_f32_16x16x32_bf16 v[10:13], v[164:167], v[224:227], v[10:13]
	v_mfma_f32_16x16x32_bf16 v[2:5], v[172:175], v[224:227], v[2:5]
	v_mfma_f32_16x16x32_bf16 v[58:61], v[168:171], v[198:201], v[58:61]
	v_mfma_f32_16x16x32_bf16 v[50:53], v[176:179], v[198:201], v[50:53]
	v_mfma_f32_16x16x32_bf16 v[42:45], v[168:171], v[206:209], v[42:45]
	v_mfma_f32_16x16x32_bf16 v[34:37], v[176:179], v[206:209], v[34:37]
	v_mfma_f32_16x16x32_bf16 v[26:29], v[168:171], v[220:223], v[26:29]
	v_mfma_f32_16x16x32_bf16 v[18:21], v[176:179], v[220:223], v[18:21]
	v_mfma_f32_16x16x32_bf16 v[10:13], v[168:171], v[228:231], v[10:13]
	v_mfma_f32_16x16x32_bf16 v[2:5], v[176:179], v[228:231], v[2:5]
	s_barrier
	s_add_i32 s64, 0, 0x18000
	v_add_u32_e32 v151, s64, v147
	s_add_i32 s65, 0, 0x1c000
	ds_read_b128 v[140:143], v151
	ds_read_b128 v[152:155], v151 offset:1024
	ds_read_b128 v[156:159], v151 offset:2048
	ds_read_b128 v[160:163], v151 offset:3072
	v_add_u32_e32 v151, s65, v147
	ds_read_b128 v[164:167], v151
	ds_read_b128 v[168:171], v151 offset:1024
	ds_read_b128 v[172:175], v151 offset:2048
	ds_read_b128 v[176:179], v151 offset:3072
	s_add_u32 s44, s44, 0x40000
	s_addc_u32 s45, s45, 0
	s_mov_b32 m0, s52
	v_lshl_add_u64 v[248:249], s[44:45], 0, v[134:135]
	ds_read_b128 v[180:183], v150 offset:32768
	ds_read_b128 v[198:201], v150 offset:33792
	ds_read_b128 v[202:205], v150 offset:34816
	ds_read_b128 v[206:209], v150 offset:35840
	ds_read_b128 v[210:213], v150 offset:36864
	ds_read_b128 v[220:223], v150 offset:37888
	ds_read_b128 v[224:227], v150 offset:38912
	ds_read_b128 v[228:231], v150 offset:39936
	global_load_lds_dwordx4 v[248:249], off
	v_lshl_add_u64 v[248:249], s[44:45], 0, v[132:133]
	s_mov_b32 m0, s53
	s_nop 0
	global_load_lds_dwordx4 v[248:249], off
	s_waitcnt vmcnt(8)
	s_waitcnt lgkmcnt(0)
	s_barrier
	s_waitcnt lgkmcnt(0)
	v_mfma_f32_16x16x32_bf16 v[126:129], v[140:143], v[180:183], v[126:129]
	v_mfma_f32_16x16x32_bf16 v[118:121], v[156:159], v[180:183], v[118:121]
	v_mfma_f32_16x16x32_bf16 v[110:113], v[140:143], v[202:205], v[110:113]
	v_mfma_f32_16x16x32_bf16 v[102:105], v[156:159], v[202:205], v[102:105]
	v_mfma_f32_16x16x32_bf16 v[94:97], v[140:143], v[210:213], v[94:97]
	v_mfma_f32_16x16x32_bf16 v[86:89], v[156:159], v[210:213], v[86:89]
	v_mfma_f32_16x16x32_bf16 v[78:81], v[140:143], v[224:227], v[78:81]
	v_mfma_f32_16x16x32_bf16 v[70:73], v[156:159], v[224:227], v[70:73]
	v_mfma_f32_16x16x32_bf16 v[126:129], v[152:155], v[198:201], v[126:129]
	v_mfma_f32_16x16x32_bf16 v[118:121], v[160:163], v[198:201], v[118:121]
	v_mfma_f32_16x16x32_bf16 v[110:113], v[152:155], v[206:209], v[110:113]
	v_mfma_f32_16x16x32_bf16 v[102:105], v[160:163], v[206:209], v[102:105]
	v_mfma_f32_16x16x32_bf16 v[94:97], v[152:155], v[220:223], v[94:97]
	v_mfma_f32_16x16x32_bf16 v[86:89], v[160:163], v[220:223], v[86:89]
	v_mfma_f32_16x16x32_bf16 v[78:81], v[152:155], v[228:231], v[78:81]
	v_mfma_f32_16x16x32_bf16 v[70:73], v[160:163], v[228:231], v[70:73]
	v_mfma_f32_16x16x32_bf16 v[122:125], v[164:167], v[180:183], v[122:125]
	v_mfma_f32_16x16x32_bf16 v[114:117], v[172:175], v[180:183], v[114:117]
	v_mfma_f32_16x16x32_bf16 v[106:109], v[164:167], v[202:205], v[106:109]
	v_mfma_f32_16x16x32_bf16 v[98:101], v[172:175], v[202:205], v[98:101]
	v_mfma_f32_16x16x32_bf16 v[90:93], v[164:167], v[210:213], v[90:93]
	v_mfma_f32_16x16x32_bf16 v[82:85], v[172:175], v[210:213], v[82:85]
	v_mfma_f32_16x16x32_bf16 v[74:77], v[164:167], v[224:227], v[74:77]
	v_mfma_f32_16x16x32_bf16 v[66:69], v[172:175], v[224:227], v[66:69]
	v_mfma_f32_16x16x32_bf16 v[122:125], v[168:171], v[198:201], v[122:125]
	v_mfma_f32_16x16x32_bf16 v[114:117], v[176:179], v[198:201], v[114:117]
	v_mfma_f32_16x16x32_bf16 v[106:109], v[168:171], v[206:209], v[106:109]
	v_mfma_f32_16x16x32_bf16 v[98:101], v[176:179], v[206:209], v[98:101]
	v_mfma_f32_16x16x32_bf16 v[90:93], v[168:171], v[220:223], v[90:93]
	v_mfma_f32_16x16x32_bf16 v[82:85], v[176:179], v[220:223], v[82:85]
	v_mfma_f32_16x16x32_bf16 v[74:77], v[168:171], v[228:231], v[74:77]
	v_mfma_f32_16x16x32_bf16 v[66:69], v[176:179], v[228:231], v[66:69]
	s_barrier
; __device__ __forceinline__ u32x4 pack8(const float* f) { u32x4 o; o.x = pk2(f[0], f[1]); o.y = pk2(f[2], f[3]); o.z = pk2(f[4], f[5]); o.w = pk2(f[6], f[7]); return o; }
; __device__ __forceinline__ float siluf_(float x) { return x * sigmoidf_(x); }
; #define PG8_STAGE(bufoff, gbase, voff) do { _Pragma("unroll") for (int _i = 0; _i < 2; ++_i) \
;         __builtin_amdgcn_global_load_lds((const unsigned*)((const char*)(gbase) + (voff)[_i]), (LAS unsigned*)(lds + (bufoff) + ldsw + _i * 8192), 16, 0, 0); } while (0)
; #define PG8_LDA(dst, b, h) do { _Pragma("unroll") for (int m = 0; m < 4; ++m) _Pragma("unroll") for (int k = 0; k < 2; ++k) dst[m][k] = *(const LAS bf16x8*)(lds + PG8_SA(b, h) + aoff + m * 2048 + k * 1024); } while (0)
; #define PG8_WAIT_V(n) asm volatile("s_waitcnt vmcnt(" #n ")" ::: "memory")
; #define PG8_WAIT_L(n) asm volatile("s_waitcnt lgkmcnt(" #n ")" ::: "memory")
; #define PG8_BAR __builtin_amdgcn_s_barrier()
; #define PG8_SCHED __builtin_amdgcn_sched_barrier(0)
; template <class Epi, class Sched, bool ALIGN_EPI = GEMM_ALIGN, bool SP2 = GEMM_SP2>
; __device__ __forceinline__ void gemm_phase(lptr lds, const Gemm g, const Sched& S, const Epi& E) {
;     ...
;             PG8_LDA(At, 1, 1); PG8_STAGE(PG8_SB(1, 0), b3, voffB); PG8_STAGE(PG8_SB(1, 1), b3 + hstepB, voffB); PG8_STAGE(PG8_SA(1, 0), a3, voffA);
;             PG8_WAIT_V(8); PG8_WAIT_L(0); PG8_BAR; PG8_MMA(1, 0, At, B0); PG8_MMA(1, 1, At, B1); PG8_BAR; PG8_SCHED;
;     __device__ __forceinline__ void operator()(const f32x4 (&acc)[2][2][4][2], const Unit& u, int wr, int wc, int fr, int fq) const {
;         const int row0 = u.pm * BM + wr * 64 + fr, col0 = u.pn * 128 + wc * 32 + 8 * fq;
;         float rsv[2][4];
; #pragma unroll
;         for (int ai = 0; ai < 2; ++ai)
; #pragma unroll
;             for (int m = 0; m < 4; ++m) rsv[ai][m] = rst[u.ord * 256 + wr * 64 + fr + ai * HALF + m * 16];
; #pragma unroll
;         for (int ai = 0; ai < 2; ++ai)
; #pragma unroll
;             for (int m = 0; m < 4; ++m) { float o[8]; const float rs = rsv[ai][m];
; #pragma unroll
;                 for (int n = 0; n < 2; ++n)
; #pragma unroll
;                     for (int j = 0; j < 4; ++j) o[n * 4 + j] = siluf_(acc[ai][0][m][n][j] * rs) * (acc[ai][1][m][n][j] * rs);
;                 *(u32x4*)(hid + (size_t)(row0 + ai * HALF + m * 16) * FF + col0) = pack8(o); }
	s_add_i32 s44, s64, s47
	v_lshl_add_u64 v[144:145], v[144:145], 0, s[6:7]
	s_mov_b32 m0, s44
	ds_read_b128 v[180:183], v150 offset:49152
	ds_read_b128 v[198:201], v150 offset:50176
	ds_read_b128 v[202:205], v150 offset:51200
	ds_read_b128 v[206:209], v150 offset:52224
	ds_read_b128 v[210:213], v150 offset:53248
	ds_read_b128 v[220:223], v150 offset:54272
	ds_read_b128 v[224:227], v150 offset:55296
	ds_read_b128 v[228:231], v150 offset:56320
	global_load_lds_dwordx4 v[144:145], off
	s_add_i32 m0, s44, 0x2000
	s_add_u32 s30, s30, 0x40080
	v_lshl_add_u64 v[144:145], v[214:215], 0, s[6:7]
	s_addc_u32 s31, s31, 0
	s_add_i32 s44, s65, s47
	global_load_lds_dwordx4 v[144:145], off
	v_lshl_add_u64 v[144:145], s[30:31], 0, v[0:1]
	s_mov_b32 m0, s44
	s_nop 0
	global_load_lds_dwordx4 v[144:145], off
	v_lshl_add_u64 v[144:145], s[30:31], 0, v[130:131]
	s_add_i32 m0, s44, 0x2000
	s_nop 0
	global_load_lds_dwordx4 v[144:145], off
	v_lshl_add_u64 v[144:145], v[232:233], 0, s[6:7]
	s_mov_b32 m0, s54
	s_nop 0
	global_load_lds_dwordx4 v[144:145], off
	v_lshl_add_u64 v[144:145], v[242:243], 0, s[6:7]
	s_mov_b32 m0, s55
	s_nop 0
	global_load_lds_dwordx4 v[144:145], off
	s_waitcnt vmcnt(8)
	s_waitcnt lgkmcnt(0)
	s_barrier
	s_waitcnt lgkmcnt(0)
	v_mfma_f32_16x16x32_bf16 v[62:65], v[140:143], v[180:183], v[62:65]
	v_mfma_f32_16x16x32_bf16 v[54:57], v[156:159], v[180:183], v[54:57]
	v_mfma_f32_16x16x32_bf16 v[46:49], v[140:143], v[202:205], v[46:49]
	v_mfma_f32_16x16x32_bf16 v[38:41], v[156:159], v[202:205], v[38:41]
	v_mfma_f32_16x16x32_bf16 v[30:33], v[140:143], v[210:213], v[30:33]
	v_mfma_f32_16x16x32_bf16 v[22:25], v[156:159], v[210:213], v[22:25]
	v_mfma_f32_16x16x32_bf16 v[14:17], v[140:143], v[224:227], v[14:17]
	v_mfma_f32_16x16x32_bf16 v[6:9], v[156:159], v[224:227], v[6:9]
	v_mfma_f32_16x16x32_bf16 v[62:65], v[152:155], v[198:201], v[62:65]
	v_mfma_f32_16x16x32_bf16 v[54:57], v[160:163], v[198:201], v[54:57]
	v_mfma_f32_16x16x32_bf16 v[46:49], v[152:155], v[206:209], v[46:49]
	v_mfma_f32_16x16x32_bf16 v[38:41], v[160:163], v[206:209], v[38:41]
	v_mfma_f32_16x16x32_bf16 v[30:33], v[152:155], v[220:223], v[30:33]
	v_mfma_f32_16x16x32_bf16 v[22:25], v[160:163], v[220:223], v[22:25]
	v_mfma_f32_16x16x32_bf16 v[14:17], v[152:155], v[228:231], v[14:17]
	v_mfma_f32_16x16x32_bf16 v[6:9], v[160:163], v[228:231], v[6:9]
	v_mfma_f32_16x16x32_bf16 v[58:61], v[164:167], v[180:183], v[58:61]
	v_mfma_f32_16x16x32_bf16 v[50:53], v[172:175], v[180:183], v[50:53]
	v_mfma_f32_16x16x32_bf16 v[42:45], v[164:167], v[202:205], v[42:45]
	v_mfma_f32_16x16x32_bf16 v[34:37], v[172:175], v[202:205], v[34:37]
	v_mfma_f32_16x16x32_bf16 v[26:29], v[164:167], v[210:213], v[26:29]
	v_mfma_f32_16x16x32_bf16 v[18:21], v[172:175], v[210:213], v[18:21]
	v_mfma_f32_16x16x32_bf16 v[10:13], v[164:167], v[224:227], v[10:13]
	v_mfma_f32_16x16x32_bf16 v[2:5], v[172:175], v[224:227], v[2:5]
	v_mfma_f32_16x16x32_bf16 v[58:61], v[168:171], v[198:201], v[58:61]
	v_mfma_f32_16x16x32_bf16 v[50:53], v[176:179], v[198:201], v[50:53]
	v_mfma_f32_16x16x32_bf16 v[42:45], v[168:171], v[206:209], v[42:45]
	v_mfma_f32_16x16x32_bf16 v[34:37], v[176:179], v[206:209], v[34:37]
	v_mfma_f32_16x16x32_bf16 v[26:29], v[168:171], v[220:223], v[26:29]
	v_mfma_f32_16x16x32_bf16 v[18:21], v[176:179], v[220:223], v[18:21]
	v_mfma_f32_16x16x32_bf16 v[10:13], v[168:171], v[228:231], v[10:13]
	v_mfma_f32_16x16x32_bf16 v[2:5], v[176:179], v[228:231], v[2:5]
	s_barrier
	s_add_i32 s63, s63, 2
	s_add_u32 s28, s28, 0x100
	s_addc_u32 s29, s29, 0
	s_add_u32 s61, s61, 0x100
	s_addc_u32 s62, s62, 0
	s_cmp_gt_u32 s63, 13
	s_cbranch_scc0 .LBB0_2336
	s_and_b64 vcc, exec, s[2:3]
	s_cbranch_vccz .LBB0_2339
	s_barrier
.LBB0_2339:
	s_setprio 0
	v_lshl_add_u32 v140, s58, 10, v148
	ds_read2_b32 v[152:153], v140 offset1:16
	ds_read2_b32 v[144:145], v140 offset0:32 offset1:48
	ds_read2_b32 v[142:143], v140 offset0:128 offset1:144
	ds_read2_b32 v[140:141], v140 offset0:160 offset1:176
	v_lshl_or_b32 v154, s25, 7, v149
	s_waitcnt lgkmcnt(0)
	v_pk_mul_f32 v[126:127], v[126:127], v[152:153] op_sel_hi:[1,0]
	v_pk_mul_f32 v[122:123], v[122:123], v[152:153] op_sel_hi:[1,0]
	v_mul_f32_e32 v156, 0xbfb8aa3b, v126
	v_mul_f32_e32 v157, 0xbfb8aa3b, v127
	v_exp_f32_e32 v156, v156
	v_exp_f32_e32 v157, v157
	v_pk_mul_f32 v[124:125], v[124:125], v[152:153] op_sel_hi:[1,0]
	v_pk_mul_f32 v[118:119], v[118:119], v[152:153] op_sel_hi:[1,0]
	v_add_f32_e32 v156, 1.0, v156
	v_add_f32_e32 v157, 1.0, v157
	v_rcp_f32_e32 v156, v156
	v_rcp_f32_e32 v157, v157
	v_pk_mul_f32 v[114:115], v[114:115], v[152:153] op_sel_hi:[1,0]
	v_pk_mul_f32 v[116:117], v[116:117], v[152:153] op_sel_hi:[1,0]
	v_lshl_add_u32 v151, s24, 8, v146
	v_pk_mul_f32 v[126:127], v[126:127], v[156:157]
	v_ashrrev_i32_e32 v155, 31, v154
	v_pk_mul_f32 v[122:123], v[122:123], v[126:127]
	v_pk_mul_f32 v[126:127], v[128:129], v[152:153] op_sel_hi:[1,0]
	s_movk_i32 s27, 0x1600
	v_mul_f32_e32 v128, 0xbfb8aa3b, v126
	v_mul_f32_e32 v129, 0xbfb8aa3b, v127
	v_exp_f32_e32 v128, v128
	v_exp_f32_e32 v129, v129
	v_pk_mul_f32 v[94:95], v[94:95], v[144:145] op_sel_hi:[1,0]
	v_pk_mul_f32 v[90:91], v[90:91], v[144:145] op_sel_hi:[1,0]
	v_add_f32_e32 v128, 1.0, v128
	v_add_f32_e32 v129, 1.0, v129
	v_rcp_f32_e32 v128, v128
	v_rcp_f32_e32 v129, v129
	v_pk_mul_f32 v[92:93], v[92:93], v[144:145] op_sel_hi:[1,0]
	v_pk_mul_f32 v[86:87], v[86:87], v[144:145] op_sel_hi:[1,0]
	v_pk_mul_f32 v[82:83], v[82:83], v[144:145] op_sel_hi:[1,0]
	v_pk_mul_f32 v[126:127], v[126:127], v[128:129]
	v_pk_mul_f32 v[84:85], v[84:85], v[144:145] op_sel_hi:[1,0]
	v_pk_mul_f32 v[124:125], v[124:125], v[126:127]
	v_mul_f32_e32 v126, 0xbfb8aa3b, v118
; __device__ __forceinline__ u32x4 pack8(const float* f) { u32x4 o; o.x = pk2(f[0], f[1]); o.y = pk2(f[2], f[3]); o.z = pk2(f[4], f[5]); o.w = pk2(f[6], f[7]); return o; }
; __device__ __forceinline__ float rcpf(float x) { return __builtin_amdgcn_rcpf(x); }
; __device__ __forceinline__ float sigmoidf_(float x) { return rcpf(1.0f + __expf(-x)); }
; __device__ __forceinline__ float siluf_(float x) { return x * sigmoidf_(x); }
;     __device__ __forceinline__ void operator()(const f32x4 (&acc)[2][2][4][2], const Unit& u, int wr, int wc, int fr, int fq) const {
;         const int row0 = u.pm * BM + wr * 64 + fr, col0 = u.pn * 128 + wc * 32 + 8 * fq;
;         float rsv[2][4];
; #pragma unroll
;         for (int ai = 0; ai < 2; ++ai)
; #pragma unroll
;             for (int m = 0; m < 4; ++m) rsv[ai][m] = rst[u.ord * 256 + wr * 64 + fr + ai * HALF + m * 16];
; #pragma unroll
;         for (int ai = 0; ai < 2; ++ai)
; #pragma unroll
;             for (int m = 0; m < 4; ++m) { float o[8]; const float rs = rsv[ai][m];
; #pragma unroll
;                 for (int n = 0; n < 2; ++n)
; #pragma unroll
;                     for (int j = 0; j < 4; ++j) o[n * 4 + j] = siluf_(acc[ai][0][m][n][j] * rs) * (acc[ai][1][m][n][j] * rs);
;                 *(u32x4*)(hid + (size_t)(row0 + ai * HALF + m * 16) * FF + col0) = pack8(o); }
	v_mul_f32_e32 v127, 0xbfb8aa3b, v119
	v_exp_f32_e32 v126, v126
	v_exp_f32_e32 v127, v127
	v_pk_mul_f32 v[62:63], v[62:63], v[142:143] op_sel_hi:[1,0]
	v_pk_mul_f32 v[58:59], v[58:59], v[142:143] op_sel_hi:[1,0]
	v_add_f32_e32 v126, 1.0, v126
	v_add_f32_e32 v127, 1.0, v127
	v_rcp_f32_e32 v126, v126
	v_rcp_f32_e32 v127, v127
	v_pk_mul_f32 v[60:61], v[60:61], v[142:143] op_sel_hi:[1,0]
	v_pk_mul_f32 v[54:55], v[54:55], v[142:143] op_sel_hi:[1,0]
	v_pk_mul_f32 v[50:51], v[50:51], v[142:143] op_sel_hi:[1,0]
	v_pk_mul_f32 v[118:119], v[118:119], v[126:127]
	v_pk_mul_f32 v[52:53], v[52:53], v[142:143] op_sel_hi:[1,0]
	v_pk_mul_f32 v[114:115], v[114:115], v[118:119]
	v_pk_mul_f32 v[118:119], v[120:121], v[152:153] op_sel_hi:[1,0]
	v_pk_mul_f32 v[30:31], v[30:31], v[140:141] op_sel_hi:[1,0]
	v_mul_f32_e32 v120, 0xbfb8aa3b, v118
	v_mul_f32_e32 v121, 0xbfb8aa3b, v119
	v_exp_f32_e32 v120, v120
	v_exp_f32_e32 v121, v121
	v_pk_mul_f32 v[26:27], v[26:27], v[140:141] op_sel_hi:[1,0]
	v_pk_mul_f32 v[28:29], v[28:29], v[140:141] op_sel_hi:[1,0]
	v_add_f32_e32 v120, 1.0, v120
	v_add_f32_e32 v121, 1.0, v121
	v_rcp_f32_e32 v120, v120
	v_rcp_f32_e32 v121, v121
	v_pk_mul_f32 v[22:23], v[22:23], v[140:141] op_sel_hi:[1,0]
	v_pk_mul_f32 v[18:19], v[18:19], v[140:141] op_sel_hi:[1,0]
	v_pk_mul_f32 v[20:21], v[20:21], v[140:141] op_sel_hi:[1,0]
	v_pk_mul_f32 v[118:119], v[118:119], v[120:121]
	v_cvt_pk_bf16_f32 v120, v114, v115
	v_pk_mul_f32 v[116:117], v[116:117], v[118:119]
	v_mov_b64_e32 v[114:115], s[68:69]
	v_cvt_pk_bf16_f32 v118, v122, v123
	v_cvt_pk_bf16_f32 v121, v116, v117
	v_mad_i64_i32 v[122:123], s[24:25], v151, s27, v[114:115]
	v_lshlrev_b64 v[116:117], 1, v[154:155]
	v_cvt_pk_bf16_f32 v119, v124, v125
	v_lshl_add_u64 v[122:123], v[122:123], 0, v[116:117]
	global_store_dwordx4 v[122:123], v[118:121], off
	s_andn2_b64 vcc, exec, s[36:37]
	s_mov_b64 s[64:65], s[88:89]
	v_mov_b32_e32 v118, v153
	v_pk_mul_f32 v[110:111], v[110:111], v[118:119] op_sel_hi:[1,0]
	s_nop 0
	v_mul_f32_e32 v119, 0xbfb8aa3b, v110
	v_exp_f32_e32 v119, v119
	s_nop 0
	v_add_f32_e32 v119, 1.0, v119
	v_rcp_f32_e32 v120, v119
	v_mul_f32_e32 v119, 0xbfb8aa3b, v111
	v_exp_f32_e32 v119, v119
	s_nop 0
	v_add_f32_e32 v119, 1.0, v119
	v_rcp_f32_e32 v121, v119
	v_pk_mul_f32 v[106:107], v[106:107], v[118:119] op_sel_hi:[1,0]
	v_pk_mul_f32 v[108:109], v[108:109], v[118:119] op_sel_hi:[1,0]
	v_pk_mul_f32 v[102:103], v[102:103], v[118:119] op_sel_hi:[1,0]
	v_pk_mul_f32 v[110:111], v[110:111], v[120:121]
	v_pk_mul_f32 v[98:99], v[98:99], v[118:119] op_sel_hi:[1,0]
	v_pk_mul_f32 v[106:107], v[106:107], v[110:111]
	v_pk_mul_f32 v[110:111], v[112:113], v[118:119] op_sel_hi:[1,0]
	v_pk_mul_f32 v[100:101], v[100:101], v[118:119] op_sel_hi:[1,0]
	v_mul_f32_e32 v112, 0xbfb8aa3b, v110
	v_mul_f32_e32 v113, 0xbfb8aa3b, v111
	v_exp_f32_e32 v112, v112
	v_exp_f32_e32 v113, v113
	v_add_f32_e32 v112, 1.0, v112
	v_add_f32_e32 v113, 1.0, v113
	v_rcp_f32_e32 v112, v112
	v_rcp_f32_e32 v113, v113
	s_nop 0
	v_pk_mul_f32 v[110:111], v[110:111], v[112:113]
	s_nop 0
	v_pk_mul_f32 v[108:109], v[108:109], v[110:111]
	v_mul_f32_e32 v110, 0xbfb8aa3b, v102
	v_mul_f32_e32 v111, 0xbfb8aa3b, v103
	v_exp_f32_e32 v110, v110
	v_exp_f32_e32 v111, v111
	v_add_f32_e32 v110, 1.0, v110
	v_add_f32_e32 v111, 1.0, v111
	v_rcp_f32_e32 v110, v110
	v_rcp_f32_e32 v111, v111
	s_nop 0
	v_pk_mul_f32 v[102:103], v[102:103], v[110:111]
	s_nop 0
	v_pk_mul_f32 v[102:103], v[98:99], v[102:103]
	v_pk_mul_f32 v[98:99], v[104:105], v[118:119] op_sel_hi:[1,0]
	s_nop 0
	v_mul_f32_e32 v104, 0xbfb8aa3b, v98
	v_mul_f32_e32 v105, 0xbfb8aa3b, v99
	v_exp_f32_e32 v104, v104
	v_exp_f32_e32 v105, v105
	v_add_f32_e32 v104, 1.0, v104
	v_add_f32_e32 v105, 1.0, v105
	v_rcp_f32_e32 v104, v104
	v_rcp_f32_e32 v105, v105
	s_nop 0
	v_pk_mul_f32 v[98:99], v[98:99], v[104:105]
	s_nop 0
	v_pk_mul_f32 v[104:105], v[100:101], v[98:99]
	v_cvt_pk_bf16_f32 v100, v102, v103
	v_or_b32_e32 v102, 16, v151
	v_mad_i64_i32 v[102:103], s[24:25], v102, s27, v[114:115]
	v_cvt_pk_bf16_f32 v98, v106, v107
	v_cvt_pk_bf16_f32 v99, v108, v109
	v_cvt_pk_bf16_f32 v101, v104, v105
	v_lshl_add_u64 v[102:103], v[102:103], 0, v[116:117]
	global_store_dwordx4 v[102:103], v[98:101], off
	s_nop 1
	v_mul_f32_e32 v98, 0xbfb8aa3b, v94
	v_mul_f32_e32 v99, 0xbfb8aa3b, v95
	v_exp_f32_e32 v98, v98
	v_exp_f32_e32 v99, v99
	v_add_f32_e32 v98, 1.0, v98
	v_add_f32_e32 v99, 1.0, v99
	v_rcp_f32_e32 v98, v98
	v_rcp_f32_e32 v99, v99
	s_nop 0
	v_pk_mul_f32 v[94:95], v[94:95], v[98:99]
	s_nop 0
	v_pk_mul_f32 v[90:91], v[90:91], v[94:95]
	v_pk_mul_f32 v[94:95], v[96:97], v[144:145] op_sel_hi:[1,0]
	s_nop 0
	v_mul_f32_e32 v96, 0xbfb8aa3b, v94
	v_mul_f32_e32 v97, 0xbfb8aa3b, v95
	v_exp_f32_e32 v96, v96
	v_exp_f32_e32 v97, v97
	v_add_f32_e32 v96, 1.0, v96
	v_add_f32_e32 v97, 1.0, v97
	v_rcp_f32_e32 v96, v96
	v_rcp_f32_e32 v97, v97
	s_nop 0
	v_pk_mul_f32 v[94:95], v[94:95], v[96:97]
	s_nop 0
	v_pk_mul_f32 v[92:93], v[92:93], v[94:95]
	v_mul_f32_e32 v94, 0xbfb8aa3b, v86
	v_mul_f32_e32 v95, 0xbfb8aa3b, v87
	v_exp_f32_e32 v94, v94
	v_exp_f32_e32 v95, v95
	v_add_f32_e32 v94, 1.0, v94
	v_add_f32_e32 v95, 1.0, v95
	v_rcp_f32_e32 v94, v94
	v_rcp_f32_e32 v95, v95
	s_nop 0
	v_pk_mul_f32 v[86:87], v[86:87], v[94:95]
	s_nop 0
	v_pk_mul_f32 v[86:87], v[82:83], v[86:87]
	v_pk_mul_f32 v[82:83], v[88:89], v[144:145] op_sel_hi:[1,0]
	s_nop 0
	v_mul_f32_e32 v88, 0xbfb8aa3b, v82
	v_mul_f32_e32 v89, 0xbfb8aa3b, v83
	v_exp_f32_e32 v88, v88
	v_exp_f32_e32 v89, v89
	v_add_f32_e32 v88, 1.0, v88
	v_add_f32_e32 v89, 1.0, v89
	v_rcp_f32_e32 v88, v88
	v_rcp_f32_e32 v89, v89
	s_nop 0
	v_pk_mul_f32 v[82:83], v[82:83], v[88:89]
	s_nop 0
; __device__ __forceinline__ u32x4 pack8(const float* f) { u32x4 o; o.x = pk2(f[0], f[1]); o.y = pk2(f[2], f[3]); o.z = pk2(f[4], f[5]); o.w = pk2(f[6], f[7]); return o; }
; __device__ __forceinline__ float rcpf(float x) { return __builtin_amdgcn_rcpf(x); }
; __device__ __forceinline__ float sigmoidf_(float x) { return rcpf(1.0f + __expf(-x)); }
; __device__ __forceinline__ float siluf_(float x) { return x * sigmoidf_(x); }
;     __device__ __forceinline__ void operator()(const f32x4 (&acc)[2][2][4][2], const Unit& u, int wr, int wc, int fr, int fq) const {
;         const int row0 = u.pm * BM + wr * 64 + fr, col0 = u.pn * 128 + wc * 32 + 8 * fq;
;         float rsv[2][4];
; #pragma unroll
;         for (int ai = 0; ai < 2; ++ai)
; #pragma unroll
;             for (int m = 0; m < 4; ++m) rsv[ai][m] = rst[u.ord * 256 + wr * 64 + fr + ai * HALF + m * 16];
; #pragma unroll
;         for (int ai = 0; ai < 2; ++ai)
; #pragma unroll
;             for (int m = 0; m < 4; ++m) { float o[8]; const float rs = rsv[ai][m];
; #pragma unroll
;                 for (int n = 0; n < 2; ++n)
; #pragma unroll
;                     for (int j = 0; j < 4; ++j) o[n * 4 + j] = siluf_(acc[ai][0][m][n][j] * rs) * (acc[ai][1][m][n][j] * rs);
;                 *(u32x4*)(hid + (size_t)(row0 + ai * HALF + m * 16) * FF + col0) = pack8(o); }
	v_pk_mul_f32 v[88:89], v[84:85], v[82:83]
	v_cvt_pk_bf16_f32 v84, v86, v87
	v_or_b32_e32 v86, 32, v151
	v_mad_i64_i32 v[86:87], s[24:25], v86, s27, v[114:115]
	v_cvt_pk_bf16_f32 v82, v90, v91
	v_cvt_pk_bf16_f32 v83, v92, v93
	v_cvt_pk_bf16_f32 v85, v88, v89
	v_lshl_add_u64 v[86:87], v[86:87], 0, v[116:117]
	global_store_dwordx4 v[86:87], v[82:85], off
	s_nop 1
	v_mov_b32_e32 v82, v145
	v_pk_mul_f32 v[78:79], v[78:79], v[82:83] op_sel_hi:[1,0]
	s_nop 0
	v_mul_f32_e32 v83, 0xbfb8aa3b, v78
	v_exp_f32_e32 v83, v83
	s_nop 0
	v_add_f32_e32 v83, 1.0, v83
	v_rcp_f32_e32 v84, v83
	v_mul_f32_e32 v83, 0xbfb8aa3b, v79
	v_exp_f32_e32 v83, v83
	s_nop 0
	v_add_f32_e32 v83, 1.0, v83
	v_rcp_f32_e32 v85, v83
	v_pk_mul_f32 v[74:75], v[74:75], v[82:83] op_sel_hi:[1,0]
	v_pk_mul_f32 v[76:77], v[76:77], v[82:83] op_sel_hi:[1,0]
	v_pk_mul_f32 v[70:71], v[70:71], v[82:83] op_sel_hi:[1,0]
	v_pk_mul_f32 v[78:79], v[78:79], v[84:85]
	v_pk_mul_f32 v[66:67], v[66:67], v[82:83] op_sel_hi:[1,0]
	v_pk_mul_f32 v[74:75], v[74:75], v[78:79]
	v_pk_mul_f32 v[78:79], v[80:81], v[82:83] op_sel_hi:[1,0]
	v_pk_mul_f32 v[68:69], v[68:69], v[82:83] op_sel_hi:[1,0]
	v_mul_f32_e32 v80, 0xbfb8aa3b, v78
	v_mul_f32_e32 v81, 0xbfb8aa3b, v79
	v_exp_f32_e32 v80, v80
	v_exp_f32_e32 v81, v81
	v_add_f32_e32 v80, 1.0, v80
	v_add_f32_e32 v81, 1.0, v81
	v_rcp_f32_e32 v80, v80
	v_rcp_f32_e32 v81, v81
	s_nop 0
	v_pk_mul_f32 v[78:79], v[78:79], v[80:81]
	s_nop 0
	v_pk_mul_f32 v[76:77], v[76:77], v[78:79]
	v_mul_f32_e32 v78, 0xbfb8aa3b, v70
	v_mul_f32_e32 v79, 0xbfb8aa3b, v71
	v_exp_f32_e32 v78, v78
	v_exp_f32_e32 v79, v79
	v_add_f32_e32 v78, 1.0, v78
	v_add_f32_e32 v79, 1.0, v79
	v_rcp_f32_e32 v78, v78
	v_rcp_f32_e32 v79, v79
	s_nop 0
	v_pk_mul_f32 v[70:71], v[70:71], v[78:79]
	s_nop 0
	v_pk_mul_f32 v[70:71], v[66:67], v[70:71]
	v_pk_mul_f32 v[66:67], v[72:73], v[82:83] op_sel_hi:[1,0]
	s_nop 0
	v_mul_f32_e32 v72, 0xbfb8aa3b, v66
	v_mul_f32_e32 v73, 0xbfb8aa3b, v67
	v_exp_f32_e32 v72, v72
	v_exp_f32_e32 v73, v73
	v_add_f32_e32 v72, 1.0, v72
	v_add_f32_e32 v73, 1.0, v73
	v_rcp_f32_e32 v72, v72
	v_rcp_f32_e32 v73, v73
	s_nop 0
	v_pk_mul_f32 v[66:67], v[66:67], v[72:73]
	s_nop 0
	v_pk_mul_f32 v[72:73], v[68:69], v[66:67]
	v_cvt_pk_bf16_f32 v68, v70, v71
	v_or_b32_e32 v70, 48, v151
	v_mad_i64_i32 v[70:71], s[24:25], v70, s27, v[114:115]
	v_cvt_pk_bf16_f32 v66, v74, v75
	v_cvt_pk_bf16_f32 v67, v76, v77
	v_cvt_pk_bf16_f32 v69, v72, v73
	v_lshl_add_u64 v[70:71], v[70:71], 0, v[116:117]
	global_store_dwordx4 v[70:71], v[66:69], off
	s_nop 1
	v_mul_f32_e32 v66, 0xbfb8aa3b, v62
	v_mul_f32_e32 v67, 0xbfb8aa3b, v63
	v_exp_f32_e32 v66, v66
	v_exp_f32_e32 v67, v67
	v_add_u32_e32 v68, 0x80, v151
	v_add_f32_e32 v66, 1.0, v66
	v_add_f32_e32 v67, 1.0, v67
	v_rcp_f32_e32 v66, v66
	v_rcp_f32_e32 v67, v67
	s_nop 0
	v_pk_mul_f32 v[62:63], v[62:63], v[66:67]
	s_nop 0
	v_pk_mul_f32 v[58:59], v[58:59], v[62:63]
	v_pk_mul_f32 v[62:63], v[64:65], v[142:143] op_sel_hi:[1,0]
	s_nop 0
	v_mul_f32_e32 v64, 0xbfb8aa3b, v62
	v_mul_f32_e32 v65, 0xbfb8aa3b, v63
	v_exp_f32_e32 v64, v64
	v_exp_f32_e32 v65, v65
	v_add_f32_e32 v64, 1.0, v64
	v_add_f32_e32 v65, 1.0, v65
	v_rcp_f32_e32 v64, v64
	v_rcp_f32_e32 v65, v65
	s_nop 0
	v_pk_mul_f32 v[62:63], v[62:63], v[64:65]
	s_nop 0
	v_pk_mul_f32 v[60:61], v[60:61], v[62:63]
	v_mul_f32_e32 v62, 0xbfb8aa3b, v54
	v_mul_f32_e32 v63, 0xbfb8aa3b, v55
	v_exp_f32_e32 v62, v62
	v_exp_f32_e32 v63, v63
	v_add_f32_e32 v62, 1.0, v62
	v_add_f32_e32 v63, 1.0, v63
	v_rcp_f32_e32 v62, v62
	v_rcp_f32_e32 v63, v63
	s_nop 0
	v_pk_mul_f32 v[54:55], v[54:55], v[62:63]
	s_nop 0
	v_pk_mul_f32 v[54:55], v[50:51], v[54:55]
	v_pk_mul_f32 v[50:51], v[56:57], v[142:143] op_sel_hi:[1,0]
	s_nop 0
	v_mul_f32_e32 v56, 0xbfb8aa3b, v50
	v_mul_f32_e32 v57, 0xbfb8aa3b, v51
	v_exp_f32_e32 v56, v56
	v_exp_f32_e32 v57, v57
	v_add_f32_e32 v56, 1.0, v56
	v_add_f32_e32 v57, 1.0, v57
	v_rcp_f32_e32 v56, v56
	v_rcp_f32_e32 v57, v57
	s_nop 0
	v_pk_mul_f32 v[50:51], v[50:51], v[56:57]
	s_nop 0
	v_pk_mul_f32 v[56:57], v[52:53], v[50:51]
	v_cvt_pk_bf16_f32 v52, v54, v55
	v_mad_i64_i32 v[54:55], s[24:25], v68, s27, v[114:115]
	v_cvt_pk_bf16_f32 v50, v58, v59
	v_cvt_pk_bf16_f32 v51, v60, v61
	v_cvt_pk_bf16_f32 v53, v56, v57
	v_lshl_add_u64 v[54:55], v[54:55], 0, v[116:117]
	global_store_dwordx4 v[54:55], v[50:53], off
	s_nop 1
	v_mov_b32_e32 v50, v143
	v_pk_mul_f32 v[46:47], v[46:47], v[50:51] op_sel_hi:[1,0]
	s_nop 0
	v_mul_f32_e32 v51, 0xbfb8aa3b, v46
	v_exp_f32_e32 v51, v51
	s_nop 0
	v_add_f32_e32 v51, 1.0, v51
	v_rcp_f32_e32 v52, v51
	v_mul_f32_e32 v51, 0xbfb8aa3b, v47
	v_exp_f32_e32 v51, v51
	s_nop 0
	v_add_f32_e32 v51, 1.0, v51
	v_rcp_f32_e32 v53, v51
	v_pk_mul_f32 v[42:43], v[42:43], v[50:51] op_sel_hi:[1,0]
	v_pk_mul_f32 v[44:45], v[44:45], v[50:51] op_sel_hi:[1,0]
	v_pk_mul_f32 v[38:39], v[38:39], v[50:51] op_sel_hi:[1,0]
	v_pk_mul_f32 v[46:47], v[46:47], v[52:53]
	v_pk_mul_f32 v[34:35], v[34:35], v[50:51] op_sel_hi:[1,0]
	v_pk_mul_f32 v[42:43], v[42:43], v[46:47]
	v_pk_mul_f32 v[46:47], v[48:49], v[50:51] op_sel_hi:[1,0]
	v_pk_mul_f32 v[36:37], v[36:37], v[50:51] op_sel_hi:[1,0]
	v_mul_f32_e32 v48, 0xbfb8aa3b, v46
	v_mul_f32_e32 v49, 0xbfb8aa3b, v47
	v_exp_f32_e32 v48, v48
	v_exp_f32_e32 v49, v49
	v_add_f32_e32 v48, 1.0, v48
; __device__ __forceinline__ u32x4 pack8(const float* f) { u32x4 o; o.x = pk2(f[0], f[1]); o.y = pk2(f[2], f[3]); o.z = pk2(f[4], f[5]); o.w = pk2(f[6], f[7]); return o; }
; __device__ __forceinline__ float siluf_(float x) { return x * sigmoidf_(x); }
; #define PG8_BAR __builtin_amdgcn_s_barrier()
; template <class Epi, class Sched, bool ALIGN_EPI = GEMM_ALIGN, bool SP2 = GEMM_SP2>
; __device__ __forceinline__ void gemm_phase(lptr lds, const Gemm g, const Sched& S, const Epi& E) {
;     ...
;         if constexpr (ALIGN_EPI) { if (wr == 0) PG8_BAR; }
;         bool zero_acc = true;
;         if constexpr (Epi::CHAIN) zero_acc = E.chain(acc, cur, wr, wc, fr, fq); else E(acc, cur, wr, wc, fr, fq);
;         if (!has_next) break;
;         if (zero_acc)
; #pragma unroll
;         for (int a = 0; a < 2; ++a)
; #pragma unroll
;             for (int b = 0; b < 2; ++b)
; #pragma unroll
;                 for (int m = 0; m < 4; ++m)
; #pragma unroll
;                     for (int n = 0; n < 2; ++n) acc[a][b][m][n] = (f32x4){0.f, 0.f, 0.f, 0.f};
;         cur = nxt; cA = nA; cB = nB; ++ui;
;         if constexpr (ALIGN_EPI) { if (wr == 1) PG8_BAR; }
;     __device__ __forceinline__ void operator()(const f32x4 (&acc)[2][2][4][2], const Unit& u, int wr, int wc, int fr, int fq) const {
;         const int row0 = u.pm * BM + wr * 64 + fr, col0 = u.pn * 128 + wc * 32 + 8 * fq;
;         float rsv[2][4];
; #pragma unroll
;         for (int ai = 0; ai < 2; ++ai)
; #pragma unroll
;             for (int m = 0; m < 4; ++m) rsv[ai][m] = rst[u.ord * 256 + wr * 64 + fr + ai * HALF + m * 16];
; #pragma unroll
;         for (int ai = 0; ai < 2; ++ai)
; #pragma unroll
;             for (int m = 0; m < 4; ++m) { float o[8]; const float rs = rsv[ai][m];
; #pragma unroll
;                 for (int n = 0; n < 2; ++n)
; #pragma unroll
;                     for (int j = 0; j < 4; ++j) o[n * 4 + j] = siluf_(acc[ai][0][m][n][j] * rs) * (acc[ai][1][m][n][j] * rs);
;                 *(u32x4*)(hid + (size_t)(row0 + ai * HALF + m * 16) * FF + col0) = pack8(o); }
	v_add_f32_e32 v49, 1.0, v49
	v_rcp_f32_e32 v48, v48
	v_rcp_f32_e32 v49, v49
	s_nop 0
	v_pk_mul_f32 v[46:47], v[46:47], v[48:49]
	s_nop 0
	v_pk_mul_f32 v[44:45], v[44:45], v[46:47]
	v_mul_f32_e32 v46, 0xbfb8aa3b, v38
	v_mul_f32_e32 v47, 0xbfb8aa3b, v39
	v_exp_f32_e32 v46, v46
	v_exp_f32_e32 v47, v47
	v_add_f32_e32 v46, 1.0, v46
	v_add_f32_e32 v47, 1.0, v47
	v_rcp_f32_e32 v46, v46
	v_rcp_f32_e32 v47, v47
	s_nop 0
	v_pk_mul_f32 v[38:39], v[38:39], v[46:47]
	s_nop 0
	v_pk_mul_f32 v[38:39], v[34:35], v[38:39]
	v_pk_mul_f32 v[34:35], v[40:41], v[50:51] op_sel_hi:[1,0]
	s_nop 0
	v_mul_f32_e32 v40, 0xbfb8aa3b, v34
	v_mul_f32_e32 v41, 0xbfb8aa3b, v35
	v_exp_f32_e32 v40, v40
	v_exp_f32_e32 v41, v41
	v_add_f32_e32 v40, 1.0, v40
	v_add_f32_e32 v41, 1.0, v41
	v_rcp_f32_e32 v40, v40
	v_rcp_f32_e32 v41, v41
	s_nop 0
	v_pk_mul_f32 v[34:35], v[34:35], v[40:41]
	s_nop 0
	v_pk_mul_f32 v[40:41], v[36:37], v[34:35]
	v_cvt_pk_bf16_f32 v36, v38, v39
	v_add_u32_e32 v38, 0x90, v151
	v_mad_i64_i32 v[38:39], s[24:25], v38, s27, v[114:115]
	v_cvt_pk_bf16_f32 v34, v42, v43
	v_cvt_pk_bf16_f32 v35, v44, v45
	v_cvt_pk_bf16_f32 v37, v40, v41
	v_lshl_add_u64 v[38:39], v[38:39], 0, v[116:117]
	global_store_dwordx4 v[38:39], v[34:37], off
	s_nop 1
	v_mul_f32_e32 v34, 0xbfb8aa3b, v30
	v_mul_f32_e32 v35, 0xbfb8aa3b, v31
	v_exp_f32_e32 v34, v34
	v_exp_f32_e32 v35, v35
	v_add_f32_e32 v34, 1.0, v34
	v_add_f32_e32 v35, 1.0, v35
	v_rcp_f32_e32 v34, v34
	v_rcp_f32_e32 v35, v35
	s_nop 0
	v_pk_mul_f32 v[30:31], v[30:31], v[34:35]
	s_nop 0
	v_pk_mul_f32 v[26:27], v[26:27], v[30:31]
	v_pk_mul_f32 v[30:31], v[32:33], v[140:141] op_sel_hi:[1,0]
	s_nop 0
	v_mul_f32_e32 v32, 0xbfb8aa3b, v30
	v_mul_f32_e32 v33, 0xbfb8aa3b, v31
	v_exp_f32_e32 v32, v32
	v_exp_f32_e32 v33, v33
	v_add_f32_e32 v32, 1.0, v32
	v_add_f32_e32 v33, 1.0, v33
	v_rcp_f32_e32 v32, v32
	v_rcp_f32_e32 v33, v33
	s_nop 0
	v_pk_mul_f32 v[30:31], v[30:31], v[32:33]
	s_nop 0
	v_pk_mul_f32 v[28:29], v[28:29], v[30:31]
	v_mul_f32_e32 v30, 0xbfb8aa3b, v22
	v_mul_f32_e32 v31, 0xbfb8aa3b, v23
	v_exp_f32_e32 v30, v30
	v_exp_f32_e32 v31, v31
	v_add_f32_e32 v30, 1.0, v30
	v_add_f32_e32 v31, 1.0, v31
	v_rcp_f32_e32 v30, v30
	v_rcp_f32_e32 v31, v31
	s_nop 0
	v_pk_mul_f32 v[22:23], v[22:23], v[30:31]
	s_nop 0
	v_pk_mul_f32 v[22:23], v[18:19], v[22:23]
	v_pk_mul_f32 v[18:19], v[24:25], v[140:141] op_sel_hi:[1,0]
	s_nop 0
	v_mul_f32_e32 v24, 0xbfb8aa3b, v18
	v_mul_f32_e32 v25, 0xbfb8aa3b, v19
	v_exp_f32_e32 v24, v24
	v_exp_f32_e32 v25, v25
	v_add_f32_e32 v24, 1.0, v24
	v_add_f32_e32 v25, 1.0, v25
	v_rcp_f32_e32 v24, v24
	v_rcp_f32_e32 v25, v25
	s_nop 0
	v_pk_mul_f32 v[18:19], v[18:19], v[24:25]
	s_nop 0
	v_pk_mul_f32 v[24:25], v[20:21], v[18:19]
	v_cvt_pk_bf16_f32 v20, v22, v23
	v_add_u32_e32 v22, 0xa0, v151
	v_mad_i64_i32 v[22:23], s[24:25], v22, s27, v[114:115]
	v_cvt_pk_bf16_f32 v18, v26, v27
	v_cvt_pk_bf16_f32 v19, v28, v29
	v_cvt_pk_bf16_f32 v21, v24, v25
	v_lshl_add_u64 v[22:23], v[22:23], 0, v[116:117]
	global_store_dwordx4 v[22:23], v[18:21], off
	s_nop 1
	v_mov_b32_e32 v18, v141
	v_pk_mul_f32 v[14:15], v[14:15], v[18:19] op_sel_hi:[1,0]
	s_nop 0
	v_mul_f32_e32 v19, 0xbfb8aa3b, v14
	v_exp_f32_e32 v19, v19
	s_nop 0
	v_add_f32_e32 v19, 1.0, v19
	v_rcp_f32_e32 v20, v19
	v_mul_f32_e32 v19, 0xbfb8aa3b, v15
	v_exp_f32_e32 v19, v19
	s_nop 0
	v_add_f32_e32 v19, 1.0, v19
	v_rcp_f32_e32 v21, v19
	v_pk_mul_f32 v[10:11], v[10:11], v[18:19] op_sel_hi:[1,0]
	v_pk_mul_f32 v[12:13], v[12:13], v[18:19] op_sel_hi:[1,0]
	v_pk_mul_f32 v[6:7], v[6:7], v[18:19] op_sel_hi:[1,0]
	v_pk_mul_f32 v[14:15], v[14:15], v[20:21]
	v_pk_mul_f32 v[2:3], v[2:3], v[18:19] op_sel_hi:[1,0]
	v_pk_mul_f32 v[10:11], v[10:11], v[14:15]
	v_pk_mul_f32 v[14:15], v[16:17], v[18:19] op_sel_hi:[1,0]
	v_pk_mul_f32 v[4:5], v[4:5], v[18:19] op_sel_hi:[1,0]
	v_mul_f32_e32 v16, 0xbfb8aa3b, v14
	v_mul_f32_e32 v17, 0xbfb8aa3b, v15
	v_exp_f32_e32 v16, v16
	v_exp_f32_e32 v17, v17
	v_add_f32_e32 v16, 1.0, v16
	v_add_f32_e32 v17, 1.0, v17
	v_rcp_f32_e32 v16, v16
	v_rcp_f32_e32 v17, v17
	s_nop 0
	v_pk_mul_f32 v[14:15], v[14:15], v[16:17]
	s_nop 0
	v_pk_mul_f32 v[12:13], v[12:13], v[14:15]
	v_mul_f32_e32 v14, 0xbfb8aa3b, v6
	v_mul_f32_e32 v15, 0xbfb8aa3b, v7
	v_exp_f32_e32 v14, v14
	v_exp_f32_e32 v15, v15
	v_add_f32_e32 v14, 1.0, v14
	v_add_f32_e32 v15, 1.0, v15
	v_rcp_f32_e32 v14, v14
	v_rcp_f32_e32 v15, v15
	s_nop 0
	v_pk_mul_f32 v[6:7], v[6:7], v[14:15]
	s_nop 0
	v_pk_mul_f32 v[6:7], v[2:3], v[6:7]
	v_pk_mul_f32 v[2:3], v[8:9], v[18:19] op_sel_hi:[1,0]
	s_nop 0
	v_mul_f32_e32 v8, 0xbfb8aa3b, v2
	v_mul_f32_e32 v9, 0xbfb8aa3b, v3
	v_exp_f32_e32 v8, v8
	v_exp_f32_e32 v9, v9
	v_add_f32_e32 v8, 1.0, v8
	v_add_f32_e32 v9, 1.0, v9
	v_rcp_f32_e32 v8, v8
	v_rcp_f32_e32 v9, v9
	s_nop 0
	v_pk_mul_f32 v[2:3], v[2:3], v[8:9]
	s_nop 0
	v_pk_mul_f32 v[8:9], v[4:5], v[2:3]
	v_cvt_pk_bf16_f32 v4, v6, v7
	v_add_u32_e32 v6, 0xb0, v151
	v_mad_i64_i32 v[6:7], s[24:25], v6, s27, v[114:115]
	v_cvt_pk_bf16_f32 v2, v10, v11
	v_cvt_pk_bf16_f32 v3, v12, v13
	v_cvt_pk_bf16_f32 v5, v8, v9
	v_lshl_add_u64 v[6:7], v[6:7], 0, v[116:117]
	s_mov_b64 s[24:25], -1
	global_store_dwordx4 v[6:7], v[2:5], off
	s_cbranch_vccnz .LBB0_2332
	s_andn2_b64 vcc, exec, s[0:1]
	s_cbranch_vccnz .LBB0_2331
	s_barrier
	s_branch .LBB0_2331

; #define PG8_STAGE(bufoff, gbase, voff) do { _Pragma("unroll") for (int _i = 0; _i < 2; ++_i) \
;         __builtin_amdgcn_global_load_lds((const unsigned*)((const char*)(gbase) + (voff)[_i]), (LAS unsigned*)(lds + (bufoff) + ldsw + _i * 8192), 16, 0, 0); } while (0)
; #define PG8_LDA(dst, b, h) do { _Pragma("unroll") for (int m = 0; m < 4; ++m) _Pragma("unroll") for (int k = 0; k < 2; ++k) dst[m][k] = *(const LAS bf16x8*)(lds + PG8_SA(b, h) + aoff + m * 2048 + k * 1024); } while (0)
; #define PG8_LDB(dst, b, h) do { _Pragma("unroll") for (int n = 0; n < 2; ++n) _Pragma("unroll") for (int k = 0; k < 2; ++k) dst[n][k] = *(const LAS bf16x8*)(lds + PG8_SB(b, h) + boff + n * 2048 + k * 1024); } while (0)
; #define PG8_MMA(ai, bj, At, Bt) do { __builtin_amdgcn_s_setprio(1); _Pragma("unroll") for (int m = 0; m < 4; ++m) _Pragma("unroll") for (int n = 0; n < 2; ++n) _Pragma("unroll") for (int k = 0; k < 2; ++k) \
;         acc[ai][bj][m][n] = __builtin_amdgcn_mfma_f32_16x16x32_bf16(Bt[n][k], At[m][k], acc[ai][bj][m][n], 0, 0, 0); __builtin_amdgcn_s_setprio(0); } while (0)
; template <class Epi, class Sched, bool ALIGN_EPI = GEMM_ALIGN, bool SP2 = GEMM_SP2>
; __device__ __forceinline__ void gemm_phase(lptr lds, const Gemm g, const Sched& S, const Epi& E) {
;     ...
;         const char* nA = has_next ? (const char*)g.A + (size_t)nxt.pm * tstepA + (size_t)nxt.acol * 2 : cA; const char* nB = has_next ? (const char*)g.Bt + (size_t)nxt.pn * tstepB : cB;
;         for (int t = 0; t < nt; t += 2) {
;             const bool last = (t == nt - 2);
;             const char* a1 = cA + (size_t)(t + 1) * kstep;
;             const char* a2 = last ? nA : cA + (size_t)(t + 2) * kstep; const char* b2 = last ? nB : cB + (size_t)(t + 2) * kstep;
;             const char* a3 = a2 + kstep; const char* b3 = b2 + kstep;
;             if constexpr (SP2) {
;             PG8_LDB(B0, 0, 0); PG8_LDB(B1, 0, 1); PG8_SCHED; PG8_LDA(At, 0, 0); PG8_STAGE(PG8_SA(1, 1), a1 + hstepA, voffA);
;             PG8_WAIT_V(8); PG8_WAIT_L(0); PG8_BAR; PG8_MMA(0, 0, At, B0); PG8_MMA(0, 1, At, B1); PG8_BAR; PG8_SCHED;
;             PG8_LDA(At, 0, 1); PG8_STAGE(PG8_SB(0, 0), b2, voffB); PG8_STAGE(PG8_SB(0, 1), b2 + hstepB, voffB); PG8_STAGE(PG8_SA(0, 0), a2, voffA);
;             PG8_WAIT_V(8); PG8_WAIT_L(0); PG8_BAR; PG8_MMA(1, 0, At, B0); PG8_MMA(1, 1, At, B1); PG8_BAR; PG8_SCHED;
.LBB0_2418:
	s_add_u32 s2, s24, 0x100
	s_addc_u32 s3, s25, 0
	s_add_i32 s67, 0, 0x10000
	s_cmp_eq_u32 s66, 40
	s_cselect_b32 s31, s45, s3
	s_cselect_b32 s30, s44, s2
	s_cselect_b32 s29, s47, s65
	s_cselect_b32 s28, s46, s49
	s_add_i32 s68, 0, 0x14000
	v_add_u32_e32 v74, s67, v248
	v_add_u32_e32 v158, s68, v248
	ds_read_b128 v[62:65], v74
	ds_read_b128 v[66:69], v74 offset:1024
	ds_read_b128 v[70:73], v74 offset:2048
	ds_read_b128 v[74:77], v74 offset:3072
	ds_read_b128 v[146:149], v158
	ds_read_b128 v[150:153], v158 offset:1024
	ds_read_b128 v[154:157], v158 offset:2048
	ds_read_b128 v[158:161], v158 offset:3072
	v_lshl_add_u64 v[182:183], s[24:25], 0, v[200:201]
	s_add_i32 m0, s53, 0xc000
	ds_read_b128 v[162:165], v250
	ds_read_b128 v[166:169], v250 offset:1024
	ds_read_b128 v[170:173], v250 offset:2048
	ds_read_b128 v[174:177], v250 offset:3072
	ds_read_b128 v[178:181], v250 offset:4096
	ds_read_b128 v[204:207], v250 offset:5120
	ds_read_b128 v[208:211], v250 offset:6144
	ds_read_b128 v[212:215], v250 offset:7168
	global_load_lds_dwordx4 v[182:183], off
	v_lshl_add_u64 v[182:183], s[24:25], 0, v[202:203]
	s_add_i32 m0, s53, 0xe000
	s_nop 0
	global_load_lds_dwordx4 v[182:183], off
	s_waitcnt vmcnt(8)
	s_waitcnt lgkmcnt(0)
	s_barrier
	s_waitcnt lgkmcnt(0)
	v_mfma_f32_16x16x32_bf16 v[142:145], v[62:65], v[162:165], v[142:145]
	v_mfma_f32_16x16x32_bf16 v[138:141], v[70:73], v[162:165], v[138:141]
	v_mfma_f32_16x16x32_bf16 v[134:137], v[62:65], v[170:173], v[134:137]
	v_mfma_f32_16x16x32_bf16 v[122:125], v[70:73], v[170:173], v[122:125]
	v_mfma_f32_16x16x32_bf16 v[110:113], v[62:65], v[178:181], v[110:113]
	v_mfma_f32_16x16x32_bf16 v[106:109], v[70:73], v[178:181], v[106:109]
	v_mfma_f32_16x16x32_bf16 v[102:105], v[62:65], v[208:211], v[102:105]
	v_mfma_f32_16x16x32_bf16 v[90:93], v[70:73], v[208:211], v[90:93]
	v_mfma_f32_16x16x32_bf16 v[142:145], v[66:69], v[166:169], v[142:145]
	v_mfma_f32_16x16x32_bf16 v[138:141], v[74:77], v[166:169], v[138:141]
	v_mfma_f32_16x16x32_bf16 v[134:137], v[66:69], v[174:177], v[134:137]
	v_mfma_f32_16x16x32_bf16 v[122:125], v[74:77], v[174:177], v[122:125]
	v_mfma_f32_16x16x32_bf16 v[110:113], v[66:69], v[204:207], v[110:113]
	v_mfma_f32_16x16x32_bf16 v[106:109], v[74:77], v[204:207], v[106:109]
	v_mfma_f32_16x16x32_bf16 v[102:105], v[66:69], v[212:215], v[102:105]
	v_mfma_f32_16x16x32_bf16 v[90:93], v[74:77], v[212:215], v[90:93]
	v_mfma_f32_16x16x32_bf16 v[130:133], v[146:149], v[162:165], v[130:133]
	v_mfma_f32_16x16x32_bf16 v[126:129], v[154:157], v[162:165], v[126:129]
	v_mfma_f32_16x16x32_bf16 v[118:121], v[146:149], v[170:173], v[118:121]
	v_mfma_f32_16x16x32_bf16 v[114:117], v[154:157], v[170:173], v[114:117]
	v_mfma_f32_16x16x32_bf16 v[98:101], v[146:149], v[178:181], v[98:101]
	v_mfma_f32_16x16x32_bf16 v[94:97], v[154:157], v[178:181], v[94:97]
	v_mfma_f32_16x16x32_bf16 v[86:89], v[146:149], v[208:211], v[86:89]
	v_mfma_f32_16x16x32_bf16 v[82:85], v[154:157], v[208:211], v[82:85]
	v_mfma_f32_16x16x32_bf16 v[130:133], v[150:153], v[166:169], v[130:133]
	v_mfma_f32_16x16x32_bf16 v[126:129], v[158:161], v[166:169], v[126:129]
	v_mfma_f32_16x16x32_bf16 v[118:121], v[150:153], v[174:177], v[118:121]
	v_mfma_f32_16x16x32_bf16 v[114:117], v[158:161], v[174:177], v[114:117]
	v_mfma_f32_16x16x32_bf16 v[98:101], v[150:153], v[204:207], v[98:101]
	v_mfma_f32_16x16x32_bf16 v[94:97], v[158:161], v[204:207], v[94:97]
	v_mfma_f32_16x16x32_bf16 v[86:89], v[150:153], v[212:215], v[86:89]
	v_mfma_f32_16x16x32_bf16 v[82:85], v[158:161], v[212:215], v[82:85]
	s_barrier
	s_add_i32 s24, s67, s52
	v_lshl_add_u64 v[182:183], s[28:29], 0, v[0:1]
	s_mov_b32 m0, s24
	ds_read_b128 v[162:165], v250 offset:16384
	ds_read_b128 v[166:169], v250 offset:17408
	ds_read_b128 v[170:173], v250 offset:18432
	ds_read_b128 v[174:177], v250 offset:19456
	ds_read_b128 v[178:181], v250 offset:20480
	ds_read_b128 v[204:207], v250 offset:21504
	ds_read_b128 v[208:211], v250 offset:22528
	ds_read_b128 v[212:215], v250 offset:23552
	global_load_lds_dwordx4 v[182:183], off
	s_add_i32 m0, s24, 0x2000
	s_add_u32 s24, s28, 0xb0000
	v_lshl_add_u64 v[220:221], s[28:29], 0, v[198:199]
	s_addc_u32 s25, s29, 0
	s_add_i32 s67, s68, s52
	global_load_lds_dwordx4 v[220:221], off
	v_lshl_add_u64 v[222:223], s[24:25], 0, v[0:1]
	s_mov_b32 m0, s67
	v_lshl_add_u64 v[224:225], s[30:31], 0, v[198:199]
	global_load_lds_dwordx4 v[222:223], off
	v_lshl_add_u64 v[222:223], s[24:25], 0, v[198:199]
	s_add_i32 m0, s67, 0x2000
	s_nop 0
	global_load_lds_dwordx4 v[222:223], off
	v_lshl_add_u64 v[222:223], s[30:31], 0, v[0:1]
	s_mov_b32 m0, s53
	s_nop 0
	global_load_lds_dwordx4 v[222:223], off
	s_mov_b32 m0, s54
	s_nop 0
	global_load_lds_dwordx4 v[224:225], off
	s_waitcnt vmcnt(8)
	s_waitcnt lgkmcnt(0)
	s_barrier
; #define PG8_STAGE(bufoff, gbase, voff) do { _Pragma("unroll") for (int _i = 0; _i < 2; ++_i) \
;         __builtin_amdgcn_global_load_lds((const unsigned*)((const char*)(gbase) + (voff)[_i]), (LAS unsigned*)(lds + (bufoff) + ldsw + _i * 8192), 16, 0, 0); } while (0)
; #define PG8_LDA(dst, b, h) do { _Pragma("unroll") for (int m = 0; m < 4; ++m) _Pragma("unroll") for (int k = 0; k < 2; ++k) dst[m][k] = *(const LAS bf16x8*)(lds + PG8_SA(b, h) + aoff + m * 2048 + k * 1024); } while (0)
; #define PG8_LDB(dst, b, h) do { _Pragma("unroll") for (int n = 0; n < 2; ++n) _Pragma("unroll") for (int k = 0; k < 2; ++k) dst[n][k] = *(const LAS bf16x8*)(lds + PG8_SB(b, h) + boff + n * 2048 + k * 1024); } while (0)
; #define PG8_MMA(ai, bj, At, Bt) do { __builtin_amdgcn_s_setprio(1); _Pragma("unroll") for (int m = 0; m < 4; ++m) _Pragma("unroll") for (int n = 0; n < 2; ++n) _Pragma("unroll") for (int k = 0; k < 2; ++k) \
;         acc[ai][bj][m][n] = __builtin_amdgcn_mfma_f32_16x16x32_bf16(Bt[n][k], At[m][k], acc[ai][bj][m][n], 0, 0, 0); __builtin_amdgcn_s_setprio(0); } while (0)
; #define PG8_WAIT_V(n) asm volatile("s_waitcnt vmcnt(" #n ")" ::: "memory")
; #define PG8_WAIT_L(n) asm volatile("s_waitcnt lgkmcnt(" #n ")" ::: "memory")
; #define PG8_BAR __builtin_amdgcn_s_barrier()
; #define PG8_SCHED __builtin_amdgcn_sched_barrier(0)
; template <class Epi, class Sched, bool ALIGN_EPI = GEMM_ALIGN, bool SP2 = GEMM_SP2>
; __device__ __forceinline__ void gemm_phase(lptr lds, const Gemm g, const Sched& S, const Epi& E) {
;     ...
;             PG8_WAIT_V(8); PG8_WAIT_L(0); PG8_BAR; PG8_MMA(1, 0, At, B0); PG8_MMA(1, 1, At, B1); PG8_BAR; PG8_SCHED;
;             PG8_LDB(B0, 1, 0); PG8_LDB(B1, 1, 1); PG8_SCHED; PG8_LDA(At, 1, 0); PG8_STAGE(PG8_SA(0, 1), a2 + hstepA, voffA);
;             PG8_WAIT_V(8); PG8_WAIT_L(0); PG8_BAR; PG8_MMA(0, 0, At, B0); PG8_MMA(0, 1, At, B1); PG8_BAR; PG8_SCHED;
;             PG8_LDA(At, 1, 1); PG8_STAGE(PG8_SB(1, 0), b3, voffB); PG8_STAGE(PG8_SB(1, 1), b3 + hstepB, voffB); PG8_STAGE(PG8_SA(1, 0), a3, voffA);
	s_waitcnt lgkmcnt(0)
	v_mfma_f32_16x16x32_bf16 v[78:81], v[62:65], v[162:165], v[78:81]
	v_mfma_f32_16x16x32_bf16 v[58:61], v[70:73], v[162:165], v[58:61]
	v_mfma_f32_16x16x32_bf16 v[54:57], v[62:65], v[170:173], v[54:57]
	v_mfma_f32_16x16x32_bf16 v[42:45], v[70:73], v[170:173], v[42:45]
	v_mfma_f32_16x16x32_bf16 v[30:33], v[62:65], v[178:181], v[30:33]
	v_mfma_f32_16x16x32_bf16 v[26:29], v[70:73], v[178:181], v[26:29]
	v_mfma_f32_16x16x32_bf16 v[22:25], v[62:65], v[208:211], v[22:25]
	v_mfma_f32_16x16x32_bf16 v[10:13], v[70:73], v[208:211], v[10:13]
	v_mfma_f32_16x16x32_bf16 v[78:81], v[66:69], v[166:169], v[78:81]
	v_mfma_f32_16x16x32_bf16 v[58:61], v[74:77], v[166:169], v[58:61]
	v_mfma_f32_16x16x32_bf16 v[54:57], v[66:69], v[174:177], v[54:57]
	v_mfma_f32_16x16x32_bf16 v[42:45], v[74:77], v[174:177], v[42:45]
	v_mfma_f32_16x16x32_bf16 v[30:33], v[66:69], v[204:207], v[30:33]
	v_mfma_f32_16x16x32_bf16 v[26:29], v[74:77], v[204:207], v[26:29]
	v_mfma_f32_16x16x32_bf16 v[22:25], v[66:69], v[212:215], v[22:25]
	v_mfma_f32_16x16x32_bf16 v[10:13], v[74:77], v[212:215], v[10:13]
	v_mfma_f32_16x16x32_bf16 v[50:53], v[146:149], v[162:165], v[50:53]
	v_mfma_f32_16x16x32_bf16 v[46:49], v[154:157], v[162:165], v[46:49]
	v_mfma_f32_16x16x32_bf16 v[38:41], v[146:149], v[170:173], v[38:41]
	v_mfma_f32_16x16x32_bf16 v[34:37], v[154:157], v[170:173], v[34:37]
	v_mfma_f32_16x16x32_bf16 v[18:21], v[146:149], v[178:181], v[18:21]
	v_mfma_f32_16x16x32_bf16 v[14:17], v[154:157], v[178:181], v[14:17]
	v_mfma_f32_16x16x32_bf16 v[6:9], v[146:149], v[208:211], v[6:9]
	v_mfma_f32_16x16x32_bf16 v[2:5], v[154:157], v[208:211], v[2:5]
	v_mfma_f32_16x16x32_bf16 v[50:53], v[150:153], v[166:169], v[50:53]
	v_mfma_f32_16x16x32_bf16 v[46:49], v[158:161], v[166:169], v[46:49]
	v_mfma_f32_16x16x32_bf16 v[38:41], v[150:153], v[174:177], v[38:41]
	v_mfma_f32_16x16x32_bf16 v[34:37], v[158:161], v[174:177], v[34:37]
	v_mfma_f32_16x16x32_bf16 v[18:21], v[150:153], v[204:207], v[18:21]
	v_mfma_f32_16x16x32_bf16 v[14:17], v[158:161], v[204:207], v[14:17]
	v_mfma_f32_16x16x32_bf16 v[6:9], v[150:153], v[212:215], v[6:9]
	v_mfma_f32_16x16x32_bf16 v[2:5], v[158:161], v[212:215], v[2:5]
	s_barrier
	s_add_i32 s67, 0, 0x18000
	s_add_i32 s68, 0, 0x1c000
	v_add_u32_e32 v74, s67, v248
	v_add_u32_e32 v158, s68, v248
	ds_read_b128 v[62:65], v74
	ds_read_b128 v[66:69], v74 offset:1024
	ds_read_b128 v[70:73], v74 offset:2048
	ds_read_b128 v[74:77], v74 offset:3072
	ds_read_b128 v[146:149], v158
	ds_read_b128 v[150:153], v158 offset:1024
	ds_read_b128 v[154:157], v158 offset:2048
	ds_read_b128 v[158:161], v158 offset:3072
	s_add_u32 s24, s30, 0xb0000
	s_addc_u32 s25, s31, 0
	s_mov_b32 m0, s55
	v_lshl_add_u64 v[226:227], s[24:25], 0, v[0:1]
	ds_read_b128 v[162:165], v250 offset:32768
	ds_read_b128 v[166:169], v250 offset:33792
	ds_read_b128 v[170:173], v250 offset:34816
	ds_read_b128 v[174:177], v250 offset:35840
	ds_read_b128 v[178:181], v250 offset:36864
	ds_read_b128 v[204:207], v250 offset:37888
	ds_read_b128 v[208:211], v250 offset:38912
	ds_read_b128 v[212:215], v250 offset:39936
	global_load_lds_dwordx4 v[226:227], off
	v_lshl_add_u64 v[226:227], s[24:25], 0, v[198:199]
	s_mov_b32 m0, s56
	s_nop 0
	global_load_lds_dwordx4 v[226:227], off
	s_waitcnt vmcnt(8)
	s_waitcnt lgkmcnt(0)
	s_barrier
	s_waitcnt lgkmcnt(0)
	v_mfma_f32_16x16x32_bf16 v[142:145], v[62:65], v[162:165], v[142:145]
	v_mfma_f32_16x16x32_bf16 v[138:141], v[70:73], v[162:165], v[138:141]
	v_mfma_f32_16x16x32_bf16 v[134:137], v[62:65], v[170:173], v[134:137]
	v_mfma_f32_16x16x32_bf16 v[122:125], v[70:73], v[170:173], v[122:125]
	v_mfma_f32_16x16x32_bf16 v[110:113], v[62:65], v[178:181], v[110:113]
	v_mfma_f32_16x16x32_bf16 v[106:109], v[70:73], v[178:181], v[106:109]
	v_mfma_f32_16x16x32_bf16 v[102:105], v[62:65], v[208:211], v[102:105]
	v_mfma_f32_16x16x32_bf16 v[90:93], v[70:73], v[208:211], v[90:93]
	v_mfma_f32_16x16x32_bf16 v[142:145], v[66:69], v[166:169], v[142:145]
	v_mfma_f32_16x16x32_bf16 v[138:141], v[74:77], v[166:169], v[138:141]
	v_mfma_f32_16x16x32_bf16 v[134:137], v[66:69], v[174:177], v[134:137]
	v_mfma_f32_16x16x32_bf16 v[122:125], v[74:77], v[174:177], v[122:125]
	v_mfma_f32_16x16x32_bf16 v[110:113], v[66:69], v[204:207], v[110:113]
	v_mfma_f32_16x16x32_bf16 v[106:109], v[74:77], v[204:207], v[106:109]
	v_mfma_f32_16x16x32_bf16 v[102:105], v[66:69], v[212:215], v[102:105]
	v_mfma_f32_16x16x32_bf16 v[90:93], v[74:77], v[212:215], v[90:93]
	v_mfma_f32_16x16x32_bf16 v[130:133], v[146:149], v[162:165], v[130:133]
	v_mfma_f32_16x16x32_bf16 v[126:129], v[154:157], v[162:165], v[126:129]
	v_mfma_f32_16x16x32_bf16 v[118:121], v[146:149], v[170:173], v[118:121]
	v_mfma_f32_16x16x32_bf16 v[114:117], v[154:157], v[170:173], v[114:117]
	v_mfma_f32_16x16x32_bf16 v[98:101], v[146:149], v[178:181], v[98:101]
	v_mfma_f32_16x16x32_bf16 v[94:97], v[154:157], v[178:181], v[94:97]
	v_mfma_f32_16x16x32_bf16 v[86:89], v[146:149], v[208:211], v[86:89]
	v_mfma_f32_16x16x32_bf16 v[82:85], v[154:157], v[208:211], v[82:85]
	v_mfma_f32_16x16x32_bf16 v[130:133], v[150:153], v[166:169], v[130:133]
	v_mfma_f32_16x16x32_bf16 v[126:129], v[158:161], v[166:169], v[126:129]
	v_mfma_f32_16x16x32_bf16 v[118:121], v[150:153], v[174:177], v[118:121]
	v_mfma_f32_16x16x32_bf16 v[114:117], v[158:161], v[174:177], v[114:117]
	v_mfma_f32_16x16x32_bf16 v[98:101], v[150:153], v[204:207], v[98:101]
	v_mfma_f32_16x16x32_bf16 v[94:97], v[158:161], v[204:207], v[94:97]
	v_mfma_f32_16x16x32_bf16 v[86:89], v[150:153], v[212:215], v[86:89]
	v_mfma_f32_16x16x32_bf16 v[82:85], v[158:161], v[212:215], v[82:85]
	s_barrier
; #define PG8_STAGE(bufoff, gbase, voff) do { _Pragma("unroll") for (int _i = 0; _i < 2; ++_i) \
;         __builtin_amdgcn_global_load_lds((const unsigned*)((const char*)(gbase) + (voff)[_i]), (LAS unsigned*)(lds + (bufoff) + ldsw + _i * 8192), 16, 0, 0); } while (0)
; #define PG8_LDA(dst, b, h) do { _Pragma("unroll") for (int m = 0; m < 4; ++m) _Pragma("unroll") for (int k = 0; k < 2; ++k) dst[m][k] = *(const LAS bf16x8*)(lds + PG8_SA(b, h) + aoff + m * 2048 + k * 1024); } while (0)
; #define PG8_MMA(ai, bj, At, Bt) do { __builtin_amdgcn_s_setprio(1); _Pragma("unroll") for (int m = 0; m < 4; ++m) _Pragma("unroll") for (int n = 0; n < 2; ++n) _Pragma("unroll") for (int k = 0; k < 2; ++k) \
;         acc[ai][bj][m][n] = __builtin_amdgcn_mfma_f32_16x16x32_bf16(Bt[n][k], At[m][k], acc[ai][bj][m][n], 0, 0, 0); __builtin_amdgcn_s_setprio(0); } while (0)
; #define PG8_WAIT_V(n) asm volatile("s_waitcnt vmcnt(" #n ")" ::: "memory")
; #define PG8_WAIT_L(n) asm volatile("s_waitcnt lgkmcnt(" #n ")" ::: "memory")
; #define PG8_BAR __builtin_amdgcn_s_barrier()
; #define PG8_SCHED __builtin_amdgcn_sched_barrier(0)
; template <class Epi, class Sched, bool ALIGN_EPI = GEMM_ALIGN, bool SP2 = GEMM_SP2>
; __device__ __forceinline__ void gemm_phase(lptr lds, const Gemm g, const Sched& S, const Epi& E) {
;     ...
;             PG8_LDA(At, 1, 1); PG8_STAGE(PG8_SB(1, 0), b3, voffB); PG8_STAGE(PG8_SB(1, 1), b3 + hstepB, voffB); PG8_STAGE(PG8_SA(1, 0), a3, voffA);
;             PG8_WAIT_V(8); PG8_WAIT_L(0); PG8_BAR; PG8_MMA(1, 0, At, B0); PG8_MMA(1, 1, At, B1); PG8_BAR; PG8_SCHED;
;     ...
;         if constexpr (ALIGN_EPI) { if (wr == 0) PG8_BAR; }
	s_add_i32 s24, s67, s52
	v_lshl_add_u64 v[182:183], v[182:183], 0, s[6:7]
	s_mov_b32 m0, s24
	ds_read_b128 v[162:165], v250 offset:49152
	ds_read_b128 v[166:169], v250 offset:50176
	ds_read_b128 v[170:173], v250 offset:51200
	ds_read_b128 v[174:177], v250 offset:52224
	ds_read_b128 v[178:181], v250 offset:53248
	ds_read_b128 v[204:207], v250 offset:54272
	ds_read_b128 v[208:211], v250 offset:55296
	ds_read_b128 v[212:215], v250 offset:56320
	global_load_lds_dwordx4 v[182:183], off
	s_add_i32 m0, s24, 0x2000
	s_add_u32 s24, s28, 0xb0080
	v_lshl_add_u64 v[182:183], v[220:221], 0, s[6:7]
	s_addc_u32 s25, s29, 0
	s_add_i32 s28, s68, s52
	global_load_lds_dwordx4 v[182:183], off
	v_lshl_add_u64 v[182:183], s[24:25], 0, v[0:1]
	s_mov_b32 m0, s28
	s_nop 0
	global_load_lds_dwordx4 v[182:183], off
	v_lshl_add_u64 v[182:183], s[24:25], 0, v[198:199]
	s_add_i32 m0, s28, 0x2000
	s_nop 0
	global_load_lds_dwordx4 v[182:183], off
	v_lshl_add_u64 v[182:183], v[222:223], 0, s[6:7]
	s_mov_b32 m0, s58
	s_nop 0
	global_load_lds_dwordx4 v[182:183], off
	v_lshl_add_u64 v[182:183], v[224:225], 0, s[6:7]
	s_mov_b32 m0, s59
	s_nop 0
	global_load_lds_dwordx4 v[182:183], off
	s_waitcnt vmcnt(8)
	s_waitcnt lgkmcnt(0)
	s_barrier
	s_waitcnt lgkmcnt(0)
	v_mfma_f32_16x16x32_bf16 v[78:81], v[62:65], v[162:165], v[78:81]
	v_mfma_f32_16x16x32_bf16 v[58:61], v[70:73], v[162:165], v[58:61]
	v_mfma_f32_16x16x32_bf16 v[54:57], v[62:65], v[170:173], v[54:57]
	v_mfma_f32_16x16x32_bf16 v[42:45], v[70:73], v[170:173], v[42:45]
	v_mfma_f32_16x16x32_bf16 v[30:33], v[62:65], v[178:181], v[30:33]
	v_mfma_f32_16x16x32_bf16 v[26:29], v[70:73], v[178:181], v[26:29]
	v_mfma_f32_16x16x32_bf16 v[22:25], v[62:65], v[208:211], v[22:25]
	v_mfma_f32_16x16x32_bf16 v[10:13], v[70:73], v[208:211], v[10:13]
	v_mfma_f32_16x16x32_bf16 v[78:81], v[66:69], v[166:169], v[78:81]
	v_mfma_f32_16x16x32_bf16 v[58:61], v[74:77], v[166:169], v[58:61]
	v_mfma_f32_16x16x32_bf16 v[54:57], v[66:69], v[174:177], v[54:57]
	v_mfma_f32_16x16x32_bf16 v[42:45], v[74:77], v[174:177], v[42:45]
	v_mfma_f32_16x16x32_bf16 v[30:33], v[66:69], v[204:207], v[30:33]
	v_mfma_f32_16x16x32_bf16 v[26:29], v[74:77], v[204:207], v[26:29]
	v_mfma_f32_16x16x32_bf16 v[22:25], v[66:69], v[212:215], v[22:25]
	v_mfma_f32_16x16x32_bf16 v[10:13], v[74:77], v[212:215], v[10:13]
	v_mfma_f32_16x16x32_bf16 v[50:53], v[146:149], v[162:165], v[50:53]
	v_mfma_f32_16x16x32_bf16 v[46:49], v[154:157], v[162:165], v[46:49]
	v_mfma_f32_16x16x32_bf16 v[38:41], v[146:149], v[170:173], v[38:41]
	v_mfma_f32_16x16x32_bf16 v[34:37], v[154:157], v[170:173], v[34:37]
	v_mfma_f32_16x16x32_bf16 v[18:21], v[146:149], v[178:181], v[18:21]
	v_mfma_f32_16x16x32_bf16 v[14:17], v[154:157], v[178:181], v[14:17]
	v_mfma_f32_16x16x32_bf16 v[6:9], v[146:149], v[208:211], v[6:9]
	v_mfma_f32_16x16x32_bf16 v[2:5], v[154:157], v[208:211], v[2:5]
	v_mfma_f32_16x16x32_bf16 v[50:53], v[150:153], v[166:169], v[50:53]
	v_mfma_f32_16x16x32_bf16 v[46:49], v[158:161], v[166:169], v[46:49]
	v_mfma_f32_16x16x32_bf16 v[38:41], v[150:153], v[174:177], v[38:41]
	v_mfma_f32_16x16x32_bf16 v[34:37], v[158:161], v[174:177], v[34:37]
	v_mfma_f32_16x16x32_bf16 v[18:21], v[150:153], v[204:207], v[18:21]
	v_mfma_f32_16x16x32_bf16 v[14:17], v[158:161], v[204:207], v[14:17]
	v_mfma_f32_16x16x32_bf16 v[6:9], v[150:153], v[212:215], v[6:9]
	v_mfma_f32_16x16x32_bf16 v[2:5], v[158:161], v[212:215], v[2:5]
	s_barrier
	s_add_i32 s66, s66, 2
	s_add_u32 s49, s49, 0x100
	s_addc_u32 s65, s65, 0
	s_cmp_gt_u32 s66, 41
	s_mov_b64 s[24:25], s[2:3]
	s_cbranch_scc0 .LBB0_2418
	s_and_b64 vcc, exec, s[42:43]
	s_cbranch_vccz .LBB0_2421
	s_barrier
; __device__ __forceinline__ unsigned pk2(float lo, float hi) { const f32x2 v = {lo, hi}; const bf16x2_t b = __builtin_convertvector(v, bf16x2_t); return __builtin_bit_cast(unsigned, b); }
;     __device__ __forceinline__ void operator()(const f32x4 (&acc)[2][2][4][2], const Unit& u, int wr, int wc, int fr, int fq) const {
;         const int row0 = u.pm * BM + wr * 64 + fr, col0 = u.pn * BM + wc * 32 + 4 * fq;
;         f32x4 gv[2][2];
; #pragma unroll
;         for (int bj = 0; bj < 2; ++bj)
; #pragma unroll
;             for (int n = 0; n < 2; ++n) gv[bj][n] = *(const f32x4*)(gnext + col0 + bj * HALF + n * 16);
; #pragma unroll
;         for (int ai = 0; ai < 2; ++ai)
; #pragma unroll
;             for (int mp = 0; mp < 2; ++mp) { f32x4 xv[2][2][2];
; #pragma unroll
;                 for (int mm = 0; mm < 2; ++mm)
; #pragma unroll
;                     for (int bj = 0; bj < 2; ++bj)
; #pragma unroll
;                         for (int n = 0; n < 2; ++n) xv[mm][bj][n] = *(const f32x4*)(xin + (size_t)(row0 + ai * HALF + (mp * 2 + mm) * 16) * DM + col0 + bj * HALF + n * 16);
; #pragma unroll
;                 for (int mm = 0; mm < 2; ++mm) { const int m = mp * 2 + mm; const int row = row0 + ai * HALF + m * 16; const size_t off = (size_t)row * DM + col0; float ss = 0.f;
; #pragma unroll
;                     for (int bj = 0; bj < 2; ++bj)
; #pragma unroll
;                         for (int n = 0; n < 2; ++n) { const f32x4 v = xv[mm][bj][n] + acc[ai][bj][m][n] * scale; *(f32x4*)(out + off + bj * HALF + n * 16) = v;
;                             if (xq) { ss += (v[0] * v[0] + v[1] * v[1]) + (v[2] * v[2] + v[3] * v[3]); const f32x4 q = v * gv[bj][n]; u32x2 w; w.x = pk2(q[0], q[1]); w.y = pk2(q[2], q[3]); *(u32x2*)(xq + off + bj * HALF + n * 16) = w; } }
;                     if (xq) { ss += __shfl_xor(ss, 16); ss += __shfl_xor(ss, 32); if (fq == 0) rowsq[(size_t)row * 16 + u.pn * 4 + wc] = ss; } } }
.LBB0_2421:
	s_setprio 0
	v_lshl_or_b32 v204, s34, 8, v249
	v_ashrrev_i32_e32 v205, 31, v204
	v_lshl_add_u32 v208, s48, 8, v197
	v_lshlrev_b64 v[146:147], 2, v[204:205]
	v_ashrrev_i32_e32 v209, 31, v208
	v_or_b32_e32 v212, 16, v208
	v_lshl_add_u64 v[62:63], s[40:41], 0, v[146:147]
	v_lshl_add_u64 v[206:207], s[86:87], 0, v[146:147]
	v_lshlrev_b64 v[146:147], 12, v[208:209]
	v_ashrrev_i32_e32 v213, 31, v212
	v_lshl_add_u64 v[214:215], v[206:207], 0, v[146:147]
	v_lshlrev_b64 v[146:147], 12, v[212:213]
	v_lshl_add_u64 v[210:211], v[206:207], 0, v[146:147]
	global_load_dwordx4 v[74:77], v[62:63], off
	global_load_dwordx4 v[70:73], v[62:63], off offset:64
	global_load_dwordx4 v[66:69], v[62:63], off offset:512
	s_nop 0
	global_load_dwordx4 v[62:65], v[62:63], off offset:576
	s_nop 0
	global_load_dwordx4 v[174:177], v[214:215], off
	global_load_dwordx4 v[170:173], v[214:215], off offset:64
	global_load_dwordx4 v[166:169], v[214:215], off offset:512
	global_load_dwordx4 v[162:165], v[214:215], off offset:576
	global_load_dwordx4 v[158:161], v[210:211], off
	global_load_dwordx4 v[154:157], v[210:211], off offset:64
	global_load_dwordx4 v[150:153], v[210:211], off offset:512
	global_load_dwordx4 v[146:149], v[210:211], off offset:576
	s_lshl_b32 s48, s34, 2
	v_cndmask_b32_e64 v178, 0, 1, s[26:27]
	s_mov_b64 s[24:25], -1
	s_ashr_i32 s49, s48, 31
	v_cmp_ne_u32_e64 s[2:3], 1, v178
	s_andn2_b64 vcc, exec, s[26:27]
	s_waitcnt vmcnt(0)
	v_pk_fma_f32 v[182:183], v[144:145], 0.5, v[176:177] op_sel_hi:[1,0,1]
	v_pk_fma_f32 v[180:181], v[142:143], 0.5, v[174:175] op_sel_hi:[1,0,1]
	v_pk_fma_f32 v[178:179], v[138:139], 0.5, v[170:171] op_sel_hi:[1,0,1]
	v_pk_fma_f32 v[174:175], v[130:131], 0.5, v[166:167] op_sel_hi:[1,0,1]
	v_pk_fma_f32 v[142:143], v[126:127], 0.5, v[162:163] op_sel_hi:[1,0,1]
	global_store_dwordx4 v[214:215], v[180:183], off
	s_cbranch_vccnz .LBB0_2425
	v_mul_f32_e32 v130, v181, v181
	v_mul_f32_e32 v131, v183, v183
	v_fmac_f32_e32 v130, v180, v180
	v_fmac_f32_e32 v131, v182, v182
	v_add_f32_e32 v144, v130, v131
	v_pk_mul_f32 v[130:131], v[76:77], v[182:183]
	v_pk_mul_f32 v[138:139], v[74:75], v[180:181]
	v_pk_fma_f32 v[180:181], v[140:141], 0.5, v[172:173] op_sel_hi:[1,0,1]
	v_lshlrev_b64 v[126:127], 10, v[208:209]
	v_cvt_pk_bf16_f32 v138, v138, v139
	v_cvt_pk_bf16_f32 v139, v130, v131
	v_readlane_b32 s24, v251, 32
	v_mul_f32_e32 v130, v179, v179
	v_mul_f32_e32 v131, v181, v181
	v_lshl_add_u64 v[126:127], v[126:127], 0, v[204:205]
	v_readlane_b32 s25, v251, 33
	v_fmac_f32_e32 v130, v178, v178
	v_fmac_f32_e32 v131, v180, v180
	v_lshl_add_u64 v[126:127], v[126:127], 1, s[24:25]
	v_add_f32_e32 v130, v130, v131
	global_store_dwordx2 v[126:127], v[138:139], off
	v_add_f32_e32 v144, v144, v130
	v_pk_mul_f32 v[130:131], v[72:73], v[180:181]
	v_pk_mul_f32 v[138:139], v[70:71], v[178:179]
	v_pk_fma_f32 v[176:177], v[132:133], 0.5, v[168:169] op_sel_hi:[1,0,1]
	v_cvt_pk_bf16_f32 v138, v138, v139
	v_cvt_pk_bf16_f32 v139, v130, v131
	v_mul_f32_e32 v130, v175, v175
	v_mul_f32_e32 v131, v177, v177
	v_fmac_f32_e32 v130, v174, v174
	v_fmac_f32_e32 v131, v176, v176
	v_add_f32_e32 v130, v130, v131
	global_store_dwordx4 v[214:215], v[178:181], off offset:64
	global_store_dwordx2 v[126:127], v[138:139], off offset:32
	v_add_f32_e32 v162, v144, v130
	v_pk_mul_f32 v[130:131], v[68:69], v[176:177]
	v_pk_mul_f32 v[138:139], v[66:67], v[174:175]
	v_pk_fma_f32 v[144:145], v[128:129], 0.5, v[164:165] op_sel_hi:[1,0,1]
	v_cvt_pk_bf16_f32 v138, v138, v139
	v_cvt_pk_bf16_f32 v139, v130, v131
	global_store_dwordx4 v[214:215], v[174:177], off offset:512
	global_store_dwordx2 v[126:127], v[138:139], off offset:256
	v_pk_mul_f32 v[130:131], v[64:65], v[144:145]
	v_pk_mul_f32 v[138:139], v[62:63], v[142:143]
	global_store_dwordx4 v[214:215], v[142:145], off offset:576
	v_cvt_pk_bf16_f32 v138, v138, v139
	v_cvt_pk_bf16_f32 v139, v130, v131
	global_store_dwordx2 v[126:127], v[138:139], off offset:288
	v_mul_f32_e32 v126, v143, v143
	v_mul_f32_e32 v127, v145, v145
	v_fmac_f32_e32 v126, v142, v142
	v_fmac_f32_e32 v127, v144, v144
	v_and_b32_e32 v130, 64, v234
	v_add_f32_e32 v126, v126, v127
	v_xor_b32_e32 v127, 16, v234
	v_add_u32_e32 v130, 64, v130
	v_cmp_lt_i32_e32 vcc, v127, v130
	v_add_f32_e32 v126, v162, v126
	s_nop 0
	v_cndmask_b32_e32 v127, v234, v127, vcc
	v_lshlrev_b32_e32 v127, 2, v127
	ds_bpermute_b32 v127, v127, v126
	s_waitcnt lgkmcnt(0)
	v_add_f32_e32 v126, v126, v127
	v_xor_b32_e32 v127, 32, v234
	v_cmp_lt_i32_e32 vcc, v127, v130
	s_nop 1
	v_cndmask_b32_e32 v127, v234, v127, vcc
	v_lshlrev_b32_e32 v127, 2, v127
	ds_bpermute_b32 v127, v127, v126
	s_and_saveexec_b64 s[24:25], s[36:37]
	s_cbranch_execz .LBB0_2424
	v_readlane_b32 s28, v251, 40
	v_lshlrev_b64 v[130:131], 6, v[208:209]
	v_readlane_b32 s29, v251, 41
	s_lshl_b32 s34, s57, 2
	s_waitcnt lgkmcnt(0)
	v_add_f32_e32 v126, v126, v127
	v_lshl_add_u64 v[130:131], s[28:29], 0, v[130:131]
	v_lshl_add_u64 v[130:131], s[48:49], 2, v[130:131]
	v_lshl_add_u64 v[130:131], v[130:131], 0, s[34:35]
	global_store_dword v[130:131], v126, off
